# c26: c16 + register-bank shift of the second MFMA input group (+2 registers) in all 13 K-loops; displaced registers parked in v252-255 across each loop
# baseline (speedup 1.0000x reference)
.LBB0_472:
	s_ashr_i32 s13, s12, 31
	s_lshl_b64 s[14:15], s[12:13], 15
	s_add_u32 s14, s28, s14
	s_addc_u32 s15, s29, s15
	s_and_b64 s[16:17], s[2:3], exec
	s_cselect_b32 s13, s15, s23
	s_cselect_b32 s76, s14, s22
	s_ashr_i32 s11, s10, 31
	s_lshl_b64 s[16:17], s[10:11], 15
	s_add_u32 s16, s30, s16
	s_addc_u32 s17, s31, s17
	s_and_b64 s[24:25], s[2:3], exec
	s_cselect_b32 s11, s17, s21
	s_cselect_b32 s77, s16, s20
	s_add_u32 s78, s20, 0x80000
	s_addc_u32 s79, s21, 0
	s_add_u32 s20, s22, 0x204000
	s_addc_u32 s21, s23, 0
	s_add_u32 s80, s22, 0x400000
	s_addc_u32 s81, s23, 0
	s_mov_b32 s82, -2
	s_waitcnt vmcnt(25)
	s_waitcnt vmcnt(24)
	s_waitcnt vmcnt(23)
	s_waitcnt vmcnt(22)
	s_waitcnt vmcnt(21)
	s_waitcnt vmcnt(20)
	s_waitcnt vmcnt(15)
	s_waitcnt vmcnt(14)
	s_waitcnt vmcnt(13)
	s_waitcnt vmcnt(12)
	s_waitcnt vmcnt(7)
	s_waitcnt vmcnt(6)
	s_waitcnt vmcnt(5)
	s_waitcnt vmcnt(4)
	s_waitcnt vmcnt(3)
	s_waitcnt vmcnt(2)
	s_waitcnt vmcnt(1)
	s_waitcnt vmcnt(0)
	v_mov_b32_e32 v252, v210
	v_mov_b32_e32 v253, v211
	ds_read_b128 v[134:137], v161
	ds_read_b128 v[138:141], v161 offset:1024
	ds_read_b128 v[142:145], v161 offset:2048
	ds_read_b128 v[146:149], v161 offset:3072
	ds_read_b128 v[150:153], v162
	ds_read_b128 v[166:169], v162 offset:1024
	ds_read_b128 v[170:173], v162 offset:2048
	ds_read_b128 v[174:177], v162 offset:3072
	s_cmpk_eq_i32 s82, 0x52
	s_cselect_b32 s23, s11, s79
	s_cselect_b32 s22, s77, s78
	s_cselect_b32 s25, s13, s81
	s_cselect_b32 s24, s76, s80
	ds_read_b128 v[180:183], v163
	ds_read_b128 v[184:187], v163 offset:1024
	ds_read_b128 v[188:191], v163 offset:2048
	ds_read_b128 v[192:195], v163 offset:3072
	ds_read_b128 v[196:199], v163 offset:4096
	ds_read_b128 v[200:203], v163 offset:5120
	ds_read_b128 v[204:207], v163 offset:6144
	ds_read_b128 v[208:211], v163 offset:7168
	s_add_u32 s86, s20, 0xffffc000
	s_addc_u32 s87, s21, -1
	s_mov_b32 s83, m0
	s_mov_b32 m0, s65
	s_nop 0
	global_load_lds_dwordx4 v1, s[86:87]
	s_mov_b32 m0, s83
	s_nop 0
	s_mov_b32 s83, m0
	s_mov_b32 m0, s67
	s_nop 0
	global_load_lds_dwordx4 v157, s[86:87]
	s_mov_b32 m0, s83
	s_nop 0
	s_mov_b32 s83, m0
	s_mov_b32 m0, s66
	s_nop 0
	global_load_lds_dwordx4 v1, s[20:21]
	s_mov_b32 m0, s83
	s_nop 0
	s_mov_b32 s83, m0
	s_mov_b32 m0, s73
	s_nop 0
	global_load_lds_dwordx4 v157, s[20:21]
	s_mov_b32 m0, s83
	s_waitcnt vmcnt(8)
	s_waitcnt lgkmcnt(0)
	s_barrier
	s_setprio 1
	s_waitcnt lgkmcnt(7)
	v_mfma_f32_16x16x32_bf16 v[126:129], v[134:137], v[180:183], 0
	v_mfma_f32_16x16x32_bf16 v[126:129], v[138:141], v[184:187], v[126:129]
	s_waitcnt lgkmcnt(5)
	v_mfma_f32_16x16x32_bf16 v[122:125], v[142:145], v[180:183], 0
	v_mfma_f32_16x16x32_bf16 v[122:125], v[146:149], v[184:187], v[122:125]
	s_waitcnt lgkmcnt(3)
	v_mfma_f32_16x16x32_bf16 v[114:117], v[142:145], v[188:191], 0
	v_mfma_f32_16x16x32_bf16 v[114:117], v[146:149], v[192:195], v[114:117]
	s_waitcnt lgkmcnt(1)
	v_mfma_f32_16x16x32_bf16 v[118:121], v[134:137], v[188:191], 0
	v_mfma_f32_16x16x32_bf16 v[118:121], v[138:141], v[192:195], v[118:121]
	v_mfma_f32_16x16x32_bf16 v[102:105], v[134:137], v[196:199], 0
	v_mfma_f32_16x16x32_bf16 v[102:105], v[138:141], v[200:203], v[102:105]
	v_mfma_f32_16x16x32_bf16 v[94:97], v[142:145], v[196:199], 0
	v_mfma_f32_16x16x32_bf16 v[94:97], v[146:149], v[200:203], v[94:97]
	v_mfma_f32_16x16x32_bf16 v[78:81], v[142:145], v[204:207], 0
	v_mfma_f32_16x16x32_bf16 v[78:81], v[146:149], v[208:211], v[78:81]
	s_waitcnt lgkmcnt(0)
	v_mfma_f32_16x16x32_bf16 v[86:89], v[134:137], v[204:207], 0
	v_mfma_f32_16x16x32_bf16 v[86:89], v[138:141], v[208:211], v[86:89]
	s_setprio 0
	s_setprio 1
	v_mfma_f32_16x16x32_bf16 v[110:113], v[150:153], v[180:183], 0
	v_mfma_f32_16x16x32_bf16 v[110:113], v[166:169], v[184:187], v[110:113]
	v_mfma_f32_16x16x32_bf16 v[106:109], v[170:173], v[180:183], 0
	v_mfma_f32_16x16x32_bf16 v[106:109], v[174:177], v[184:187], v[106:109]
	v_mfma_f32_16x16x32_bf16 v[90:93], v[170:173], v[188:191], 0
	v_mfma_f32_16x16x32_bf16 v[90:93], v[174:177], v[192:195], v[90:93]
	v_mfma_f32_16x16x32_bf16 v[98:101], v[150:153], v[188:191], 0
	v_mfma_f32_16x16x32_bf16 v[98:101], v[166:169], v[192:195], v[98:101]
	v_mfma_f32_16x16x32_bf16 v[82:85], v[150:153], v[196:199], 0
	v_mfma_f32_16x16x32_bf16 v[82:85], v[166:169], v[200:203], v[82:85]
	v_mfma_f32_16x16x32_bf16 v[74:77], v[170:173], v[196:199], 0
	v_mfma_f32_16x16x32_bf16 v[74:77], v[174:177], v[200:203], v[74:77]
	v_mfma_f32_16x16x32_bf16 v[66:69], v[170:173], v[204:207], 0
	v_mfma_f32_16x16x32_bf16 v[66:69], v[174:177], v[208:211], v[66:69]
	s_setprio 2
	s_barrier
	v_mfma_f32_16x16x32_bf16 v[70:73], v[150:153], v[204:207], 0
	v_mfma_f32_16x16x32_bf16 v[70:73], v[166:169], v[208:211], v[70:73]
	s_setprio 0
	ds_read_b128 v[180:183], v163 offset:16384
	ds_read_b128 v[184:187], v163 offset:17408
	ds_read_b128 v[188:191], v163 offset:18432
	ds_read_b128 v[192:195], v163 offset:19456
	ds_read_b128 v[196:199], v163 offset:20480
	ds_read_b128 v[200:203], v163 offset:21504
	ds_read_b128 v[204:207], v163 offset:22528
	ds_read_b128 v[208:211], v163 offset:23552
	s_mov_b32 s83, m0
	s_mov_b32 m0, s19
	s_nop 0
	global_load_lds_dwordx4 v156, s[22:23]
	s_mov_b32 m0, s83
	s_add_u32 s86, s22, 0x4000
	s_mov_b32 s83, m0
	s_mov_b32 m0, s35
	s_nop 0
	global_load_lds_dwordx4 v158, s[22:23]
	s_mov_b32 m0, s83
	s_addc_u32 s87, s23, 0
	s_mov_b32 s83, m0
	s_mov_b32 m0, s36
	s_nop 0
	global_load_lds_dwordx4 v156, s[86:87]
	s_mov_b32 m0, s83
	s_nop 0
	s_mov_b32 s83, m0
	s_mov_b32 m0, s37
	s_nop 0
	global_load_lds_dwordx4 v158, s[86:87]
	s_mov_b32 m0, s83
	s_waitcnt vmcnt(4)
	s_waitcnt lgkmcnt(0)
	s_barrier
	s_setprio 1
	s_waitcnt lgkmcnt(7)
	v_mfma_f32_16x16x32_bf16 v[62:65], v[134:137], v[180:183], 0
	v_mfma_f32_16x16x32_bf16 v[62:65], v[138:141], v[184:187], v[62:65]
	s_waitcnt lgkmcnt(5)
	v_mfma_f32_16x16x32_bf16 v[58:61], v[142:145], v[180:183], 0
	v_mfma_f32_16x16x32_bf16 v[58:61], v[146:149], v[184:187], v[58:61]
	s_waitcnt lgkmcnt(3)
	v_mfma_f32_16x16x32_bf16 v[46:49], v[142:145], v[188:191], 0
	v_mfma_f32_16x16x32_bf16 v[46:49], v[146:149], v[192:195], v[46:49]
	s_waitcnt lgkmcnt(1)
	v_mfma_f32_16x16x32_bf16 v[54:57], v[134:137], v[188:191], 0
	v_mfma_f32_16x16x32_bf16 v[54:57], v[138:141], v[192:195], v[54:57]
	v_mfma_f32_16x16x32_bf16 v[38:41], v[134:137], v[196:199], 0
	v_mfma_f32_16x16x32_bf16 v[38:41], v[138:141], v[200:203], v[38:41]
	v_mfma_f32_16x16x32_bf16 v[30:33], v[142:145], v[196:199], 0
	v_mfma_f32_16x16x32_bf16 v[30:33], v[146:149], v[200:203], v[30:33]
	v_mfma_f32_16x16x32_bf16 v[14:17], v[142:145], v[204:207], 0
	v_mfma_f32_16x16x32_bf16 v[14:17], v[146:149], v[208:211], v[14:17]
	s_waitcnt lgkmcnt(0)
	v_mfma_f32_16x16x32_bf16 v[22:25], v[134:137], v[204:207], 0
	v_mfma_f32_16x16x32_bf16 v[22:25], v[138:141], v[208:211], v[22:25]
	s_setprio 0
	s_setprio 1
	v_mfma_f32_16x16x32_bf16 v[50:53], v[150:153], v[180:183], 0
	v_mfma_f32_16x16x32_bf16 v[50:53], v[166:169], v[184:187], v[50:53]
	v_mfma_f32_16x16x32_bf16 v[42:45], v[170:173], v[180:183], 0
	v_mfma_f32_16x16x32_bf16 v[42:45], v[174:177], v[184:187], v[42:45]
	v_mfma_f32_16x16x32_bf16 v[26:29], v[170:173], v[188:191], 0
	v_mfma_f32_16x16x32_bf16 v[26:29], v[174:177], v[192:195], v[26:29]
	v_mfma_f32_16x16x32_bf16 v[34:37], v[150:153], v[188:191], 0
	v_mfma_f32_16x16x32_bf16 v[34:37], v[166:169], v[192:195], v[34:37]
	v_mfma_f32_16x16x32_bf16 v[18:21], v[150:153], v[196:199], 0
	v_mfma_f32_16x16x32_bf16 v[18:21], v[166:169], v[200:203], v[18:21]
	v_mfma_f32_16x16x32_bf16 v[10:13], v[170:173], v[196:199], 0
	v_mfma_f32_16x16x32_bf16 v[10:13], v[174:177], v[200:203], v[10:13]
	v_mfma_f32_16x16x32_bf16 v[2:5], v[170:173], v[204:207], 0
	v_mfma_f32_16x16x32_bf16 v[2:5], v[174:177], v[208:211], v[2:5]
	s_setprio 2
	s_barrier
	v_mfma_f32_16x16x32_bf16 v[6:9], v[150:153], v[204:207], 0
	v_mfma_f32_16x16x32_bf16 v[6:9], v[166:169], v[208:211], v[6:9]
	s_setprio 0
	ds_read_b128 v[134:137], v164
	ds_read_b128 v[138:141], v164 offset:1024
	ds_read_b128 v[142:145], v164 offset:2048
	ds_read_b128 v[146:149], v164 offset:3072
	ds_read_b128 v[150:153], v165
	ds_read_b128 v[166:169], v165 offset:1024
	ds_read_b128 v[170:173], v165 offset:2048
	ds_read_b128 v[174:177], v165 offset:3072
	ds_read_b128 v[180:183], v163 offset:32768
	ds_read_b128 v[184:187], v163 offset:33792
	ds_read_b128 v[188:191], v163 offset:34816
	ds_read_b128 v[192:195], v163 offset:35840
	ds_read_b128 v[196:199], v163 offset:36864
	ds_read_b128 v[200:203], v163 offset:37888
	ds_read_b128 v[204:207], v163 offset:38912
	ds_read_b128 v[208:211], v163 offset:39936
	s_mov_b32 s83, m0
	s_mov_b32 m0, s34
	s_nop 0
	global_load_lds_dwordx4 v1, s[24:25]
	s_mov_b32 m0, s83
	s_nop 0
	s_mov_b32 s83, m0
	s_mov_b32 m0, s42
	s_nop 0
	global_load_lds_dwordx4 v157, s[24:25]
	s_mov_b32 m0, s83
	s_add_u32 s24, s24, 0x4000
	s_addc_u32 s25, s25, 0
	s_mov_b32 s83, m0
	s_mov_b32 m0, s43
	s_nop 0
	global_load_lds_dwordx4 v1, s[24:25]
	s_mov_b32 m0, s83
	s_nop 0
	s_mov_b32 s83, m0
	s_mov_b32 m0, s46
	s_nop 0
	global_load_lds_dwordx4 v157, s[24:25]
	s_mov_b32 m0, s83
	s_waitcnt vmcnt(8)
	s_waitcnt lgkmcnt(0)
	s_barrier
	s_setprio 1
	s_waitcnt lgkmcnt(7)
	v_mfma_f32_16x16x32_bf16 v[126:129], v[134:137], v[180:183], v[126:129]
	v_mfma_f32_16x16x32_bf16 v[126:129], v[138:141], v[184:187], v[126:129]
	s_waitcnt lgkmcnt(5)
	v_mfma_f32_16x16x32_bf16 v[122:125], v[142:145], v[180:183], v[122:125]
	v_mfma_f32_16x16x32_bf16 v[122:125], v[146:149], v[184:187], v[122:125]
	s_waitcnt lgkmcnt(3)
	v_mfma_f32_16x16x32_bf16 v[114:117], v[142:145], v[188:191], v[114:117]
	v_mfma_f32_16x16x32_bf16 v[114:117], v[146:149], v[192:195], v[114:117]
	s_waitcnt lgkmcnt(1)
	v_mfma_f32_16x16x32_bf16 v[118:121], v[134:137], v[188:191], v[118:121]
	v_mfma_f32_16x16x32_bf16 v[118:121], v[138:141], v[192:195], v[118:121]
	v_mfma_f32_16x16x32_bf16 v[102:105], v[134:137], v[196:199], v[102:105]
	v_mfma_f32_16x16x32_bf16 v[102:105], v[138:141], v[200:203], v[102:105]
	v_mfma_f32_16x16x32_bf16 v[94:97], v[142:145], v[196:199], v[94:97]
	v_mfma_f32_16x16x32_bf16 v[94:97], v[146:149], v[200:203], v[94:97]
	v_mfma_f32_16x16x32_bf16 v[78:81], v[142:145], v[204:207], v[78:81]
	v_mfma_f32_16x16x32_bf16 v[78:81], v[146:149], v[208:211], v[78:81]
	s_waitcnt lgkmcnt(0)
	v_mfma_f32_16x16x32_bf16 v[86:89], v[134:137], v[204:207], v[86:89]
	v_mfma_f32_16x16x32_bf16 v[86:89], v[138:141], v[208:211], v[86:89]
	s_setprio 0
	s_setprio 1
	v_mfma_f32_16x16x32_bf16 v[110:113], v[150:153], v[180:183], v[110:113]
	v_mfma_f32_16x16x32_bf16 v[110:113], v[166:169], v[184:187], v[110:113]
	v_mfma_f32_16x16x32_bf16 v[106:109], v[170:173], v[180:183], v[106:109]
	v_mfma_f32_16x16x32_bf16 v[106:109], v[174:177], v[184:187], v[106:109]
	v_mfma_f32_16x16x32_bf16 v[90:93], v[170:173], v[188:191], v[90:93]
	v_mfma_f32_16x16x32_bf16 v[90:93], v[174:177], v[192:195], v[90:93]
	v_mfma_f32_16x16x32_bf16 v[98:101], v[150:153], v[188:191], v[98:101]
	v_mfma_f32_16x16x32_bf16 v[98:101], v[166:169], v[192:195], v[98:101]
	v_mfma_f32_16x16x32_bf16 v[82:85], v[150:153], v[196:199], v[82:85]
	v_mfma_f32_16x16x32_bf16 v[82:85], v[166:169], v[200:203], v[82:85]
	v_mfma_f32_16x16x32_bf16 v[74:77], v[170:173], v[196:199], v[74:77]
	v_mfma_f32_16x16x32_bf16 v[74:77], v[174:177], v[200:203], v[74:77]
	v_mfma_f32_16x16x32_bf16 v[66:69], v[170:173], v[204:207], v[66:69]
	v_mfma_f32_16x16x32_bf16 v[66:69], v[174:177], v[208:211], v[66:69]
	s_setprio 2
	s_barrier
	v_mfma_f32_16x16x32_bf16 v[70:73], v[150:153], v[204:207], v[70:73]
	v_mfma_f32_16x16x32_bf16 v[70:73], v[166:169], v[208:211], v[70:73]
	s_setprio 0
	ds_read_b128 v[180:183], v163 offset:49152
	ds_read_b128 v[184:187], v163 offset:50176
	ds_read_b128 v[188:191], v163 offset:51200
	ds_read_b128 v[192:195], v163 offset:52224
	ds_read_b128 v[196:199], v163 offset:53248
	ds_read_b128 v[200:203], v163 offset:54272
	ds_read_b128 v[204:207], v163 offset:55296
	ds_read_b128 v[208:211], v163 offset:56320
	s_add_u32 s24, s22, 0x40000
	s_addc_u32 s25, s23, 0
	s_mov_b32 s83, m0
	s_mov_b32 m0, s47
	s_nop 0
	global_load_lds_dwordx4 v156, s[24:25]
	s_mov_b32 m0, s83
	s_add_u32 s22, s22, 0x44000
	s_mov_b32 s83, m0
	s_mov_b32 m0, s48
	s_nop 0
	global_load_lds_dwordx4 v158, s[24:25]
	s_mov_b32 m0, s83
	s_addc_u32 s23, s23, 0
	s_mov_b32 s24, m0
	s_mov_b32 m0, s49
	s_nop 0
	global_load_lds_dwordx4 v156, s[22:23]
	s_mov_b32 m0, s24
	s_nop 0
	s_mov_b32 s24, m0
	s_mov_b32 m0, s56
	s_nop 0
	global_load_lds_dwordx4 v158, s[22:23]
	s_mov_b32 m0, s24
	s_waitcnt vmcnt(4)
	s_waitcnt lgkmcnt(0)
	s_barrier
	s_setprio 1
	s_waitcnt lgkmcnt(7)
	v_mfma_f32_16x16x32_bf16 v[62:65], v[134:137], v[180:183], v[62:65]
	v_mfma_f32_16x16x32_bf16 v[62:65], v[138:141], v[184:187], v[62:65]
	s_waitcnt lgkmcnt(5)
	v_mfma_f32_16x16x32_bf16 v[58:61], v[142:145], v[180:183], v[58:61]
	v_mfma_f32_16x16x32_bf16 v[58:61], v[146:149], v[184:187], v[58:61]
	s_waitcnt lgkmcnt(3)
	v_mfma_f32_16x16x32_bf16 v[46:49], v[142:145], v[188:191], v[46:49]
	v_mfma_f32_16x16x32_bf16 v[46:49], v[146:149], v[192:195], v[46:49]
	s_waitcnt lgkmcnt(1)
	v_mfma_f32_16x16x32_bf16 v[54:57], v[134:137], v[188:191], v[54:57]
	v_mfma_f32_16x16x32_bf16 v[54:57], v[138:141], v[192:195], v[54:57]
	v_mfma_f32_16x16x32_bf16 v[38:41], v[134:137], v[196:199], v[38:41]
	v_mfma_f32_16x16x32_bf16 v[38:41], v[138:141], v[200:203], v[38:41]
	v_mfma_f32_16x16x32_bf16 v[30:33], v[142:145], v[196:199], v[30:33]
	v_mfma_f32_16x16x32_bf16 v[30:33], v[146:149], v[200:203], v[30:33]
	v_mfma_f32_16x16x32_bf16 v[14:17], v[142:145], v[204:207], v[14:17]
	v_mfma_f32_16x16x32_bf16 v[14:17], v[146:149], v[208:211], v[14:17]
	s_waitcnt lgkmcnt(0)
	v_mfma_f32_16x16x32_bf16 v[22:25], v[134:137], v[204:207], v[22:25]
	v_mfma_f32_16x16x32_bf16 v[22:25], v[138:141], v[208:211], v[22:25]
	s_setprio 0
	s_setprio 1
	v_mfma_f32_16x16x32_bf16 v[50:53], v[150:153], v[180:183], v[50:53]
	v_mfma_f32_16x16x32_bf16 v[50:53], v[166:169], v[184:187], v[50:53]
	v_mfma_f32_16x16x32_bf16 v[42:45], v[170:173], v[180:183], v[42:45]
	v_mfma_f32_16x16x32_bf16 v[42:45], v[174:177], v[184:187], v[42:45]
	v_mfma_f32_16x16x32_bf16 v[26:29], v[170:173], v[188:191], v[26:29]
	v_mfma_f32_16x16x32_bf16 v[26:29], v[174:177], v[192:195], v[26:29]
	v_mfma_f32_16x16x32_bf16 v[34:37], v[150:153], v[188:191], v[34:37]
	v_mfma_f32_16x16x32_bf16 v[34:37], v[166:169], v[192:195], v[34:37]
	v_mfma_f32_16x16x32_bf16 v[18:21], v[150:153], v[196:199], v[18:21]
	v_mfma_f32_16x16x32_bf16 v[18:21], v[166:169], v[200:203], v[18:21]
	v_mfma_f32_16x16x32_bf16 v[10:13], v[170:173], v[196:199], v[10:13]
	v_mfma_f32_16x16x32_bf16 v[10:13], v[174:177], v[200:203], v[10:13]
	v_mfma_f32_16x16x32_bf16 v[2:5], v[170:173], v[204:207], v[2:5]
	v_mfma_f32_16x16x32_bf16 v[2:5], v[174:177], v[208:211], v[2:5]
	s_setprio 2
	s_barrier
	v_mfma_f32_16x16x32_bf16 v[6:9], v[150:153], v[204:207], v[6:9]
	v_mfma_f32_16x16x32_bf16 v[6:9], v[166:169], v[208:211], v[6:9]
	s_setprio 0
	s_add_i32 s82, s82, 2
	s_add_u32 s78, s78, 0x80000
	s_addc_u32 s79, s79, 0
	s_add_u32 s20, s20, 0x400000
	s_addc_u32 s21, s21, 0
	s_add_u32 s80, s80, 0x400000
	s_addc_u32 s81, s81, 0
	s_cmpk_gt_u32 s82, 0x53
	.p2align 6
.LBB0_473:
	ds_read_b128 v[134:137], v161
	ds_read_b128 v[138:141], v161 offset:1024
	ds_read_b128 v[142:145], v161 offset:2048
	ds_read_b128 v[146:149], v161 offset:3072
	ds_read_b128 v[150:153], v162
	ds_read_b128 v[166:169], v162 offset:1024
	ds_read_b128 v[170:173], v162 offset:2048
	ds_read_b128 v[174:177], v162 offset:3072
	s_cmpk_eq_i32 s82, 0x52
	s_cselect_b32 s23, s11, s79
	s_cselect_b32 s22, s77, s78
	s_cselect_b32 s25, s13, s81
	s_cselect_b32 s24, s76, s80
	ds_read_b128 v[180:183], v163
	ds_read_b128 v[184:187], v163 offset:1024
	ds_read_b128 v[188:191], v163 offset:2048
	ds_read_b128 v[192:195], v163 offset:3072
	ds_read_b128 v[196:199], v163 offset:4096
	ds_read_b128 v[200:203], v163 offset:5120
	ds_read_b128 v[204:207], v163 offset:6144
	ds_read_b128 v[208:211], v163 offset:7168
	s_add_u32 s86, s20, 0xffffc000
	s_addc_u32 s87, s21, -1
	s_mov_b32 s83, m0
	s_mov_b32 m0, s65
	s_nop 0
	global_load_lds_dwordx4 v1, s[86:87]
	s_mov_b32 m0, s83
	s_nop 0
	s_mov_b32 s83, m0
	s_mov_b32 m0, s67
	s_nop 0
	global_load_lds_dwordx4 v157, s[86:87]
	s_mov_b32 m0, s83
	s_nop 0
	s_mov_b32 s83, m0
	s_mov_b32 m0, s66
	s_nop 0
	global_load_lds_dwordx4 v1, s[20:21]
	s_mov_b32 m0, s83
	s_nop 0
	s_mov_b32 s83, m0
	s_mov_b32 m0, s73
	s_nop 0
	global_load_lds_dwordx4 v157, s[20:21]
	s_mov_b32 m0, s83
	s_waitcnt vmcnt(8)
	s_waitcnt lgkmcnt(0)
	s_barrier
	s_setprio 1
	s_waitcnt lgkmcnt(7)
	v_mfma_f32_16x16x32_bf16 v[126:129], v[134:137], v[180:183], v[126:129]
	v_mfma_f32_16x16x32_bf16 v[126:129], v[138:141], v[184:187], v[126:129]
	s_waitcnt lgkmcnt(5)
	v_mfma_f32_16x16x32_bf16 v[122:125], v[142:145], v[180:183], v[122:125]
	v_mfma_f32_16x16x32_bf16 v[122:125], v[146:149], v[184:187], v[122:125]
	s_waitcnt lgkmcnt(3)
	v_mfma_f32_16x16x32_bf16 v[114:117], v[142:145], v[188:191], v[114:117]
	v_mfma_f32_16x16x32_bf16 v[114:117], v[146:149], v[192:195], v[114:117]
	s_waitcnt lgkmcnt(1)
	v_mfma_f32_16x16x32_bf16 v[118:121], v[134:137], v[188:191], v[118:121]
	v_mfma_f32_16x16x32_bf16 v[118:121], v[138:141], v[192:195], v[118:121]
	v_mfma_f32_16x16x32_bf16 v[102:105], v[134:137], v[196:199], v[102:105]
	v_mfma_f32_16x16x32_bf16 v[102:105], v[138:141], v[200:203], v[102:105]
	v_mfma_f32_16x16x32_bf16 v[94:97], v[142:145], v[196:199], v[94:97]
	v_mfma_f32_16x16x32_bf16 v[94:97], v[146:149], v[200:203], v[94:97]
	v_mfma_f32_16x16x32_bf16 v[78:81], v[142:145], v[204:207], v[78:81]
	v_mfma_f32_16x16x32_bf16 v[78:81], v[146:149], v[208:211], v[78:81]
	s_waitcnt lgkmcnt(0)
	v_mfma_f32_16x16x32_bf16 v[86:89], v[134:137], v[204:207], v[86:89]
	v_mfma_f32_16x16x32_bf16 v[86:89], v[138:141], v[208:211], v[86:89]
	s_setprio 0
	s_setprio 1
	v_mfma_f32_16x16x32_bf16 v[110:113], v[150:153], v[180:183], v[110:113]
	v_mfma_f32_16x16x32_bf16 v[110:113], v[166:169], v[184:187], v[110:113]
	v_mfma_f32_16x16x32_bf16 v[106:109], v[170:173], v[180:183], v[106:109]
	v_mfma_f32_16x16x32_bf16 v[106:109], v[174:177], v[184:187], v[106:109]
	v_mfma_f32_16x16x32_bf16 v[90:93], v[170:173], v[188:191], v[90:93]
	v_mfma_f32_16x16x32_bf16 v[90:93], v[174:177], v[192:195], v[90:93]
	v_mfma_f32_16x16x32_bf16 v[98:101], v[150:153], v[188:191], v[98:101]
	v_mfma_f32_16x16x32_bf16 v[98:101], v[166:169], v[192:195], v[98:101]
	v_mfma_f32_16x16x32_bf16 v[82:85], v[150:153], v[196:199], v[82:85]
	v_mfma_f32_16x16x32_bf16 v[82:85], v[166:169], v[200:203], v[82:85]
	v_mfma_f32_16x16x32_bf16 v[74:77], v[170:173], v[196:199], v[74:77]
	v_mfma_f32_16x16x32_bf16 v[74:77], v[174:177], v[200:203], v[74:77]
	v_mfma_f32_16x16x32_bf16 v[66:69], v[170:173], v[204:207], v[66:69]
	v_mfma_f32_16x16x32_bf16 v[66:69], v[174:177], v[208:211], v[66:69]
	s_setprio 2
	s_barrier
	v_mfma_f32_16x16x32_bf16 v[70:73], v[150:153], v[204:207], v[70:73]
	v_mfma_f32_16x16x32_bf16 v[70:73], v[166:169], v[208:211], v[70:73]
	s_setprio 0
	ds_read_b128 v[180:183], v163 offset:16384
	ds_read_b128 v[184:187], v163 offset:17408
	ds_read_b128 v[188:191], v163 offset:18432
	ds_read_b128 v[192:195], v163 offset:19456
	ds_read_b128 v[196:199], v163 offset:20480
	ds_read_b128 v[200:203], v163 offset:21504
	ds_read_b128 v[204:207], v163 offset:22528
	ds_read_b128 v[208:211], v163 offset:23552
	s_mov_b32 s83, m0
	s_mov_b32 m0, s19
	s_nop 0
	global_load_lds_dwordx4 v156, s[22:23]
	s_mov_b32 m0, s83
	s_add_u32 s86, s22, 0x4000
	s_mov_b32 s83, m0
	s_mov_b32 m0, s35
	s_nop 0
	global_load_lds_dwordx4 v158, s[22:23]
	s_mov_b32 m0, s83
	s_addc_u32 s87, s23, 0
	s_mov_b32 s83, m0
	s_mov_b32 m0, s36
	s_nop 0
	global_load_lds_dwordx4 v156, s[86:87]
	s_mov_b32 m0, s83
	s_nop 0
	s_mov_b32 s83, m0
	s_mov_b32 m0, s37
	s_nop 0
	global_load_lds_dwordx4 v158, s[86:87]
	s_mov_b32 m0, s83
	s_waitcnt vmcnt(4)
	s_waitcnt lgkmcnt(0)
	s_barrier
	s_setprio 1
	s_waitcnt lgkmcnt(7)
	v_mfma_f32_16x16x32_bf16 v[62:65], v[134:137], v[180:183], v[62:65]
	v_mfma_f32_16x16x32_bf16 v[62:65], v[138:141], v[184:187], v[62:65]
	s_waitcnt lgkmcnt(5)
	v_mfma_f32_16x16x32_bf16 v[58:61], v[142:145], v[180:183], v[58:61]
	v_mfma_f32_16x16x32_bf16 v[58:61], v[146:149], v[184:187], v[58:61]
	s_waitcnt lgkmcnt(3)
	v_mfma_f32_16x16x32_bf16 v[46:49], v[142:145], v[188:191], v[46:49]
	v_mfma_f32_16x16x32_bf16 v[46:49], v[146:149], v[192:195], v[46:49]
	s_waitcnt lgkmcnt(1)
	v_mfma_f32_16x16x32_bf16 v[54:57], v[134:137], v[188:191], v[54:57]
	v_mfma_f32_16x16x32_bf16 v[54:57], v[138:141], v[192:195], v[54:57]
	v_mfma_f32_16x16x32_bf16 v[38:41], v[134:137], v[196:199], v[38:41]
	v_mfma_f32_16x16x32_bf16 v[38:41], v[138:141], v[200:203], v[38:41]
	v_mfma_f32_16x16x32_bf16 v[30:33], v[142:145], v[196:199], v[30:33]
	v_mfma_f32_16x16x32_bf16 v[30:33], v[146:149], v[200:203], v[30:33]
	v_mfma_f32_16x16x32_bf16 v[14:17], v[142:145], v[204:207], v[14:17]
	v_mfma_f32_16x16x32_bf16 v[14:17], v[146:149], v[208:211], v[14:17]
	s_waitcnt lgkmcnt(0)
	v_mfma_f32_16x16x32_bf16 v[22:25], v[134:137], v[204:207], v[22:25]
	v_mfma_f32_16x16x32_bf16 v[22:25], v[138:141], v[208:211], v[22:25]
	s_setprio 0
	s_setprio 1
	v_mfma_f32_16x16x32_bf16 v[50:53], v[150:153], v[180:183], v[50:53]
	v_mfma_f32_16x16x32_bf16 v[50:53], v[166:169], v[184:187], v[50:53]
	v_mfma_f32_16x16x32_bf16 v[42:45], v[170:173], v[180:183], v[42:45]
	v_mfma_f32_16x16x32_bf16 v[42:45], v[174:177], v[184:187], v[42:45]
	v_mfma_f32_16x16x32_bf16 v[26:29], v[170:173], v[188:191], v[26:29]
	v_mfma_f32_16x16x32_bf16 v[26:29], v[174:177], v[192:195], v[26:29]
	v_mfma_f32_16x16x32_bf16 v[34:37], v[150:153], v[188:191], v[34:37]
	v_mfma_f32_16x16x32_bf16 v[34:37], v[166:169], v[192:195], v[34:37]
	v_mfma_f32_16x16x32_bf16 v[18:21], v[150:153], v[196:199], v[18:21]
	v_mfma_f32_16x16x32_bf16 v[18:21], v[166:169], v[200:203], v[18:21]
	v_mfma_f32_16x16x32_bf16 v[10:13], v[170:173], v[196:199], v[10:13]
	v_mfma_f32_16x16x32_bf16 v[10:13], v[174:177], v[200:203], v[10:13]
	v_mfma_f32_16x16x32_bf16 v[2:5], v[170:173], v[204:207], v[2:5]
	v_mfma_f32_16x16x32_bf16 v[2:5], v[174:177], v[208:211], v[2:5]
	s_setprio 2
	s_barrier
	v_mfma_f32_16x16x32_bf16 v[6:9], v[150:153], v[204:207], v[6:9]
	v_mfma_f32_16x16x32_bf16 v[6:9], v[166:169], v[208:211], v[6:9]
	s_setprio 0
	ds_read_b128 v[134:137], v164
	ds_read_b128 v[138:141], v164 offset:1024
	ds_read_b128 v[142:145], v164 offset:2048
	ds_read_b128 v[146:149], v164 offset:3072
	ds_read_b128 v[150:153], v165
	ds_read_b128 v[166:169], v165 offset:1024
	ds_read_b128 v[170:173], v165 offset:2048
	ds_read_b128 v[174:177], v165 offset:3072
	ds_read_b128 v[180:183], v163 offset:32768
	ds_read_b128 v[184:187], v163 offset:33792
	ds_read_b128 v[188:191], v163 offset:34816
	ds_read_b128 v[192:195], v163 offset:35840
	ds_read_b128 v[196:199], v163 offset:36864
	ds_read_b128 v[200:203], v163 offset:37888
	ds_read_b128 v[204:207], v163 offset:38912
	ds_read_b128 v[208:211], v163 offset:39936
	s_mov_b32 s83, m0
	s_mov_b32 m0, s34
	s_nop 0
	global_load_lds_dwordx4 v1, s[24:25]
	s_mov_b32 m0, s83
	s_nop 0
	s_mov_b32 s83, m0
	s_mov_b32 m0, s42
	s_nop 0
	global_load_lds_dwordx4 v157, s[24:25]
	s_mov_b32 m0, s83
	s_add_u32 s24, s24, 0x4000
	s_addc_u32 s25, s25, 0
	s_mov_b32 s83, m0
	s_mov_b32 m0, s43
	s_nop 0
	global_load_lds_dwordx4 v1, s[24:25]
	s_mov_b32 m0, s83
	s_nop 0
	s_mov_b32 s83, m0
	s_mov_b32 m0, s46
	s_nop 0
	global_load_lds_dwordx4 v157, s[24:25]
	s_mov_b32 m0, s83
	s_waitcnt vmcnt(8)
	s_waitcnt lgkmcnt(0)
	s_barrier
	s_setprio 1
	s_waitcnt lgkmcnt(7)
	v_mfma_f32_16x16x32_bf16 v[126:129], v[134:137], v[180:183], v[126:129]
	v_mfma_f32_16x16x32_bf16 v[126:129], v[138:141], v[184:187], v[126:129]
	s_waitcnt lgkmcnt(5)
	v_mfma_f32_16x16x32_bf16 v[122:125], v[142:145], v[180:183], v[122:125]
	v_mfma_f32_16x16x32_bf16 v[122:125], v[146:149], v[184:187], v[122:125]
	s_waitcnt lgkmcnt(3)
	v_mfma_f32_16x16x32_bf16 v[114:117], v[142:145], v[188:191], v[114:117]
	v_mfma_f32_16x16x32_bf16 v[114:117], v[146:149], v[192:195], v[114:117]
	s_waitcnt lgkmcnt(1)
	v_mfma_f32_16x16x32_bf16 v[118:121], v[134:137], v[188:191], v[118:121]
	v_mfma_f32_16x16x32_bf16 v[118:121], v[138:141], v[192:195], v[118:121]
	v_mfma_f32_16x16x32_bf16 v[102:105], v[134:137], v[196:199], v[102:105]
	v_mfma_f32_16x16x32_bf16 v[102:105], v[138:141], v[200:203], v[102:105]
	v_mfma_f32_16x16x32_bf16 v[94:97], v[142:145], v[196:199], v[94:97]
	v_mfma_f32_16x16x32_bf16 v[94:97], v[146:149], v[200:203], v[94:97]
	v_mfma_f32_16x16x32_bf16 v[78:81], v[142:145], v[204:207], v[78:81]
	v_mfma_f32_16x16x32_bf16 v[78:81], v[146:149], v[208:211], v[78:81]
	s_waitcnt lgkmcnt(0)
	v_mfma_f32_16x16x32_bf16 v[86:89], v[134:137], v[204:207], v[86:89]
	v_mfma_f32_16x16x32_bf16 v[86:89], v[138:141], v[208:211], v[86:89]
	s_setprio 0
	s_setprio 1
	v_mfma_f32_16x16x32_bf16 v[110:113], v[150:153], v[180:183], v[110:113]
	v_mfma_f32_16x16x32_bf16 v[110:113], v[166:169], v[184:187], v[110:113]
	v_mfma_f32_16x16x32_bf16 v[106:109], v[170:173], v[180:183], v[106:109]
	v_mfma_f32_16x16x32_bf16 v[106:109], v[174:177], v[184:187], v[106:109]
	v_mfma_f32_16x16x32_bf16 v[90:93], v[170:173], v[188:191], v[90:93]
	v_mfma_f32_16x16x32_bf16 v[90:93], v[174:177], v[192:195], v[90:93]
	v_mfma_f32_16x16x32_bf16 v[98:101], v[150:153], v[188:191], v[98:101]
	v_mfma_f32_16x16x32_bf16 v[98:101], v[166:169], v[192:195], v[98:101]
	v_mfma_f32_16x16x32_bf16 v[82:85], v[150:153], v[196:199], v[82:85]
	v_mfma_f32_16x16x32_bf16 v[82:85], v[166:169], v[200:203], v[82:85]
	v_mfma_f32_16x16x32_bf16 v[74:77], v[170:173], v[196:199], v[74:77]
	v_mfma_f32_16x16x32_bf16 v[74:77], v[174:177], v[200:203], v[74:77]
	v_mfma_f32_16x16x32_bf16 v[66:69], v[170:173], v[204:207], v[66:69]
	v_mfma_f32_16x16x32_bf16 v[66:69], v[174:177], v[208:211], v[66:69]
	s_setprio 2
	s_barrier
	v_mfma_f32_16x16x32_bf16 v[70:73], v[150:153], v[204:207], v[70:73]
	v_mfma_f32_16x16x32_bf16 v[70:73], v[166:169], v[208:211], v[70:73]
	s_setprio 0
	ds_read_b128 v[180:183], v163 offset:49152
	ds_read_b128 v[184:187], v163 offset:50176
	ds_read_b128 v[188:191], v163 offset:51200
	ds_read_b128 v[192:195], v163 offset:52224
	ds_read_b128 v[196:199], v163 offset:53248
	ds_read_b128 v[200:203], v163 offset:54272
	ds_read_b128 v[204:207], v163 offset:55296
	ds_read_b128 v[208:211], v163 offset:56320
	s_add_u32 s24, s22, 0x40000
	s_addc_u32 s25, s23, 0
	s_mov_b32 s83, m0
	s_mov_b32 m0, s47
	s_nop 0
	global_load_lds_dwordx4 v156, s[24:25]
	s_mov_b32 m0, s83
	s_add_u32 s22, s22, 0x44000
	s_mov_b32 s83, m0
	s_mov_b32 m0, s48
	s_nop 0
	global_load_lds_dwordx4 v158, s[24:25]
	s_mov_b32 m0, s83
	s_addc_u32 s23, s23, 0
	s_mov_b32 s24, m0
	s_mov_b32 m0, s49
	s_nop 0
	global_load_lds_dwordx4 v156, s[22:23]
	s_mov_b32 m0, s24
	s_nop 0
	s_mov_b32 s24, m0
	s_mov_b32 m0, s56
	s_nop 0
	global_load_lds_dwordx4 v158, s[22:23]
	s_mov_b32 m0, s24
	s_waitcnt vmcnt(4)
	s_waitcnt lgkmcnt(0)
	s_barrier
	s_setprio 1
	s_waitcnt lgkmcnt(7)
	v_mfma_f32_16x16x32_bf16 v[62:65], v[134:137], v[180:183], v[62:65]
	v_mfma_f32_16x16x32_bf16 v[62:65], v[138:141], v[184:187], v[62:65]
	s_waitcnt lgkmcnt(5)
	v_mfma_f32_16x16x32_bf16 v[58:61], v[142:145], v[180:183], v[58:61]
	v_mfma_f32_16x16x32_bf16 v[58:61], v[146:149], v[184:187], v[58:61]
	s_waitcnt lgkmcnt(3)
	v_mfma_f32_16x16x32_bf16 v[46:49], v[142:145], v[188:191], v[46:49]
	v_mfma_f32_16x16x32_bf16 v[46:49], v[146:149], v[192:195], v[46:49]
	s_waitcnt lgkmcnt(1)
	v_mfma_f32_16x16x32_bf16 v[54:57], v[134:137], v[188:191], v[54:57]
	v_mfma_f32_16x16x32_bf16 v[54:57], v[138:141], v[192:195], v[54:57]
	v_mfma_f32_16x16x32_bf16 v[38:41], v[134:137], v[196:199], v[38:41]
	v_mfma_f32_16x16x32_bf16 v[38:41], v[138:141], v[200:203], v[38:41]
	v_mfma_f32_16x16x32_bf16 v[30:33], v[142:145], v[196:199], v[30:33]
	v_mfma_f32_16x16x32_bf16 v[30:33], v[146:149], v[200:203], v[30:33]
	v_mfma_f32_16x16x32_bf16 v[14:17], v[142:145], v[204:207], v[14:17]
	v_mfma_f32_16x16x32_bf16 v[14:17], v[146:149], v[208:211], v[14:17]
	s_waitcnt lgkmcnt(0)
	v_mfma_f32_16x16x32_bf16 v[22:25], v[134:137], v[204:207], v[22:25]
	v_mfma_f32_16x16x32_bf16 v[22:25], v[138:141], v[208:211], v[22:25]
	s_setprio 0
	s_setprio 1
	v_mfma_f32_16x16x32_bf16 v[50:53], v[150:153], v[180:183], v[50:53]
	v_mfma_f32_16x16x32_bf16 v[50:53], v[166:169], v[184:187], v[50:53]
	v_mfma_f32_16x16x32_bf16 v[42:45], v[170:173], v[180:183], v[42:45]
	v_mfma_f32_16x16x32_bf16 v[42:45], v[174:177], v[184:187], v[42:45]
	v_mfma_f32_16x16x32_bf16 v[26:29], v[170:173], v[188:191], v[26:29]
	v_mfma_f32_16x16x32_bf16 v[26:29], v[174:177], v[192:195], v[26:29]
	v_mfma_f32_16x16x32_bf16 v[34:37], v[150:153], v[188:191], v[34:37]
	v_mfma_f32_16x16x32_bf16 v[34:37], v[166:169], v[192:195], v[34:37]
	v_mfma_f32_16x16x32_bf16 v[18:21], v[150:153], v[196:199], v[18:21]
	v_mfma_f32_16x16x32_bf16 v[18:21], v[166:169], v[200:203], v[18:21]
	v_mfma_f32_16x16x32_bf16 v[10:13], v[170:173], v[196:199], v[10:13]
	v_mfma_f32_16x16x32_bf16 v[10:13], v[174:177], v[200:203], v[10:13]
	v_mfma_f32_16x16x32_bf16 v[2:5], v[170:173], v[204:207], v[2:5]
	v_mfma_f32_16x16x32_bf16 v[2:5], v[174:177], v[208:211], v[2:5]
	s_setprio 2
	s_barrier
	v_mfma_f32_16x16x32_bf16 v[6:9], v[150:153], v[204:207], v[6:9]
	v_mfma_f32_16x16x32_bf16 v[6:9], v[166:169], v[208:211], v[6:9]
	s_setprio 0
	s_add_i32 s82, s82, 2
	s_add_u32 s78, s78, 0x80000
	s_addc_u32 s79, s79, 0
	s_add_u32 s20, s20, 0x400000
	s_addc_u32 s21, s21, 0
	s_add_u32 s80, s80, 0x400000
	s_addc_u32 s81, s81, 0
	s_cmpk_gt_u32 s82, 0x53
	s_cbranch_scc0 .LBB0_473
	v_mov_b32_e32 v210, v252
	v_mov_b32_e32 v211, v253
	s_and_b64 vcc, exec, s[8:9]
	s_cbranch_vccz .LBB0_476
	s_barrier

.LBB0_653:
	s_ashr_i32 s23, s22, 31
	s_lshl_b64 s[24:25], s[22:23], 20
	s_add_u32 s24, s35, s24
	s_addc_u32 s25, s36, s25
	s_and_b64 s[26:27], s[2:3], exec
	s_cselect_b32 s7, s25, s11
	s_cselect_b32 s9, s24, s10
	s_ashr_i32 s21, s20, 31
	s_lshl_b64 s[26:27], s[20:21], 20
	s_add_u32 s26, s37, s26
	s_addc_u32 s27, s40, s27
	s_and_b64 s[28:29], s[2:3], exec
	s_cselect_b32 s21, s27, s5
	s_cselect_b32 s23, s26, s4
	s_add_u32 s30, s4, 0x100
	s_addc_u32 s31, s5, 0
	s_add_u32 s4, s10, 0x80080
	s_addc_u32 s5, s11, 0
	s_add_u32 s33, s10, 0x100
	s_addc_u32 s73, s11, 0
	s_mov_b32 s74, -2
	s_waitcnt vmcnt(25)
	s_waitcnt vmcnt(24)
	s_waitcnt vmcnt(15)
	s_waitcnt vmcnt(14)
	s_waitcnt vmcnt(13)
	s_waitcnt vmcnt(12)
	s_waitcnt vmcnt(11)
	s_waitcnt vmcnt(10)
	s_waitcnt vmcnt(9)
	s_waitcnt vmcnt(8)
	s_waitcnt vmcnt(7)
	s_waitcnt vmcnt(6)
	s_waitcnt vmcnt(5)
	s_waitcnt vmcnt(4)
	s_waitcnt vmcnt(3)
	s_waitcnt vmcnt(2)
	s_waitcnt vmcnt(1)
	s_waitcnt vmcnt(0)
	v_mov_b32_e32 v252, v212
	v_mov_b32_e32 v253, v213
	ds_read_b128 v[130:133], v161
	ds_read_b128 v[138:141], v161 offset:1024
	ds_read_b128 v[142:145], v161 offset:2048
	ds_read_b128 v[146:149], v161 offset:3072
	ds_read_b128 v[150:153], v162
	ds_read_b128 v[168:171], v162 offset:1024
	ds_read_b128 v[172:175], v162 offset:2048
	ds_read_b128 v[176:179], v162 offset:3072
	s_cmp_eq_u32 s74, 28
	s_cselect_b32 s11, s21, s31
	s_cselect_b32 s10, s23, s30
	s_cselect_b32 s29, s7, s73
	s_cselect_b32 s28, s9, s33
	ds_read_b128 v[182:185], v163
	ds_read_b128 v[186:189], v163 offset:1024
	ds_read_b128 v[190:193], v163 offset:2048
	ds_read_b128 v[194:197], v163 offset:3072
	ds_read_b128 v[198:201], v163 offset:4096
	ds_read_b128 v[202:205], v163 offset:5120
	ds_read_b128 v[206:209], v163 offset:6144
	ds_read_b128 v[210:213], v163 offset:7168
	s_add_u32 s76, s4, 0xfff80000
	s_addc_u32 s77, s5, -1
	s_mov_b32 s75, m0
	s_mov_b32 m0, s80
	s_nop 0
	global_load_lds_dwordx4 v1, s[76:77]
	s_mov_b32 m0, s75
	s_nop 0
	s_mov_b32 s75, m0
	s_mov_b32 m0, s82
	s_nop 0
	global_load_lds_dwordx4 v157, s[76:77]
	s_mov_b32 m0, s75
	s_nop 0
	s_mov_b32 s75, m0
	s_mov_b32 m0, s81
	s_nop 0
	global_load_lds_dwordx4 v1, s[4:5]
	s_mov_b32 m0, s75
	s_nop 0
	s_mov_b32 s75, m0
	s_mov_b32 m0, s83
	s_nop 0
	global_load_lds_dwordx4 v157, s[4:5]
	s_mov_b32 m0, s75
	s_waitcnt vmcnt(8)
	s_waitcnt lgkmcnt(0)
	s_barrier
	s_setprio 1
	s_waitcnt lgkmcnt(7)
	v_mfma_f32_16x16x32_bf16 v[126:129], v[130:133], v[182:185], 0
	v_mfma_f32_16x16x32_bf16 v[126:129], v[138:141], v[186:189], v[126:129]
	s_waitcnt lgkmcnt(5)
	v_mfma_f32_16x16x32_bf16 v[122:125], v[142:145], v[182:185], 0
	v_mfma_f32_16x16x32_bf16 v[122:125], v[146:149], v[186:189], v[122:125]
	s_waitcnt lgkmcnt(3)
	v_mfma_f32_16x16x32_bf16 v[106:109], v[142:145], v[190:193], 0
	v_mfma_f32_16x16x32_bf16 v[106:109], v[146:149], v[194:197], v[106:109]
	s_waitcnt lgkmcnt(1)
	v_mfma_f32_16x16x32_bf16 v[110:113], v[130:133], v[190:193], 0
	v_mfma_f32_16x16x32_bf16 v[110:113], v[138:141], v[194:197], v[110:113]
	v_mfma_f32_16x16x32_bf16 v[94:97], v[130:133], v[198:201], 0
	v_mfma_f32_16x16x32_bf16 v[94:97], v[138:141], v[202:205], v[94:97]
	v_mfma_f32_16x16x32_bf16 v[90:93], v[142:145], v[198:201], 0
	v_mfma_f32_16x16x32_bf16 v[90:93], v[146:149], v[202:205], v[90:93]
	v_mfma_f32_16x16x32_bf16 v[74:77], v[142:145], v[206:209], 0
	v_mfma_f32_16x16x32_bf16 v[74:77], v[146:149], v[210:213], v[74:77]
	s_waitcnt lgkmcnt(0)
	v_mfma_f32_16x16x32_bf16 v[78:81], v[130:133], v[206:209], 0
	v_mfma_f32_16x16x32_bf16 v[78:81], v[138:141], v[210:213], v[78:81]
	s_setprio 0
	s_setprio 1
	v_mfma_f32_16x16x32_bf16 v[118:121], v[150:153], v[182:185], 0
	v_mfma_f32_16x16x32_bf16 v[118:121], v[168:171], v[186:189], v[118:121]
	v_mfma_f32_16x16x32_bf16 v[114:117], v[172:175], v[182:185], 0
	v_mfma_f32_16x16x32_bf16 v[114:117], v[176:179], v[186:189], v[114:117]
	v_mfma_f32_16x16x32_bf16 v[98:101], v[172:175], v[190:193], 0
	v_mfma_f32_16x16x32_bf16 v[98:101], v[176:179], v[194:197], v[98:101]
	v_mfma_f32_16x16x32_bf16 v[102:105], v[150:153], v[190:193], 0
	v_mfma_f32_16x16x32_bf16 v[102:105], v[168:171], v[194:197], v[102:105]
	v_mfma_f32_16x16x32_bf16 v[86:89], v[150:153], v[198:201], 0
	v_mfma_f32_16x16x32_bf16 v[86:89], v[168:171], v[202:205], v[86:89]
	v_mfma_f32_16x16x32_bf16 v[82:85], v[172:175], v[198:201], 0
	v_mfma_f32_16x16x32_bf16 v[82:85], v[176:179], v[202:205], v[82:85]
	v_mfma_f32_16x16x32_bf16 v[66:69], v[172:175], v[206:209], 0
	v_mfma_f32_16x16x32_bf16 v[66:69], v[176:179], v[210:213], v[66:69]
	s_setprio 2
	s_barrier
	v_mfma_f32_16x16x32_bf16 v[70:73], v[150:153], v[206:209], 0
	v_mfma_f32_16x16x32_bf16 v[70:73], v[168:171], v[210:213], v[70:73]
	s_setprio 0
	ds_read_b128 v[182:185], v163 offset:16384
	ds_read_b128 v[186:189], v163 offset:17408
	ds_read_b128 v[190:193], v163 offset:18432
	ds_read_b128 v[194:197], v163 offset:19456
	ds_read_b128 v[198:201], v163 offset:20480
	ds_read_b128 v[202:205], v163 offset:21504
	ds_read_b128 v[206:209], v163 offset:22528
	ds_read_b128 v[210:213], v163 offset:23552
	s_mov_b32 s75, m0
	s_mov_b32 m0, s43
	s_nop 0
	global_load_lds_dwordx4 v156, s[10:11]
	s_mov_b32 m0, s75
	s_add_u32 s76, s10, 0x80000
	s_mov_b32 s75, m0
	s_mov_b32 m0, s46
	s_nop 0
	global_load_lds_dwordx4 v158, s[10:11]
	s_mov_b32 m0, s75
	s_addc_u32 s77, s11, 0
	s_mov_b32 s75, m0
	s_mov_b32 m0, s47
	s_nop 0
	global_load_lds_dwordx4 v156, s[76:77]
	s_mov_b32 m0, s75
	s_nop 0
	s_mov_b32 s75, m0
	s_mov_b32 m0, s48
	s_nop 0
	global_load_lds_dwordx4 v158, s[76:77]
	s_mov_b32 m0, s75
	s_waitcnt vmcnt(4)
	s_waitcnt lgkmcnt(0)
	s_barrier
	s_setprio 1
	s_waitcnt lgkmcnt(7)
	v_mfma_f32_16x16x32_bf16 v[62:65], v[130:133], v[182:185], 0
	v_mfma_f32_16x16x32_bf16 v[62:65], v[138:141], v[186:189], v[62:65]
	s_waitcnt lgkmcnt(5)
	v_mfma_f32_16x16x32_bf16 v[58:61], v[142:145], v[182:185], 0
	v_mfma_f32_16x16x32_bf16 v[58:61], v[146:149], v[186:189], v[58:61]
	s_waitcnt lgkmcnt(3)
	v_mfma_f32_16x16x32_bf16 v[42:45], v[142:145], v[190:193], 0
	v_mfma_f32_16x16x32_bf16 v[42:45], v[146:149], v[194:197], v[42:45]
	s_waitcnt lgkmcnt(1)
	v_mfma_f32_16x16x32_bf16 v[46:49], v[130:133], v[190:193], 0
	v_mfma_f32_16x16x32_bf16 v[46:49], v[138:141], v[194:197], v[46:49]
	v_mfma_f32_16x16x32_bf16 v[30:33], v[130:133], v[198:201], 0
	v_mfma_f32_16x16x32_bf16 v[30:33], v[138:141], v[202:205], v[30:33]
	v_mfma_f32_16x16x32_bf16 v[26:29], v[142:145], v[198:201], 0
	v_mfma_f32_16x16x32_bf16 v[26:29], v[146:149], v[202:205], v[26:29]
	v_mfma_f32_16x16x32_bf16 v[10:13], v[142:145], v[206:209], 0
	v_mfma_f32_16x16x32_bf16 v[10:13], v[146:149], v[210:213], v[10:13]
	s_waitcnt lgkmcnt(0)
	v_mfma_f32_16x16x32_bf16 v[14:17], v[130:133], v[206:209], 0
	v_mfma_f32_16x16x32_bf16 v[14:17], v[138:141], v[210:213], v[14:17]
	s_setprio 0
	s_setprio 1
	v_mfma_f32_16x16x32_bf16 v[54:57], v[150:153], v[182:185], 0
	v_mfma_f32_16x16x32_bf16 v[54:57], v[168:171], v[186:189], v[54:57]
	v_mfma_f32_16x16x32_bf16 v[50:53], v[172:175], v[182:185], 0
	v_mfma_f32_16x16x32_bf16 v[50:53], v[176:179], v[186:189], v[50:53]
	v_mfma_f32_16x16x32_bf16 v[34:37], v[172:175], v[190:193], 0
	v_mfma_f32_16x16x32_bf16 v[34:37], v[176:179], v[194:197], v[34:37]
	v_mfma_f32_16x16x32_bf16 v[38:41], v[150:153], v[190:193], 0
	v_mfma_f32_16x16x32_bf16 v[38:41], v[168:171], v[194:197], v[38:41]
	v_mfma_f32_16x16x32_bf16 v[22:25], v[150:153], v[198:201], 0
	v_mfma_f32_16x16x32_bf16 v[22:25], v[168:171], v[202:205], v[22:25]
	v_mfma_f32_16x16x32_bf16 v[18:21], v[172:175], v[198:201], 0
	v_mfma_f32_16x16x32_bf16 v[18:21], v[176:179], v[202:205], v[18:21]
	v_mfma_f32_16x16x32_bf16 v[2:5], v[172:175], v[206:209], 0
	v_mfma_f32_16x16x32_bf16 v[2:5], v[176:179], v[210:213], v[2:5]
	s_setprio 2
	s_barrier
	v_mfma_f32_16x16x32_bf16 v[6:9], v[150:153], v[206:209], 0
	v_mfma_f32_16x16x32_bf16 v[6:9], v[168:171], v[210:213], v[6:9]
	s_setprio 0
	ds_read_b128 v[130:133], v164
	ds_read_b128 v[138:141], v164 offset:1024
	ds_read_b128 v[142:145], v164 offset:2048
	ds_read_b128 v[146:149], v164 offset:3072
	ds_read_b128 v[150:153], v165
	ds_read_b128 v[168:171], v165 offset:1024
	ds_read_b128 v[172:175], v165 offset:2048
	ds_read_b128 v[176:179], v165 offset:3072
	ds_read_b128 v[182:185], v163 offset:32768
	ds_read_b128 v[186:189], v163 offset:33792
	ds_read_b128 v[190:193], v163 offset:34816
	ds_read_b128 v[194:197], v163 offset:35840
	ds_read_b128 v[198:201], v163 offset:36864
	ds_read_b128 v[202:205], v163 offset:37888
	ds_read_b128 v[206:209], v163 offset:38912
	ds_read_b128 v[210:213], v163 offset:39936
	s_mov_b32 s75, m0
	s_mov_b32 m0, s42
	s_nop 0
	global_load_lds_dwordx4 v1, s[28:29]
	s_mov_b32 m0, s75
	s_nop 0
	s_mov_b32 s75, m0
	s_mov_b32 m0, s49
	s_nop 0
	global_load_lds_dwordx4 v157, s[28:29]
	s_mov_b32 m0, s75
	s_add_u32 s28, s28, 0x80000
	s_addc_u32 s29, s29, 0
	s_mov_b32 s75, m0
	s_mov_b32 m0, s56
	s_nop 0
	global_load_lds_dwordx4 v1, s[28:29]
	s_mov_b32 m0, s75
	s_nop 0
	s_mov_b32 s75, m0
	s_mov_b32 m0, s57
	s_nop 0
	global_load_lds_dwordx4 v157, s[28:29]
	s_mov_b32 m0, s75
	s_waitcnt vmcnt(8)
	s_waitcnt lgkmcnt(0)
	s_barrier
	s_setprio 1
	s_waitcnt lgkmcnt(7)
	v_mfma_f32_16x16x32_bf16 v[126:129], v[130:133], v[182:185], v[126:129]
	v_mfma_f32_16x16x32_bf16 v[126:129], v[138:141], v[186:189], v[126:129]
	s_waitcnt lgkmcnt(5)
	v_mfma_f32_16x16x32_bf16 v[122:125], v[142:145], v[182:185], v[122:125]
	v_mfma_f32_16x16x32_bf16 v[122:125], v[146:149], v[186:189], v[122:125]
	s_waitcnt lgkmcnt(3)
	v_mfma_f32_16x16x32_bf16 v[106:109], v[142:145], v[190:193], v[106:109]
	v_mfma_f32_16x16x32_bf16 v[106:109], v[146:149], v[194:197], v[106:109]
	s_waitcnt lgkmcnt(1)
	v_mfma_f32_16x16x32_bf16 v[110:113], v[130:133], v[190:193], v[110:113]
	v_mfma_f32_16x16x32_bf16 v[110:113], v[138:141], v[194:197], v[110:113]
	v_mfma_f32_16x16x32_bf16 v[94:97], v[130:133], v[198:201], v[94:97]
	v_mfma_f32_16x16x32_bf16 v[94:97], v[138:141], v[202:205], v[94:97]
	v_mfma_f32_16x16x32_bf16 v[90:93], v[142:145], v[198:201], v[90:93]
	v_mfma_f32_16x16x32_bf16 v[90:93], v[146:149], v[202:205], v[90:93]
	v_mfma_f32_16x16x32_bf16 v[74:77], v[142:145], v[206:209], v[74:77]
	v_mfma_f32_16x16x32_bf16 v[74:77], v[146:149], v[210:213], v[74:77]
	s_waitcnt lgkmcnt(0)
	v_mfma_f32_16x16x32_bf16 v[78:81], v[130:133], v[206:209], v[78:81]
	v_mfma_f32_16x16x32_bf16 v[78:81], v[138:141], v[210:213], v[78:81]
	s_setprio 0
	s_setprio 1
	v_mfma_f32_16x16x32_bf16 v[118:121], v[150:153], v[182:185], v[118:121]
	v_mfma_f32_16x16x32_bf16 v[118:121], v[168:171], v[186:189], v[118:121]
	v_mfma_f32_16x16x32_bf16 v[114:117], v[172:175], v[182:185], v[114:117]
	v_mfma_f32_16x16x32_bf16 v[114:117], v[176:179], v[186:189], v[114:117]
	v_mfma_f32_16x16x32_bf16 v[98:101], v[172:175], v[190:193], v[98:101]
	v_mfma_f32_16x16x32_bf16 v[98:101], v[176:179], v[194:197], v[98:101]
	v_mfma_f32_16x16x32_bf16 v[102:105], v[150:153], v[190:193], v[102:105]
	v_mfma_f32_16x16x32_bf16 v[102:105], v[168:171], v[194:197], v[102:105]
	v_mfma_f32_16x16x32_bf16 v[86:89], v[150:153], v[198:201], v[86:89]
	v_mfma_f32_16x16x32_bf16 v[86:89], v[168:171], v[202:205], v[86:89]
	v_mfma_f32_16x16x32_bf16 v[82:85], v[172:175], v[198:201], v[82:85]
	v_mfma_f32_16x16x32_bf16 v[82:85], v[176:179], v[202:205], v[82:85]
	v_mfma_f32_16x16x32_bf16 v[66:69], v[172:175], v[206:209], v[66:69]
	v_mfma_f32_16x16x32_bf16 v[66:69], v[176:179], v[210:213], v[66:69]
	s_setprio 2
	s_barrier
	v_mfma_f32_16x16x32_bf16 v[70:73], v[150:153], v[206:209], v[70:73]
	v_mfma_f32_16x16x32_bf16 v[70:73], v[168:171], v[210:213], v[70:73]
	s_setprio 0
	ds_read_b128 v[182:185], v163 offset:49152
	ds_read_b128 v[186:189], v163 offset:50176
	ds_read_b128 v[190:193], v163 offset:51200
	ds_read_b128 v[194:197], v163 offset:52224
	ds_read_b128 v[198:201], v163 offset:53248
	ds_read_b128 v[202:205], v163 offset:54272
	ds_read_b128 v[206:209], v163 offset:55296
	ds_read_b128 v[210:213], v163 offset:56320
	s_add_u32 s28, s10, 0x80
	s_addc_u32 s29, s11, 0
	s_mov_b32 s75, m0
	s_mov_b32 m0, s64
	s_nop 0
	global_load_lds_dwordx4 v156, s[28:29]
	s_mov_b32 m0, s75
	s_add_u32 s10, s10, 0x80080
	s_mov_b32 s75, m0
	s_mov_b32 m0, s65
	s_nop 0
	global_load_lds_dwordx4 v158, s[28:29]
	s_mov_b32 m0, s75
	s_addc_u32 s11, s11, 0
	s_mov_b32 s28, m0
	s_mov_b32 m0, s66
	s_nop 0
	global_load_lds_dwordx4 v156, s[10:11]
	s_mov_b32 m0, s28
	s_nop 0
	s_mov_b32 s28, m0
	s_mov_b32 m0, s67
	s_nop 0
	global_load_lds_dwordx4 v158, s[10:11]
	s_mov_b32 m0, s28
	s_waitcnt vmcnt(4)
	s_waitcnt lgkmcnt(0)
	s_barrier
	s_setprio 1
	s_waitcnt lgkmcnt(7)
	v_mfma_f32_16x16x32_bf16 v[62:65], v[130:133], v[182:185], v[62:65]
	v_mfma_f32_16x16x32_bf16 v[62:65], v[138:141], v[186:189], v[62:65]
	s_waitcnt lgkmcnt(5)
	v_mfma_f32_16x16x32_bf16 v[58:61], v[142:145], v[182:185], v[58:61]
	v_mfma_f32_16x16x32_bf16 v[58:61], v[146:149], v[186:189], v[58:61]
	s_waitcnt lgkmcnt(3)
	v_mfma_f32_16x16x32_bf16 v[42:45], v[142:145], v[190:193], v[42:45]
	v_mfma_f32_16x16x32_bf16 v[42:45], v[146:149], v[194:197], v[42:45]
	s_waitcnt lgkmcnt(1)
	v_mfma_f32_16x16x32_bf16 v[46:49], v[130:133], v[190:193], v[46:49]
	v_mfma_f32_16x16x32_bf16 v[46:49], v[138:141], v[194:197], v[46:49]
	v_mfma_f32_16x16x32_bf16 v[30:33], v[130:133], v[198:201], v[30:33]
	v_mfma_f32_16x16x32_bf16 v[30:33], v[138:141], v[202:205], v[30:33]
	v_mfma_f32_16x16x32_bf16 v[26:29], v[142:145], v[198:201], v[26:29]
	v_mfma_f32_16x16x32_bf16 v[26:29], v[146:149], v[202:205], v[26:29]
	v_mfma_f32_16x16x32_bf16 v[10:13], v[142:145], v[206:209], v[10:13]
	v_mfma_f32_16x16x32_bf16 v[10:13], v[146:149], v[210:213], v[10:13]
	s_waitcnt lgkmcnt(0)
	v_mfma_f32_16x16x32_bf16 v[14:17], v[130:133], v[206:209], v[14:17]
	v_mfma_f32_16x16x32_bf16 v[14:17], v[138:141], v[210:213], v[14:17]
	s_setprio 0
	s_setprio 1
	v_mfma_f32_16x16x32_bf16 v[54:57], v[150:153], v[182:185], v[54:57]
	v_mfma_f32_16x16x32_bf16 v[54:57], v[168:171], v[186:189], v[54:57]
	v_mfma_f32_16x16x32_bf16 v[50:53], v[172:175], v[182:185], v[50:53]
	v_mfma_f32_16x16x32_bf16 v[50:53], v[176:179], v[186:189], v[50:53]
	v_mfma_f32_16x16x32_bf16 v[34:37], v[172:175], v[190:193], v[34:37]
	v_mfma_f32_16x16x32_bf16 v[34:37], v[176:179], v[194:197], v[34:37]
	v_mfma_f32_16x16x32_bf16 v[38:41], v[150:153], v[190:193], v[38:41]
	v_mfma_f32_16x16x32_bf16 v[38:41], v[168:171], v[194:197], v[38:41]
	v_mfma_f32_16x16x32_bf16 v[22:25], v[150:153], v[198:201], v[22:25]
	v_mfma_f32_16x16x32_bf16 v[22:25], v[168:171], v[202:205], v[22:25]
	v_mfma_f32_16x16x32_bf16 v[18:21], v[172:175], v[198:201], v[18:21]
	v_mfma_f32_16x16x32_bf16 v[18:21], v[176:179], v[202:205], v[18:21]
	v_mfma_f32_16x16x32_bf16 v[2:5], v[172:175], v[206:209], v[2:5]
	v_mfma_f32_16x16x32_bf16 v[2:5], v[176:179], v[210:213], v[2:5]
	s_setprio 2
	s_barrier
	v_mfma_f32_16x16x32_bf16 v[6:9], v[150:153], v[206:209], v[6:9]
	v_mfma_f32_16x16x32_bf16 v[6:9], v[168:171], v[210:213], v[6:9]
	s_setprio 0
	s_add_i32 s74, s74, 2
	s_add_u32 s30, s30, 0x100
	s_addc_u32 s31, s31, 0
	s_add_u32 s4, s4, 0x100
	s_addc_u32 s5, s5, 0
	s_add_u32 s33, s33, 0x100
	s_addc_u32 s73, s73, 0
	s_cmp_gt_u32 s74, 29
	.p2align 6
.LBB0_654:
	ds_read_b128 v[130:133], v161
	ds_read_b128 v[138:141], v161 offset:1024
	ds_read_b128 v[142:145], v161 offset:2048
	ds_read_b128 v[146:149], v161 offset:3072
	ds_read_b128 v[150:153], v162
	ds_read_b128 v[168:171], v162 offset:1024
	ds_read_b128 v[172:175], v162 offset:2048
	ds_read_b128 v[176:179], v162 offset:3072
	s_cmp_eq_u32 s74, 28
	s_cselect_b32 s11, s21, s31
	s_cselect_b32 s10, s23, s30
	s_cselect_b32 s29, s7, s73
	s_cselect_b32 s28, s9, s33
	ds_read_b128 v[182:185], v163
	ds_read_b128 v[186:189], v163 offset:1024
	ds_read_b128 v[190:193], v163 offset:2048
	ds_read_b128 v[194:197], v163 offset:3072
	ds_read_b128 v[198:201], v163 offset:4096
	ds_read_b128 v[202:205], v163 offset:5120
	ds_read_b128 v[206:209], v163 offset:6144
	ds_read_b128 v[210:213], v163 offset:7168
	s_add_u32 s76, s4, 0xfff80000
	s_addc_u32 s77, s5, -1
	s_mov_b32 s75, m0
	s_mov_b32 m0, s80
	s_nop 0
	global_load_lds_dwordx4 v1, s[76:77]
	s_mov_b32 m0, s75
	s_nop 0
	s_mov_b32 s75, m0
	s_mov_b32 m0, s82
	s_nop 0
	global_load_lds_dwordx4 v157, s[76:77]
	s_mov_b32 m0, s75
	s_nop 0
	s_mov_b32 s75, m0
	s_mov_b32 m0, s81
	s_nop 0
	global_load_lds_dwordx4 v1, s[4:5]
	s_mov_b32 m0, s75
	s_nop 0
	s_mov_b32 s75, m0
	s_mov_b32 m0, s83
	s_nop 0
	global_load_lds_dwordx4 v157, s[4:5]
	s_mov_b32 m0, s75
	s_waitcnt vmcnt(8)
	s_waitcnt lgkmcnt(0)
	s_barrier
	s_setprio 1
	s_waitcnt lgkmcnt(7)
	v_mfma_f32_16x16x32_bf16 v[126:129], v[130:133], v[182:185], v[126:129]
	v_mfma_f32_16x16x32_bf16 v[126:129], v[138:141], v[186:189], v[126:129]
	s_waitcnt lgkmcnt(5)
	v_mfma_f32_16x16x32_bf16 v[122:125], v[142:145], v[182:185], v[122:125]
	v_mfma_f32_16x16x32_bf16 v[122:125], v[146:149], v[186:189], v[122:125]
	s_waitcnt lgkmcnt(3)
	v_mfma_f32_16x16x32_bf16 v[106:109], v[142:145], v[190:193], v[106:109]
	v_mfma_f32_16x16x32_bf16 v[106:109], v[146:149], v[194:197], v[106:109]
	s_waitcnt lgkmcnt(1)
	v_mfma_f32_16x16x32_bf16 v[110:113], v[130:133], v[190:193], v[110:113]
	v_mfma_f32_16x16x32_bf16 v[110:113], v[138:141], v[194:197], v[110:113]
	v_mfma_f32_16x16x32_bf16 v[94:97], v[130:133], v[198:201], v[94:97]
	v_mfma_f32_16x16x32_bf16 v[94:97], v[138:141], v[202:205], v[94:97]
	v_mfma_f32_16x16x32_bf16 v[90:93], v[142:145], v[198:201], v[90:93]
	v_mfma_f32_16x16x32_bf16 v[90:93], v[146:149], v[202:205], v[90:93]
	v_mfma_f32_16x16x32_bf16 v[74:77], v[142:145], v[206:209], v[74:77]
	v_mfma_f32_16x16x32_bf16 v[74:77], v[146:149], v[210:213], v[74:77]
	s_waitcnt lgkmcnt(0)
	v_mfma_f32_16x16x32_bf16 v[78:81], v[130:133], v[206:209], v[78:81]
	v_mfma_f32_16x16x32_bf16 v[78:81], v[138:141], v[210:213], v[78:81]
	s_setprio 0
	s_setprio 1
	v_mfma_f32_16x16x32_bf16 v[118:121], v[150:153], v[182:185], v[118:121]
	v_mfma_f32_16x16x32_bf16 v[118:121], v[168:171], v[186:189], v[118:121]
	v_mfma_f32_16x16x32_bf16 v[114:117], v[172:175], v[182:185], v[114:117]
	v_mfma_f32_16x16x32_bf16 v[114:117], v[176:179], v[186:189], v[114:117]
	v_mfma_f32_16x16x32_bf16 v[98:101], v[172:175], v[190:193], v[98:101]
	v_mfma_f32_16x16x32_bf16 v[98:101], v[176:179], v[194:197], v[98:101]
	v_mfma_f32_16x16x32_bf16 v[102:105], v[150:153], v[190:193], v[102:105]
	v_mfma_f32_16x16x32_bf16 v[102:105], v[168:171], v[194:197], v[102:105]
	v_mfma_f32_16x16x32_bf16 v[86:89], v[150:153], v[198:201], v[86:89]
	v_mfma_f32_16x16x32_bf16 v[86:89], v[168:171], v[202:205], v[86:89]
	v_mfma_f32_16x16x32_bf16 v[82:85], v[172:175], v[198:201], v[82:85]
	v_mfma_f32_16x16x32_bf16 v[82:85], v[176:179], v[202:205], v[82:85]
	v_mfma_f32_16x16x32_bf16 v[66:69], v[172:175], v[206:209], v[66:69]
	v_mfma_f32_16x16x32_bf16 v[66:69], v[176:179], v[210:213], v[66:69]
	s_setprio 2
	s_barrier
	v_mfma_f32_16x16x32_bf16 v[70:73], v[150:153], v[206:209], v[70:73]
	v_mfma_f32_16x16x32_bf16 v[70:73], v[168:171], v[210:213], v[70:73]
	s_setprio 0
	ds_read_b128 v[182:185], v163 offset:16384
	ds_read_b128 v[186:189], v163 offset:17408
	ds_read_b128 v[190:193], v163 offset:18432
	ds_read_b128 v[194:197], v163 offset:19456
	ds_read_b128 v[198:201], v163 offset:20480
	ds_read_b128 v[202:205], v163 offset:21504
	ds_read_b128 v[206:209], v163 offset:22528
	ds_read_b128 v[210:213], v163 offset:23552
	s_mov_b32 s75, m0
	s_mov_b32 m0, s43
	s_nop 0
	global_load_lds_dwordx4 v156, s[10:11]
	s_mov_b32 m0, s75
	s_add_u32 s76, s10, 0x80000
	s_mov_b32 s75, m0
	s_mov_b32 m0, s46
	s_nop 0
	global_load_lds_dwordx4 v158, s[10:11]
	s_mov_b32 m0, s75
	s_addc_u32 s77, s11, 0
	s_mov_b32 s75, m0
	s_mov_b32 m0, s47
	s_nop 0
	global_load_lds_dwordx4 v156, s[76:77]
	s_mov_b32 m0, s75
	s_nop 0
	s_mov_b32 s75, m0
	s_mov_b32 m0, s48
	s_nop 0
	global_load_lds_dwordx4 v158, s[76:77]
	s_mov_b32 m0, s75
	s_waitcnt vmcnt(4)
	s_waitcnt lgkmcnt(0)
	s_barrier
	s_setprio 1
	s_waitcnt lgkmcnt(7)
	v_mfma_f32_16x16x32_bf16 v[62:65], v[130:133], v[182:185], v[62:65]
	v_mfma_f32_16x16x32_bf16 v[62:65], v[138:141], v[186:189], v[62:65]
	s_waitcnt lgkmcnt(5)
	v_mfma_f32_16x16x32_bf16 v[58:61], v[142:145], v[182:185], v[58:61]
	v_mfma_f32_16x16x32_bf16 v[58:61], v[146:149], v[186:189], v[58:61]
	s_waitcnt lgkmcnt(3)
	v_mfma_f32_16x16x32_bf16 v[42:45], v[142:145], v[190:193], v[42:45]
	v_mfma_f32_16x16x32_bf16 v[42:45], v[146:149], v[194:197], v[42:45]
	s_waitcnt lgkmcnt(1)
	v_mfma_f32_16x16x32_bf16 v[46:49], v[130:133], v[190:193], v[46:49]
	v_mfma_f32_16x16x32_bf16 v[46:49], v[138:141], v[194:197], v[46:49]
	v_mfma_f32_16x16x32_bf16 v[30:33], v[130:133], v[198:201], v[30:33]
	v_mfma_f32_16x16x32_bf16 v[30:33], v[138:141], v[202:205], v[30:33]
	v_mfma_f32_16x16x32_bf16 v[26:29], v[142:145], v[198:201], v[26:29]
	v_mfma_f32_16x16x32_bf16 v[26:29], v[146:149], v[202:205], v[26:29]
	v_mfma_f32_16x16x32_bf16 v[10:13], v[142:145], v[206:209], v[10:13]
	v_mfma_f32_16x16x32_bf16 v[10:13], v[146:149], v[210:213], v[10:13]
	s_waitcnt lgkmcnt(0)
	v_mfma_f32_16x16x32_bf16 v[14:17], v[130:133], v[206:209], v[14:17]
	v_mfma_f32_16x16x32_bf16 v[14:17], v[138:141], v[210:213], v[14:17]
	s_setprio 0
	s_setprio 1
	v_mfma_f32_16x16x32_bf16 v[54:57], v[150:153], v[182:185], v[54:57]
	v_mfma_f32_16x16x32_bf16 v[54:57], v[168:171], v[186:189], v[54:57]
	v_mfma_f32_16x16x32_bf16 v[50:53], v[172:175], v[182:185], v[50:53]
	v_mfma_f32_16x16x32_bf16 v[50:53], v[176:179], v[186:189], v[50:53]
	v_mfma_f32_16x16x32_bf16 v[34:37], v[172:175], v[190:193], v[34:37]
	v_mfma_f32_16x16x32_bf16 v[34:37], v[176:179], v[194:197], v[34:37]
	v_mfma_f32_16x16x32_bf16 v[38:41], v[150:153], v[190:193], v[38:41]
	v_mfma_f32_16x16x32_bf16 v[38:41], v[168:171], v[194:197], v[38:41]
	v_mfma_f32_16x16x32_bf16 v[22:25], v[150:153], v[198:201], v[22:25]
	v_mfma_f32_16x16x32_bf16 v[22:25], v[168:171], v[202:205], v[22:25]
	v_mfma_f32_16x16x32_bf16 v[18:21], v[172:175], v[198:201], v[18:21]
	v_mfma_f32_16x16x32_bf16 v[18:21], v[176:179], v[202:205], v[18:21]
	v_mfma_f32_16x16x32_bf16 v[2:5], v[172:175], v[206:209], v[2:5]
	v_mfma_f32_16x16x32_bf16 v[2:5], v[176:179], v[210:213], v[2:5]
	s_setprio 2
	s_barrier
	v_mfma_f32_16x16x32_bf16 v[6:9], v[150:153], v[206:209], v[6:9]
	v_mfma_f32_16x16x32_bf16 v[6:9], v[168:171], v[210:213], v[6:9]
	s_setprio 0
	ds_read_b128 v[130:133], v164
	ds_read_b128 v[138:141], v164 offset:1024
	ds_read_b128 v[142:145], v164 offset:2048
	ds_read_b128 v[146:149], v164 offset:3072
	ds_read_b128 v[150:153], v165
	ds_read_b128 v[168:171], v165 offset:1024
	ds_read_b128 v[172:175], v165 offset:2048
	ds_read_b128 v[176:179], v165 offset:3072
	ds_read_b128 v[182:185], v163 offset:32768
	ds_read_b128 v[186:189], v163 offset:33792
	ds_read_b128 v[190:193], v163 offset:34816
	ds_read_b128 v[194:197], v163 offset:35840
	ds_read_b128 v[198:201], v163 offset:36864
	ds_read_b128 v[202:205], v163 offset:37888
	ds_read_b128 v[206:209], v163 offset:38912
	ds_read_b128 v[210:213], v163 offset:39936
	s_mov_b32 s75, m0
	s_mov_b32 m0, s42
	s_nop 0
	global_load_lds_dwordx4 v1, s[28:29]
	s_mov_b32 m0, s75
	s_nop 0
	s_mov_b32 s75, m0
	s_mov_b32 m0, s49
	s_nop 0
	global_load_lds_dwordx4 v157, s[28:29]
	s_mov_b32 m0, s75
	s_add_u32 s28, s28, 0x80000
	s_addc_u32 s29, s29, 0
	s_mov_b32 s75, m0
	s_mov_b32 m0, s56
	s_nop 0
	global_load_lds_dwordx4 v1, s[28:29]
	s_mov_b32 m0, s75
	s_nop 0
	s_mov_b32 s75, m0
	s_mov_b32 m0, s57
	s_nop 0
	global_load_lds_dwordx4 v157, s[28:29]
	s_mov_b32 m0, s75
	s_waitcnt vmcnt(8)
	s_waitcnt lgkmcnt(0)
	s_barrier
	s_setprio 1
	s_waitcnt lgkmcnt(7)
	v_mfma_f32_16x16x32_bf16 v[126:129], v[130:133], v[182:185], v[126:129]
	v_mfma_f32_16x16x32_bf16 v[126:129], v[138:141], v[186:189], v[126:129]
	s_waitcnt lgkmcnt(5)
	v_mfma_f32_16x16x32_bf16 v[122:125], v[142:145], v[182:185], v[122:125]
	v_mfma_f32_16x16x32_bf16 v[122:125], v[146:149], v[186:189], v[122:125]
	s_waitcnt lgkmcnt(3)
	v_mfma_f32_16x16x32_bf16 v[106:109], v[142:145], v[190:193], v[106:109]
	v_mfma_f32_16x16x32_bf16 v[106:109], v[146:149], v[194:197], v[106:109]
	s_waitcnt lgkmcnt(1)
	v_mfma_f32_16x16x32_bf16 v[110:113], v[130:133], v[190:193], v[110:113]
	v_mfma_f32_16x16x32_bf16 v[110:113], v[138:141], v[194:197], v[110:113]
	v_mfma_f32_16x16x32_bf16 v[94:97], v[130:133], v[198:201], v[94:97]
	v_mfma_f32_16x16x32_bf16 v[94:97], v[138:141], v[202:205], v[94:97]
	v_mfma_f32_16x16x32_bf16 v[90:93], v[142:145], v[198:201], v[90:93]
	v_mfma_f32_16x16x32_bf16 v[90:93], v[146:149], v[202:205], v[90:93]
	v_mfma_f32_16x16x32_bf16 v[74:77], v[142:145], v[206:209], v[74:77]
	v_mfma_f32_16x16x32_bf16 v[74:77], v[146:149], v[210:213], v[74:77]
	s_waitcnt lgkmcnt(0)
	v_mfma_f32_16x16x32_bf16 v[78:81], v[130:133], v[206:209], v[78:81]
	v_mfma_f32_16x16x32_bf16 v[78:81], v[138:141], v[210:213], v[78:81]
	s_setprio 0
	s_setprio 1
	v_mfma_f32_16x16x32_bf16 v[118:121], v[150:153], v[182:185], v[118:121]
	v_mfma_f32_16x16x32_bf16 v[118:121], v[168:171], v[186:189], v[118:121]
	v_mfma_f32_16x16x32_bf16 v[114:117], v[172:175], v[182:185], v[114:117]
	v_mfma_f32_16x16x32_bf16 v[114:117], v[176:179], v[186:189], v[114:117]
	v_mfma_f32_16x16x32_bf16 v[98:101], v[172:175], v[190:193], v[98:101]
	v_mfma_f32_16x16x32_bf16 v[98:101], v[176:179], v[194:197], v[98:101]
	v_mfma_f32_16x16x32_bf16 v[102:105], v[150:153], v[190:193], v[102:105]
	v_mfma_f32_16x16x32_bf16 v[102:105], v[168:171], v[194:197], v[102:105]
	v_mfma_f32_16x16x32_bf16 v[86:89], v[150:153], v[198:201], v[86:89]
	v_mfma_f32_16x16x32_bf16 v[86:89], v[168:171], v[202:205], v[86:89]
	v_mfma_f32_16x16x32_bf16 v[82:85], v[172:175], v[198:201], v[82:85]
	v_mfma_f32_16x16x32_bf16 v[82:85], v[176:179], v[202:205], v[82:85]
	v_mfma_f32_16x16x32_bf16 v[66:69], v[172:175], v[206:209], v[66:69]
	v_mfma_f32_16x16x32_bf16 v[66:69], v[176:179], v[210:213], v[66:69]
	s_setprio 2
	s_barrier
	v_mfma_f32_16x16x32_bf16 v[70:73], v[150:153], v[206:209], v[70:73]
	v_mfma_f32_16x16x32_bf16 v[70:73], v[168:171], v[210:213], v[70:73]
	s_setprio 0
	ds_read_b128 v[182:185], v163 offset:49152
	ds_read_b128 v[186:189], v163 offset:50176
	ds_read_b128 v[190:193], v163 offset:51200
	ds_read_b128 v[194:197], v163 offset:52224
	ds_read_b128 v[198:201], v163 offset:53248
	ds_read_b128 v[202:205], v163 offset:54272
	ds_read_b128 v[206:209], v163 offset:55296
	ds_read_b128 v[210:213], v163 offset:56320
	s_add_u32 s28, s10, 0x80
	s_addc_u32 s29, s11, 0
	s_mov_b32 s75, m0
	s_mov_b32 m0, s64
	s_nop 0
	global_load_lds_dwordx4 v156, s[28:29]
	s_mov_b32 m0, s75
	s_add_u32 s10, s10, 0x80080
	s_mov_b32 s75, m0
	s_mov_b32 m0, s65
	s_nop 0
	global_load_lds_dwordx4 v158, s[28:29]
	s_mov_b32 m0, s75
	s_addc_u32 s11, s11, 0
	s_mov_b32 s28, m0
	s_mov_b32 m0, s66
	s_nop 0
	global_load_lds_dwordx4 v156, s[10:11]
	s_mov_b32 m0, s28
	s_nop 0
	s_mov_b32 s28, m0
	s_mov_b32 m0, s67
	s_nop 0
	global_load_lds_dwordx4 v158, s[10:11]
	s_mov_b32 m0, s28
	s_waitcnt vmcnt(4)
	s_waitcnt lgkmcnt(0)
	s_barrier
	s_setprio 1
	s_waitcnt lgkmcnt(7)
	v_mfma_f32_16x16x32_bf16 v[62:65], v[130:133], v[182:185], v[62:65]
	v_mfma_f32_16x16x32_bf16 v[62:65], v[138:141], v[186:189], v[62:65]
	s_waitcnt lgkmcnt(5)
	v_mfma_f32_16x16x32_bf16 v[58:61], v[142:145], v[182:185], v[58:61]
	v_mfma_f32_16x16x32_bf16 v[58:61], v[146:149], v[186:189], v[58:61]
	s_waitcnt lgkmcnt(3)
	v_mfma_f32_16x16x32_bf16 v[42:45], v[142:145], v[190:193], v[42:45]
	v_mfma_f32_16x16x32_bf16 v[42:45], v[146:149], v[194:197], v[42:45]
	s_waitcnt lgkmcnt(1)
	v_mfma_f32_16x16x32_bf16 v[46:49], v[130:133], v[190:193], v[46:49]
	v_mfma_f32_16x16x32_bf16 v[46:49], v[138:141], v[194:197], v[46:49]
	v_mfma_f32_16x16x32_bf16 v[30:33], v[130:133], v[198:201], v[30:33]
	v_mfma_f32_16x16x32_bf16 v[30:33], v[138:141], v[202:205], v[30:33]
	v_mfma_f32_16x16x32_bf16 v[26:29], v[142:145], v[198:201], v[26:29]
	v_mfma_f32_16x16x32_bf16 v[26:29], v[146:149], v[202:205], v[26:29]
	v_mfma_f32_16x16x32_bf16 v[10:13], v[142:145], v[206:209], v[10:13]
	v_mfma_f32_16x16x32_bf16 v[10:13], v[146:149], v[210:213], v[10:13]
	s_waitcnt lgkmcnt(0)
	v_mfma_f32_16x16x32_bf16 v[14:17], v[130:133], v[206:209], v[14:17]
	v_mfma_f32_16x16x32_bf16 v[14:17], v[138:141], v[210:213], v[14:17]
	s_setprio 0
	s_setprio 1
	v_mfma_f32_16x16x32_bf16 v[54:57], v[150:153], v[182:185], v[54:57]
	v_mfma_f32_16x16x32_bf16 v[54:57], v[168:171], v[186:189], v[54:57]
	v_mfma_f32_16x16x32_bf16 v[50:53], v[172:175], v[182:185], v[50:53]
	v_mfma_f32_16x16x32_bf16 v[50:53], v[176:179], v[186:189], v[50:53]
	v_mfma_f32_16x16x32_bf16 v[34:37], v[172:175], v[190:193], v[34:37]
	v_mfma_f32_16x16x32_bf16 v[34:37], v[176:179], v[194:197], v[34:37]
	v_mfma_f32_16x16x32_bf16 v[38:41], v[150:153], v[190:193], v[38:41]
	v_mfma_f32_16x16x32_bf16 v[38:41], v[168:171], v[194:197], v[38:41]
	v_mfma_f32_16x16x32_bf16 v[22:25], v[150:153], v[198:201], v[22:25]
	v_mfma_f32_16x16x32_bf16 v[22:25], v[168:171], v[202:205], v[22:25]
	v_mfma_f32_16x16x32_bf16 v[18:21], v[172:175], v[198:201], v[18:21]
	v_mfma_f32_16x16x32_bf16 v[18:21], v[176:179], v[202:205], v[18:21]
	v_mfma_f32_16x16x32_bf16 v[2:5], v[172:175], v[206:209], v[2:5]
	v_mfma_f32_16x16x32_bf16 v[2:5], v[176:179], v[210:213], v[2:5]
	s_setprio 2
	s_barrier
	v_mfma_f32_16x16x32_bf16 v[6:9], v[150:153], v[206:209], v[6:9]
	v_mfma_f32_16x16x32_bf16 v[6:9], v[168:171], v[210:213], v[6:9]
	s_setprio 0
	s_add_i32 s74, s74, 2
	s_add_u32 s30, s30, 0x100
	s_addc_u32 s31, s31, 0
	s_add_u32 s4, s4, 0x100
	s_addc_u32 s5, s5, 0
	s_add_u32 s33, s33, 0x100
	s_addc_u32 s73, s73, 0
	s_cmp_gt_u32 s74, 29
	s_cbranch_scc0 .LBB0_654
	v_mov_b32_e32 v212, v252
	v_mov_b32_e32 v213, v253
	s_and_b64 vcc, exec, s[18:19]
	s_cbranch_vccz .LBB0_657
	s_barrier

.LBB0_1052:
	s_ashr_i32 s13, s12, 31
	s_lshl_b64 s[14:15], s[12:13], 20
	s_add_u32 s14, s28, s14
	s_addc_u32 s15, s29, s15
	s_and_b64 s[16:17], s[2:3], exec
	s_cselect_b32 s13, s15, s23
	s_cselect_b32 s67, s14, s22
	s_ashr_i32 s11, s10, 31
	s_lshl_b64 s[16:17], s[10:11], 20
	s_add_u32 s16, s30, s16
	s_addc_u32 s17, s31, s17
	s_and_b64 s[24:25], s[2:3], exec
	s_cselect_b32 s11, s17, s21
	s_cselect_b32 s73, s16, s20
	s_add_u32 s74, s20, 0x100
	s_addc_u32 s75, s21, 0
	s_add_u32 s20, s22, 0x80080
	s_addc_u32 s21, s23, 0
	s_add_u32 s76, s22, 0x100
	s_addc_u32 s77, s23, 0
	s_mov_b32 s78, -2
	s_waitcnt vmcnt(25)
	s_waitcnt vmcnt(24)
	s_waitcnt vmcnt(15)
	s_waitcnt vmcnt(14)
	s_waitcnt vmcnt(13)
	s_waitcnt vmcnt(12)
	s_waitcnt vmcnt(11)
	s_waitcnt vmcnt(10)
	s_waitcnt vmcnt(9)
	s_waitcnt vmcnt(8)
	s_waitcnt vmcnt(7)
	s_waitcnt vmcnt(6)
	s_waitcnt vmcnt(5)
	s_waitcnt vmcnt(4)
	s_waitcnt vmcnt(3)
	s_waitcnt vmcnt(2)
	s_waitcnt vmcnt(1)
	s_waitcnt vmcnt(0)
	v_mov_b32_e32 v252, v174
	v_mov_b32_e32 v253, v175
	v_mov_b32_e32 v254, v210
	v_mov_b32_e32 v255, v211
	ds_read_b128 v[130:133], v181
	ds_read_b128 v[134:137], v181 offset:1024
	ds_read_b128 v[138:141], v181 offset:2048
	ds_read_b128 v[142:145], v181 offset:3072
	ds_read_b128 v[146:149], v182
	ds_read_b128 v[150:153], v182 offset:1024
	ds_read_b128 v[154:157], v182 offset:2048
	ds_read_b128 v[158:161], v182 offset:3072
	s_cmp_eq_u32 s78, 28
	s_cselect_b32 s23, s11, s75
	s_cselect_b32 s22, s73, s74
	s_cselect_b32 s25, s13, s77
	s_cselect_b32 s24, s67, s76
	ds_read_b128 v[168:171], v183
	ds_read_b128 v[172:175], v183 offset:1024
	ds_read_b128 v[188:191], v183 offset:2048
	ds_read_b128 v[192:195], v183 offset:3072
	ds_read_b128 v[196:199], v183 offset:4096
	ds_read_b128 v[200:203], v183 offset:5120
	ds_read_b128 v[204:207], v183 offset:6144
	ds_read_b128 v[208:211], v183 offset:7168
	s_add_u32 s80, s20, 0xfff80000
	s_addc_u32 s81, s21, -1
	s_mov_b32 s79, m0
	s_mov_b32 m0, s58
	s_nop 0
	global_load_lds_dwordx4 v1, s[80:81]
	s_mov_b32 m0, s79
	s_nop 0
	s_mov_b32 s79, m0
	s_mov_b32 m0, s64
	s_nop 0
	global_load_lds_dwordx4 v177, s[80:81]
	s_mov_b32 m0, s79
	s_nop 0
	s_mov_b32 s79, m0
	s_mov_b32 m0, s59
	s_nop 0
	global_load_lds_dwordx4 v1, s[20:21]
	s_mov_b32 m0, s79
	s_nop 0
	s_mov_b32 s79, m0
	s_mov_b32 m0, s65
	s_nop 0
	global_load_lds_dwordx4 v177, s[20:21]
	s_mov_b32 m0, s79
	s_waitcnt vmcnt(8)
	s_waitcnt lgkmcnt(0)
	s_barrier
	s_setprio 1
	s_waitcnt lgkmcnt(7)
	v_mfma_f32_16x16x32_bf16 v[126:129], v[130:133], v[168:171], 0
	v_mfma_f32_16x16x32_bf16 v[126:129], v[134:137], v[172:175], v[126:129]
	s_waitcnt lgkmcnt(5)
	v_mfma_f32_16x16x32_bf16 v[122:125], v[138:141], v[168:171], 0
	v_mfma_f32_16x16x32_bf16 v[122:125], v[142:145], v[172:175], v[122:125]
	s_waitcnt lgkmcnt(3)
	v_mfma_f32_16x16x32_bf16 v[114:117], v[138:141], v[188:191], 0
	v_mfma_f32_16x16x32_bf16 v[114:117], v[142:145], v[192:195], v[114:117]
	s_waitcnt lgkmcnt(1)
	v_mfma_f32_16x16x32_bf16 v[118:121], v[130:133], v[188:191], 0
	v_mfma_f32_16x16x32_bf16 v[118:121], v[134:137], v[192:195], v[118:121]
	v_mfma_f32_16x16x32_bf16 v[94:97], v[130:133], v[196:199], 0
	v_mfma_f32_16x16x32_bf16 v[94:97], v[134:137], v[200:203], v[94:97]
	v_mfma_f32_16x16x32_bf16 v[90:93], v[138:141], v[196:199], 0
	v_mfma_f32_16x16x32_bf16 v[90:93], v[142:145], v[200:203], v[90:93]
	v_mfma_f32_16x16x32_bf16 v[78:81], v[138:141], v[204:207], 0
	v_mfma_f32_16x16x32_bf16 v[78:81], v[142:145], v[208:211], v[78:81]
	s_waitcnt lgkmcnt(0)
	v_mfma_f32_16x16x32_bf16 v[86:89], v[130:133], v[204:207], 0
	v_mfma_f32_16x16x32_bf16 v[86:89], v[134:137], v[208:211], v[86:89]
	s_setprio 0
	s_setprio 1
	v_mfma_f32_16x16x32_bf16 v[110:113], v[146:149], v[168:171], 0
	v_mfma_f32_16x16x32_bf16 v[110:113], v[150:153], v[172:175], v[110:113]
	v_mfma_f32_16x16x32_bf16 v[106:109], v[154:157], v[168:171], 0
	v_mfma_f32_16x16x32_bf16 v[106:109], v[158:161], v[172:175], v[106:109]
	v_mfma_f32_16x16x32_bf16 v[98:101], v[154:157], v[188:191], 0
	v_mfma_f32_16x16x32_bf16 v[98:101], v[158:161], v[192:195], v[98:101]
	v_mfma_f32_16x16x32_bf16 v[102:105], v[146:149], v[188:191], 0
	v_mfma_f32_16x16x32_bf16 v[102:105], v[150:153], v[192:195], v[102:105]
	v_mfma_f32_16x16x32_bf16 v[82:85], v[146:149], v[196:199], 0
	v_mfma_f32_16x16x32_bf16 v[82:85], v[150:153], v[200:203], v[82:85]
	v_mfma_f32_16x16x32_bf16 v[74:77], v[154:157], v[196:199], 0
	v_mfma_f32_16x16x32_bf16 v[74:77], v[158:161], v[200:203], v[74:77]
	v_mfma_f32_16x16x32_bf16 v[66:69], v[154:157], v[204:207], 0
	v_mfma_f32_16x16x32_bf16 v[66:69], v[158:161], v[208:211], v[66:69]
	s_setprio 2
	s_barrier
	v_mfma_f32_16x16x32_bf16 v[70:73], v[146:149], v[204:207], 0
	v_mfma_f32_16x16x32_bf16 v[70:73], v[150:153], v[208:211], v[70:73]
	s_setprio 0
	ds_read_b128 v[168:171], v183 offset:16384
	ds_read_b128 v[172:175], v183 offset:17408
	ds_read_b128 v[188:191], v183 offset:18432
	ds_read_b128 v[192:195], v183 offset:19456
	ds_read_b128 v[196:199], v183 offset:20480
	ds_read_b128 v[200:203], v183 offset:21504
	ds_read_b128 v[204:207], v183 offset:22528
	ds_read_b128 v[208:211], v183 offset:23552
	s_mov_b32 s79, m0
	s_mov_b32 m0, s35
	s_nop 0
	global_load_lds_dwordx4 v176, s[22:23]
	s_mov_b32 m0, s79
	s_add_u32 s80, s22, 0x80000
	s_mov_b32 s79, m0
	s_mov_b32 m0, s36
	s_nop 0
	global_load_lds_dwordx4 v178, s[22:23]
	s_mov_b32 m0, s79
	s_addc_u32 s81, s23, 0
	s_mov_b32 s79, m0
	s_mov_b32 m0, s37
	s_nop 0
	global_load_lds_dwordx4 v176, s[80:81]
	s_mov_b32 m0, s79
	s_nop 0
	s_mov_b32 s79, m0
	s_mov_b32 m0, s40
	s_nop 0
	global_load_lds_dwordx4 v178, s[80:81]
	s_mov_b32 m0, s79
	s_waitcnt vmcnt(4)
	s_waitcnt lgkmcnt(0)
	s_barrier
	s_setprio 1
	s_waitcnt lgkmcnt(7)
	v_mfma_f32_16x16x32_bf16 v[62:65], v[130:133], v[168:171], 0
	v_mfma_f32_16x16x32_bf16 v[62:65], v[134:137], v[172:175], v[62:65]
	s_waitcnt lgkmcnt(5)
	v_mfma_f32_16x16x32_bf16 v[58:61], v[138:141], v[168:171], 0
	v_mfma_f32_16x16x32_bf16 v[58:61], v[142:145], v[172:175], v[58:61]
	s_waitcnt lgkmcnt(3)
	v_mfma_f32_16x16x32_bf16 v[42:45], v[138:141], v[188:191], 0
	v_mfma_f32_16x16x32_bf16 v[42:45], v[142:145], v[192:195], v[42:45]
	s_waitcnt lgkmcnt(1)
	v_mfma_f32_16x16x32_bf16 v[46:49], v[130:133], v[188:191], 0
	v_mfma_f32_16x16x32_bf16 v[46:49], v[134:137], v[192:195], v[46:49]
	v_mfma_f32_16x16x32_bf16 v[30:33], v[130:133], v[196:199], 0
	v_mfma_f32_16x16x32_bf16 v[30:33], v[134:137], v[200:203], v[30:33]
	v_mfma_f32_16x16x32_bf16 v[26:29], v[138:141], v[196:199], 0
	v_mfma_f32_16x16x32_bf16 v[26:29], v[142:145], v[200:203], v[26:29]
	v_mfma_f32_16x16x32_bf16 v[10:13], v[138:141], v[204:207], 0
	v_mfma_f32_16x16x32_bf16 v[10:13], v[142:145], v[208:211], v[10:13]
	s_waitcnt lgkmcnt(0)
	v_mfma_f32_16x16x32_bf16 v[14:17], v[130:133], v[204:207], 0
	v_mfma_f32_16x16x32_bf16 v[14:17], v[134:137], v[208:211], v[14:17]
	s_setprio 0
	s_setprio 1
	v_mfma_f32_16x16x32_bf16 v[54:57], v[146:149], v[168:171], 0
	v_mfma_f32_16x16x32_bf16 v[54:57], v[150:153], v[172:175], v[54:57]
	v_mfma_f32_16x16x32_bf16 v[50:53], v[154:157], v[168:171], 0
	v_mfma_f32_16x16x32_bf16 v[50:53], v[158:161], v[172:175], v[50:53]
	v_mfma_f32_16x16x32_bf16 v[34:37], v[154:157], v[188:191], 0
	v_mfma_f32_16x16x32_bf16 v[34:37], v[158:161], v[192:195], v[34:37]
	v_mfma_f32_16x16x32_bf16 v[38:41], v[146:149], v[188:191], 0
	v_mfma_f32_16x16x32_bf16 v[38:41], v[150:153], v[192:195], v[38:41]
	v_mfma_f32_16x16x32_bf16 v[22:25], v[146:149], v[196:199], 0
	v_mfma_f32_16x16x32_bf16 v[22:25], v[150:153], v[200:203], v[22:25]
	v_mfma_f32_16x16x32_bf16 v[18:21], v[154:157], v[196:199], 0
	v_mfma_f32_16x16x32_bf16 v[18:21], v[158:161], v[200:203], v[18:21]
	v_mfma_f32_16x16x32_bf16 v[2:5], v[154:157], v[204:207], 0
	v_mfma_f32_16x16x32_bf16 v[2:5], v[158:161], v[208:211], v[2:5]
	s_setprio 2
	s_barrier
	v_mfma_f32_16x16x32_bf16 v[6:9], v[146:149], v[204:207], 0
	v_mfma_f32_16x16x32_bf16 v[6:9], v[150:153], v[208:211], v[6:9]
	s_setprio 0
	ds_read_b128 v[130:133], v184
	ds_read_b128 v[134:137], v184 offset:1024
	ds_read_b128 v[138:141], v184 offset:2048
	ds_read_b128 v[142:145], v184 offset:3072
	ds_read_b128 v[146:149], v185
	ds_read_b128 v[150:153], v185 offset:1024
	ds_read_b128 v[154:157], v185 offset:2048
	ds_read_b128 v[158:161], v185 offset:3072
	ds_read_b128 v[168:171], v183 offset:32768
	ds_read_b128 v[172:175], v183 offset:33792
	ds_read_b128 v[188:191], v183 offset:34816
	ds_read_b128 v[192:195], v183 offset:35840
	ds_read_b128 v[196:199], v183 offset:36864
	ds_read_b128 v[200:203], v183 offset:37888
	ds_read_b128 v[204:207], v183 offset:38912
	ds_read_b128 v[208:211], v183 offset:39936
	s_mov_b32 s79, m0
	s_mov_b32 m0, s34
	s_nop 0
	global_load_lds_dwordx4 v1, s[24:25]
	s_mov_b32 m0, s79
	s_nop 0
	s_mov_b32 s79, m0
	s_mov_b32 m0, s41
	s_nop 0
	global_load_lds_dwordx4 v177, s[24:25]
	s_mov_b32 m0, s79
	s_add_u32 s24, s24, 0x80000
	s_addc_u32 s25, s25, 0
	s_mov_b32 s79, m0
	s_mov_b32 m0, s42
	s_nop 0
	global_load_lds_dwordx4 v1, s[24:25]
	s_mov_b32 m0, s79
	s_nop 0
	s_mov_b32 s79, m0
	s_mov_b32 m0, s43
	s_nop 0
	global_load_lds_dwordx4 v177, s[24:25]
	s_mov_b32 m0, s79
	s_waitcnt vmcnt(8)
	s_waitcnt lgkmcnt(0)
	s_barrier
	s_setprio 1
	s_waitcnt lgkmcnt(7)
	v_mfma_f32_16x16x32_bf16 v[126:129], v[130:133], v[168:171], v[126:129]
	v_mfma_f32_16x16x32_bf16 v[126:129], v[134:137], v[172:175], v[126:129]
	s_waitcnt lgkmcnt(5)
	v_mfma_f32_16x16x32_bf16 v[122:125], v[138:141], v[168:171], v[122:125]
	v_mfma_f32_16x16x32_bf16 v[122:125], v[142:145], v[172:175], v[122:125]
	s_waitcnt lgkmcnt(3)
	v_mfma_f32_16x16x32_bf16 v[114:117], v[138:141], v[188:191], v[114:117]
	v_mfma_f32_16x16x32_bf16 v[114:117], v[142:145], v[192:195], v[114:117]
	s_waitcnt lgkmcnt(1)
	v_mfma_f32_16x16x32_bf16 v[118:121], v[130:133], v[188:191], v[118:121]
	v_mfma_f32_16x16x32_bf16 v[118:121], v[134:137], v[192:195], v[118:121]
	v_mfma_f32_16x16x32_bf16 v[94:97], v[130:133], v[196:199], v[94:97]
	v_mfma_f32_16x16x32_bf16 v[94:97], v[134:137], v[200:203], v[94:97]
	v_mfma_f32_16x16x32_bf16 v[90:93], v[138:141], v[196:199], v[90:93]
	v_mfma_f32_16x16x32_bf16 v[90:93], v[142:145], v[200:203], v[90:93]
	v_mfma_f32_16x16x32_bf16 v[78:81], v[138:141], v[204:207], v[78:81]
	v_mfma_f32_16x16x32_bf16 v[78:81], v[142:145], v[208:211], v[78:81]
	s_waitcnt lgkmcnt(0)
	v_mfma_f32_16x16x32_bf16 v[86:89], v[130:133], v[204:207], v[86:89]
	v_mfma_f32_16x16x32_bf16 v[86:89], v[134:137], v[208:211], v[86:89]
	s_setprio 0
	s_setprio 1
	v_mfma_f32_16x16x32_bf16 v[110:113], v[146:149], v[168:171], v[110:113]
	v_mfma_f32_16x16x32_bf16 v[110:113], v[150:153], v[172:175], v[110:113]
	v_mfma_f32_16x16x32_bf16 v[106:109], v[154:157], v[168:171], v[106:109]
	v_mfma_f32_16x16x32_bf16 v[106:109], v[158:161], v[172:175], v[106:109]
	v_mfma_f32_16x16x32_bf16 v[98:101], v[154:157], v[188:191], v[98:101]
	v_mfma_f32_16x16x32_bf16 v[98:101], v[158:161], v[192:195], v[98:101]
	v_mfma_f32_16x16x32_bf16 v[102:105], v[146:149], v[188:191], v[102:105]
	v_mfma_f32_16x16x32_bf16 v[102:105], v[150:153], v[192:195], v[102:105]
	v_mfma_f32_16x16x32_bf16 v[82:85], v[146:149], v[196:199], v[82:85]
	v_mfma_f32_16x16x32_bf16 v[82:85], v[150:153], v[200:203], v[82:85]
	v_mfma_f32_16x16x32_bf16 v[74:77], v[154:157], v[196:199], v[74:77]
	v_mfma_f32_16x16x32_bf16 v[74:77], v[158:161], v[200:203], v[74:77]
	v_mfma_f32_16x16x32_bf16 v[66:69], v[154:157], v[204:207], v[66:69]
	v_mfma_f32_16x16x32_bf16 v[66:69], v[158:161], v[208:211], v[66:69]
	s_setprio 2
	s_barrier
	v_mfma_f32_16x16x32_bf16 v[70:73], v[146:149], v[204:207], v[70:73]
	v_mfma_f32_16x16x32_bf16 v[70:73], v[150:153], v[208:211], v[70:73]
	s_setprio 0
	ds_read_b128 v[168:171], v183 offset:49152
	ds_read_b128 v[172:175], v183 offset:50176
	ds_read_b128 v[188:191], v183 offset:51200
	ds_read_b128 v[192:195], v183 offset:52224
	ds_read_b128 v[196:199], v183 offset:53248
	ds_read_b128 v[200:203], v183 offset:54272
	ds_read_b128 v[204:207], v183 offset:55296
	ds_read_b128 v[208:211], v183 offset:56320
	s_add_u32 s24, s22, 0x80
	s_addc_u32 s25, s23, 0
	s_mov_b32 s79, m0
	s_mov_b32 m0, s46
	s_nop 0
	global_load_lds_dwordx4 v176, s[24:25]
	s_mov_b32 m0, s79
	s_add_u32 s22, s22, 0x80080
	s_mov_b32 s79, m0
	s_mov_b32 m0, s47
	s_nop 0
	global_load_lds_dwordx4 v178, s[24:25]
	s_mov_b32 m0, s79
	s_addc_u32 s23, s23, 0
	s_mov_b32 s24, m0
	s_mov_b32 m0, s48
	s_nop 0
	global_load_lds_dwordx4 v176, s[22:23]
	s_mov_b32 m0, s24
	s_nop 0
	s_mov_b32 s24, m0
	s_mov_b32 m0, s49
	s_nop 0
	global_load_lds_dwordx4 v178, s[22:23]
	s_mov_b32 m0, s24
	s_waitcnt vmcnt(4)
	s_waitcnt lgkmcnt(0)
	s_barrier
	s_setprio 1
	s_waitcnt lgkmcnt(7)
	v_mfma_f32_16x16x32_bf16 v[62:65], v[130:133], v[168:171], v[62:65]
	v_mfma_f32_16x16x32_bf16 v[62:65], v[134:137], v[172:175], v[62:65]
	s_waitcnt lgkmcnt(5)
	v_mfma_f32_16x16x32_bf16 v[58:61], v[138:141], v[168:171], v[58:61]
	v_mfma_f32_16x16x32_bf16 v[58:61], v[142:145], v[172:175], v[58:61]
	s_waitcnt lgkmcnt(3)
	v_mfma_f32_16x16x32_bf16 v[42:45], v[138:141], v[188:191], v[42:45]
	v_mfma_f32_16x16x32_bf16 v[42:45], v[142:145], v[192:195], v[42:45]
	s_waitcnt lgkmcnt(1)
	v_mfma_f32_16x16x32_bf16 v[46:49], v[130:133], v[188:191], v[46:49]
	v_mfma_f32_16x16x32_bf16 v[46:49], v[134:137], v[192:195], v[46:49]
	v_mfma_f32_16x16x32_bf16 v[30:33], v[130:133], v[196:199], v[30:33]
	v_mfma_f32_16x16x32_bf16 v[30:33], v[134:137], v[200:203], v[30:33]
	v_mfma_f32_16x16x32_bf16 v[26:29], v[138:141], v[196:199], v[26:29]
	v_mfma_f32_16x16x32_bf16 v[26:29], v[142:145], v[200:203], v[26:29]
	v_mfma_f32_16x16x32_bf16 v[10:13], v[138:141], v[204:207], v[10:13]
	v_mfma_f32_16x16x32_bf16 v[10:13], v[142:145], v[208:211], v[10:13]
	s_waitcnt lgkmcnt(0)
	v_mfma_f32_16x16x32_bf16 v[14:17], v[130:133], v[204:207], v[14:17]
	v_mfma_f32_16x16x32_bf16 v[14:17], v[134:137], v[208:211], v[14:17]
	s_setprio 0
	s_setprio 1
	v_mfma_f32_16x16x32_bf16 v[54:57], v[146:149], v[168:171], v[54:57]
	v_mfma_f32_16x16x32_bf16 v[54:57], v[150:153], v[172:175], v[54:57]
	v_mfma_f32_16x16x32_bf16 v[50:53], v[154:157], v[168:171], v[50:53]
	v_mfma_f32_16x16x32_bf16 v[50:53], v[158:161], v[172:175], v[50:53]
	v_mfma_f32_16x16x32_bf16 v[34:37], v[154:157], v[188:191], v[34:37]
	v_mfma_f32_16x16x32_bf16 v[34:37], v[158:161], v[192:195], v[34:37]
	v_mfma_f32_16x16x32_bf16 v[38:41], v[146:149], v[188:191], v[38:41]
	v_mfma_f32_16x16x32_bf16 v[38:41], v[150:153], v[192:195], v[38:41]
	v_mfma_f32_16x16x32_bf16 v[22:25], v[146:149], v[196:199], v[22:25]
	v_mfma_f32_16x16x32_bf16 v[22:25], v[150:153], v[200:203], v[22:25]
	v_mfma_f32_16x16x32_bf16 v[18:21], v[154:157], v[196:199], v[18:21]
	v_mfma_f32_16x16x32_bf16 v[18:21], v[158:161], v[200:203], v[18:21]
	v_mfma_f32_16x16x32_bf16 v[2:5], v[154:157], v[204:207], v[2:5]
	v_mfma_f32_16x16x32_bf16 v[2:5], v[158:161], v[208:211], v[2:5]
	s_setprio 2
	s_barrier
	v_mfma_f32_16x16x32_bf16 v[6:9], v[146:149], v[204:207], v[6:9]
	v_mfma_f32_16x16x32_bf16 v[6:9], v[150:153], v[208:211], v[6:9]
	s_setprio 0
	s_add_i32 s78, s78, 2
	s_add_u32 s74, s74, 0x100
	s_addc_u32 s75, s75, 0
	s_add_u32 s20, s20, 0x100
	s_addc_u32 s21, s21, 0
	s_add_u32 s76, s76, 0x100
	s_addc_u32 s77, s77, 0
	s_cmp_gt_u32 s78, 29
	.p2align 6
.LBB0_1053:
	ds_read_b128 v[130:133], v181
	ds_read_b128 v[134:137], v181 offset:1024
	ds_read_b128 v[138:141], v181 offset:2048
	ds_read_b128 v[142:145], v181 offset:3072
	ds_read_b128 v[146:149], v182
	ds_read_b128 v[150:153], v182 offset:1024
	ds_read_b128 v[154:157], v182 offset:2048
	ds_read_b128 v[158:161], v182 offset:3072
	s_cmp_eq_u32 s78, 28
	s_cselect_b32 s23, s11, s75
	s_cselect_b32 s22, s73, s74
	s_cselect_b32 s25, s13, s77
	s_cselect_b32 s24, s67, s76
	ds_read_b128 v[168:171], v183
	ds_read_b128 v[172:175], v183 offset:1024
	ds_read_b128 v[188:191], v183 offset:2048
	ds_read_b128 v[192:195], v183 offset:3072
	ds_read_b128 v[196:199], v183 offset:4096
	ds_read_b128 v[200:203], v183 offset:5120
	ds_read_b128 v[204:207], v183 offset:6144
	ds_read_b128 v[208:211], v183 offset:7168
	s_add_u32 s80, s20, 0xfff80000
	s_addc_u32 s81, s21, -1
	s_mov_b32 s79, m0
	s_mov_b32 m0, s58
	s_nop 0
	global_load_lds_dwordx4 v1, s[80:81]
	s_mov_b32 m0, s79
	s_nop 0
	s_mov_b32 s79, m0
	s_mov_b32 m0, s64
	s_nop 0
	global_load_lds_dwordx4 v177, s[80:81]
	s_mov_b32 m0, s79
	s_nop 0
	s_mov_b32 s79, m0
	s_mov_b32 m0, s59
	s_nop 0
	global_load_lds_dwordx4 v1, s[20:21]
	s_mov_b32 m0, s79
	s_nop 0
	s_mov_b32 s79, m0
	s_mov_b32 m0, s65
	s_nop 0
	global_load_lds_dwordx4 v177, s[20:21]
	s_mov_b32 m0, s79
	s_waitcnt vmcnt(8)
	s_waitcnt lgkmcnt(0)
	s_barrier
	s_setprio 1
	s_waitcnt lgkmcnt(7)
	v_mfma_f32_16x16x32_bf16 v[126:129], v[130:133], v[168:171], v[126:129]
	v_mfma_f32_16x16x32_bf16 v[126:129], v[134:137], v[172:175], v[126:129]
	s_waitcnt lgkmcnt(5)
	v_mfma_f32_16x16x32_bf16 v[122:125], v[138:141], v[168:171], v[122:125]
	v_mfma_f32_16x16x32_bf16 v[122:125], v[142:145], v[172:175], v[122:125]
	s_waitcnt lgkmcnt(3)
	v_mfma_f32_16x16x32_bf16 v[114:117], v[138:141], v[188:191], v[114:117]
	v_mfma_f32_16x16x32_bf16 v[114:117], v[142:145], v[192:195], v[114:117]
	s_waitcnt lgkmcnt(1)
	v_mfma_f32_16x16x32_bf16 v[118:121], v[130:133], v[188:191], v[118:121]
	v_mfma_f32_16x16x32_bf16 v[118:121], v[134:137], v[192:195], v[118:121]
	v_mfma_f32_16x16x32_bf16 v[94:97], v[130:133], v[196:199], v[94:97]
	v_mfma_f32_16x16x32_bf16 v[94:97], v[134:137], v[200:203], v[94:97]
	v_mfma_f32_16x16x32_bf16 v[90:93], v[138:141], v[196:199], v[90:93]
	v_mfma_f32_16x16x32_bf16 v[90:93], v[142:145], v[200:203], v[90:93]
	v_mfma_f32_16x16x32_bf16 v[78:81], v[138:141], v[204:207], v[78:81]
	v_mfma_f32_16x16x32_bf16 v[78:81], v[142:145], v[208:211], v[78:81]
	s_waitcnt lgkmcnt(0)
	v_mfma_f32_16x16x32_bf16 v[86:89], v[130:133], v[204:207], v[86:89]
	v_mfma_f32_16x16x32_bf16 v[86:89], v[134:137], v[208:211], v[86:89]
	s_setprio 0
	s_setprio 1
	v_mfma_f32_16x16x32_bf16 v[110:113], v[146:149], v[168:171], v[110:113]
	v_mfma_f32_16x16x32_bf16 v[110:113], v[150:153], v[172:175], v[110:113]
	v_mfma_f32_16x16x32_bf16 v[106:109], v[154:157], v[168:171], v[106:109]
	v_mfma_f32_16x16x32_bf16 v[106:109], v[158:161], v[172:175], v[106:109]
	v_mfma_f32_16x16x32_bf16 v[98:101], v[154:157], v[188:191], v[98:101]
	v_mfma_f32_16x16x32_bf16 v[98:101], v[158:161], v[192:195], v[98:101]
	v_mfma_f32_16x16x32_bf16 v[102:105], v[146:149], v[188:191], v[102:105]
	v_mfma_f32_16x16x32_bf16 v[102:105], v[150:153], v[192:195], v[102:105]
	v_mfma_f32_16x16x32_bf16 v[82:85], v[146:149], v[196:199], v[82:85]
	v_mfma_f32_16x16x32_bf16 v[82:85], v[150:153], v[200:203], v[82:85]
	v_mfma_f32_16x16x32_bf16 v[74:77], v[154:157], v[196:199], v[74:77]
	v_mfma_f32_16x16x32_bf16 v[74:77], v[158:161], v[200:203], v[74:77]
	v_mfma_f32_16x16x32_bf16 v[66:69], v[154:157], v[204:207], v[66:69]
	v_mfma_f32_16x16x32_bf16 v[66:69], v[158:161], v[208:211], v[66:69]
	s_setprio 2
	s_barrier
	v_mfma_f32_16x16x32_bf16 v[70:73], v[146:149], v[204:207], v[70:73]
	v_mfma_f32_16x16x32_bf16 v[70:73], v[150:153], v[208:211], v[70:73]
	s_setprio 0
	ds_read_b128 v[168:171], v183 offset:16384
	ds_read_b128 v[172:175], v183 offset:17408
	ds_read_b128 v[188:191], v183 offset:18432
	ds_read_b128 v[192:195], v183 offset:19456
	ds_read_b128 v[196:199], v183 offset:20480
	ds_read_b128 v[200:203], v183 offset:21504
	ds_read_b128 v[204:207], v183 offset:22528
	ds_read_b128 v[208:211], v183 offset:23552
	s_mov_b32 s79, m0
	s_mov_b32 m0, s35
	s_nop 0
	global_load_lds_dwordx4 v176, s[22:23]
	s_mov_b32 m0, s79
	s_add_u32 s80, s22, 0x80000
	s_mov_b32 s79, m0
	s_mov_b32 m0, s36
	s_nop 0
	global_load_lds_dwordx4 v178, s[22:23]
	s_mov_b32 m0, s79
	s_addc_u32 s81, s23, 0
	s_mov_b32 s79, m0
	s_mov_b32 m0, s37
	s_nop 0
	global_load_lds_dwordx4 v176, s[80:81]
	s_mov_b32 m0, s79
	s_nop 0
	s_mov_b32 s79, m0
	s_mov_b32 m0, s40
	s_nop 0
	global_load_lds_dwordx4 v178, s[80:81]
	s_mov_b32 m0, s79
	s_waitcnt vmcnt(4)
	s_waitcnt lgkmcnt(0)
	s_barrier
	s_setprio 1
	s_waitcnt lgkmcnt(7)
	v_mfma_f32_16x16x32_bf16 v[62:65], v[130:133], v[168:171], v[62:65]
	v_mfma_f32_16x16x32_bf16 v[62:65], v[134:137], v[172:175], v[62:65]
	s_waitcnt lgkmcnt(5)
	v_mfma_f32_16x16x32_bf16 v[58:61], v[138:141], v[168:171], v[58:61]
	v_mfma_f32_16x16x32_bf16 v[58:61], v[142:145], v[172:175], v[58:61]
	s_waitcnt lgkmcnt(3)
	v_mfma_f32_16x16x32_bf16 v[42:45], v[138:141], v[188:191], v[42:45]
	v_mfma_f32_16x16x32_bf16 v[42:45], v[142:145], v[192:195], v[42:45]
	s_waitcnt lgkmcnt(1)
	v_mfma_f32_16x16x32_bf16 v[46:49], v[130:133], v[188:191], v[46:49]
	v_mfma_f32_16x16x32_bf16 v[46:49], v[134:137], v[192:195], v[46:49]
	v_mfma_f32_16x16x32_bf16 v[30:33], v[130:133], v[196:199], v[30:33]
	v_mfma_f32_16x16x32_bf16 v[30:33], v[134:137], v[200:203], v[30:33]
	v_mfma_f32_16x16x32_bf16 v[26:29], v[138:141], v[196:199], v[26:29]
	v_mfma_f32_16x16x32_bf16 v[26:29], v[142:145], v[200:203], v[26:29]
	v_mfma_f32_16x16x32_bf16 v[10:13], v[138:141], v[204:207], v[10:13]
	v_mfma_f32_16x16x32_bf16 v[10:13], v[142:145], v[208:211], v[10:13]
	s_waitcnt lgkmcnt(0)
	v_mfma_f32_16x16x32_bf16 v[14:17], v[130:133], v[204:207], v[14:17]
	v_mfma_f32_16x16x32_bf16 v[14:17], v[134:137], v[208:211], v[14:17]
	s_setprio 0
	s_setprio 1
	v_mfma_f32_16x16x32_bf16 v[54:57], v[146:149], v[168:171], v[54:57]
	v_mfma_f32_16x16x32_bf16 v[54:57], v[150:153], v[172:175], v[54:57]
	v_mfma_f32_16x16x32_bf16 v[50:53], v[154:157], v[168:171], v[50:53]
	v_mfma_f32_16x16x32_bf16 v[50:53], v[158:161], v[172:175], v[50:53]
	v_mfma_f32_16x16x32_bf16 v[34:37], v[154:157], v[188:191], v[34:37]
	v_mfma_f32_16x16x32_bf16 v[34:37], v[158:161], v[192:195], v[34:37]
	v_mfma_f32_16x16x32_bf16 v[38:41], v[146:149], v[188:191], v[38:41]
	v_mfma_f32_16x16x32_bf16 v[38:41], v[150:153], v[192:195], v[38:41]
	v_mfma_f32_16x16x32_bf16 v[22:25], v[146:149], v[196:199], v[22:25]
	v_mfma_f32_16x16x32_bf16 v[22:25], v[150:153], v[200:203], v[22:25]
	v_mfma_f32_16x16x32_bf16 v[18:21], v[154:157], v[196:199], v[18:21]
	v_mfma_f32_16x16x32_bf16 v[18:21], v[158:161], v[200:203], v[18:21]
	v_mfma_f32_16x16x32_bf16 v[2:5], v[154:157], v[204:207], v[2:5]
	v_mfma_f32_16x16x32_bf16 v[2:5], v[158:161], v[208:211], v[2:5]
	s_setprio 2
	s_barrier
	v_mfma_f32_16x16x32_bf16 v[6:9], v[146:149], v[204:207], v[6:9]
	v_mfma_f32_16x16x32_bf16 v[6:9], v[150:153], v[208:211], v[6:9]
	s_setprio 0
	ds_read_b128 v[130:133], v184
	ds_read_b128 v[134:137], v184 offset:1024
	ds_read_b128 v[138:141], v184 offset:2048
	ds_read_b128 v[142:145], v184 offset:3072
	ds_read_b128 v[146:149], v185
	ds_read_b128 v[150:153], v185 offset:1024
	ds_read_b128 v[154:157], v185 offset:2048
	ds_read_b128 v[158:161], v185 offset:3072
	ds_read_b128 v[168:171], v183 offset:32768
	ds_read_b128 v[172:175], v183 offset:33792
	ds_read_b128 v[188:191], v183 offset:34816
	ds_read_b128 v[192:195], v183 offset:35840
	ds_read_b128 v[196:199], v183 offset:36864
	ds_read_b128 v[200:203], v183 offset:37888
	ds_read_b128 v[204:207], v183 offset:38912
	ds_read_b128 v[208:211], v183 offset:39936
	s_mov_b32 s79, m0
	s_mov_b32 m0, s34
	s_nop 0
	global_load_lds_dwordx4 v1, s[24:25]
	s_mov_b32 m0, s79
	s_nop 0
	s_mov_b32 s79, m0
	s_mov_b32 m0, s41
	s_nop 0
	global_load_lds_dwordx4 v177, s[24:25]
	s_mov_b32 m0, s79
	s_add_u32 s24, s24, 0x80000
	s_addc_u32 s25, s25, 0
	s_mov_b32 s79, m0
	s_mov_b32 m0, s42
	s_nop 0
	global_load_lds_dwordx4 v1, s[24:25]
	s_mov_b32 m0, s79
	s_nop 0
	s_mov_b32 s79, m0
	s_mov_b32 m0, s43
	s_nop 0
	global_load_lds_dwordx4 v177, s[24:25]
	s_mov_b32 m0, s79
	s_waitcnt vmcnt(8)
	s_waitcnt lgkmcnt(0)
	s_barrier
	s_setprio 1
	s_waitcnt lgkmcnt(7)
	v_mfma_f32_16x16x32_bf16 v[126:129], v[130:133], v[168:171], v[126:129]
	v_mfma_f32_16x16x32_bf16 v[126:129], v[134:137], v[172:175], v[126:129]
	s_waitcnt lgkmcnt(5)
	v_mfma_f32_16x16x32_bf16 v[122:125], v[138:141], v[168:171], v[122:125]
	v_mfma_f32_16x16x32_bf16 v[122:125], v[142:145], v[172:175], v[122:125]
	s_waitcnt lgkmcnt(3)
	v_mfma_f32_16x16x32_bf16 v[114:117], v[138:141], v[188:191], v[114:117]
	v_mfma_f32_16x16x32_bf16 v[114:117], v[142:145], v[192:195], v[114:117]
	s_waitcnt lgkmcnt(1)
	v_mfma_f32_16x16x32_bf16 v[118:121], v[130:133], v[188:191], v[118:121]
	v_mfma_f32_16x16x32_bf16 v[118:121], v[134:137], v[192:195], v[118:121]
	v_mfma_f32_16x16x32_bf16 v[94:97], v[130:133], v[196:199], v[94:97]
	v_mfma_f32_16x16x32_bf16 v[94:97], v[134:137], v[200:203], v[94:97]
	v_mfma_f32_16x16x32_bf16 v[90:93], v[138:141], v[196:199], v[90:93]
	v_mfma_f32_16x16x32_bf16 v[90:93], v[142:145], v[200:203], v[90:93]
	v_mfma_f32_16x16x32_bf16 v[78:81], v[138:141], v[204:207], v[78:81]
	v_mfma_f32_16x16x32_bf16 v[78:81], v[142:145], v[208:211], v[78:81]
	s_waitcnt lgkmcnt(0)
	v_mfma_f32_16x16x32_bf16 v[86:89], v[130:133], v[204:207], v[86:89]
	v_mfma_f32_16x16x32_bf16 v[86:89], v[134:137], v[208:211], v[86:89]
	s_setprio 0
	s_setprio 1
	v_mfma_f32_16x16x32_bf16 v[110:113], v[146:149], v[168:171], v[110:113]
	v_mfma_f32_16x16x32_bf16 v[110:113], v[150:153], v[172:175], v[110:113]
	v_mfma_f32_16x16x32_bf16 v[106:109], v[154:157], v[168:171], v[106:109]
	v_mfma_f32_16x16x32_bf16 v[106:109], v[158:161], v[172:175], v[106:109]
	v_mfma_f32_16x16x32_bf16 v[98:101], v[154:157], v[188:191], v[98:101]
	v_mfma_f32_16x16x32_bf16 v[98:101], v[158:161], v[192:195], v[98:101]
	v_mfma_f32_16x16x32_bf16 v[102:105], v[146:149], v[188:191], v[102:105]
	v_mfma_f32_16x16x32_bf16 v[102:105], v[150:153], v[192:195], v[102:105]
	v_mfma_f32_16x16x32_bf16 v[82:85], v[146:149], v[196:199], v[82:85]
	v_mfma_f32_16x16x32_bf16 v[82:85], v[150:153], v[200:203], v[82:85]
	v_mfma_f32_16x16x32_bf16 v[74:77], v[154:157], v[196:199], v[74:77]
	v_mfma_f32_16x16x32_bf16 v[74:77], v[158:161], v[200:203], v[74:77]
	v_mfma_f32_16x16x32_bf16 v[66:69], v[154:157], v[204:207], v[66:69]
	v_mfma_f32_16x16x32_bf16 v[66:69], v[158:161], v[208:211], v[66:69]
	s_setprio 2
	s_barrier
	v_mfma_f32_16x16x32_bf16 v[70:73], v[146:149], v[204:207], v[70:73]
	v_mfma_f32_16x16x32_bf16 v[70:73], v[150:153], v[208:211], v[70:73]
	s_setprio 0
	ds_read_b128 v[168:171], v183 offset:49152
	ds_read_b128 v[172:175], v183 offset:50176
	ds_read_b128 v[188:191], v183 offset:51200
	ds_read_b128 v[192:195], v183 offset:52224
	ds_read_b128 v[196:199], v183 offset:53248
	ds_read_b128 v[200:203], v183 offset:54272
	ds_read_b128 v[204:207], v183 offset:55296
	ds_read_b128 v[208:211], v183 offset:56320
	s_add_u32 s24, s22, 0x80
	s_addc_u32 s25, s23, 0
	s_mov_b32 s79, m0
	s_mov_b32 m0, s46
	s_nop 0
	global_load_lds_dwordx4 v176, s[24:25]
	s_mov_b32 m0, s79
	s_add_u32 s22, s22, 0x80080
	s_mov_b32 s79, m0
	s_mov_b32 m0, s47
	s_nop 0
	global_load_lds_dwordx4 v178, s[24:25]
	s_mov_b32 m0, s79
	s_addc_u32 s23, s23, 0
	s_mov_b32 s24, m0
	s_mov_b32 m0, s48
	s_nop 0
	global_load_lds_dwordx4 v176, s[22:23]
	s_mov_b32 m0, s24
	s_nop 0
	s_mov_b32 s24, m0
	s_mov_b32 m0, s49
	s_nop 0
	global_load_lds_dwordx4 v178, s[22:23]
	s_mov_b32 m0, s24
	s_waitcnt vmcnt(4)
	s_waitcnt lgkmcnt(0)
	s_barrier
	s_setprio 1
	s_waitcnt lgkmcnt(7)
	v_mfma_f32_16x16x32_bf16 v[62:65], v[130:133], v[168:171], v[62:65]
	v_mfma_f32_16x16x32_bf16 v[62:65], v[134:137], v[172:175], v[62:65]
	s_waitcnt lgkmcnt(5)
	v_mfma_f32_16x16x32_bf16 v[58:61], v[138:141], v[168:171], v[58:61]
	v_mfma_f32_16x16x32_bf16 v[58:61], v[142:145], v[172:175], v[58:61]
	s_waitcnt lgkmcnt(3)
	v_mfma_f32_16x16x32_bf16 v[42:45], v[138:141], v[188:191], v[42:45]
	v_mfma_f32_16x16x32_bf16 v[42:45], v[142:145], v[192:195], v[42:45]
	s_waitcnt lgkmcnt(1)
	v_mfma_f32_16x16x32_bf16 v[46:49], v[130:133], v[188:191], v[46:49]
	v_mfma_f32_16x16x32_bf16 v[46:49], v[134:137], v[192:195], v[46:49]
	v_mfma_f32_16x16x32_bf16 v[30:33], v[130:133], v[196:199], v[30:33]
	v_mfma_f32_16x16x32_bf16 v[30:33], v[134:137], v[200:203], v[30:33]
	v_mfma_f32_16x16x32_bf16 v[26:29], v[138:141], v[196:199], v[26:29]
	v_mfma_f32_16x16x32_bf16 v[26:29], v[142:145], v[200:203], v[26:29]
	v_mfma_f32_16x16x32_bf16 v[10:13], v[138:141], v[204:207], v[10:13]
	v_mfma_f32_16x16x32_bf16 v[10:13], v[142:145], v[208:211], v[10:13]
	s_waitcnt lgkmcnt(0)
	v_mfma_f32_16x16x32_bf16 v[14:17], v[130:133], v[204:207], v[14:17]
	v_mfma_f32_16x16x32_bf16 v[14:17], v[134:137], v[208:211], v[14:17]
	s_setprio 0
	s_setprio 1
	v_mfma_f32_16x16x32_bf16 v[54:57], v[146:149], v[168:171], v[54:57]
	v_mfma_f32_16x16x32_bf16 v[54:57], v[150:153], v[172:175], v[54:57]
	v_mfma_f32_16x16x32_bf16 v[50:53], v[154:157], v[168:171], v[50:53]
	v_mfma_f32_16x16x32_bf16 v[50:53], v[158:161], v[172:175], v[50:53]
	v_mfma_f32_16x16x32_bf16 v[34:37], v[154:157], v[188:191], v[34:37]
	v_mfma_f32_16x16x32_bf16 v[34:37], v[158:161], v[192:195], v[34:37]
	v_mfma_f32_16x16x32_bf16 v[38:41], v[146:149], v[188:191], v[38:41]
	v_mfma_f32_16x16x32_bf16 v[38:41], v[150:153], v[192:195], v[38:41]
	v_mfma_f32_16x16x32_bf16 v[22:25], v[146:149], v[196:199], v[22:25]
	v_mfma_f32_16x16x32_bf16 v[22:25], v[150:153], v[200:203], v[22:25]
	v_mfma_f32_16x16x32_bf16 v[18:21], v[154:157], v[196:199], v[18:21]
	v_mfma_f32_16x16x32_bf16 v[18:21], v[158:161], v[200:203], v[18:21]
	v_mfma_f32_16x16x32_bf16 v[2:5], v[154:157], v[204:207], v[2:5]
	v_mfma_f32_16x16x32_bf16 v[2:5], v[158:161], v[208:211], v[2:5]
	s_setprio 2
	s_barrier
	v_mfma_f32_16x16x32_bf16 v[6:9], v[146:149], v[204:207], v[6:9]
	v_mfma_f32_16x16x32_bf16 v[6:9], v[150:153], v[208:211], v[6:9]
	s_setprio 0
	s_add_i32 s78, s78, 2
	s_add_u32 s74, s74, 0x100
	s_addc_u32 s75, s75, 0
	s_add_u32 s20, s20, 0x100
	s_addc_u32 s21, s21, 0
	s_add_u32 s76, s76, 0x100
	s_addc_u32 s77, s77, 0
	s_cmp_gt_u32 s78, 29
	s_cbranch_scc0 .LBB0_1053
	v_mov_b32_e32 v174, v252
	v_mov_b32_e32 v175, v253
	v_mov_b32_e32 v210, v254
	v_mov_b32_e32 v211, v255
	s_and_b64 vcc, exec, s[8:9]
	s_cbranch_vccz .LBB0_1056
	s_barrier

.LBB0_1356:
	s_ashr_i32 s13, s12, 31
	s_lshl_b64 s[14:15], s[12:13], 15
	s_add_u32 s14, s28, s14
	s_addc_u32 s15, s29, s15
	s_and_b64 s[16:17], s[2:3], exec
	s_cselect_b32 s13, s15, s23
	s_cselect_b32 s67, s14, s22
	s_ashr_i32 s11, s10, 31
	s_lshl_b64 s[16:17], s[10:11], 15
	s_add_u32 s16, s30, s16
	s_addc_u32 s17, s31, s17
	s_and_b64 s[24:25], s[2:3], exec
	s_cselect_b32 s11, s17, s21
	s_cselect_b32 s73, s16, s20
	s_add_u32 s74, s20, 0x80000
	s_addc_u32 s75, s21, 0
	s_add_u32 s20, s22, 0x204000
	s_addc_u32 s21, s23, 0
	s_add_u32 s76, s22, 0x400000
	s_addc_u32 s77, s23, 0
	s_mov_b32 s78, -2
	s_waitcnt vmcnt(25)
	s_waitcnt vmcnt(24)
	s_waitcnt vmcnt(15)
	s_waitcnt vmcnt(14)
	s_waitcnt vmcnt(13)
	s_waitcnt vmcnt(12)
	s_waitcnt vmcnt(11)
	s_waitcnt vmcnt(10)
	s_waitcnt vmcnt(9)
	s_waitcnt vmcnt(8)
	s_waitcnt vmcnt(7)
	s_waitcnt vmcnt(6)
	s_waitcnt vmcnt(5)
	s_waitcnt vmcnt(4)
	s_waitcnt vmcnt(3)
	s_waitcnt vmcnt(2)
	s_waitcnt vmcnt(1)
	s_waitcnt vmcnt(0)
	v_mov_b32_e32 v252, v174
	v_mov_b32_e32 v253, v175
	v_mov_b32_e32 v254, v210
	v_mov_b32_e32 v255, v211
	ds_read_b128 v[130:133], v181
	ds_read_b128 v[134:137], v181 offset:1024
	ds_read_b128 v[138:141], v181 offset:2048
	ds_read_b128 v[142:145], v181 offset:3072
	ds_read_b128 v[150:153], v182
	ds_read_b128 v[154:157], v182 offset:1024
	ds_read_b128 v[158:161], v182 offset:2048
	ds_read_b128 v[162:165], v182 offset:3072
	s_cmpk_eq_i32 s78, 0x52
	s_cselect_b32 s23, s11, s75
	s_cselect_b32 s22, s73, s74
	s_cselect_b32 s25, s13, s77
	s_cselect_b32 s24, s67, s76
	ds_read_b128 v[168:171], v183
	ds_read_b128 v[172:175], v183 offset:1024
	ds_read_b128 v[188:191], v183 offset:2048
	ds_read_b128 v[192:195], v183 offset:3072
	ds_read_b128 v[196:199], v183 offset:4096
	ds_read_b128 v[200:203], v183 offset:5120
	ds_read_b128 v[204:207], v183 offset:6144
	ds_read_b128 v[208:211], v183 offset:7168
	s_add_u32 s80, s20, 0xffffc000
	s_addc_u32 s81, s21, -1
	s_mov_b32 s79, m0
	s_mov_b32 m0, s58
	s_nop 0
	global_load_lds_dwordx4 v1, s[80:81]
	s_mov_b32 m0, s79
	s_nop 0
	s_mov_b32 s79, m0
	s_mov_b32 m0, s64
	s_nop 0
	global_load_lds_dwordx4 v177, s[80:81]
	s_mov_b32 m0, s79
	s_nop 0
	s_mov_b32 s79, m0
	s_mov_b32 m0, s59
	s_nop 0
	global_load_lds_dwordx4 v1, s[20:21]
	s_mov_b32 m0, s79
	s_nop 0
	s_mov_b32 s79, m0
	s_mov_b32 m0, s65
	s_nop 0
	global_load_lds_dwordx4 v177, s[20:21]
	s_mov_b32 m0, s79
	s_waitcnt vmcnt(8)
	s_waitcnt lgkmcnt(0)
	s_barrier
	s_setprio 1
	s_waitcnt lgkmcnt(7)
	v_mfma_f32_16x16x32_bf16 v[126:129], v[130:133], v[168:171], 0
	v_mfma_f32_16x16x32_bf16 v[126:129], v[134:137], v[172:175], v[126:129]
	s_waitcnt lgkmcnt(5)
	v_mfma_f32_16x16x32_bf16 v[122:125], v[138:141], v[168:171], 0
	v_mfma_f32_16x16x32_bf16 v[122:125], v[142:145], v[172:175], v[122:125]
	s_waitcnt lgkmcnt(3)
	v_mfma_f32_16x16x32_bf16 v[110:113], v[138:141], v[188:191], 0
	v_mfma_f32_16x16x32_bf16 v[110:113], v[142:145], v[192:195], v[110:113]
	s_waitcnt lgkmcnt(1)
	v_mfma_f32_16x16x32_bf16 v[118:121], v[130:133], v[188:191], 0
	v_mfma_f32_16x16x32_bf16 v[118:121], v[134:137], v[192:195], v[118:121]
	v_mfma_f32_16x16x32_bf16 v[94:97], v[130:133], v[196:199], 0
	v_mfma_f32_16x16x32_bf16 v[94:97], v[134:137], v[200:203], v[94:97]
	v_mfma_f32_16x16x32_bf16 v[90:93], v[138:141], v[196:199], 0
	v_mfma_f32_16x16x32_bf16 v[90:93], v[142:145], v[200:203], v[90:93]
	v_mfma_f32_16x16x32_bf16 v[78:81], v[138:141], v[204:207], 0
	v_mfma_f32_16x16x32_bf16 v[78:81], v[142:145], v[208:211], v[78:81]
	s_waitcnt lgkmcnt(0)
	v_mfma_f32_16x16x32_bf16 v[86:89], v[130:133], v[204:207], 0
	v_mfma_f32_16x16x32_bf16 v[86:89], v[134:137], v[208:211], v[86:89]
	s_setprio 0
	s_setprio 1
	v_mfma_f32_16x16x32_bf16 v[114:117], v[150:153], v[168:171], 0
	v_mfma_f32_16x16x32_bf16 v[114:117], v[154:157], v[172:175], v[114:117]
	v_mfma_f32_16x16x32_bf16 v[106:109], v[158:161], v[168:171], 0
	v_mfma_f32_16x16x32_bf16 v[106:109], v[162:165], v[172:175], v[106:109]
	v_mfma_f32_16x16x32_bf16 v[98:101], v[158:161], v[188:191], 0
	v_mfma_f32_16x16x32_bf16 v[98:101], v[162:165], v[192:195], v[98:101]
	v_mfma_f32_16x16x32_bf16 v[102:105], v[150:153], v[188:191], 0
	v_mfma_f32_16x16x32_bf16 v[102:105], v[154:157], v[192:195], v[102:105]
	v_mfma_f32_16x16x32_bf16 v[82:85], v[150:153], v[196:199], 0
	v_mfma_f32_16x16x32_bf16 v[82:85], v[154:157], v[200:203], v[82:85]
	v_mfma_f32_16x16x32_bf16 v[74:77], v[158:161], v[196:199], 0
	v_mfma_f32_16x16x32_bf16 v[74:77], v[162:165], v[200:203], v[74:77]
	v_mfma_f32_16x16x32_bf16 v[66:69], v[158:161], v[204:207], 0
	v_mfma_f32_16x16x32_bf16 v[66:69], v[162:165], v[208:211], v[66:69]
	s_setprio 2
	s_barrier
	v_mfma_f32_16x16x32_bf16 v[70:73], v[150:153], v[204:207], 0
	v_mfma_f32_16x16x32_bf16 v[70:73], v[154:157], v[208:211], v[70:73]
	s_setprio 0
	ds_read_b128 v[168:171], v183 offset:16384
	ds_read_b128 v[172:175], v183 offset:17408
	ds_read_b128 v[188:191], v183 offset:18432
	ds_read_b128 v[192:195], v183 offset:19456
	ds_read_b128 v[196:199], v183 offset:20480
	ds_read_b128 v[200:203], v183 offset:21504
	ds_read_b128 v[204:207], v183 offset:22528
	ds_read_b128 v[208:211], v183 offset:23552
	s_mov_b32 s79, m0
	s_mov_b32 m0, s35
	s_nop 0
	global_load_lds_dwordx4 v176, s[22:23]
	s_mov_b32 m0, s79
	s_add_u32 s80, s22, 0x4000
	s_mov_b32 s79, m0
	s_mov_b32 m0, s36
	s_nop 0
	global_load_lds_dwordx4 v178, s[22:23]
	s_mov_b32 m0, s79
	s_addc_u32 s81, s23, 0
	s_mov_b32 s79, m0
	s_mov_b32 m0, s37
	s_nop 0
	global_load_lds_dwordx4 v176, s[80:81]
	s_mov_b32 m0, s79
	s_nop 0
	s_mov_b32 s79, m0
	s_mov_b32 m0, s40
	s_nop 0
	global_load_lds_dwordx4 v178, s[80:81]
	s_mov_b32 m0, s79
	s_waitcnt vmcnt(4)
	s_waitcnt lgkmcnt(0)
	s_barrier
	s_setprio 1
	s_waitcnt lgkmcnt(7)
	v_mfma_f32_16x16x32_bf16 v[62:65], v[130:133], v[168:171], 0
	v_mfma_f32_16x16x32_bf16 v[62:65], v[134:137], v[172:175], v[62:65]
	s_waitcnt lgkmcnt(5)
	v_mfma_f32_16x16x32_bf16 v[58:61], v[138:141], v[168:171], 0
	v_mfma_f32_16x16x32_bf16 v[58:61], v[142:145], v[172:175], v[58:61]
	s_waitcnt lgkmcnt(3)
	v_mfma_f32_16x16x32_bf16 v[42:45], v[138:141], v[188:191], 0
	v_mfma_f32_16x16x32_bf16 v[42:45], v[142:145], v[192:195], v[42:45]
	s_waitcnt lgkmcnt(1)
	v_mfma_f32_16x16x32_bf16 v[46:49], v[130:133], v[188:191], 0
	v_mfma_f32_16x16x32_bf16 v[46:49], v[134:137], v[192:195], v[46:49]
	v_mfma_f32_16x16x32_bf16 v[30:33], v[130:133], v[196:199], 0
	v_mfma_f32_16x16x32_bf16 v[30:33], v[134:137], v[200:203], v[30:33]
	v_mfma_f32_16x16x32_bf16 v[26:29], v[138:141], v[196:199], 0
	v_mfma_f32_16x16x32_bf16 v[26:29], v[142:145], v[200:203], v[26:29]
	v_mfma_f32_16x16x32_bf16 v[10:13], v[138:141], v[204:207], 0
	v_mfma_f32_16x16x32_bf16 v[10:13], v[142:145], v[208:211], v[10:13]
	s_waitcnt lgkmcnt(0)
	v_mfma_f32_16x16x32_bf16 v[14:17], v[130:133], v[204:207], 0
	v_mfma_f32_16x16x32_bf16 v[14:17], v[134:137], v[208:211], v[14:17]
	s_setprio 0
	s_setprio 1
	v_mfma_f32_16x16x32_bf16 v[54:57], v[150:153], v[168:171], 0
	v_mfma_f32_16x16x32_bf16 v[54:57], v[154:157], v[172:175], v[54:57]
	v_mfma_f32_16x16x32_bf16 v[50:53], v[158:161], v[168:171], 0
	v_mfma_f32_16x16x32_bf16 v[50:53], v[162:165], v[172:175], v[50:53]
	v_mfma_f32_16x16x32_bf16 v[34:37], v[158:161], v[188:191], 0
	v_mfma_f32_16x16x32_bf16 v[34:37], v[162:165], v[192:195], v[34:37]
	v_mfma_f32_16x16x32_bf16 v[38:41], v[150:153], v[188:191], 0
	v_mfma_f32_16x16x32_bf16 v[38:41], v[154:157], v[192:195], v[38:41]
	v_mfma_f32_16x16x32_bf16 v[22:25], v[150:153], v[196:199], 0
	v_mfma_f32_16x16x32_bf16 v[22:25], v[154:157], v[200:203], v[22:25]
	v_mfma_f32_16x16x32_bf16 v[18:21], v[158:161], v[196:199], 0
	v_mfma_f32_16x16x32_bf16 v[18:21], v[162:165], v[200:203], v[18:21]
	v_mfma_f32_16x16x32_bf16 v[2:5], v[158:161], v[204:207], 0
	v_mfma_f32_16x16x32_bf16 v[2:5], v[162:165], v[208:211], v[2:5]
	s_setprio 2
	s_barrier
	v_mfma_f32_16x16x32_bf16 v[6:9], v[150:153], v[204:207], 0
	v_mfma_f32_16x16x32_bf16 v[6:9], v[154:157], v[208:211], v[6:9]
	s_setprio 0
	ds_read_b128 v[130:133], v184
	ds_read_b128 v[134:137], v184 offset:1024
	ds_read_b128 v[138:141], v184 offset:2048
	ds_read_b128 v[142:145], v184 offset:3072
	ds_read_b128 v[150:153], v185
	ds_read_b128 v[154:157], v185 offset:1024
	ds_read_b128 v[158:161], v185 offset:2048
	ds_read_b128 v[162:165], v185 offset:3072
	ds_read_b128 v[168:171], v183 offset:32768
	ds_read_b128 v[172:175], v183 offset:33792
	ds_read_b128 v[188:191], v183 offset:34816
	ds_read_b128 v[192:195], v183 offset:35840
	ds_read_b128 v[196:199], v183 offset:36864
	ds_read_b128 v[200:203], v183 offset:37888
	ds_read_b128 v[204:207], v183 offset:38912
	ds_read_b128 v[208:211], v183 offset:39936
	s_mov_b32 s79, m0
	s_mov_b32 m0, s34
	s_nop 0
	global_load_lds_dwordx4 v1, s[24:25]
	s_mov_b32 m0, s79
	s_nop 0
	s_mov_b32 s79, m0
	s_mov_b32 m0, s41
	s_nop 0
	global_load_lds_dwordx4 v177, s[24:25]
	s_mov_b32 m0, s79
	s_add_u32 s24, s24, 0x4000
	s_addc_u32 s25, s25, 0
	s_mov_b32 s79, m0
	s_mov_b32 m0, s42
	s_nop 0
	global_load_lds_dwordx4 v1, s[24:25]
	s_mov_b32 m0, s79
	s_nop 0
	s_mov_b32 s79, m0
	s_mov_b32 m0, s43
	s_nop 0
	global_load_lds_dwordx4 v177, s[24:25]
	s_mov_b32 m0, s79
	s_waitcnt vmcnt(8)
	s_waitcnt lgkmcnt(0)
	s_barrier
	s_setprio 1
	s_waitcnt lgkmcnt(7)
	v_mfma_f32_16x16x32_bf16 v[126:129], v[130:133], v[168:171], v[126:129]
	v_mfma_f32_16x16x32_bf16 v[126:129], v[134:137], v[172:175], v[126:129]
	s_waitcnt lgkmcnt(5)
	v_mfma_f32_16x16x32_bf16 v[122:125], v[138:141], v[168:171], v[122:125]
	v_mfma_f32_16x16x32_bf16 v[122:125], v[142:145], v[172:175], v[122:125]
	s_waitcnt lgkmcnt(3)
	v_mfma_f32_16x16x32_bf16 v[110:113], v[138:141], v[188:191], v[110:113]
	v_mfma_f32_16x16x32_bf16 v[110:113], v[142:145], v[192:195], v[110:113]
	s_waitcnt lgkmcnt(1)
	v_mfma_f32_16x16x32_bf16 v[118:121], v[130:133], v[188:191], v[118:121]
	v_mfma_f32_16x16x32_bf16 v[118:121], v[134:137], v[192:195], v[118:121]
	v_mfma_f32_16x16x32_bf16 v[94:97], v[130:133], v[196:199], v[94:97]
	v_mfma_f32_16x16x32_bf16 v[94:97], v[134:137], v[200:203], v[94:97]
	v_mfma_f32_16x16x32_bf16 v[90:93], v[138:141], v[196:199], v[90:93]
	v_mfma_f32_16x16x32_bf16 v[90:93], v[142:145], v[200:203], v[90:93]
	v_mfma_f32_16x16x32_bf16 v[78:81], v[138:141], v[204:207], v[78:81]
	v_mfma_f32_16x16x32_bf16 v[78:81], v[142:145], v[208:211], v[78:81]
	s_waitcnt lgkmcnt(0)
	v_mfma_f32_16x16x32_bf16 v[86:89], v[130:133], v[204:207], v[86:89]
	v_mfma_f32_16x16x32_bf16 v[86:89], v[134:137], v[208:211], v[86:89]
	s_setprio 0
	s_setprio 1
	v_mfma_f32_16x16x32_bf16 v[114:117], v[150:153], v[168:171], v[114:117]
	v_mfma_f32_16x16x32_bf16 v[114:117], v[154:157], v[172:175], v[114:117]
	v_mfma_f32_16x16x32_bf16 v[106:109], v[158:161], v[168:171], v[106:109]
	v_mfma_f32_16x16x32_bf16 v[106:109], v[162:165], v[172:175], v[106:109]
	v_mfma_f32_16x16x32_bf16 v[98:101], v[158:161], v[188:191], v[98:101]
	v_mfma_f32_16x16x32_bf16 v[98:101], v[162:165], v[192:195], v[98:101]
	v_mfma_f32_16x16x32_bf16 v[102:105], v[150:153], v[188:191], v[102:105]
	v_mfma_f32_16x16x32_bf16 v[102:105], v[154:157], v[192:195], v[102:105]
	v_mfma_f32_16x16x32_bf16 v[82:85], v[150:153], v[196:199], v[82:85]
	v_mfma_f32_16x16x32_bf16 v[82:85], v[154:157], v[200:203], v[82:85]
	v_mfma_f32_16x16x32_bf16 v[74:77], v[158:161], v[196:199], v[74:77]
	v_mfma_f32_16x16x32_bf16 v[74:77], v[162:165], v[200:203], v[74:77]
	v_mfma_f32_16x16x32_bf16 v[66:69], v[158:161], v[204:207], v[66:69]
	v_mfma_f32_16x16x32_bf16 v[66:69], v[162:165], v[208:211], v[66:69]
	s_setprio 2
	s_barrier
	v_mfma_f32_16x16x32_bf16 v[70:73], v[150:153], v[204:207], v[70:73]
	v_mfma_f32_16x16x32_bf16 v[70:73], v[154:157], v[208:211], v[70:73]
	s_setprio 0
	ds_read_b128 v[168:171], v183 offset:49152
	ds_read_b128 v[172:175], v183 offset:50176
	ds_read_b128 v[188:191], v183 offset:51200
	ds_read_b128 v[192:195], v183 offset:52224
	ds_read_b128 v[196:199], v183 offset:53248
	ds_read_b128 v[200:203], v183 offset:54272
	ds_read_b128 v[204:207], v183 offset:55296
	ds_read_b128 v[208:211], v183 offset:56320
	s_add_u32 s24, s22, 0x40000
	s_addc_u32 s25, s23, 0
	s_mov_b32 s79, m0
	s_mov_b32 m0, s46
	s_nop 0
	global_load_lds_dwordx4 v176, s[24:25]
	s_mov_b32 m0, s79
	s_add_u32 s22, s22, 0x44000
	s_mov_b32 s79, m0
	s_mov_b32 m0, s47
	s_nop 0
	global_load_lds_dwordx4 v178, s[24:25]
	s_mov_b32 m0, s79
	s_addc_u32 s23, s23, 0
	s_mov_b32 s24, m0
	s_mov_b32 m0, s48
	s_nop 0
	global_load_lds_dwordx4 v176, s[22:23]
	s_mov_b32 m0, s24
	s_nop 0
	s_mov_b32 s24, m0
	s_mov_b32 m0, s49
	s_nop 0
	global_load_lds_dwordx4 v178, s[22:23]
	s_mov_b32 m0, s24
	s_waitcnt vmcnt(4)
	s_waitcnt lgkmcnt(0)
	s_barrier
	s_setprio 1
	s_waitcnt lgkmcnt(7)
	v_mfma_f32_16x16x32_bf16 v[62:65], v[130:133], v[168:171], v[62:65]
	v_mfma_f32_16x16x32_bf16 v[62:65], v[134:137], v[172:175], v[62:65]
	s_waitcnt lgkmcnt(5)
	v_mfma_f32_16x16x32_bf16 v[58:61], v[138:141], v[168:171], v[58:61]
	v_mfma_f32_16x16x32_bf16 v[58:61], v[142:145], v[172:175], v[58:61]
	s_waitcnt lgkmcnt(3)
	v_mfma_f32_16x16x32_bf16 v[42:45], v[138:141], v[188:191], v[42:45]
	v_mfma_f32_16x16x32_bf16 v[42:45], v[142:145], v[192:195], v[42:45]
	s_waitcnt lgkmcnt(1)
	v_mfma_f32_16x16x32_bf16 v[46:49], v[130:133], v[188:191], v[46:49]
	v_mfma_f32_16x16x32_bf16 v[46:49], v[134:137], v[192:195], v[46:49]
	v_mfma_f32_16x16x32_bf16 v[30:33], v[130:133], v[196:199], v[30:33]
	v_mfma_f32_16x16x32_bf16 v[30:33], v[134:137], v[200:203], v[30:33]
	v_mfma_f32_16x16x32_bf16 v[26:29], v[138:141], v[196:199], v[26:29]
	v_mfma_f32_16x16x32_bf16 v[26:29], v[142:145], v[200:203], v[26:29]
	v_mfma_f32_16x16x32_bf16 v[10:13], v[138:141], v[204:207], v[10:13]
	v_mfma_f32_16x16x32_bf16 v[10:13], v[142:145], v[208:211], v[10:13]
	s_waitcnt lgkmcnt(0)
	v_mfma_f32_16x16x32_bf16 v[14:17], v[130:133], v[204:207], v[14:17]
	v_mfma_f32_16x16x32_bf16 v[14:17], v[134:137], v[208:211], v[14:17]
	s_setprio 0
	s_setprio 1
	v_mfma_f32_16x16x32_bf16 v[54:57], v[150:153], v[168:171], v[54:57]
	v_mfma_f32_16x16x32_bf16 v[54:57], v[154:157], v[172:175], v[54:57]
	v_mfma_f32_16x16x32_bf16 v[50:53], v[158:161], v[168:171], v[50:53]
	v_mfma_f32_16x16x32_bf16 v[50:53], v[162:165], v[172:175], v[50:53]
	v_mfma_f32_16x16x32_bf16 v[34:37], v[158:161], v[188:191], v[34:37]
	v_mfma_f32_16x16x32_bf16 v[34:37], v[162:165], v[192:195], v[34:37]
	v_mfma_f32_16x16x32_bf16 v[38:41], v[150:153], v[188:191], v[38:41]
	v_mfma_f32_16x16x32_bf16 v[38:41], v[154:157], v[192:195], v[38:41]
	v_mfma_f32_16x16x32_bf16 v[22:25], v[150:153], v[196:199], v[22:25]
	v_mfma_f32_16x16x32_bf16 v[22:25], v[154:157], v[200:203], v[22:25]
	v_mfma_f32_16x16x32_bf16 v[18:21], v[158:161], v[196:199], v[18:21]
	v_mfma_f32_16x16x32_bf16 v[18:21], v[162:165], v[200:203], v[18:21]
	v_mfma_f32_16x16x32_bf16 v[2:5], v[158:161], v[204:207], v[2:5]
	v_mfma_f32_16x16x32_bf16 v[2:5], v[162:165], v[208:211], v[2:5]
	s_setprio 2
	s_barrier
	v_mfma_f32_16x16x32_bf16 v[6:9], v[150:153], v[204:207], v[6:9]
	v_mfma_f32_16x16x32_bf16 v[6:9], v[154:157], v[208:211], v[6:9]
	s_setprio 0
	s_add_i32 s78, s78, 2
	s_add_u32 s74, s74, 0x80000
	s_addc_u32 s75, s75, 0
	s_add_u32 s20, s20, 0x400000
	s_addc_u32 s21, s21, 0
	s_add_u32 s76, s76, 0x400000
	s_addc_u32 s77, s77, 0
	s_cmpk_gt_u32 s78, 0x53
	.p2align 6
.LBB0_1357:
	ds_read_b128 v[130:133], v181
	ds_read_b128 v[134:137], v181 offset:1024
	ds_read_b128 v[138:141], v181 offset:2048
	ds_read_b128 v[142:145], v181 offset:3072
	ds_read_b128 v[150:153], v182
	ds_read_b128 v[154:157], v182 offset:1024
	ds_read_b128 v[158:161], v182 offset:2048
	ds_read_b128 v[162:165], v182 offset:3072
	s_cmpk_eq_i32 s78, 0x52
	s_cselect_b32 s23, s11, s75
	s_cselect_b32 s22, s73, s74
	s_cselect_b32 s25, s13, s77
	s_cselect_b32 s24, s67, s76
	ds_read_b128 v[168:171], v183
	ds_read_b128 v[172:175], v183 offset:1024
	ds_read_b128 v[188:191], v183 offset:2048
	ds_read_b128 v[192:195], v183 offset:3072
	ds_read_b128 v[196:199], v183 offset:4096
	ds_read_b128 v[200:203], v183 offset:5120
	ds_read_b128 v[204:207], v183 offset:6144
	ds_read_b128 v[208:211], v183 offset:7168
	s_add_u32 s80, s20, 0xffffc000
	s_addc_u32 s81, s21, -1
	s_mov_b32 s79, m0
	s_mov_b32 m0, s58
	s_nop 0
	global_load_lds_dwordx4 v1, s[80:81]
	s_mov_b32 m0, s79
	s_nop 0
	s_mov_b32 s79, m0
	s_mov_b32 m0, s64
	s_nop 0
	global_load_lds_dwordx4 v177, s[80:81]
	s_mov_b32 m0, s79
	s_nop 0
	s_mov_b32 s79, m0
	s_mov_b32 m0, s59
	s_nop 0
	global_load_lds_dwordx4 v1, s[20:21]
	s_mov_b32 m0, s79
	s_nop 0
	s_mov_b32 s79, m0
	s_mov_b32 m0, s65
	s_nop 0
	global_load_lds_dwordx4 v177, s[20:21]
	s_mov_b32 m0, s79
	s_waitcnt vmcnt(8)
	s_waitcnt lgkmcnt(0)
	s_barrier
	s_setprio 1
	s_waitcnt lgkmcnt(7)
	v_mfma_f32_16x16x32_bf16 v[126:129], v[130:133], v[168:171], v[126:129]
	v_mfma_f32_16x16x32_bf16 v[126:129], v[134:137], v[172:175], v[126:129]
	s_waitcnt lgkmcnt(5)
	v_mfma_f32_16x16x32_bf16 v[122:125], v[138:141], v[168:171], v[122:125]
	v_mfma_f32_16x16x32_bf16 v[122:125], v[142:145], v[172:175], v[122:125]
	s_waitcnt lgkmcnt(3)
	v_mfma_f32_16x16x32_bf16 v[110:113], v[138:141], v[188:191], v[110:113]
	v_mfma_f32_16x16x32_bf16 v[110:113], v[142:145], v[192:195], v[110:113]
	s_waitcnt lgkmcnt(1)
	v_mfma_f32_16x16x32_bf16 v[118:121], v[130:133], v[188:191], v[118:121]
	v_mfma_f32_16x16x32_bf16 v[118:121], v[134:137], v[192:195], v[118:121]
	v_mfma_f32_16x16x32_bf16 v[94:97], v[130:133], v[196:199], v[94:97]
	v_mfma_f32_16x16x32_bf16 v[94:97], v[134:137], v[200:203], v[94:97]
	v_mfma_f32_16x16x32_bf16 v[90:93], v[138:141], v[196:199], v[90:93]
	v_mfma_f32_16x16x32_bf16 v[90:93], v[142:145], v[200:203], v[90:93]
	v_mfma_f32_16x16x32_bf16 v[78:81], v[138:141], v[204:207], v[78:81]
	v_mfma_f32_16x16x32_bf16 v[78:81], v[142:145], v[208:211], v[78:81]
	s_waitcnt lgkmcnt(0)
	v_mfma_f32_16x16x32_bf16 v[86:89], v[130:133], v[204:207], v[86:89]
	v_mfma_f32_16x16x32_bf16 v[86:89], v[134:137], v[208:211], v[86:89]
	s_setprio 0
	s_setprio 1
	v_mfma_f32_16x16x32_bf16 v[114:117], v[150:153], v[168:171], v[114:117]
	v_mfma_f32_16x16x32_bf16 v[114:117], v[154:157], v[172:175], v[114:117]
	v_mfma_f32_16x16x32_bf16 v[106:109], v[158:161], v[168:171], v[106:109]
	v_mfma_f32_16x16x32_bf16 v[106:109], v[162:165], v[172:175], v[106:109]
	v_mfma_f32_16x16x32_bf16 v[98:101], v[158:161], v[188:191], v[98:101]
	v_mfma_f32_16x16x32_bf16 v[98:101], v[162:165], v[192:195], v[98:101]
	v_mfma_f32_16x16x32_bf16 v[102:105], v[150:153], v[188:191], v[102:105]
	v_mfma_f32_16x16x32_bf16 v[102:105], v[154:157], v[192:195], v[102:105]
	v_mfma_f32_16x16x32_bf16 v[82:85], v[150:153], v[196:199], v[82:85]
	v_mfma_f32_16x16x32_bf16 v[82:85], v[154:157], v[200:203], v[82:85]
	v_mfma_f32_16x16x32_bf16 v[74:77], v[158:161], v[196:199], v[74:77]
	v_mfma_f32_16x16x32_bf16 v[74:77], v[162:165], v[200:203], v[74:77]
	v_mfma_f32_16x16x32_bf16 v[66:69], v[158:161], v[204:207], v[66:69]
	v_mfma_f32_16x16x32_bf16 v[66:69], v[162:165], v[208:211], v[66:69]
	s_setprio 2
	s_barrier
	v_mfma_f32_16x16x32_bf16 v[70:73], v[150:153], v[204:207], v[70:73]
	v_mfma_f32_16x16x32_bf16 v[70:73], v[154:157], v[208:211], v[70:73]
	s_setprio 0
	ds_read_b128 v[168:171], v183 offset:16384
	ds_read_b128 v[172:175], v183 offset:17408
	ds_read_b128 v[188:191], v183 offset:18432
	ds_read_b128 v[192:195], v183 offset:19456
	ds_read_b128 v[196:199], v183 offset:20480
	ds_read_b128 v[200:203], v183 offset:21504
	ds_read_b128 v[204:207], v183 offset:22528
	ds_read_b128 v[208:211], v183 offset:23552
	s_mov_b32 s79, m0
	s_mov_b32 m0, s35
	s_nop 0
	global_load_lds_dwordx4 v176, s[22:23]
	s_mov_b32 m0, s79
	s_add_u32 s80, s22, 0x4000
	s_mov_b32 s79, m0
	s_mov_b32 m0, s36
	s_nop 0
	global_load_lds_dwordx4 v178, s[22:23]
	s_mov_b32 m0, s79
	s_addc_u32 s81, s23, 0
	s_mov_b32 s79, m0
	s_mov_b32 m0, s37
	s_nop 0
	global_load_lds_dwordx4 v176, s[80:81]
	s_mov_b32 m0, s79
	s_nop 0
	s_mov_b32 s79, m0
	s_mov_b32 m0, s40
	s_nop 0
	global_load_lds_dwordx4 v178, s[80:81]
	s_mov_b32 m0, s79
	s_waitcnt vmcnt(4)
	s_waitcnt lgkmcnt(0)
	s_barrier
	s_setprio 1
	s_waitcnt lgkmcnt(7)
	v_mfma_f32_16x16x32_bf16 v[62:65], v[130:133], v[168:171], v[62:65]
	v_mfma_f32_16x16x32_bf16 v[62:65], v[134:137], v[172:175], v[62:65]
	s_waitcnt lgkmcnt(5)
	v_mfma_f32_16x16x32_bf16 v[58:61], v[138:141], v[168:171], v[58:61]
	v_mfma_f32_16x16x32_bf16 v[58:61], v[142:145], v[172:175], v[58:61]
	s_waitcnt lgkmcnt(3)
	v_mfma_f32_16x16x32_bf16 v[42:45], v[138:141], v[188:191], v[42:45]
	v_mfma_f32_16x16x32_bf16 v[42:45], v[142:145], v[192:195], v[42:45]
	s_waitcnt lgkmcnt(1)
	v_mfma_f32_16x16x32_bf16 v[46:49], v[130:133], v[188:191], v[46:49]
	v_mfma_f32_16x16x32_bf16 v[46:49], v[134:137], v[192:195], v[46:49]
	v_mfma_f32_16x16x32_bf16 v[30:33], v[130:133], v[196:199], v[30:33]
	v_mfma_f32_16x16x32_bf16 v[30:33], v[134:137], v[200:203], v[30:33]
	v_mfma_f32_16x16x32_bf16 v[26:29], v[138:141], v[196:199], v[26:29]
	v_mfma_f32_16x16x32_bf16 v[26:29], v[142:145], v[200:203], v[26:29]
	v_mfma_f32_16x16x32_bf16 v[10:13], v[138:141], v[204:207], v[10:13]
	v_mfma_f32_16x16x32_bf16 v[10:13], v[142:145], v[208:211], v[10:13]
	s_waitcnt lgkmcnt(0)
	v_mfma_f32_16x16x32_bf16 v[14:17], v[130:133], v[204:207], v[14:17]
	v_mfma_f32_16x16x32_bf16 v[14:17], v[134:137], v[208:211], v[14:17]
	s_setprio 0
	s_setprio 1
	v_mfma_f32_16x16x32_bf16 v[54:57], v[150:153], v[168:171], v[54:57]
	v_mfma_f32_16x16x32_bf16 v[54:57], v[154:157], v[172:175], v[54:57]
	v_mfma_f32_16x16x32_bf16 v[50:53], v[158:161], v[168:171], v[50:53]
	v_mfma_f32_16x16x32_bf16 v[50:53], v[162:165], v[172:175], v[50:53]
	v_mfma_f32_16x16x32_bf16 v[34:37], v[158:161], v[188:191], v[34:37]
	v_mfma_f32_16x16x32_bf16 v[34:37], v[162:165], v[192:195], v[34:37]
	v_mfma_f32_16x16x32_bf16 v[38:41], v[150:153], v[188:191], v[38:41]
	v_mfma_f32_16x16x32_bf16 v[38:41], v[154:157], v[192:195], v[38:41]
	v_mfma_f32_16x16x32_bf16 v[22:25], v[150:153], v[196:199], v[22:25]
	v_mfma_f32_16x16x32_bf16 v[22:25], v[154:157], v[200:203], v[22:25]
	v_mfma_f32_16x16x32_bf16 v[18:21], v[158:161], v[196:199], v[18:21]
	v_mfma_f32_16x16x32_bf16 v[18:21], v[162:165], v[200:203], v[18:21]
	v_mfma_f32_16x16x32_bf16 v[2:5], v[158:161], v[204:207], v[2:5]
	v_mfma_f32_16x16x32_bf16 v[2:5], v[162:165], v[208:211], v[2:5]
	s_setprio 2
	s_barrier
	v_mfma_f32_16x16x32_bf16 v[6:9], v[150:153], v[204:207], v[6:9]
	v_mfma_f32_16x16x32_bf16 v[6:9], v[154:157], v[208:211], v[6:9]
	s_setprio 0
	ds_read_b128 v[130:133], v184
	ds_read_b128 v[134:137], v184 offset:1024
	ds_read_b128 v[138:141], v184 offset:2048
	ds_read_b128 v[142:145], v184 offset:3072
	ds_read_b128 v[150:153], v185
	ds_read_b128 v[154:157], v185 offset:1024
	ds_read_b128 v[158:161], v185 offset:2048
	ds_read_b128 v[162:165], v185 offset:3072
	ds_read_b128 v[168:171], v183 offset:32768
	ds_read_b128 v[172:175], v183 offset:33792
	ds_read_b128 v[188:191], v183 offset:34816
	ds_read_b128 v[192:195], v183 offset:35840
	ds_read_b128 v[196:199], v183 offset:36864
	ds_read_b128 v[200:203], v183 offset:37888
	ds_read_b128 v[204:207], v183 offset:38912
	ds_read_b128 v[208:211], v183 offset:39936
	s_mov_b32 s79, m0
	s_mov_b32 m0, s34
	s_nop 0
	global_load_lds_dwordx4 v1, s[24:25]
	s_mov_b32 m0, s79
	s_nop 0
	s_mov_b32 s79, m0
	s_mov_b32 m0, s41
	s_nop 0
	global_load_lds_dwordx4 v177, s[24:25]
	s_mov_b32 m0, s79
	s_add_u32 s24, s24, 0x4000
	s_addc_u32 s25, s25, 0
	s_mov_b32 s79, m0
	s_mov_b32 m0, s42
	s_nop 0
	global_load_lds_dwordx4 v1, s[24:25]
	s_mov_b32 m0, s79
	s_nop 0
	s_mov_b32 s79, m0
	s_mov_b32 m0, s43
	s_nop 0
	global_load_lds_dwordx4 v177, s[24:25]
	s_mov_b32 m0, s79
	s_waitcnt vmcnt(8)
	s_waitcnt lgkmcnt(0)
	s_barrier
	s_setprio 1
	s_waitcnt lgkmcnt(7)
	v_mfma_f32_16x16x32_bf16 v[126:129], v[130:133], v[168:171], v[126:129]
	v_mfma_f32_16x16x32_bf16 v[126:129], v[134:137], v[172:175], v[126:129]
	s_waitcnt lgkmcnt(5)
	v_mfma_f32_16x16x32_bf16 v[122:125], v[138:141], v[168:171], v[122:125]
	v_mfma_f32_16x16x32_bf16 v[122:125], v[142:145], v[172:175], v[122:125]
	s_waitcnt lgkmcnt(3)
	v_mfma_f32_16x16x32_bf16 v[110:113], v[138:141], v[188:191], v[110:113]
	v_mfma_f32_16x16x32_bf16 v[110:113], v[142:145], v[192:195], v[110:113]
	s_waitcnt lgkmcnt(1)
	v_mfma_f32_16x16x32_bf16 v[118:121], v[130:133], v[188:191], v[118:121]
	v_mfma_f32_16x16x32_bf16 v[118:121], v[134:137], v[192:195], v[118:121]
	v_mfma_f32_16x16x32_bf16 v[94:97], v[130:133], v[196:199], v[94:97]
	v_mfma_f32_16x16x32_bf16 v[94:97], v[134:137], v[200:203], v[94:97]
	v_mfma_f32_16x16x32_bf16 v[90:93], v[138:141], v[196:199], v[90:93]
	v_mfma_f32_16x16x32_bf16 v[90:93], v[142:145], v[200:203], v[90:93]
	v_mfma_f32_16x16x32_bf16 v[78:81], v[138:141], v[204:207], v[78:81]
	v_mfma_f32_16x16x32_bf16 v[78:81], v[142:145], v[208:211], v[78:81]
	s_waitcnt lgkmcnt(0)
	v_mfma_f32_16x16x32_bf16 v[86:89], v[130:133], v[204:207], v[86:89]
	v_mfma_f32_16x16x32_bf16 v[86:89], v[134:137], v[208:211], v[86:89]
	s_setprio 0
	s_setprio 1
	v_mfma_f32_16x16x32_bf16 v[114:117], v[150:153], v[168:171], v[114:117]
	v_mfma_f32_16x16x32_bf16 v[114:117], v[154:157], v[172:175], v[114:117]
	v_mfma_f32_16x16x32_bf16 v[106:109], v[158:161], v[168:171], v[106:109]
	v_mfma_f32_16x16x32_bf16 v[106:109], v[162:165], v[172:175], v[106:109]
	v_mfma_f32_16x16x32_bf16 v[98:101], v[158:161], v[188:191], v[98:101]
	v_mfma_f32_16x16x32_bf16 v[98:101], v[162:165], v[192:195], v[98:101]
	v_mfma_f32_16x16x32_bf16 v[102:105], v[150:153], v[188:191], v[102:105]
	v_mfma_f32_16x16x32_bf16 v[102:105], v[154:157], v[192:195], v[102:105]
	v_mfma_f32_16x16x32_bf16 v[82:85], v[150:153], v[196:199], v[82:85]
	v_mfma_f32_16x16x32_bf16 v[82:85], v[154:157], v[200:203], v[82:85]
	v_mfma_f32_16x16x32_bf16 v[74:77], v[158:161], v[196:199], v[74:77]
	v_mfma_f32_16x16x32_bf16 v[74:77], v[162:165], v[200:203], v[74:77]
	v_mfma_f32_16x16x32_bf16 v[66:69], v[158:161], v[204:207], v[66:69]
	v_mfma_f32_16x16x32_bf16 v[66:69], v[162:165], v[208:211], v[66:69]
	s_setprio 2
	s_barrier
	v_mfma_f32_16x16x32_bf16 v[70:73], v[150:153], v[204:207], v[70:73]
	v_mfma_f32_16x16x32_bf16 v[70:73], v[154:157], v[208:211], v[70:73]
	s_setprio 0
	ds_read_b128 v[168:171], v183 offset:49152
	ds_read_b128 v[172:175], v183 offset:50176
	ds_read_b128 v[188:191], v183 offset:51200
	ds_read_b128 v[192:195], v183 offset:52224
	ds_read_b128 v[196:199], v183 offset:53248
	ds_read_b128 v[200:203], v183 offset:54272
	ds_read_b128 v[204:207], v183 offset:55296
	ds_read_b128 v[208:211], v183 offset:56320
	s_add_u32 s24, s22, 0x40000
	s_addc_u32 s25, s23, 0
	s_mov_b32 s79, m0
	s_mov_b32 m0, s46
	s_nop 0
	global_load_lds_dwordx4 v176, s[24:25]
	s_mov_b32 m0, s79
	s_add_u32 s22, s22, 0x44000
	s_mov_b32 s79, m0
	s_mov_b32 m0, s47
	s_nop 0
	global_load_lds_dwordx4 v178, s[24:25]
	s_mov_b32 m0, s79
	s_addc_u32 s23, s23, 0
	s_mov_b32 s24, m0
	s_mov_b32 m0, s48
	s_nop 0
	global_load_lds_dwordx4 v176, s[22:23]
	s_mov_b32 m0, s24
	s_nop 0
	s_mov_b32 s24, m0
	s_mov_b32 m0, s49
	s_nop 0
	global_load_lds_dwordx4 v178, s[22:23]
	s_mov_b32 m0, s24
	s_waitcnt vmcnt(4)
	s_waitcnt lgkmcnt(0)
	s_barrier
	s_setprio 1
	s_waitcnt lgkmcnt(7)
	v_mfma_f32_16x16x32_bf16 v[62:65], v[130:133], v[168:171], v[62:65]
	v_mfma_f32_16x16x32_bf16 v[62:65], v[134:137], v[172:175], v[62:65]
	s_waitcnt lgkmcnt(5)
	v_mfma_f32_16x16x32_bf16 v[58:61], v[138:141], v[168:171], v[58:61]
	v_mfma_f32_16x16x32_bf16 v[58:61], v[142:145], v[172:175], v[58:61]
	s_waitcnt lgkmcnt(3)
	v_mfma_f32_16x16x32_bf16 v[42:45], v[138:141], v[188:191], v[42:45]
	v_mfma_f32_16x16x32_bf16 v[42:45], v[142:145], v[192:195], v[42:45]
	s_waitcnt lgkmcnt(1)
	v_mfma_f32_16x16x32_bf16 v[46:49], v[130:133], v[188:191], v[46:49]
	v_mfma_f32_16x16x32_bf16 v[46:49], v[134:137], v[192:195], v[46:49]
	v_mfma_f32_16x16x32_bf16 v[30:33], v[130:133], v[196:199], v[30:33]
	v_mfma_f32_16x16x32_bf16 v[30:33], v[134:137], v[200:203], v[30:33]
	v_mfma_f32_16x16x32_bf16 v[26:29], v[138:141], v[196:199], v[26:29]
	v_mfma_f32_16x16x32_bf16 v[26:29], v[142:145], v[200:203], v[26:29]
	v_mfma_f32_16x16x32_bf16 v[10:13], v[138:141], v[204:207], v[10:13]
	v_mfma_f32_16x16x32_bf16 v[10:13], v[142:145], v[208:211], v[10:13]
	s_waitcnt lgkmcnt(0)
	v_mfma_f32_16x16x32_bf16 v[14:17], v[130:133], v[204:207], v[14:17]
	v_mfma_f32_16x16x32_bf16 v[14:17], v[134:137], v[208:211], v[14:17]
	s_setprio 0
	s_setprio 1
	v_mfma_f32_16x16x32_bf16 v[54:57], v[150:153], v[168:171], v[54:57]
	v_mfma_f32_16x16x32_bf16 v[54:57], v[154:157], v[172:175], v[54:57]
	v_mfma_f32_16x16x32_bf16 v[50:53], v[158:161], v[168:171], v[50:53]
	v_mfma_f32_16x16x32_bf16 v[50:53], v[162:165], v[172:175], v[50:53]
	v_mfma_f32_16x16x32_bf16 v[34:37], v[158:161], v[188:191], v[34:37]
	v_mfma_f32_16x16x32_bf16 v[34:37], v[162:165], v[192:195], v[34:37]
	v_mfma_f32_16x16x32_bf16 v[38:41], v[150:153], v[188:191], v[38:41]
	v_mfma_f32_16x16x32_bf16 v[38:41], v[154:157], v[192:195], v[38:41]
	v_mfma_f32_16x16x32_bf16 v[22:25], v[150:153], v[196:199], v[22:25]
	v_mfma_f32_16x16x32_bf16 v[22:25], v[154:157], v[200:203], v[22:25]
	v_mfma_f32_16x16x32_bf16 v[18:21], v[158:161], v[196:199], v[18:21]
	v_mfma_f32_16x16x32_bf16 v[18:21], v[162:165], v[200:203], v[18:21]
	v_mfma_f32_16x16x32_bf16 v[2:5], v[158:161], v[204:207], v[2:5]
	v_mfma_f32_16x16x32_bf16 v[2:5], v[162:165], v[208:211], v[2:5]
	s_setprio 2
	s_barrier
	v_mfma_f32_16x16x32_bf16 v[6:9], v[150:153], v[204:207], v[6:9]
	v_mfma_f32_16x16x32_bf16 v[6:9], v[154:157], v[208:211], v[6:9]
	s_setprio 0
	s_add_i32 s78, s78, 2
	s_add_u32 s74, s74, 0x80000
	s_addc_u32 s75, s75, 0
	s_add_u32 s20, s20, 0x400000
	s_addc_u32 s21, s21, 0
	s_add_u32 s76, s76, 0x400000
	s_addc_u32 s77, s77, 0
	s_cmpk_gt_u32 s78, 0x53
	s_cbranch_scc0 .LBB0_1357
	v_mov_b32_e32 v174, v252
	v_mov_b32_e32 v175, v253
	v_mov_b32_e32 v210, v254
	v_mov_b32_e32 v211, v255
	s_and_b64 vcc, exec, s[8:9]
	s_cbranch_vccz .LBB0_1360
	s_barrier

.LBB0_1537:
	s_ashr_i32 s23, s22, 31
	s_lshl_b64 s[24:25], s[22:23], 20
	s_add_u32 s24, s41, s24
	s_addc_u32 s25, s42, s25
	s_and_b64 s[26:27], s[4:5], exec
	s_cselect_b32 s7, s25, s35
	s_cselect_b32 s23, s24, s34
	s_ashr_i32 s21, s20, 31
	s_lshl_b64 s[26:27], s[20:21], 20
	s_add_u32 s26, s43, s26
	s_addc_u32 s27, s46, s27
	s_and_b64 s[36:37], s[4:5], exec
	s_cselect_b32 s21, s27, s31
	s_cselect_b32 s29, s26, s30
	s_add_u32 s79, s30, 0x100
	s_addc_u32 s80, s31, 0
	s_add_u32 s30, s34, 0x80080
	s_addc_u32 s31, s35, 0
	s_add_u32 s81, s34, 0x100
	s_addc_u32 s82, s35, 0
	s_mov_b32 s83, -2
	s_waitcnt vmcnt(25)
	s_waitcnt vmcnt(24)
	s_waitcnt vmcnt(4)
	s_waitcnt vmcnt(14)
	s_waitcnt vmcnt(13)
	s_waitcnt vmcnt(12)
	s_waitcnt vmcnt(2)
	s_waitcnt vmcnt(10)
	s_waitcnt vmcnt(9)
	s_waitcnt vmcnt(8)
	s_waitcnt vmcnt(7)
	s_waitcnt vmcnt(6)
	s_waitcnt vmcnt(5)
	s_waitcnt vmcnt(4)
	s_waitcnt vmcnt(3)
	s_waitcnt vmcnt(2)
	s_waitcnt vmcnt(1)
	s_waitcnt vmcnt(0)
	v_mov_b32_e32 v252, v174
	v_mov_b32_e32 v253, v175
	v_mov_b32_e32 v254, v216
	v_mov_b32_e32 v255, v217
	ds_read_b128 v[46:49], v182
	ds_read_b128 v[54:57], v182 offset:1024
	ds_read_b128 v[58:61], v182 offset:2048
	ds_read_b128 v[62:65], v182 offset:3072
	ds_read_b128 v[146:149], v183
	ds_read_b128 v[150:153], v183 offset:1024
	ds_read_b128 v[154:157], v183 offset:2048
	ds_read_b128 v[158:161], v183 offset:3072
	s_cmp_eq_u32 s83, 28
	s_cselect_b32 s35, s21, s80
	s_cselect_b32 s34, s29, s79
	s_cselect_b32 s37, s7, s82
	s_cselect_b32 s36, s23, s81
	ds_read_b128 v[172:175], v184
	ds_read_b128 v[190:193], v184 offset:1024
	ds_read_b128 v[194:197], v184 offset:2048
	ds_read_b128 v[198:201], v184 offset:3072
	ds_read_b128 v[202:205], v184 offset:4096
	ds_read_b128 v[206:209], v184 offset:5120
	ds_read_b128 v[210:213], v184 offset:6144
	ds_read_b128 v[214:217], v184 offset:7168
	s_add_u32 s86, s30, 0xfff80000
	s_addc_u32 s87, s31, -1
	s_mov_b32 s92, m0
	s_mov_b32 m0, s73
	s_nop 0
	global_load_lds_dwordx4 v176, s[86:87]
	s_mov_b32 m0, s92
	s_nop 0
	s_mov_b32 s92, m0
	s_mov_b32 m0, s75
	s_nop 0
	global_load_lds_dwordx4 v178, s[86:87]
	s_mov_b32 m0, s92
	s_mov_b32 s86, m0
	s_mov_b32 m0, s74
	s_nop 0
	global_load_lds_dwordx4 v176, s[30:31]
	s_mov_b32 m0, s86
	s_nop 0
	s_mov_b32 s86, m0
	s_mov_b32 m0, s76
	s_nop 0
	global_load_lds_dwordx4 v178, s[30:31]
	s_mov_b32 m0, s86
	s_waitcnt vmcnt(8)
	s_waitcnt lgkmcnt(0)
	s_barrier
	s_setprio 1
	s_waitcnt lgkmcnt(7)
	v_mfma_f32_16x16x32_bf16 v[142:145], v[46:49], v[172:175], 0
	v_mfma_f32_16x16x32_bf16 v[142:145], v[54:57], v[190:193], v[142:145]
	s_waitcnt lgkmcnt(5)
	v_mfma_f32_16x16x32_bf16 v[138:141], v[58:61], v[172:175], 0
	v_mfma_f32_16x16x32_bf16 v[138:141], v[62:65], v[190:193], v[138:141]
	s_waitcnt lgkmcnt(3)
	v_mfma_f32_16x16x32_bf16 v[126:129], v[46:49], v[194:197], 0
	v_mfma_f32_16x16x32_bf16 v[126:129], v[54:57], v[198:201], v[126:129]
	s_waitcnt lgkmcnt(1)
	v_mfma_f32_16x16x32_bf16 v[122:125], v[58:61], v[194:197], 0
	v_mfma_f32_16x16x32_bf16 v[122:125], v[62:65], v[198:201], v[122:125]
	v_mfma_f32_16x16x32_bf16 v[110:113], v[46:49], v[202:205], 0
	v_mfma_f32_16x16x32_bf16 v[110:113], v[54:57], v[206:209], v[110:113]
	v_mfma_f32_16x16x32_bf16 v[106:109], v[58:61], v[202:205], 0
	v_mfma_f32_16x16x32_bf16 v[106:109], v[62:65], v[206:209], v[106:109]
	v_mfma_f32_16x16x32_bf16 v[94:97], v[46:49], v[210:213], 0
	v_mfma_f32_16x16x32_bf16 v[94:97], v[54:57], v[214:217], v[94:97]
	s_waitcnt lgkmcnt(0)
	v_mfma_f32_16x16x32_bf16 v[90:93], v[58:61], v[210:213], 0
	v_mfma_f32_16x16x32_bf16 v[90:93], v[62:65], v[214:217], v[90:93]
	s_setprio 0
	s_setprio 1
	v_mfma_f32_16x16x32_bf16 v[134:137], v[146:149], v[172:175], 0
	v_mfma_f32_16x16x32_bf16 v[134:137], v[150:153], v[190:193], v[134:137]
	v_mfma_f32_16x16x32_bf16 v[130:133], v[154:157], v[172:175], 0
	v_mfma_f32_16x16x32_bf16 v[130:133], v[158:161], v[190:193], v[130:133]
	v_mfma_f32_16x16x32_bf16 v[118:121], v[146:149], v[194:197], 0
	v_mfma_f32_16x16x32_bf16 v[118:121], v[150:153], v[198:201], v[118:121]
	v_mfma_f32_16x16x32_bf16 v[114:117], v[154:157], v[194:197], 0
	v_mfma_f32_16x16x32_bf16 v[114:117], v[158:161], v[198:201], v[114:117]
	v_mfma_f32_16x16x32_bf16 v[102:105], v[146:149], v[202:205], 0
	v_mfma_f32_16x16x32_bf16 v[102:105], v[150:153], v[206:209], v[102:105]
	v_mfma_f32_16x16x32_bf16 v[98:101], v[154:157], v[202:205], 0
	v_mfma_f32_16x16x32_bf16 v[98:101], v[158:161], v[206:209], v[98:101]
	v_mfma_f32_16x16x32_bf16 v[86:89], v[146:149], v[210:213], 0
	v_mfma_f32_16x16x32_bf16 v[86:89], v[150:153], v[214:217], v[86:89]
	s_setprio 2
	s_barrier
	v_mfma_f32_16x16x32_bf16 v[82:85], v[154:157], v[210:213], 0
	v_mfma_f32_16x16x32_bf16 v[82:85], v[158:161], v[214:217], v[82:85]
	s_setprio 0
	ds_read_b128 v[172:175], v184 offset:16384
	ds_read_b128 v[190:193], v184 offset:17408
	ds_read_b128 v[194:197], v184 offset:18432
	ds_read_b128 v[198:201], v184 offset:19456
	ds_read_b128 v[202:205], v184 offset:20480
	ds_read_b128 v[206:209], v184 offset:21504
	ds_read_b128 v[210:213], v184 offset:22528
	ds_read_b128 v[214:217], v184 offset:23552
	s_mov_b32 s86, m0
	s_mov_b32 m0, s49
	s_nop 0
	global_load_lds_dwordx4 v177, s[34:35]
	s_mov_b32 m0, s86
	s_nop 0
	s_mov_b32 s86, m0
	s_mov_b32 m0, s56
	s_nop 0
	global_load_lds_dwordx4 v179, s[34:35]
	s_mov_b32 m0, s86
	s_add_u32 s86, s34, 0x80000
	s_addc_u32 s87, s35, 0
	s_mov_b32 s92, m0
	s_mov_b32 m0, s57
	s_nop 0
	global_load_lds_dwordx4 v177, s[86:87]
	s_mov_b32 m0, s92
	s_nop 0
	s_mov_b32 s92, m0
	s_mov_b32 m0, s58
	s_nop 0
	global_load_lds_dwordx4 v179, s[86:87]
	s_mov_b32 m0, s92
	s_waitcnt vmcnt(4)
	s_waitcnt lgkmcnt(0)
	s_barrier
	s_setprio 1
	s_waitcnt lgkmcnt(7)
	v_mfma_f32_16x16x32_bf16 v[78:81], v[46:49], v[172:175], 0
	v_mfma_f32_16x16x32_bf16 v[78:81], v[54:57], v[190:193], v[78:81]
	s_waitcnt lgkmcnt(5)
	v_mfma_f32_16x16x32_bf16 v[74:77], v[58:61], v[172:175], 0
	v_mfma_f32_16x16x32_bf16 v[74:77], v[62:65], v[190:193], v[74:77]
	s_waitcnt lgkmcnt(3)
	v_mfma_f32_16x16x32_bf16 v[50:53], v[46:49], v[194:197], 0
	v_mfma_f32_16x16x32_bf16 v[50:53], v[54:57], v[198:201], v[50:53]
	s_waitcnt lgkmcnt(1)
	v_mfma_f32_16x16x32_bf16 v[42:45], v[58:61], v[194:197], 0
	v_mfma_f32_16x16x32_bf16 v[42:45], v[62:65], v[198:201], v[42:45]
	v_mfma_f32_16x16x32_bf16 v[30:33], v[46:49], v[202:205], 0
	v_mfma_f32_16x16x32_bf16 v[30:33], v[54:57], v[206:209], v[30:33]
	v_mfma_f32_16x16x32_bf16 v[26:29], v[58:61], v[202:205], 0
	v_mfma_f32_16x16x32_bf16 v[26:29], v[62:65], v[206:209], v[26:29]
	v_mfma_f32_16x16x32_bf16 v[14:17], v[46:49], v[210:213], 0
	v_mfma_f32_16x16x32_bf16 v[14:17], v[54:57], v[214:217], v[14:17]
	s_waitcnt lgkmcnt(0)
	v_mfma_f32_16x16x32_bf16 v[10:13], v[58:61], v[210:213], 0
	v_mfma_f32_16x16x32_bf16 v[10:13], v[62:65], v[214:217], v[10:13]
	s_setprio 0
	s_setprio 1
	v_mfma_f32_16x16x32_bf16 v[38:41], v[146:149], v[194:197], 0
	v_mfma_f32_16x16x32_bf16 v[38:41], v[150:153], v[198:201], v[38:41]
	v_mfma_f32_16x16x32_bf16 v[34:37], v[154:157], v[194:197], 0
	v_mfma_f32_16x16x32_bf16 v[34:37], v[158:161], v[198:201], v[34:37]
	v_mfma_f32_16x16x32_bf16 v[22:25], v[146:149], v[202:205], 0
	v_mfma_f32_16x16x32_bf16 v[22:25], v[150:153], v[206:209], v[22:25]
	v_mfma_f32_16x16x32_bf16 v[18:21], v[154:157], v[202:205], 0
	v_mfma_f32_16x16x32_bf16 v[18:21], v[158:161], v[206:209], v[18:21]
	v_mfma_f32_16x16x32_bf16 v[6:9], v[146:149], v[210:213], 0
	v_mfma_f32_16x16x32_bf16 v[6:9], v[150:153], v[214:217], v[6:9]
	v_mfma_f32_16x16x32_bf16 v[2:5], v[154:157], v[210:213], 0
	v_mfma_f32_16x16x32_bf16 v[2:5], v[158:161], v[214:217], v[2:5]
	v_mfma_f32_16x16x32_bf16 v[46:49], v[146:149], v[172:175], 0
	v_mfma_f32_16x16x32_bf16 v[46:49], v[150:153], v[190:193], v[46:49]
	s_setprio 2
	s_barrier
	v_mfma_f32_16x16x32_bf16 v[54:57], v[154:157], v[172:175], 0
	v_mfma_f32_16x16x32_bf16 v[54:57], v[158:161], v[190:193], v[54:57]
	s_setprio 0
	ds_read_b128 v[58:61], v185
	ds_read_b128 v[62:65], v185 offset:1024
	ds_read_b128 v[66:69], v185 offset:2048
	ds_read_b128 v[70:73], v185 offset:3072
	ds_read_b128 v[146:149], v186
	ds_read_b128 v[150:153], v186 offset:1024
	ds_read_b128 v[154:157], v186 offset:2048
	ds_read_b128 v[158:161], v186 offset:3072
	ds_read_b128 v[172:175], v184 offset:32768
	ds_read_b128 v[190:193], v184 offset:33792
	ds_read_b128 v[194:197], v184 offset:34816
	ds_read_b128 v[198:201], v184 offset:35840
	ds_read_b128 v[202:205], v184 offset:36864
	ds_read_b128 v[206:209], v184 offset:37888
	ds_read_b128 v[210:213], v184 offset:38912
	ds_read_b128 v[214:217], v184 offset:39936
	s_mov_b32 s86, m0
	s_mov_b32 m0, s48
	s_nop 0
	global_load_lds_dwordx4 v176, s[36:37]
	s_mov_b32 m0, s86
	s_nop 0
	s_mov_b32 s86, m0
	s_mov_b32 m0, s59
	s_nop 0
	global_load_lds_dwordx4 v178, s[36:37]
	s_mov_b32 m0, s86
	s_add_u32 s36, s36, 0x80000
	s_addc_u32 s37, s37, 0
	s_mov_b32 s86, m0
	s_mov_b32 m0, s62
	s_nop 0
	global_load_lds_dwordx4 v176, s[36:37]
	s_mov_b32 m0, s86
	s_nop 0
	s_mov_b32 s86, m0
	s_mov_b32 m0, s63
	s_nop 0
	global_load_lds_dwordx4 v178, s[36:37]
	s_mov_b32 m0, s86
	s_waitcnt vmcnt(8)
	s_waitcnt lgkmcnt(0)
	s_barrier
	s_setprio 1
	s_waitcnt lgkmcnt(7)
	v_mfma_f32_16x16x32_bf16 v[142:145], v[58:61], v[172:175], v[142:145]
	v_mfma_f32_16x16x32_bf16 v[142:145], v[62:65], v[190:193], v[142:145]
	s_waitcnt lgkmcnt(5)
	v_mfma_f32_16x16x32_bf16 v[138:141], v[66:69], v[172:175], v[138:141]
	v_mfma_f32_16x16x32_bf16 v[138:141], v[70:73], v[190:193], v[138:141]
	s_waitcnt lgkmcnt(3)
	v_mfma_f32_16x16x32_bf16 v[126:129], v[58:61], v[194:197], v[126:129]
	v_mfma_f32_16x16x32_bf16 v[126:129], v[62:65], v[198:201], v[126:129]
	s_waitcnt lgkmcnt(1)
	v_mfma_f32_16x16x32_bf16 v[122:125], v[66:69], v[194:197], v[122:125]
	v_mfma_f32_16x16x32_bf16 v[122:125], v[70:73], v[198:201], v[122:125]
	v_mfma_f32_16x16x32_bf16 v[110:113], v[58:61], v[202:205], v[110:113]
	v_mfma_f32_16x16x32_bf16 v[110:113], v[62:65], v[206:209], v[110:113]
	v_mfma_f32_16x16x32_bf16 v[106:109], v[66:69], v[202:205], v[106:109]
	v_mfma_f32_16x16x32_bf16 v[106:109], v[70:73], v[206:209], v[106:109]
	v_mfma_f32_16x16x32_bf16 v[94:97], v[58:61], v[210:213], v[94:97]
	v_mfma_f32_16x16x32_bf16 v[94:97], v[62:65], v[214:217], v[94:97]
	s_waitcnt lgkmcnt(0)
	v_mfma_f32_16x16x32_bf16 v[90:93], v[66:69], v[210:213], v[90:93]
	v_mfma_f32_16x16x32_bf16 v[90:93], v[70:73], v[214:217], v[90:93]
	s_setprio 0
	s_setprio 1
	v_mfma_f32_16x16x32_bf16 v[134:137], v[146:149], v[172:175], v[134:137]
	v_mfma_f32_16x16x32_bf16 v[134:137], v[150:153], v[190:193], v[134:137]
	v_mfma_f32_16x16x32_bf16 v[130:133], v[154:157], v[172:175], v[130:133]
	v_mfma_f32_16x16x32_bf16 v[130:133], v[158:161], v[190:193], v[130:133]
	v_mfma_f32_16x16x32_bf16 v[118:121], v[146:149], v[194:197], v[118:121]
	v_mfma_f32_16x16x32_bf16 v[118:121], v[150:153], v[198:201], v[118:121]
	v_mfma_f32_16x16x32_bf16 v[114:117], v[154:157], v[194:197], v[114:117]
	v_mfma_f32_16x16x32_bf16 v[114:117], v[158:161], v[198:201], v[114:117]
	v_mfma_f32_16x16x32_bf16 v[102:105], v[146:149], v[202:205], v[102:105]
	v_mfma_f32_16x16x32_bf16 v[102:105], v[150:153], v[206:209], v[102:105]
	v_mfma_f32_16x16x32_bf16 v[98:101], v[154:157], v[202:205], v[98:101]
	v_mfma_f32_16x16x32_bf16 v[98:101], v[158:161], v[206:209], v[98:101]
	v_mfma_f32_16x16x32_bf16 v[86:89], v[146:149], v[210:213], v[86:89]
	v_mfma_f32_16x16x32_bf16 v[86:89], v[150:153], v[214:217], v[86:89]
	s_setprio 2
	s_barrier
	v_mfma_f32_16x16x32_bf16 v[82:85], v[154:157], v[210:213], v[82:85]
	v_mfma_f32_16x16x32_bf16 v[82:85], v[158:161], v[214:217], v[82:85]
	s_setprio 0
	ds_read_b128 v[172:175], v184 offset:49152
	ds_read_b128 v[190:193], v184 offset:50176
	ds_read_b128 v[194:197], v184 offset:51200
	ds_read_b128 v[198:201], v184 offset:52224
	ds_read_b128 v[202:205], v184 offset:53248
	ds_read_b128 v[206:209], v184 offset:54272
	ds_read_b128 v[210:213], v184 offset:55296
	ds_read_b128 v[214:217], v184 offset:56320
	s_add_u32 s36, s34, 0x80
	s_addc_u32 s37, s35, 0
	s_mov_b32 s86, m0
	s_mov_b32 m0, s64
	s_nop 0
	global_load_lds_dwordx4 v177, s[36:37]
	s_mov_b32 m0, s86
	s_add_u32 s34, s34, 0x80080
	s_mov_b32 s86, m0
	s_mov_b32 m0, s65
	s_nop 0
	global_load_lds_dwordx4 v179, s[36:37]
	s_mov_b32 m0, s86
	s_addc_u32 s35, s35, 0
	s_mov_b32 s36, m0
	s_mov_b32 m0, s66
	s_nop 0
	global_load_lds_dwordx4 v177, s[34:35]
	s_mov_b32 m0, s36
	s_nop 0
	s_mov_b32 s36, m0
	s_mov_b32 m0, s67
	s_nop 0
	global_load_lds_dwordx4 v179, s[34:35]
	s_mov_b32 m0, s36
	s_waitcnt vmcnt(4)
	s_waitcnt lgkmcnt(0)
	s_barrier
	s_setprio 1
	s_waitcnt lgkmcnt(7)
	v_mfma_f32_16x16x32_bf16 v[78:81], v[58:61], v[172:175], v[78:81]
	v_mfma_f32_16x16x32_bf16 v[78:81], v[62:65], v[190:193], v[78:81]
	s_waitcnt lgkmcnt(5)
	v_mfma_f32_16x16x32_bf16 v[74:77], v[66:69], v[172:175], v[74:77]
	v_mfma_f32_16x16x32_bf16 v[74:77], v[70:73], v[190:193], v[74:77]
	s_waitcnt lgkmcnt(3)
	v_mfma_f32_16x16x32_bf16 v[50:53], v[58:61], v[194:197], v[50:53]
	v_mfma_f32_16x16x32_bf16 v[50:53], v[62:65], v[198:201], v[50:53]
	s_waitcnt lgkmcnt(1)
	v_mfma_f32_16x16x32_bf16 v[42:45], v[66:69], v[194:197], v[42:45]
	v_mfma_f32_16x16x32_bf16 v[42:45], v[70:73], v[198:201], v[42:45]
	v_mfma_f32_16x16x32_bf16 v[30:33], v[58:61], v[202:205], v[30:33]
	v_mfma_f32_16x16x32_bf16 v[30:33], v[62:65], v[206:209], v[30:33]
	v_mfma_f32_16x16x32_bf16 v[26:29], v[66:69], v[202:205], v[26:29]
	v_mfma_f32_16x16x32_bf16 v[26:29], v[70:73], v[206:209], v[26:29]
	v_mfma_f32_16x16x32_bf16 v[14:17], v[58:61], v[210:213], v[14:17]
	v_mfma_f32_16x16x32_bf16 v[14:17], v[62:65], v[214:217], v[14:17]
	s_waitcnt lgkmcnt(0)
	v_mfma_f32_16x16x32_bf16 v[10:13], v[66:69], v[210:213], v[10:13]
	v_mfma_f32_16x16x32_bf16 v[10:13], v[70:73], v[214:217], v[10:13]
	s_setprio 0
	s_setprio 1
	v_mfma_f32_16x16x32_bf16 v[46:49], v[146:149], v[172:175], v[46:49]
	v_mfma_f32_16x16x32_bf16 v[70:73], v[150:153], v[190:193], v[46:49]
	v_mfma_f32_16x16x32_bf16 v[46:49], v[154:157], v[172:175], v[54:57]
	v_mfma_f32_16x16x32_bf16 v[66:69], v[158:161], v[190:193], v[46:49]
	v_mfma_f32_16x16x32_bf16 v[38:41], v[146:149], v[194:197], v[38:41]
	v_mfma_f32_16x16x32_bf16 v[38:41], v[150:153], v[198:201], v[38:41]
	v_mfma_f32_16x16x32_bf16 v[34:37], v[154:157], v[194:197], v[34:37]
	v_mfma_f32_16x16x32_bf16 v[34:37], v[158:161], v[198:201], v[34:37]
	v_mfma_f32_16x16x32_bf16 v[22:25], v[146:149], v[202:205], v[22:25]
	v_mfma_f32_16x16x32_bf16 v[22:25], v[150:153], v[206:209], v[22:25]
	v_mfma_f32_16x16x32_bf16 v[18:21], v[154:157], v[202:205], v[18:21]
	v_mfma_f32_16x16x32_bf16 v[18:21], v[158:161], v[206:209], v[18:21]
	v_mfma_f32_16x16x32_bf16 v[6:9], v[146:149], v[210:213], v[6:9]
	v_mfma_f32_16x16x32_bf16 v[6:9], v[150:153], v[214:217], v[6:9]
	s_setprio 2
	s_barrier
	v_mfma_f32_16x16x32_bf16 v[2:5], v[154:157], v[210:213], v[2:5]
	v_mfma_f32_16x16x32_bf16 v[2:5], v[158:161], v[214:217], v[2:5]
	s_setprio 0
	s_add_i32 s83, s83, 2
	s_add_u32 s79, s79, 0x100
	s_addc_u32 s80, s80, 0
	s_add_u32 s30, s30, 0x100
	s_addc_u32 s31, s31, 0
	s_add_u32 s81, s81, 0x100
	s_addc_u32 s82, s82, 0
	s_cmp_gt_u32 s83, 29
	.p2align 6
.LBB0_1538:
	ds_read_b128 v[46:49], v182
	ds_read_b128 v[54:57], v182 offset:1024
	ds_read_b128 v[58:61], v182 offset:2048
	ds_read_b128 v[62:65], v182 offset:3072
	ds_read_b128 v[146:149], v183
	ds_read_b128 v[150:153], v183 offset:1024
	ds_read_b128 v[154:157], v183 offset:2048
	ds_read_b128 v[158:161], v183 offset:3072
	s_cmp_eq_u32 s83, 28
	s_cselect_b32 s35, s21, s80
	s_cselect_b32 s34, s29, s79
	s_cselect_b32 s37, s7, s82
	s_cselect_b32 s36, s23, s81
	ds_read_b128 v[172:175], v184
	ds_read_b128 v[190:193], v184 offset:1024
	ds_read_b128 v[194:197], v184 offset:2048
	ds_read_b128 v[198:201], v184 offset:3072
	ds_read_b128 v[202:205], v184 offset:4096
	ds_read_b128 v[206:209], v184 offset:5120
	ds_read_b128 v[210:213], v184 offset:6144
	ds_read_b128 v[214:217], v184 offset:7168
	s_add_u32 s86, s30, 0xfff80000
	s_addc_u32 s87, s31, -1
	s_mov_b32 s92, m0
	s_mov_b32 m0, s73
	s_nop 0
	global_load_lds_dwordx4 v176, s[86:87]
	s_mov_b32 m0, s92
	s_nop 0
	s_mov_b32 s92, m0
	s_mov_b32 m0, s75
	s_nop 0
	global_load_lds_dwordx4 v178, s[86:87]
	s_mov_b32 m0, s92
	s_mov_b32 s86, m0
	s_mov_b32 m0, s74
	s_nop 0
	global_load_lds_dwordx4 v176, s[30:31]
	s_mov_b32 m0, s86
	s_nop 0
	s_mov_b32 s86, m0
	s_mov_b32 m0, s76
	s_nop 0
	global_load_lds_dwordx4 v178, s[30:31]
	s_mov_b32 m0, s86
	s_waitcnt vmcnt(8)
	s_waitcnt lgkmcnt(0)
	s_barrier
	s_setprio 1
	s_waitcnt lgkmcnt(7)
	v_mfma_f32_16x16x32_bf16 v[142:145], v[46:49], v[172:175], v[142:145]
	v_mfma_f32_16x16x32_bf16 v[142:145], v[54:57], v[190:193], v[142:145]
	s_waitcnt lgkmcnt(5)
	v_mfma_f32_16x16x32_bf16 v[138:141], v[58:61], v[172:175], v[138:141]
	v_mfma_f32_16x16x32_bf16 v[138:141], v[62:65], v[190:193], v[138:141]
	s_waitcnt lgkmcnt(3)
	v_mfma_f32_16x16x32_bf16 v[126:129], v[46:49], v[194:197], v[126:129]
	v_mfma_f32_16x16x32_bf16 v[126:129], v[54:57], v[198:201], v[126:129]
	s_waitcnt lgkmcnt(1)
	v_mfma_f32_16x16x32_bf16 v[122:125], v[58:61], v[194:197], v[122:125]
	v_mfma_f32_16x16x32_bf16 v[122:125], v[62:65], v[198:201], v[122:125]
	v_mfma_f32_16x16x32_bf16 v[110:113], v[46:49], v[202:205], v[110:113]
	v_mfma_f32_16x16x32_bf16 v[110:113], v[54:57], v[206:209], v[110:113]
	v_mfma_f32_16x16x32_bf16 v[106:109], v[58:61], v[202:205], v[106:109]
	v_mfma_f32_16x16x32_bf16 v[106:109], v[62:65], v[206:209], v[106:109]
	v_mfma_f32_16x16x32_bf16 v[94:97], v[46:49], v[210:213], v[94:97]
	v_mfma_f32_16x16x32_bf16 v[94:97], v[54:57], v[214:217], v[94:97]
	s_waitcnt lgkmcnt(0)
	v_mfma_f32_16x16x32_bf16 v[90:93], v[58:61], v[210:213], v[90:93]
	v_mfma_f32_16x16x32_bf16 v[90:93], v[62:65], v[214:217], v[90:93]
	s_setprio 0
	s_setprio 1
	v_mfma_f32_16x16x32_bf16 v[134:137], v[146:149], v[172:175], v[134:137]
	v_mfma_f32_16x16x32_bf16 v[134:137], v[150:153], v[190:193], v[134:137]
	v_mfma_f32_16x16x32_bf16 v[130:133], v[154:157], v[172:175], v[130:133]
	v_mfma_f32_16x16x32_bf16 v[130:133], v[158:161], v[190:193], v[130:133]
	v_mfma_f32_16x16x32_bf16 v[118:121], v[146:149], v[194:197], v[118:121]
	v_mfma_f32_16x16x32_bf16 v[118:121], v[150:153], v[198:201], v[118:121]
	v_mfma_f32_16x16x32_bf16 v[114:117], v[154:157], v[194:197], v[114:117]
	v_mfma_f32_16x16x32_bf16 v[114:117], v[158:161], v[198:201], v[114:117]
	v_mfma_f32_16x16x32_bf16 v[102:105], v[146:149], v[202:205], v[102:105]
	v_mfma_f32_16x16x32_bf16 v[102:105], v[150:153], v[206:209], v[102:105]
	v_mfma_f32_16x16x32_bf16 v[98:101], v[154:157], v[202:205], v[98:101]
	v_mfma_f32_16x16x32_bf16 v[98:101], v[158:161], v[206:209], v[98:101]
	v_mfma_f32_16x16x32_bf16 v[86:89], v[146:149], v[210:213], v[86:89]
	v_mfma_f32_16x16x32_bf16 v[86:89], v[150:153], v[214:217], v[86:89]
	s_setprio 2
	s_barrier
	v_mfma_f32_16x16x32_bf16 v[82:85], v[154:157], v[210:213], v[82:85]
	v_mfma_f32_16x16x32_bf16 v[82:85], v[158:161], v[214:217], v[82:85]
	s_setprio 0
	ds_read_b128 v[172:175], v184 offset:16384
	ds_read_b128 v[190:193], v184 offset:17408
	ds_read_b128 v[194:197], v184 offset:18432
	ds_read_b128 v[198:201], v184 offset:19456
	ds_read_b128 v[202:205], v184 offset:20480
	ds_read_b128 v[206:209], v184 offset:21504
	ds_read_b128 v[210:213], v184 offset:22528
	ds_read_b128 v[214:217], v184 offset:23552
	s_mov_b32 s86, m0
	s_mov_b32 m0, s49
	s_nop 0
	global_load_lds_dwordx4 v177, s[34:35]
	s_mov_b32 m0, s86
	s_nop 0
	s_mov_b32 s86, m0
	s_mov_b32 m0, s56
	s_nop 0
	global_load_lds_dwordx4 v179, s[34:35]
	s_mov_b32 m0, s86
	s_add_u32 s86, s34, 0x80000
	s_addc_u32 s87, s35, 0
	s_mov_b32 s92, m0
	s_mov_b32 m0, s57
	s_nop 0
	global_load_lds_dwordx4 v177, s[86:87]
	s_mov_b32 m0, s92
	s_nop 0
	s_mov_b32 s92, m0
	s_mov_b32 m0, s58
	s_nop 0
	global_load_lds_dwordx4 v179, s[86:87]
	s_mov_b32 m0, s92
	s_waitcnt vmcnt(4)
	s_waitcnt lgkmcnt(0)
	s_barrier
	s_setprio 1
	s_waitcnt lgkmcnt(7)
	v_mfma_f32_16x16x32_bf16 v[78:81], v[46:49], v[172:175], v[78:81]
	v_mfma_f32_16x16x32_bf16 v[78:81], v[54:57], v[190:193], v[78:81]
	s_waitcnt lgkmcnt(5)
	v_mfma_f32_16x16x32_bf16 v[74:77], v[58:61], v[172:175], v[74:77]
	v_mfma_f32_16x16x32_bf16 v[74:77], v[62:65], v[190:193], v[74:77]
	s_waitcnt lgkmcnt(3)
	v_mfma_f32_16x16x32_bf16 v[50:53], v[46:49], v[194:197], v[50:53]
	v_mfma_f32_16x16x32_bf16 v[50:53], v[54:57], v[198:201], v[50:53]
	s_waitcnt lgkmcnt(1)
	v_mfma_f32_16x16x32_bf16 v[42:45], v[58:61], v[194:197], v[42:45]
	v_mfma_f32_16x16x32_bf16 v[42:45], v[62:65], v[198:201], v[42:45]
	v_mfma_f32_16x16x32_bf16 v[30:33], v[46:49], v[202:205], v[30:33]
	v_mfma_f32_16x16x32_bf16 v[30:33], v[54:57], v[206:209], v[30:33]
	v_mfma_f32_16x16x32_bf16 v[26:29], v[58:61], v[202:205], v[26:29]
	v_mfma_f32_16x16x32_bf16 v[26:29], v[62:65], v[206:209], v[26:29]
	v_mfma_f32_16x16x32_bf16 v[14:17], v[46:49], v[210:213], v[14:17]
	v_mfma_f32_16x16x32_bf16 v[14:17], v[54:57], v[214:217], v[14:17]
	s_waitcnt lgkmcnt(0)
	v_mfma_f32_16x16x32_bf16 v[10:13], v[58:61], v[210:213], v[10:13]
	v_mfma_f32_16x16x32_bf16 v[10:13], v[62:65], v[214:217], v[10:13]
	s_setprio 0
	s_setprio 1
	v_mfma_f32_16x16x32_bf16 v[38:41], v[146:149], v[194:197], v[38:41]
	v_mfma_f32_16x16x32_bf16 v[38:41], v[150:153], v[198:201], v[38:41]
	v_mfma_f32_16x16x32_bf16 v[34:37], v[154:157], v[194:197], v[34:37]
	v_mfma_f32_16x16x32_bf16 v[34:37], v[158:161], v[198:201], v[34:37]
	v_mfma_f32_16x16x32_bf16 v[22:25], v[146:149], v[202:205], v[22:25]
	v_mfma_f32_16x16x32_bf16 v[22:25], v[150:153], v[206:209], v[22:25]
	v_mfma_f32_16x16x32_bf16 v[18:21], v[154:157], v[202:205], v[18:21]
	v_mfma_f32_16x16x32_bf16 v[18:21], v[158:161], v[206:209], v[18:21]
	v_mfma_f32_16x16x32_bf16 v[6:9], v[146:149], v[210:213], v[6:9]
	v_mfma_f32_16x16x32_bf16 v[6:9], v[150:153], v[214:217], v[6:9]
	v_mfma_f32_16x16x32_bf16 v[2:5], v[154:157], v[210:213], v[2:5]
	v_mfma_f32_16x16x32_bf16 v[2:5], v[158:161], v[214:217], v[2:5]
	v_mfma_f32_16x16x32_bf16 v[46:49], v[146:149], v[172:175], v[70:73]
	v_mfma_f32_16x16x32_bf16 v[46:49], v[150:153], v[190:193], v[46:49]
	s_setprio 2
	s_barrier
	v_mfma_f32_16x16x32_bf16 v[54:57], v[154:157], v[172:175], v[66:69]
	v_mfma_f32_16x16x32_bf16 v[54:57], v[158:161], v[190:193], v[54:57]
	s_setprio 0
	ds_read_b128 v[58:61], v185
	ds_read_b128 v[62:65], v185 offset:1024
	ds_read_b128 v[66:69], v185 offset:2048
	ds_read_b128 v[70:73], v185 offset:3072
	ds_read_b128 v[146:149], v186
	ds_read_b128 v[150:153], v186 offset:1024
	ds_read_b128 v[154:157], v186 offset:2048
	ds_read_b128 v[158:161], v186 offset:3072
	ds_read_b128 v[172:175], v184 offset:32768
	ds_read_b128 v[190:193], v184 offset:33792
	ds_read_b128 v[194:197], v184 offset:34816
	ds_read_b128 v[198:201], v184 offset:35840
	ds_read_b128 v[202:205], v184 offset:36864
	ds_read_b128 v[206:209], v184 offset:37888
	ds_read_b128 v[210:213], v184 offset:38912
	ds_read_b128 v[214:217], v184 offset:39936
	s_mov_b32 s86, m0
	s_mov_b32 m0, s48
	s_nop 0
	global_load_lds_dwordx4 v176, s[36:37]
	s_mov_b32 m0, s86
	s_nop 0
	s_mov_b32 s86, m0
	s_mov_b32 m0, s59
	s_nop 0
	global_load_lds_dwordx4 v178, s[36:37]
	s_mov_b32 m0, s86
	s_add_u32 s36, s36, 0x80000
	s_addc_u32 s37, s37, 0
	s_mov_b32 s86, m0
	s_mov_b32 m0, s62
	s_nop 0
	global_load_lds_dwordx4 v176, s[36:37]
	s_mov_b32 m0, s86
	s_nop 0
	s_mov_b32 s86, m0
	s_mov_b32 m0, s63
	s_nop 0
	global_load_lds_dwordx4 v178, s[36:37]
	s_mov_b32 m0, s86
	s_waitcnt vmcnt(8)
	s_waitcnt lgkmcnt(0)
	s_barrier
	s_setprio 1
	s_waitcnt lgkmcnt(7)
	v_mfma_f32_16x16x32_bf16 v[142:145], v[58:61], v[172:175], v[142:145]
	v_mfma_f32_16x16x32_bf16 v[142:145], v[62:65], v[190:193], v[142:145]
	s_waitcnt lgkmcnt(5)
	v_mfma_f32_16x16x32_bf16 v[138:141], v[66:69], v[172:175], v[138:141]
	v_mfma_f32_16x16x32_bf16 v[138:141], v[70:73], v[190:193], v[138:141]
	s_waitcnt lgkmcnt(3)
	v_mfma_f32_16x16x32_bf16 v[126:129], v[58:61], v[194:197], v[126:129]
	v_mfma_f32_16x16x32_bf16 v[126:129], v[62:65], v[198:201], v[126:129]
	s_waitcnt lgkmcnt(1)
	v_mfma_f32_16x16x32_bf16 v[122:125], v[66:69], v[194:197], v[122:125]
	v_mfma_f32_16x16x32_bf16 v[122:125], v[70:73], v[198:201], v[122:125]
	v_mfma_f32_16x16x32_bf16 v[110:113], v[58:61], v[202:205], v[110:113]
	v_mfma_f32_16x16x32_bf16 v[110:113], v[62:65], v[206:209], v[110:113]
	v_mfma_f32_16x16x32_bf16 v[106:109], v[66:69], v[202:205], v[106:109]
	v_mfma_f32_16x16x32_bf16 v[106:109], v[70:73], v[206:209], v[106:109]
	v_mfma_f32_16x16x32_bf16 v[94:97], v[58:61], v[210:213], v[94:97]
	v_mfma_f32_16x16x32_bf16 v[94:97], v[62:65], v[214:217], v[94:97]
	s_waitcnt lgkmcnt(0)
	v_mfma_f32_16x16x32_bf16 v[90:93], v[66:69], v[210:213], v[90:93]
	v_mfma_f32_16x16x32_bf16 v[90:93], v[70:73], v[214:217], v[90:93]
	s_setprio 0
	s_setprio 1
	v_mfma_f32_16x16x32_bf16 v[134:137], v[146:149], v[172:175], v[134:137]
	v_mfma_f32_16x16x32_bf16 v[134:137], v[150:153], v[190:193], v[134:137]
	v_mfma_f32_16x16x32_bf16 v[130:133], v[154:157], v[172:175], v[130:133]
	v_mfma_f32_16x16x32_bf16 v[130:133], v[158:161], v[190:193], v[130:133]
	v_mfma_f32_16x16x32_bf16 v[118:121], v[146:149], v[194:197], v[118:121]
	v_mfma_f32_16x16x32_bf16 v[118:121], v[150:153], v[198:201], v[118:121]
	v_mfma_f32_16x16x32_bf16 v[114:117], v[154:157], v[194:197], v[114:117]
	v_mfma_f32_16x16x32_bf16 v[114:117], v[158:161], v[198:201], v[114:117]
	v_mfma_f32_16x16x32_bf16 v[102:105], v[146:149], v[202:205], v[102:105]
	v_mfma_f32_16x16x32_bf16 v[102:105], v[150:153], v[206:209], v[102:105]
	v_mfma_f32_16x16x32_bf16 v[98:101], v[154:157], v[202:205], v[98:101]
	v_mfma_f32_16x16x32_bf16 v[98:101], v[158:161], v[206:209], v[98:101]
	v_mfma_f32_16x16x32_bf16 v[86:89], v[146:149], v[210:213], v[86:89]
	v_mfma_f32_16x16x32_bf16 v[86:89], v[150:153], v[214:217], v[86:89]
	s_setprio 2
	s_barrier
	v_mfma_f32_16x16x32_bf16 v[82:85], v[154:157], v[210:213], v[82:85]
	v_mfma_f32_16x16x32_bf16 v[82:85], v[158:161], v[214:217], v[82:85]
	s_setprio 0
	ds_read_b128 v[172:175], v184 offset:49152
	ds_read_b128 v[190:193], v184 offset:50176
	ds_read_b128 v[194:197], v184 offset:51200
	ds_read_b128 v[198:201], v184 offset:52224
	ds_read_b128 v[202:205], v184 offset:53248
	ds_read_b128 v[206:209], v184 offset:54272
	ds_read_b128 v[210:213], v184 offset:55296
	ds_read_b128 v[214:217], v184 offset:56320
	s_add_u32 s36, s34, 0x80
	s_addc_u32 s37, s35, 0
	s_mov_b32 s86, m0
	s_mov_b32 m0, s64
	s_nop 0
	global_load_lds_dwordx4 v177, s[36:37]
	s_mov_b32 m0, s86
	s_add_u32 s34, s34, 0x80080
	s_mov_b32 s86, m0
	s_mov_b32 m0, s65
	s_nop 0
	global_load_lds_dwordx4 v179, s[36:37]
	s_mov_b32 m0, s86
	s_addc_u32 s35, s35, 0
	s_mov_b32 s36, m0
	s_mov_b32 m0, s66
	s_nop 0
	global_load_lds_dwordx4 v177, s[34:35]
	s_mov_b32 m0, s36
	s_nop 0
	s_mov_b32 s36, m0
	s_mov_b32 m0, s67
	s_nop 0
	global_load_lds_dwordx4 v179, s[34:35]
	s_mov_b32 m0, s36
	s_waitcnt vmcnt(4)
	s_waitcnt lgkmcnt(0)
	s_barrier
	s_setprio 1
	s_waitcnt lgkmcnt(7)
	v_mfma_f32_16x16x32_bf16 v[78:81], v[58:61], v[172:175], v[78:81]
	v_mfma_f32_16x16x32_bf16 v[78:81], v[62:65], v[190:193], v[78:81]
	s_waitcnt lgkmcnt(5)
	v_mfma_f32_16x16x32_bf16 v[74:77], v[66:69], v[172:175], v[74:77]
	v_mfma_f32_16x16x32_bf16 v[74:77], v[70:73], v[190:193], v[74:77]
	s_waitcnt lgkmcnt(3)
	v_mfma_f32_16x16x32_bf16 v[50:53], v[58:61], v[194:197], v[50:53]
	v_mfma_f32_16x16x32_bf16 v[50:53], v[62:65], v[198:201], v[50:53]
	s_waitcnt lgkmcnt(1)
	v_mfma_f32_16x16x32_bf16 v[42:45], v[66:69], v[194:197], v[42:45]
	v_mfma_f32_16x16x32_bf16 v[42:45], v[70:73], v[198:201], v[42:45]
	v_mfma_f32_16x16x32_bf16 v[30:33], v[58:61], v[202:205], v[30:33]
	v_mfma_f32_16x16x32_bf16 v[30:33], v[62:65], v[206:209], v[30:33]
	v_mfma_f32_16x16x32_bf16 v[26:29], v[66:69], v[202:205], v[26:29]
	v_mfma_f32_16x16x32_bf16 v[26:29], v[70:73], v[206:209], v[26:29]
	v_mfma_f32_16x16x32_bf16 v[14:17], v[58:61], v[210:213], v[14:17]
	v_mfma_f32_16x16x32_bf16 v[14:17], v[62:65], v[214:217], v[14:17]
	s_waitcnt lgkmcnt(0)
	v_mfma_f32_16x16x32_bf16 v[10:13], v[66:69], v[210:213], v[10:13]
	v_mfma_f32_16x16x32_bf16 v[10:13], v[70:73], v[214:217], v[10:13]
	s_setprio 0
	s_setprio 1
	v_mfma_f32_16x16x32_bf16 v[46:49], v[146:149], v[172:175], v[46:49]
	v_mfma_f32_16x16x32_bf16 v[70:73], v[150:153], v[190:193], v[46:49]
	v_mfma_f32_16x16x32_bf16 v[46:49], v[154:157], v[172:175], v[54:57]
	v_mfma_f32_16x16x32_bf16 v[66:69], v[158:161], v[190:193], v[46:49]
	v_mfma_f32_16x16x32_bf16 v[38:41], v[146:149], v[194:197], v[38:41]
	v_mfma_f32_16x16x32_bf16 v[38:41], v[150:153], v[198:201], v[38:41]
	v_mfma_f32_16x16x32_bf16 v[34:37], v[154:157], v[194:197], v[34:37]
	v_mfma_f32_16x16x32_bf16 v[34:37], v[158:161], v[198:201], v[34:37]
	v_mfma_f32_16x16x32_bf16 v[22:25], v[146:149], v[202:205], v[22:25]
	v_mfma_f32_16x16x32_bf16 v[22:25], v[150:153], v[206:209], v[22:25]
	v_mfma_f32_16x16x32_bf16 v[18:21], v[154:157], v[202:205], v[18:21]
	v_mfma_f32_16x16x32_bf16 v[18:21], v[158:161], v[206:209], v[18:21]
	v_mfma_f32_16x16x32_bf16 v[6:9], v[146:149], v[210:213], v[6:9]
	v_mfma_f32_16x16x32_bf16 v[6:9], v[150:153], v[214:217], v[6:9]
	s_setprio 2
	s_barrier
	v_mfma_f32_16x16x32_bf16 v[2:5], v[154:157], v[210:213], v[2:5]
	v_mfma_f32_16x16x32_bf16 v[2:5], v[158:161], v[214:217], v[2:5]
	s_setprio 0
	s_add_i32 s83, s83, 2
	s_add_u32 s79, s79, 0x100
	s_addc_u32 s80, s80, 0
	s_add_u32 s30, s30, 0x100
	s_addc_u32 s31, s31, 0
	s_add_u32 s81, s81, 0x100
	s_addc_u32 s82, s82, 0
	s_cmp_gt_u32 s83, 29
	s_cbranch_scc0 .LBB0_1538
	v_mov_b32_e32 v174, v252
	v_mov_b32_e32 v175, v253
	v_mov_b32_e32 v216, v254
	v_mov_b32_e32 v217, v255
	s_and_b64 vcc, exec, s[16:17]
	s_cbranch_vccz .LBB0_1541
	s_barrier

.LBB0_1951:
	s_ashr_i32 s13, s12, 31
	s_lshl_b64 s[14:15], s[12:13], 15
	s_add_u32 s14, s28, s14
	s_addc_u32 s15, s29, s15
	s_and_b64 s[16:17], s[2:3], exec
	s_cselect_b32 s13, s15, s23
	s_cselect_b32 s65, s14, s22
	s_ashr_i32 s11, s10, 31
	s_lshl_b64 s[16:17], s[10:11], 15
	s_add_u32 s16, s30, s16
	s_addc_u32 s17, s31, s17
	s_and_b64 s[24:25], s[2:3], exec
	s_cselect_b32 s11, s17, s21
	s_cselect_b32 s66, s16, s20
	s_add_u32 s67, s20, 0x80000
	s_addc_u32 s70, s21, 0
	s_add_u32 s20, s22, 0x204000
	s_addc_u32 s21, s23, 0
	s_add_u32 s71, s22, 0x400000
	s_addc_u32 s73, s23, 0
	s_mov_b32 s74, -2
	s_waitcnt vmcnt(25)
	s_waitcnt vmcnt(24)
	s_waitcnt vmcnt(4)
	s_waitcnt vmcnt(2)
	s_waitcnt vmcnt(1)
	s_waitcnt vmcnt(0)
	v_mov_b32_e32 v252, v174
	v_mov_b32_e32 v253, v175
	v_mov_b32_e32 v254, v210
	v_mov_b32_e32 v255, v211
	ds_read_b128 v[130:133], v181
	ds_read_b128 v[134:137], v181 offset:1024
	ds_read_b128 v[138:141], v181 offset:2048
	ds_read_b128 v[142:145], v181 offset:3072
	ds_read_b128 v[150:153], v182
	ds_read_b128 v[154:157], v182 offset:1024
	ds_read_b128 v[158:161], v182 offset:2048
	ds_read_b128 v[162:165], v182 offset:3072
	s_cmpk_eq_i32 s74, 0x52
	s_cselect_b32 s23, s11, s70
	s_cselect_b32 s22, s66, s67
	s_cselect_b32 s25, s13, s73
	s_cselect_b32 s24, s65, s71
	ds_read_b128 v[168:171], v183
	ds_read_b128 v[172:175], v183 offset:1024
	ds_read_b128 v[188:191], v183 offset:2048
	ds_read_b128 v[192:195], v183 offset:3072
	ds_read_b128 v[196:199], v183 offset:4096
	ds_read_b128 v[200:203], v183 offset:5120
	ds_read_b128 v[204:207], v183 offset:6144
	ds_read_b128 v[208:211], v183 offset:7168
	s_add_u32 s76, s20, 0xffffc000
	s_addc_u32 s77, s21, -1
	s_mov_b32 s75, m0
	s_mov_b32 m0, s58
	s_nop 0
	global_load_lds_dwordx4 v1, s[76:77]
	s_mov_b32 m0, s75
	s_nop 0
	s_mov_b32 s75, m0
	s_mov_b32 m0, s62
	s_nop 0
	global_load_lds_dwordx4 v177, s[76:77]
	s_mov_b32 m0, s75
	s_nop 0
	s_mov_b32 s75, m0
	s_mov_b32 m0, s59
	s_nop 0
	global_load_lds_dwordx4 v1, s[20:21]
	s_mov_b32 m0, s75
	s_nop 0
	s_mov_b32 s75, m0
	s_mov_b32 m0, s63
	s_nop 0
	global_load_lds_dwordx4 v177, s[20:21]
	s_mov_b32 m0, s75
	s_waitcnt vmcnt(8)
	s_waitcnt lgkmcnt(0)
	s_barrier
	s_setprio 1
	s_waitcnt lgkmcnt(7)
	v_mfma_f32_16x16x32_bf16 v[126:129], v[130:133], v[168:171], 0
	v_mfma_f32_16x16x32_bf16 v[126:129], v[134:137], v[172:175], v[126:129]
	s_waitcnt lgkmcnt(5)
	v_mfma_f32_16x16x32_bf16 v[122:125], v[138:141], v[168:171], 0
	v_mfma_f32_16x16x32_bf16 v[122:125], v[142:145], v[172:175], v[122:125]
	s_waitcnt lgkmcnt(3)
	v_mfma_f32_16x16x32_bf16 v[110:113], v[138:141], v[188:191], 0
	v_mfma_f32_16x16x32_bf16 v[110:113], v[142:145], v[192:195], v[110:113]
	s_waitcnt lgkmcnt(1)
	v_mfma_f32_16x16x32_bf16 v[118:121], v[130:133], v[188:191], 0
	v_mfma_f32_16x16x32_bf16 v[118:121], v[134:137], v[192:195], v[118:121]
	v_mfma_f32_16x16x32_bf16 v[94:97], v[130:133], v[196:199], 0
	v_mfma_f32_16x16x32_bf16 v[94:97], v[134:137], v[200:203], v[94:97]
	v_mfma_f32_16x16x32_bf16 v[90:93], v[138:141], v[196:199], 0
	v_mfma_f32_16x16x32_bf16 v[90:93], v[142:145], v[200:203], v[90:93]
	v_mfma_f32_16x16x32_bf16 v[78:81], v[138:141], v[204:207], 0
	v_mfma_f32_16x16x32_bf16 v[78:81], v[142:145], v[208:211], v[78:81]
	s_waitcnt lgkmcnt(0)
	v_mfma_f32_16x16x32_bf16 v[86:89], v[130:133], v[204:207], 0
	v_mfma_f32_16x16x32_bf16 v[86:89], v[134:137], v[208:211], v[86:89]
	s_setprio 0
	s_setprio 1
	v_mfma_f32_16x16x32_bf16 v[114:117], v[150:153], v[168:171], 0
	v_mfma_f32_16x16x32_bf16 v[114:117], v[154:157], v[172:175], v[114:117]
	v_mfma_f32_16x16x32_bf16 v[106:109], v[158:161], v[168:171], 0
	v_mfma_f32_16x16x32_bf16 v[106:109], v[162:165], v[172:175], v[106:109]
	v_mfma_f32_16x16x32_bf16 v[98:101], v[158:161], v[188:191], 0
	v_mfma_f32_16x16x32_bf16 v[98:101], v[162:165], v[192:195], v[98:101]
	v_mfma_f32_16x16x32_bf16 v[102:105], v[150:153], v[188:191], 0
	v_mfma_f32_16x16x32_bf16 v[102:105], v[154:157], v[192:195], v[102:105]
	v_mfma_f32_16x16x32_bf16 v[82:85], v[150:153], v[196:199], 0
	v_mfma_f32_16x16x32_bf16 v[82:85], v[154:157], v[200:203], v[82:85]
	v_mfma_f32_16x16x32_bf16 v[74:77], v[158:161], v[196:199], 0
	v_mfma_f32_16x16x32_bf16 v[74:77], v[162:165], v[200:203], v[74:77]
	v_mfma_f32_16x16x32_bf16 v[66:69], v[158:161], v[204:207], 0
	v_mfma_f32_16x16x32_bf16 v[66:69], v[162:165], v[208:211], v[66:69]
	s_setprio 2
	s_barrier
	v_mfma_f32_16x16x32_bf16 v[70:73], v[150:153], v[204:207], 0
	v_mfma_f32_16x16x32_bf16 v[70:73], v[154:157], v[208:211], v[70:73]
	s_setprio 0
	ds_read_b128 v[168:171], v183 offset:16384
	ds_read_b128 v[172:175], v183 offset:17408
	ds_read_b128 v[188:191], v183 offset:18432
	ds_read_b128 v[192:195], v183 offset:19456
	ds_read_b128 v[196:199], v183 offset:20480
	ds_read_b128 v[200:203], v183 offset:21504
	ds_read_b128 v[204:207], v183 offset:22528
	ds_read_b128 v[208:211], v183 offset:23552
	s_mov_b32 s75, m0
	s_mov_b32 m0, s35
	s_nop 0
	global_load_lds_dwordx4 v176, s[22:23]
	s_mov_b32 m0, s75
	s_add_u32 s76, s22, 0x4000
	s_mov_b32 s75, m0
	s_mov_b32 m0, s36
	s_nop 0
	global_load_lds_dwordx4 v178, s[22:23]
	s_mov_b32 m0, s75
	s_addc_u32 s77, s23, 0
	s_mov_b32 s75, m0
	s_mov_b32 m0, s37
	s_nop 0
	global_load_lds_dwordx4 v176, s[76:77]
	s_mov_b32 m0, s75
	s_nop 0
	s_mov_b32 s75, m0
	s_mov_b32 m0, s40
	s_nop 0
	global_load_lds_dwordx4 v178, s[76:77]
	s_mov_b32 m0, s75
	s_waitcnt vmcnt(4)
	s_waitcnt lgkmcnt(0)
	s_barrier
	s_setprio 1
	s_waitcnt lgkmcnt(7)
	v_mfma_f32_16x16x32_bf16 v[62:65], v[130:133], v[168:171], 0
	v_mfma_f32_16x16x32_bf16 v[62:65], v[134:137], v[172:175], v[62:65]
	s_waitcnt lgkmcnt(5)
	v_mfma_f32_16x16x32_bf16 v[58:61], v[138:141], v[168:171], 0
	v_mfma_f32_16x16x32_bf16 v[58:61], v[142:145], v[172:175], v[58:61]
	s_waitcnt lgkmcnt(3)
	v_mfma_f32_16x16x32_bf16 v[42:45], v[138:141], v[188:191], 0
	v_mfma_f32_16x16x32_bf16 v[42:45], v[142:145], v[192:195], v[42:45]
	s_waitcnt lgkmcnt(1)
	v_mfma_f32_16x16x32_bf16 v[46:49], v[130:133], v[188:191], 0
	v_mfma_f32_16x16x32_bf16 v[46:49], v[134:137], v[192:195], v[46:49]
	v_mfma_f32_16x16x32_bf16 v[30:33], v[130:133], v[196:199], 0
	v_mfma_f32_16x16x32_bf16 v[30:33], v[134:137], v[200:203], v[30:33]
	v_mfma_f32_16x16x32_bf16 v[26:29], v[138:141], v[196:199], 0
	v_mfma_f32_16x16x32_bf16 v[26:29], v[142:145], v[200:203], v[26:29]
	v_mfma_f32_16x16x32_bf16 v[10:13], v[138:141], v[204:207], 0
	v_mfma_f32_16x16x32_bf16 v[10:13], v[142:145], v[208:211], v[10:13]
	s_waitcnt lgkmcnt(0)
	v_mfma_f32_16x16x32_bf16 v[14:17], v[130:133], v[204:207], 0
	v_mfma_f32_16x16x32_bf16 v[14:17], v[134:137], v[208:211], v[14:17]
	s_setprio 0
	s_setprio 1
	v_mfma_f32_16x16x32_bf16 v[54:57], v[150:153], v[168:171], 0
	v_mfma_f32_16x16x32_bf16 v[54:57], v[154:157], v[172:175], v[54:57]
	v_mfma_f32_16x16x32_bf16 v[50:53], v[158:161], v[168:171], 0
	v_mfma_f32_16x16x32_bf16 v[50:53], v[162:165], v[172:175], v[50:53]
	v_mfma_f32_16x16x32_bf16 v[34:37], v[158:161], v[188:191], 0
	v_mfma_f32_16x16x32_bf16 v[34:37], v[162:165], v[192:195], v[34:37]
	v_mfma_f32_16x16x32_bf16 v[38:41], v[150:153], v[188:191], 0
	v_mfma_f32_16x16x32_bf16 v[38:41], v[154:157], v[192:195], v[38:41]
	v_mfma_f32_16x16x32_bf16 v[22:25], v[150:153], v[196:199], 0
	v_mfma_f32_16x16x32_bf16 v[22:25], v[154:157], v[200:203], v[22:25]
	v_mfma_f32_16x16x32_bf16 v[18:21], v[158:161], v[196:199], 0
	v_mfma_f32_16x16x32_bf16 v[18:21], v[162:165], v[200:203], v[18:21]
	v_mfma_f32_16x16x32_bf16 v[2:5], v[158:161], v[204:207], 0
	v_mfma_f32_16x16x32_bf16 v[2:5], v[162:165], v[208:211], v[2:5]
	s_setprio 2
	s_barrier
	v_mfma_f32_16x16x32_bf16 v[6:9], v[150:153], v[204:207], 0
	v_mfma_f32_16x16x32_bf16 v[6:9], v[154:157], v[208:211], v[6:9]
	s_setprio 0
	ds_read_b128 v[130:133], v184
	ds_read_b128 v[134:137], v184 offset:1024
	ds_read_b128 v[138:141], v184 offset:2048
	ds_read_b128 v[142:145], v184 offset:3072
	ds_read_b128 v[150:153], v185
	ds_read_b128 v[154:157], v185 offset:1024
	ds_read_b128 v[158:161], v185 offset:2048
	ds_read_b128 v[162:165], v185 offset:3072
	ds_read_b128 v[168:171], v183 offset:32768
	ds_read_b128 v[172:175], v183 offset:33792
	ds_read_b128 v[188:191], v183 offset:34816
	ds_read_b128 v[192:195], v183 offset:35840
	ds_read_b128 v[196:199], v183 offset:36864
	ds_read_b128 v[200:203], v183 offset:37888
	ds_read_b128 v[204:207], v183 offset:38912
	ds_read_b128 v[208:211], v183 offset:39936
	s_mov_b32 s75, m0
	s_mov_b32 m0, s34
	s_nop 0
	global_load_lds_dwordx4 v1, s[24:25]
	s_mov_b32 m0, s75
	s_nop 0
	s_mov_b32 s75, m0
	s_mov_b32 m0, s41
	s_nop 0
	global_load_lds_dwordx4 v177, s[24:25]
	s_mov_b32 m0, s75
	s_add_u32 s24, s24, 0x4000
	s_addc_u32 s25, s25, 0
	s_mov_b32 s75, m0
	s_mov_b32 m0, s42
	s_nop 0
	global_load_lds_dwordx4 v1, s[24:25]
	s_mov_b32 m0, s75
	s_nop 0
	s_mov_b32 s75, m0
	s_mov_b32 m0, s43
	s_nop 0
	global_load_lds_dwordx4 v177, s[24:25]
	s_mov_b32 m0, s75
	s_waitcnt vmcnt(8)
	s_waitcnt lgkmcnt(0)
	s_barrier
	s_setprio 1
	s_waitcnt lgkmcnt(7)
	v_mfma_f32_16x16x32_bf16 v[126:129], v[130:133], v[168:171], v[126:129]
	v_mfma_f32_16x16x32_bf16 v[126:129], v[134:137], v[172:175], v[126:129]
	s_waitcnt lgkmcnt(5)
	v_mfma_f32_16x16x32_bf16 v[122:125], v[138:141], v[168:171], v[122:125]
	v_mfma_f32_16x16x32_bf16 v[122:125], v[142:145], v[172:175], v[122:125]
	s_waitcnt lgkmcnt(3)
	v_mfma_f32_16x16x32_bf16 v[110:113], v[138:141], v[188:191], v[110:113]
	v_mfma_f32_16x16x32_bf16 v[110:113], v[142:145], v[192:195], v[110:113]
	s_waitcnt lgkmcnt(1)
	v_mfma_f32_16x16x32_bf16 v[118:121], v[130:133], v[188:191], v[118:121]
	v_mfma_f32_16x16x32_bf16 v[118:121], v[134:137], v[192:195], v[118:121]
	v_mfma_f32_16x16x32_bf16 v[94:97], v[130:133], v[196:199], v[94:97]
	v_mfma_f32_16x16x32_bf16 v[94:97], v[134:137], v[200:203], v[94:97]
	v_mfma_f32_16x16x32_bf16 v[90:93], v[138:141], v[196:199], v[90:93]
	v_mfma_f32_16x16x32_bf16 v[90:93], v[142:145], v[200:203], v[90:93]
	v_mfma_f32_16x16x32_bf16 v[78:81], v[138:141], v[204:207], v[78:81]
	v_mfma_f32_16x16x32_bf16 v[78:81], v[142:145], v[208:211], v[78:81]
	s_waitcnt lgkmcnt(0)
	v_mfma_f32_16x16x32_bf16 v[86:89], v[130:133], v[204:207], v[86:89]
	v_mfma_f32_16x16x32_bf16 v[86:89], v[134:137], v[208:211], v[86:89]
	s_setprio 0
	s_setprio 1
	v_mfma_f32_16x16x32_bf16 v[114:117], v[150:153], v[168:171], v[114:117]
	v_mfma_f32_16x16x32_bf16 v[114:117], v[154:157], v[172:175], v[114:117]
	v_mfma_f32_16x16x32_bf16 v[106:109], v[158:161], v[168:171], v[106:109]
	v_mfma_f32_16x16x32_bf16 v[106:109], v[162:165], v[172:175], v[106:109]
	v_mfma_f32_16x16x32_bf16 v[98:101], v[158:161], v[188:191], v[98:101]
	v_mfma_f32_16x16x32_bf16 v[98:101], v[162:165], v[192:195], v[98:101]
	v_mfma_f32_16x16x32_bf16 v[102:105], v[150:153], v[188:191], v[102:105]
	v_mfma_f32_16x16x32_bf16 v[102:105], v[154:157], v[192:195], v[102:105]
	v_mfma_f32_16x16x32_bf16 v[82:85], v[150:153], v[196:199], v[82:85]
	v_mfma_f32_16x16x32_bf16 v[82:85], v[154:157], v[200:203], v[82:85]
	v_mfma_f32_16x16x32_bf16 v[74:77], v[158:161], v[196:199], v[74:77]
	v_mfma_f32_16x16x32_bf16 v[74:77], v[162:165], v[200:203], v[74:77]
	v_mfma_f32_16x16x32_bf16 v[66:69], v[158:161], v[204:207], v[66:69]
	v_mfma_f32_16x16x32_bf16 v[66:69], v[162:165], v[208:211], v[66:69]
	s_setprio 2
	s_barrier
	v_mfma_f32_16x16x32_bf16 v[70:73], v[150:153], v[204:207], v[70:73]
	v_mfma_f32_16x16x32_bf16 v[70:73], v[154:157], v[208:211], v[70:73]
	s_setprio 0
	ds_read_b128 v[168:171], v183 offset:49152
	ds_read_b128 v[172:175], v183 offset:50176
	ds_read_b128 v[188:191], v183 offset:51200
	ds_read_b128 v[192:195], v183 offset:52224
	ds_read_b128 v[196:199], v183 offset:53248
	ds_read_b128 v[200:203], v183 offset:54272
	ds_read_b128 v[204:207], v183 offset:55296
	ds_read_b128 v[208:211], v183 offset:56320
	s_add_u32 s24, s22, 0x40000
	s_addc_u32 s25, s23, 0
	s_mov_b32 s75, m0
	s_mov_b32 m0, s46
	s_nop 0
	global_load_lds_dwordx4 v176, s[24:25]
	s_mov_b32 m0, s75
	s_add_u32 s22, s22, 0x44000
	s_mov_b32 s75, m0
	s_mov_b32 m0, s47
	s_nop 0
	global_load_lds_dwordx4 v178, s[24:25]
	s_mov_b32 m0, s75
	s_addc_u32 s23, s23, 0
	s_mov_b32 s24, m0
	s_mov_b32 m0, s48
	s_nop 0
	global_load_lds_dwordx4 v176, s[22:23]
	s_mov_b32 m0, s24
	s_nop 0
	s_mov_b32 s24, m0
	s_mov_b32 m0, s49
	s_nop 0
	global_load_lds_dwordx4 v178, s[22:23]
	s_mov_b32 m0, s24
	s_waitcnt vmcnt(4)
	s_waitcnt lgkmcnt(0)
	s_barrier
	s_setprio 1
	s_waitcnt lgkmcnt(7)
	v_mfma_f32_16x16x32_bf16 v[62:65], v[130:133], v[168:171], v[62:65]
	v_mfma_f32_16x16x32_bf16 v[62:65], v[134:137], v[172:175], v[62:65]
	s_waitcnt lgkmcnt(5)
	v_mfma_f32_16x16x32_bf16 v[58:61], v[138:141], v[168:171], v[58:61]
	v_mfma_f32_16x16x32_bf16 v[58:61], v[142:145], v[172:175], v[58:61]
	s_waitcnt lgkmcnt(3)
	v_mfma_f32_16x16x32_bf16 v[42:45], v[138:141], v[188:191], v[42:45]
	v_mfma_f32_16x16x32_bf16 v[42:45], v[142:145], v[192:195], v[42:45]
	s_waitcnt lgkmcnt(1)
	v_mfma_f32_16x16x32_bf16 v[46:49], v[130:133], v[188:191], v[46:49]
	v_mfma_f32_16x16x32_bf16 v[46:49], v[134:137], v[192:195], v[46:49]
	v_mfma_f32_16x16x32_bf16 v[30:33], v[130:133], v[196:199], v[30:33]
	v_mfma_f32_16x16x32_bf16 v[30:33], v[134:137], v[200:203], v[30:33]
	v_mfma_f32_16x16x32_bf16 v[26:29], v[138:141], v[196:199], v[26:29]
	v_mfma_f32_16x16x32_bf16 v[26:29], v[142:145], v[200:203], v[26:29]
	v_mfma_f32_16x16x32_bf16 v[10:13], v[138:141], v[204:207], v[10:13]
	v_mfma_f32_16x16x32_bf16 v[10:13], v[142:145], v[208:211], v[10:13]
	s_waitcnt lgkmcnt(0)
	v_mfma_f32_16x16x32_bf16 v[14:17], v[130:133], v[204:207], v[14:17]
	v_mfma_f32_16x16x32_bf16 v[14:17], v[134:137], v[208:211], v[14:17]
	s_setprio 0
	s_setprio 1
	v_mfma_f32_16x16x32_bf16 v[54:57], v[150:153], v[168:171], v[54:57]
	v_mfma_f32_16x16x32_bf16 v[54:57], v[154:157], v[172:175], v[54:57]
	v_mfma_f32_16x16x32_bf16 v[50:53], v[158:161], v[168:171], v[50:53]
	v_mfma_f32_16x16x32_bf16 v[50:53], v[162:165], v[172:175], v[50:53]
	v_mfma_f32_16x16x32_bf16 v[34:37], v[158:161], v[188:191], v[34:37]
	v_mfma_f32_16x16x32_bf16 v[34:37], v[162:165], v[192:195], v[34:37]
	v_mfma_f32_16x16x32_bf16 v[38:41], v[150:153], v[188:191], v[38:41]
	v_mfma_f32_16x16x32_bf16 v[38:41], v[154:157], v[192:195], v[38:41]
	v_mfma_f32_16x16x32_bf16 v[22:25], v[150:153], v[196:199], v[22:25]
	v_mfma_f32_16x16x32_bf16 v[22:25], v[154:157], v[200:203], v[22:25]
	v_mfma_f32_16x16x32_bf16 v[18:21], v[158:161], v[196:199], v[18:21]
	v_mfma_f32_16x16x32_bf16 v[18:21], v[162:165], v[200:203], v[18:21]
	v_mfma_f32_16x16x32_bf16 v[2:5], v[158:161], v[204:207], v[2:5]
	v_mfma_f32_16x16x32_bf16 v[2:5], v[162:165], v[208:211], v[2:5]
	s_setprio 2
	s_barrier
	v_mfma_f32_16x16x32_bf16 v[6:9], v[150:153], v[204:207], v[6:9]
	v_mfma_f32_16x16x32_bf16 v[6:9], v[154:157], v[208:211], v[6:9]
	s_setprio 0
	s_add_i32 s74, s74, 2
	s_add_u32 s67, s67, 0x80000
	s_addc_u32 s70, s70, 0
	s_add_u32 s20, s20, 0x400000
	s_addc_u32 s21, s21, 0
	s_add_u32 s71, s71, 0x400000
	s_addc_u32 s73, s73, 0
	s_cmpk_gt_u32 s74, 0x53
	.p2align 6
.LBB0_1952:
	ds_read_b128 v[130:133], v181
	ds_read_b128 v[134:137], v181 offset:1024
	ds_read_b128 v[138:141], v181 offset:2048
	ds_read_b128 v[142:145], v181 offset:3072
	ds_read_b128 v[150:153], v182
	ds_read_b128 v[154:157], v182 offset:1024
	ds_read_b128 v[158:161], v182 offset:2048
	ds_read_b128 v[162:165], v182 offset:3072
	s_cmpk_eq_i32 s74, 0x52
	s_cselect_b32 s23, s11, s70
	s_cselect_b32 s22, s66, s67
	s_cselect_b32 s25, s13, s73
	s_cselect_b32 s24, s65, s71
	ds_read_b128 v[168:171], v183
	ds_read_b128 v[172:175], v183 offset:1024
	ds_read_b128 v[188:191], v183 offset:2048
	ds_read_b128 v[192:195], v183 offset:3072
	ds_read_b128 v[196:199], v183 offset:4096
	ds_read_b128 v[200:203], v183 offset:5120
	ds_read_b128 v[204:207], v183 offset:6144
	ds_read_b128 v[208:211], v183 offset:7168
	s_add_u32 s76, s20, 0xffffc000
	s_addc_u32 s77, s21, -1
	s_mov_b32 s75, m0
	s_mov_b32 m0, s58
	s_nop 0
	global_load_lds_dwordx4 v1, s[76:77]
	s_mov_b32 m0, s75
	s_nop 0
	s_mov_b32 s75, m0
	s_mov_b32 m0, s62
	s_nop 0
	global_load_lds_dwordx4 v177, s[76:77]
	s_mov_b32 m0, s75
	s_nop 0
	s_mov_b32 s75, m0
	s_mov_b32 m0, s59
	s_nop 0
	global_load_lds_dwordx4 v1, s[20:21]
	s_mov_b32 m0, s75
	s_nop 0
	s_mov_b32 s75, m0
	s_mov_b32 m0, s63
	s_nop 0
	global_load_lds_dwordx4 v177, s[20:21]
	s_mov_b32 m0, s75
	s_waitcnt vmcnt(8)
	s_waitcnt lgkmcnt(0)
	s_barrier
	s_setprio 1
	s_waitcnt lgkmcnt(7)
	v_mfma_f32_16x16x32_bf16 v[126:129], v[130:133], v[168:171], v[126:129]
	v_mfma_f32_16x16x32_bf16 v[126:129], v[134:137], v[172:175], v[126:129]
	s_waitcnt lgkmcnt(5)
	v_mfma_f32_16x16x32_bf16 v[122:125], v[138:141], v[168:171], v[122:125]
	v_mfma_f32_16x16x32_bf16 v[122:125], v[142:145], v[172:175], v[122:125]
	s_waitcnt lgkmcnt(3)
	v_mfma_f32_16x16x32_bf16 v[110:113], v[138:141], v[188:191], v[110:113]
	v_mfma_f32_16x16x32_bf16 v[110:113], v[142:145], v[192:195], v[110:113]
	s_waitcnt lgkmcnt(1)
	v_mfma_f32_16x16x32_bf16 v[118:121], v[130:133], v[188:191], v[118:121]
	v_mfma_f32_16x16x32_bf16 v[118:121], v[134:137], v[192:195], v[118:121]
	v_mfma_f32_16x16x32_bf16 v[94:97], v[130:133], v[196:199], v[94:97]
	v_mfma_f32_16x16x32_bf16 v[94:97], v[134:137], v[200:203], v[94:97]
	v_mfma_f32_16x16x32_bf16 v[90:93], v[138:141], v[196:199], v[90:93]
	v_mfma_f32_16x16x32_bf16 v[90:93], v[142:145], v[200:203], v[90:93]
	v_mfma_f32_16x16x32_bf16 v[78:81], v[138:141], v[204:207], v[78:81]
	v_mfma_f32_16x16x32_bf16 v[78:81], v[142:145], v[208:211], v[78:81]
	s_waitcnt lgkmcnt(0)
	v_mfma_f32_16x16x32_bf16 v[86:89], v[130:133], v[204:207], v[86:89]
	v_mfma_f32_16x16x32_bf16 v[86:89], v[134:137], v[208:211], v[86:89]
	s_setprio 0
	s_setprio 1
	v_mfma_f32_16x16x32_bf16 v[114:117], v[150:153], v[168:171], v[114:117]
	v_mfma_f32_16x16x32_bf16 v[114:117], v[154:157], v[172:175], v[114:117]
	v_mfma_f32_16x16x32_bf16 v[106:109], v[158:161], v[168:171], v[106:109]
	v_mfma_f32_16x16x32_bf16 v[106:109], v[162:165], v[172:175], v[106:109]
	v_mfma_f32_16x16x32_bf16 v[98:101], v[158:161], v[188:191], v[98:101]
	v_mfma_f32_16x16x32_bf16 v[98:101], v[162:165], v[192:195], v[98:101]
	v_mfma_f32_16x16x32_bf16 v[102:105], v[150:153], v[188:191], v[102:105]
	v_mfma_f32_16x16x32_bf16 v[102:105], v[154:157], v[192:195], v[102:105]
	v_mfma_f32_16x16x32_bf16 v[82:85], v[150:153], v[196:199], v[82:85]
	v_mfma_f32_16x16x32_bf16 v[82:85], v[154:157], v[200:203], v[82:85]
	v_mfma_f32_16x16x32_bf16 v[74:77], v[158:161], v[196:199], v[74:77]
	v_mfma_f32_16x16x32_bf16 v[74:77], v[162:165], v[200:203], v[74:77]
	v_mfma_f32_16x16x32_bf16 v[66:69], v[158:161], v[204:207], v[66:69]
	v_mfma_f32_16x16x32_bf16 v[66:69], v[162:165], v[208:211], v[66:69]
	s_setprio 2
	s_barrier
	v_mfma_f32_16x16x32_bf16 v[70:73], v[150:153], v[204:207], v[70:73]
	v_mfma_f32_16x16x32_bf16 v[70:73], v[154:157], v[208:211], v[70:73]
	s_setprio 0
	ds_read_b128 v[168:171], v183 offset:16384
	ds_read_b128 v[172:175], v183 offset:17408
	ds_read_b128 v[188:191], v183 offset:18432
	ds_read_b128 v[192:195], v183 offset:19456
	ds_read_b128 v[196:199], v183 offset:20480
	ds_read_b128 v[200:203], v183 offset:21504
	ds_read_b128 v[204:207], v183 offset:22528
	ds_read_b128 v[208:211], v183 offset:23552
	s_mov_b32 s75, m0
	s_mov_b32 m0, s35
	s_nop 0
	global_load_lds_dwordx4 v176, s[22:23]
	s_mov_b32 m0, s75
	s_add_u32 s76, s22, 0x4000
	s_mov_b32 s75, m0
	s_mov_b32 m0, s36
	s_nop 0
	global_load_lds_dwordx4 v178, s[22:23]
	s_mov_b32 m0, s75
	s_addc_u32 s77, s23, 0
	s_mov_b32 s75, m0
	s_mov_b32 m0, s37
	s_nop 0
	global_load_lds_dwordx4 v176, s[76:77]
	s_mov_b32 m0, s75
	s_nop 0
	s_mov_b32 s75, m0
	s_mov_b32 m0, s40
	s_nop 0
	global_load_lds_dwordx4 v178, s[76:77]
	s_mov_b32 m0, s75
	s_waitcnt vmcnt(4)
	s_waitcnt lgkmcnt(0)
	s_barrier
	s_setprio 1
	s_waitcnt lgkmcnt(7)
	v_mfma_f32_16x16x32_bf16 v[62:65], v[130:133], v[168:171], v[62:65]
	v_mfma_f32_16x16x32_bf16 v[62:65], v[134:137], v[172:175], v[62:65]
	s_waitcnt lgkmcnt(5)
	v_mfma_f32_16x16x32_bf16 v[58:61], v[138:141], v[168:171], v[58:61]
	v_mfma_f32_16x16x32_bf16 v[58:61], v[142:145], v[172:175], v[58:61]
	s_waitcnt lgkmcnt(3)
	v_mfma_f32_16x16x32_bf16 v[42:45], v[138:141], v[188:191], v[42:45]
	v_mfma_f32_16x16x32_bf16 v[42:45], v[142:145], v[192:195], v[42:45]
	s_waitcnt lgkmcnt(1)
	v_mfma_f32_16x16x32_bf16 v[46:49], v[130:133], v[188:191], v[46:49]
	v_mfma_f32_16x16x32_bf16 v[46:49], v[134:137], v[192:195], v[46:49]
	v_mfma_f32_16x16x32_bf16 v[30:33], v[130:133], v[196:199], v[30:33]
	v_mfma_f32_16x16x32_bf16 v[30:33], v[134:137], v[200:203], v[30:33]
	v_mfma_f32_16x16x32_bf16 v[26:29], v[138:141], v[196:199], v[26:29]
	v_mfma_f32_16x16x32_bf16 v[26:29], v[142:145], v[200:203], v[26:29]
	v_mfma_f32_16x16x32_bf16 v[10:13], v[138:141], v[204:207], v[10:13]
	v_mfma_f32_16x16x32_bf16 v[10:13], v[142:145], v[208:211], v[10:13]
	s_waitcnt lgkmcnt(0)
	v_mfma_f32_16x16x32_bf16 v[14:17], v[130:133], v[204:207], v[14:17]
	v_mfma_f32_16x16x32_bf16 v[14:17], v[134:137], v[208:211], v[14:17]
	s_setprio 0
	s_setprio 1
	v_mfma_f32_16x16x32_bf16 v[54:57], v[150:153], v[168:171], v[54:57]
	v_mfma_f32_16x16x32_bf16 v[54:57], v[154:157], v[172:175], v[54:57]
	v_mfma_f32_16x16x32_bf16 v[50:53], v[158:161], v[168:171], v[50:53]
	v_mfma_f32_16x16x32_bf16 v[50:53], v[162:165], v[172:175], v[50:53]
	v_mfma_f32_16x16x32_bf16 v[34:37], v[158:161], v[188:191], v[34:37]
	v_mfma_f32_16x16x32_bf16 v[34:37], v[162:165], v[192:195], v[34:37]
	v_mfma_f32_16x16x32_bf16 v[38:41], v[150:153], v[188:191], v[38:41]
	v_mfma_f32_16x16x32_bf16 v[38:41], v[154:157], v[192:195], v[38:41]
	v_mfma_f32_16x16x32_bf16 v[22:25], v[150:153], v[196:199], v[22:25]
	v_mfma_f32_16x16x32_bf16 v[22:25], v[154:157], v[200:203], v[22:25]
	v_mfma_f32_16x16x32_bf16 v[18:21], v[158:161], v[196:199], v[18:21]
	v_mfma_f32_16x16x32_bf16 v[18:21], v[162:165], v[200:203], v[18:21]
	v_mfma_f32_16x16x32_bf16 v[2:5], v[158:161], v[204:207], v[2:5]
	v_mfma_f32_16x16x32_bf16 v[2:5], v[162:165], v[208:211], v[2:5]
	s_setprio 2
	s_barrier
	v_mfma_f32_16x16x32_bf16 v[6:9], v[150:153], v[204:207], v[6:9]
	v_mfma_f32_16x16x32_bf16 v[6:9], v[154:157], v[208:211], v[6:9]
	s_setprio 0
	ds_read_b128 v[130:133], v184
	ds_read_b128 v[134:137], v184 offset:1024
	ds_read_b128 v[138:141], v184 offset:2048
	ds_read_b128 v[142:145], v184 offset:3072
	ds_read_b128 v[150:153], v185
	ds_read_b128 v[154:157], v185 offset:1024
	ds_read_b128 v[158:161], v185 offset:2048
	ds_read_b128 v[162:165], v185 offset:3072
	ds_read_b128 v[168:171], v183 offset:32768
	ds_read_b128 v[172:175], v183 offset:33792
	ds_read_b128 v[188:191], v183 offset:34816
	ds_read_b128 v[192:195], v183 offset:35840
	ds_read_b128 v[196:199], v183 offset:36864
	ds_read_b128 v[200:203], v183 offset:37888
	ds_read_b128 v[204:207], v183 offset:38912
	ds_read_b128 v[208:211], v183 offset:39936
	s_mov_b32 s75, m0
	s_mov_b32 m0, s34
	s_nop 0
	global_load_lds_dwordx4 v1, s[24:25]
	s_mov_b32 m0, s75
	s_nop 0
	s_mov_b32 s75, m0
	s_mov_b32 m0, s41
	s_nop 0
	global_load_lds_dwordx4 v177, s[24:25]
	s_mov_b32 m0, s75
	s_add_u32 s24, s24, 0x4000
	s_addc_u32 s25, s25, 0
	s_mov_b32 s75, m0
	s_mov_b32 m0, s42
	s_nop 0
	global_load_lds_dwordx4 v1, s[24:25]
	s_mov_b32 m0, s75
	s_nop 0
	s_mov_b32 s75, m0
	s_mov_b32 m0, s43
	s_nop 0
	global_load_lds_dwordx4 v177, s[24:25]
	s_mov_b32 m0, s75
	s_waitcnt vmcnt(8)
	s_waitcnt lgkmcnt(0)
	s_barrier
	s_setprio 1
	s_waitcnt lgkmcnt(7)
	v_mfma_f32_16x16x32_bf16 v[126:129], v[130:133], v[168:171], v[126:129]
	v_mfma_f32_16x16x32_bf16 v[126:129], v[134:137], v[172:175], v[126:129]
	s_waitcnt lgkmcnt(5)
	v_mfma_f32_16x16x32_bf16 v[122:125], v[138:141], v[168:171], v[122:125]
	v_mfma_f32_16x16x32_bf16 v[122:125], v[142:145], v[172:175], v[122:125]
	s_waitcnt lgkmcnt(3)
	v_mfma_f32_16x16x32_bf16 v[110:113], v[138:141], v[188:191], v[110:113]
	v_mfma_f32_16x16x32_bf16 v[110:113], v[142:145], v[192:195], v[110:113]
	s_waitcnt lgkmcnt(1)
	v_mfma_f32_16x16x32_bf16 v[118:121], v[130:133], v[188:191], v[118:121]
	v_mfma_f32_16x16x32_bf16 v[118:121], v[134:137], v[192:195], v[118:121]
	v_mfma_f32_16x16x32_bf16 v[94:97], v[130:133], v[196:199], v[94:97]
	v_mfma_f32_16x16x32_bf16 v[94:97], v[134:137], v[200:203], v[94:97]
	v_mfma_f32_16x16x32_bf16 v[90:93], v[138:141], v[196:199], v[90:93]
	v_mfma_f32_16x16x32_bf16 v[90:93], v[142:145], v[200:203], v[90:93]
	v_mfma_f32_16x16x32_bf16 v[78:81], v[138:141], v[204:207], v[78:81]
	v_mfma_f32_16x16x32_bf16 v[78:81], v[142:145], v[208:211], v[78:81]
	s_waitcnt lgkmcnt(0)
	v_mfma_f32_16x16x32_bf16 v[86:89], v[130:133], v[204:207], v[86:89]
	v_mfma_f32_16x16x32_bf16 v[86:89], v[134:137], v[208:211], v[86:89]
	s_setprio 0
	s_setprio 1
	v_mfma_f32_16x16x32_bf16 v[114:117], v[150:153], v[168:171], v[114:117]
	v_mfma_f32_16x16x32_bf16 v[114:117], v[154:157], v[172:175], v[114:117]
	v_mfma_f32_16x16x32_bf16 v[106:109], v[158:161], v[168:171], v[106:109]
	v_mfma_f32_16x16x32_bf16 v[106:109], v[162:165], v[172:175], v[106:109]
	v_mfma_f32_16x16x32_bf16 v[98:101], v[158:161], v[188:191], v[98:101]
	v_mfma_f32_16x16x32_bf16 v[98:101], v[162:165], v[192:195], v[98:101]
	v_mfma_f32_16x16x32_bf16 v[102:105], v[150:153], v[188:191], v[102:105]
	v_mfma_f32_16x16x32_bf16 v[102:105], v[154:157], v[192:195], v[102:105]
	v_mfma_f32_16x16x32_bf16 v[82:85], v[150:153], v[196:199], v[82:85]
	v_mfma_f32_16x16x32_bf16 v[82:85], v[154:157], v[200:203], v[82:85]
	v_mfma_f32_16x16x32_bf16 v[74:77], v[158:161], v[196:199], v[74:77]
	v_mfma_f32_16x16x32_bf16 v[74:77], v[162:165], v[200:203], v[74:77]
	v_mfma_f32_16x16x32_bf16 v[66:69], v[158:161], v[204:207], v[66:69]
	v_mfma_f32_16x16x32_bf16 v[66:69], v[162:165], v[208:211], v[66:69]
	s_setprio 2
	s_barrier
	v_mfma_f32_16x16x32_bf16 v[70:73], v[150:153], v[204:207], v[70:73]
	v_mfma_f32_16x16x32_bf16 v[70:73], v[154:157], v[208:211], v[70:73]
	s_setprio 0
	ds_read_b128 v[168:171], v183 offset:49152
	ds_read_b128 v[172:175], v183 offset:50176
	ds_read_b128 v[188:191], v183 offset:51200
	ds_read_b128 v[192:195], v183 offset:52224
	ds_read_b128 v[196:199], v183 offset:53248
	ds_read_b128 v[200:203], v183 offset:54272
	ds_read_b128 v[204:207], v183 offset:55296
	ds_read_b128 v[208:211], v183 offset:56320
	s_add_u32 s24, s22, 0x40000
	s_addc_u32 s25, s23, 0
	s_mov_b32 s75, m0
	s_mov_b32 m0, s46
	s_nop 0
	global_load_lds_dwordx4 v176, s[24:25]
	s_mov_b32 m0, s75
	s_add_u32 s22, s22, 0x44000
	s_mov_b32 s75, m0
	s_mov_b32 m0, s47
	s_nop 0
	global_load_lds_dwordx4 v178, s[24:25]
	s_mov_b32 m0, s75
	s_addc_u32 s23, s23, 0
	s_mov_b32 s24, m0
	s_mov_b32 m0, s48
	s_nop 0
	global_load_lds_dwordx4 v176, s[22:23]
	s_mov_b32 m0, s24
	s_nop 0
	s_mov_b32 s24, m0
	s_mov_b32 m0, s49
	s_nop 0
	global_load_lds_dwordx4 v178, s[22:23]
	s_mov_b32 m0, s24
	s_waitcnt vmcnt(4)
	s_waitcnt lgkmcnt(0)
	s_barrier
	s_setprio 1
	s_waitcnt lgkmcnt(7)
	v_mfma_f32_16x16x32_bf16 v[62:65], v[130:133], v[168:171], v[62:65]
	v_mfma_f32_16x16x32_bf16 v[62:65], v[134:137], v[172:175], v[62:65]
	s_waitcnt lgkmcnt(5)
	v_mfma_f32_16x16x32_bf16 v[58:61], v[138:141], v[168:171], v[58:61]
	v_mfma_f32_16x16x32_bf16 v[58:61], v[142:145], v[172:175], v[58:61]
	s_waitcnt lgkmcnt(3)
	v_mfma_f32_16x16x32_bf16 v[42:45], v[138:141], v[188:191], v[42:45]
	v_mfma_f32_16x16x32_bf16 v[42:45], v[142:145], v[192:195], v[42:45]
	s_waitcnt lgkmcnt(1)
	v_mfma_f32_16x16x32_bf16 v[46:49], v[130:133], v[188:191], v[46:49]
	v_mfma_f32_16x16x32_bf16 v[46:49], v[134:137], v[192:195], v[46:49]
	v_mfma_f32_16x16x32_bf16 v[30:33], v[130:133], v[196:199], v[30:33]
	v_mfma_f32_16x16x32_bf16 v[30:33], v[134:137], v[200:203], v[30:33]
	v_mfma_f32_16x16x32_bf16 v[26:29], v[138:141], v[196:199], v[26:29]
	v_mfma_f32_16x16x32_bf16 v[26:29], v[142:145], v[200:203], v[26:29]
	v_mfma_f32_16x16x32_bf16 v[10:13], v[138:141], v[204:207], v[10:13]
	v_mfma_f32_16x16x32_bf16 v[10:13], v[142:145], v[208:211], v[10:13]
	s_waitcnt lgkmcnt(0)
	v_mfma_f32_16x16x32_bf16 v[14:17], v[130:133], v[204:207], v[14:17]
	v_mfma_f32_16x16x32_bf16 v[14:17], v[134:137], v[208:211], v[14:17]
	s_setprio 0
	s_setprio 1
	v_mfma_f32_16x16x32_bf16 v[54:57], v[150:153], v[168:171], v[54:57]
	v_mfma_f32_16x16x32_bf16 v[54:57], v[154:157], v[172:175], v[54:57]
	v_mfma_f32_16x16x32_bf16 v[50:53], v[158:161], v[168:171], v[50:53]
	v_mfma_f32_16x16x32_bf16 v[50:53], v[162:165], v[172:175], v[50:53]
	v_mfma_f32_16x16x32_bf16 v[34:37], v[158:161], v[188:191], v[34:37]
	v_mfma_f32_16x16x32_bf16 v[34:37], v[162:165], v[192:195], v[34:37]
	v_mfma_f32_16x16x32_bf16 v[38:41], v[150:153], v[188:191], v[38:41]
	v_mfma_f32_16x16x32_bf16 v[38:41], v[154:157], v[192:195], v[38:41]
	v_mfma_f32_16x16x32_bf16 v[22:25], v[150:153], v[196:199], v[22:25]
	v_mfma_f32_16x16x32_bf16 v[22:25], v[154:157], v[200:203], v[22:25]
	v_mfma_f32_16x16x32_bf16 v[18:21], v[158:161], v[196:199], v[18:21]
	v_mfma_f32_16x16x32_bf16 v[18:21], v[162:165], v[200:203], v[18:21]
	v_mfma_f32_16x16x32_bf16 v[2:5], v[158:161], v[204:207], v[2:5]
	v_mfma_f32_16x16x32_bf16 v[2:5], v[162:165], v[208:211], v[2:5]
	s_setprio 2
	s_barrier
	v_mfma_f32_16x16x32_bf16 v[6:9], v[150:153], v[204:207], v[6:9]
	v_mfma_f32_16x16x32_bf16 v[6:9], v[154:157], v[208:211], v[6:9]
	s_setprio 0
	s_add_i32 s74, s74, 2
	s_add_u32 s67, s67, 0x80000
	s_addc_u32 s70, s70, 0
	s_add_u32 s20, s20, 0x400000
	s_addc_u32 s21, s21, 0
	s_add_u32 s71, s71, 0x400000
	s_addc_u32 s73, s73, 0
	s_cmpk_gt_u32 s74, 0x53
	s_cbranch_scc0 .LBB0_1952
	v_mov_b32_e32 v174, v252
	v_mov_b32_e32 v175, v253
	v_mov_b32_e32 v210, v254
	v_mov_b32_e32 v211, v255
	s_and_b64 vcc, exec, s[8:9]
	s_cbranch_vccz .LBB0_1955
	s_barrier

.LBB0_2145:
	s_ashr_i32 s25, s24, 31
	s_lshl_b64 s[26:27], s[24:25], 20
	s_add_u32 s26, s33, s26
	s_addc_u32 s27, s42, s27
	s_and_b64 s[28:29], s[2:3], exec
	s_cselect_b32 s5, s27, s37
	s_cselect_b32 s25, s26, s36
	s_ashr_i32 s23, s22, 31
	s_lshl_b64 s[28:29], s[22:23], 20
	s_add_u32 s28, s43, s28
	s_addc_u32 s29, s46, s29
	s_and_b64 s[40:41], s[2:3], exec
	s_cselect_b32 s23, s29, s35
	s_cselect_b32 s31, s28, s34
	s_add_u32 s77, s34, 0x100
	s_addc_u32 s78, s35, 0
	s_add_u32 s34, s36, 0x80080
	s_addc_u32 s35, s37, 0
	s_add_u32 s79, s36, 0x100
	s_addc_u32 s80, s37, 0
	s_mov_b32 s81, -2
	s_waitcnt vmcnt(25)
	s_waitcnt vmcnt(24)
	s_waitcnt vmcnt(4)
	s_waitcnt vmcnt(2)
	s_waitcnt vmcnt(1)
	s_waitcnt vmcnt(0)
	v_mov_b32_e32 v252, v174
	v_mov_b32_e32 v253, v175
	v_mov_b32_e32 v254, v216
	v_mov_b32_e32 v255, v217
	ds_read_b128 v[42:45], v181
	ds_read_b128 v[46:49], v181 offset:1024
	ds_read_b128 v[58:61], v181 offset:2048
	ds_read_b128 v[62:65], v181 offset:3072
	ds_read_b128 v[146:149], v182
	ds_read_b128 v[150:153], v182 offset:1024
	ds_read_b128 v[154:157], v182 offset:2048
	ds_read_b128 v[158:161], v182 offset:3072
	s_cmp_eq_u32 s81, 28
	s_cselect_b32 s37, s23, s78
	s_cselect_b32 s36, s31, s77
	s_cselect_b32 s41, s5, s80
	s_cselect_b32 s40, s25, s79
	ds_read_b128 v[172:175], v183
	ds_read_b128 v[190:193], v183 offset:1024
	ds_read_b128 v[194:197], v183 offset:2048
	ds_read_b128 v[198:201], v183 offset:3072
	ds_read_b128 v[202:205], v183 offset:4096
	ds_read_b128 v[206:209], v183 offset:5120
	ds_read_b128 v[210:213], v183 offset:6144
	ds_read_b128 v[214:217], v183 offset:7168
	s_add_u32 s82, s34, 0xfff80000
	s_addc_u32 s83, s35, -1
	s_mov_b32 s86, m0
	s_mov_b32 m0, s70
	s_nop 0
	global_load_lds_dwordx4 v1, s[82:83]
	s_mov_b32 m0, s86
	s_nop 0
	s_mov_b32 s86, m0
	s_mov_b32 m0, s73
	s_nop 0
	global_load_lds_dwordx4 v177, s[82:83]
	s_mov_b32 m0, s86
	s_mov_b32 s82, m0
	s_mov_b32 m0, s71
	s_nop 0
	global_load_lds_dwordx4 v1, s[34:35]
	s_mov_b32 m0, s82
	s_nop 0
	s_mov_b32 s82, m0
	s_mov_b32 m0, s74
	s_nop 0
	global_load_lds_dwordx4 v177, s[34:35]
	s_mov_b32 m0, s82
	s_waitcnt vmcnt(8)
	s_waitcnt lgkmcnt(0)
	s_barrier
	s_setprio 1
	s_waitcnt lgkmcnt(7)
	v_mfma_f32_16x16x32_bf16 v[142:145], v[42:45], v[172:175], 0
	v_mfma_f32_16x16x32_bf16 v[142:145], v[46:49], v[190:193], v[142:145]
	s_waitcnt lgkmcnt(5)
	v_mfma_f32_16x16x32_bf16 v[138:141], v[58:61], v[172:175], 0
	v_mfma_f32_16x16x32_bf16 v[138:141], v[62:65], v[190:193], v[138:141]
	s_waitcnt lgkmcnt(3)
	v_mfma_f32_16x16x32_bf16 v[126:129], v[42:45], v[194:197], 0
	v_mfma_f32_16x16x32_bf16 v[126:129], v[46:49], v[198:201], v[126:129]
	s_waitcnt lgkmcnt(1)
	v_mfma_f32_16x16x32_bf16 v[122:125], v[58:61], v[194:197], 0
	v_mfma_f32_16x16x32_bf16 v[122:125], v[62:65], v[198:201], v[122:125]
	v_mfma_f32_16x16x32_bf16 v[110:113], v[42:45], v[202:205], 0
	v_mfma_f32_16x16x32_bf16 v[110:113], v[46:49], v[206:209], v[110:113]
	v_mfma_f32_16x16x32_bf16 v[106:109], v[58:61], v[202:205], 0
	v_mfma_f32_16x16x32_bf16 v[106:109], v[62:65], v[206:209], v[106:109]
	v_mfma_f32_16x16x32_bf16 v[94:97], v[42:45], v[210:213], 0
	v_mfma_f32_16x16x32_bf16 v[94:97], v[46:49], v[214:217], v[94:97]
	s_waitcnt lgkmcnt(0)
	v_mfma_f32_16x16x32_bf16 v[90:93], v[58:61], v[210:213], 0
	v_mfma_f32_16x16x32_bf16 v[90:93], v[62:65], v[214:217], v[90:93]
	s_setprio 0
	s_setprio 1
	v_mfma_f32_16x16x32_bf16 v[134:137], v[146:149], v[172:175], 0
	v_mfma_f32_16x16x32_bf16 v[134:137], v[150:153], v[190:193], v[134:137]
	v_mfma_f32_16x16x32_bf16 v[130:133], v[154:157], v[172:175], 0
	v_mfma_f32_16x16x32_bf16 v[130:133], v[158:161], v[190:193], v[130:133]
	v_mfma_f32_16x16x32_bf16 v[118:121], v[146:149], v[194:197], 0
	v_mfma_f32_16x16x32_bf16 v[118:121], v[150:153], v[198:201], v[118:121]
	v_mfma_f32_16x16x32_bf16 v[114:117], v[154:157], v[194:197], 0
	v_mfma_f32_16x16x32_bf16 v[114:117], v[158:161], v[198:201], v[114:117]
	v_mfma_f32_16x16x32_bf16 v[102:105], v[146:149], v[202:205], 0
	v_mfma_f32_16x16x32_bf16 v[102:105], v[150:153], v[206:209], v[102:105]
	v_mfma_f32_16x16x32_bf16 v[98:101], v[154:157], v[202:205], 0
	v_mfma_f32_16x16x32_bf16 v[98:101], v[158:161], v[206:209], v[98:101]
	v_mfma_f32_16x16x32_bf16 v[86:89], v[146:149], v[210:213], 0
	v_mfma_f32_16x16x32_bf16 v[86:89], v[150:153], v[214:217], v[86:89]
	s_setprio 2
	s_barrier
	v_mfma_f32_16x16x32_bf16 v[82:85], v[154:157], v[210:213], 0
	v_mfma_f32_16x16x32_bf16 v[82:85], v[158:161], v[214:217], v[82:85]
	s_setprio 0
	ds_read_b128 v[172:175], v183 offset:16384
	ds_read_b128 v[190:193], v183 offset:17408
	ds_read_b128 v[194:197], v183 offset:18432
	ds_read_b128 v[198:201], v183 offset:19456
	ds_read_b128 v[202:205], v183 offset:20480
	ds_read_b128 v[206:209], v183 offset:21504
	ds_read_b128 v[210:213], v183 offset:22528
	ds_read_b128 v[214:217], v183 offset:23552
	s_mov_b32 s82, m0
	s_mov_b32 m0, s49
	s_nop 0
	global_load_lds_dwordx4 v176, s[36:37]
	s_mov_b32 m0, s82
	s_nop 0
	s_mov_b32 s82, m0
	s_mov_b32 m0, s56
	s_nop 0
	global_load_lds_dwordx4 v178, s[36:37]
	s_mov_b32 m0, s82
	s_add_u32 s82, s36, 0x80000
	s_addc_u32 s83, s37, 0
	s_mov_b32 s86, m0
	s_mov_b32 m0, s57
	s_nop 0
	global_load_lds_dwordx4 v176, s[82:83]
	s_mov_b32 m0, s86
	s_nop 0
	s_mov_b32 s86, m0
	s_mov_b32 m0, s58
	s_nop 0
	global_load_lds_dwordx4 v178, s[82:83]
	s_mov_b32 m0, s86
	s_waitcnt vmcnt(4)
	s_waitcnt lgkmcnt(0)
	s_barrier
	s_setprio 1
	s_waitcnt lgkmcnt(7)
	v_mfma_f32_16x16x32_bf16 v[78:81], v[42:45], v[172:175], 0
	v_mfma_f32_16x16x32_bf16 v[78:81], v[46:49], v[190:193], v[78:81]
	s_waitcnt lgkmcnt(5)
	v_mfma_f32_16x16x32_bf16 v[74:77], v[58:61], v[172:175], 0
	v_mfma_f32_16x16x32_bf16 v[74:77], v[62:65], v[190:193], v[74:77]
	s_waitcnt lgkmcnt(3)
	v_mfma_f32_16x16x32_bf16 v[54:57], v[42:45], v[194:197], 0
	v_mfma_f32_16x16x32_bf16 v[54:57], v[46:49], v[198:201], v[54:57]
	s_waitcnt lgkmcnt(1)
	v_mfma_f32_16x16x32_bf16 v[50:53], v[58:61], v[194:197], 0
	v_mfma_f32_16x16x32_bf16 v[50:53], v[62:65], v[198:201], v[50:53]
	v_mfma_f32_16x16x32_bf16 v[30:33], v[42:45], v[202:205], 0
	v_mfma_f32_16x16x32_bf16 v[30:33], v[46:49], v[206:209], v[30:33]
	v_mfma_f32_16x16x32_bf16 v[26:29], v[58:61], v[202:205], 0
	v_mfma_f32_16x16x32_bf16 v[26:29], v[62:65], v[206:209], v[26:29]
	v_mfma_f32_16x16x32_bf16 v[14:17], v[42:45], v[210:213], 0
	v_mfma_f32_16x16x32_bf16 v[14:17], v[46:49], v[214:217], v[14:17]
	s_waitcnt lgkmcnt(0)
	v_mfma_f32_16x16x32_bf16 v[10:13], v[58:61], v[210:213], 0
	v_mfma_f32_16x16x32_bf16 v[10:13], v[62:65], v[214:217], v[10:13]
	s_setprio 0
	s_setprio 1
	v_mfma_f32_16x16x32_bf16 v[38:41], v[146:149], v[194:197], 0
	v_mfma_f32_16x16x32_bf16 v[38:41], v[150:153], v[198:201], v[38:41]
	v_mfma_f32_16x16x32_bf16 v[34:37], v[154:157], v[194:197], 0
	v_mfma_f32_16x16x32_bf16 v[34:37], v[158:161], v[198:201], v[34:37]
	v_mfma_f32_16x16x32_bf16 v[22:25], v[146:149], v[202:205], 0
	v_mfma_f32_16x16x32_bf16 v[22:25], v[150:153], v[206:209], v[22:25]
	v_mfma_f32_16x16x32_bf16 v[18:21], v[154:157], v[202:205], 0
	v_mfma_f32_16x16x32_bf16 v[18:21], v[158:161], v[206:209], v[18:21]
	v_mfma_f32_16x16x32_bf16 v[6:9], v[146:149], v[210:213], 0
	v_mfma_f32_16x16x32_bf16 v[6:9], v[150:153], v[214:217], v[6:9]
	v_mfma_f32_16x16x32_bf16 v[2:5], v[154:157], v[210:213], 0
	v_mfma_f32_16x16x32_bf16 v[2:5], v[158:161], v[214:217], v[2:5]
	v_mfma_f32_16x16x32_bf16 v[42:45], v[146:149], v[172:175], 0
	v_mfma_f32_16x16x32_bf16 v[42:45], v[150:153], v[190:193], v[42:45]
	s_setprio 2
	s_barrier
	v_mfma_f32_16x16x32_bf16 v[46:49], v[154:157], v[172:175], 0
	v_mfma_f32_16x16x32_bf16 v[46:49], v[158:161], v[190:193], v[46:49]
	s_setprio 0
	ds_read_b128 v[58:61], v184
	ds_read_b128 v[62:65], v184 offset:1024
	ds_read_b128 v[66:69], v184 offset:2048
	ds_read_b128 v[70:73], v184 offset:3072
	ds_read_b128 v[146:149], v185
	ds_read_b128 v[150:153], v185 offset:1024
	ds_read_b128 v[154:157], v185 offset:2048
	ds_read_b128 v[158:161], v185 offset:3072
	ds_read_b128 v[172:175], v183 offset:32768
	ds_read_b128 v[190:193], v183 offset:33792
	ds_read_b128 v[194:197], v183 offset:34816
	ds_read_b128 v[198:201], v183 offset:35840
	ds_read_b128 v[202:205], v183 offset:36864
	ds_read_b128 v[206:209], v183 offset:37888
	ds_read_b128 v[210:213], v183 offset:38912
	ds_read_b128 v[214:217], v183 offset:39936
	s_mov_b32 s82, m0
	s_mov_b32 m0, s48
	s_nop 0
	global_load_lds_dwordx4 v1, s[40:41]
	s_mov_b32 m0, s82
	s_nop 0
	s_mov_b32 s82, m0
	s_mov_b32 m0, s59
	s_nop 0
	global_load_lds_dwordx4 v177, s[40:41]
	s_mov_b32 m0, s82
	s_add_u32 s40, s40, 0x80000
	s_addc_u32 s41, s41, 0
	s_mov_b32 s82, m0
	s_mov_b32 m0, s62
	s_nop 0
	global_load_lds_dwordx4 v1, s[40:41]
	s_mov_b32 m0, s82
	s_nop 0
	s_mov_b32 s82, m0
	s_mov_b32 m0, s63
	s_nop 0
	global_load_lds_dwordx4 v177, s[40:41]
	s_mov_b32 m0, s82
	s_waitcnt vmcnt(8)
	s_waitcnt lgkmcnt(0)
	s_barrier
	s_setprio 1
	s_waitcnt lgkmcnt(7)
	v_mfma_f32_16x16x32_bf16 v[142:145], v[58:61], v[172:175], v[142:145]
	v_mfma_f32_16x16x32_bf16 v[142:145], v[62:65], v[190:193], v[142:145]
	s_waitcnt lgkmcnt(5)
	v_mfma_f32_16x16x32_bf16 v[138:141], v[66:69], v[172:175], v[138:141]
	v_mfma_f32_16x16x32_bf16 v[138:141], v[70:73], v[190:193], v[138:141]
	s_waitcnt lgkmcnt(3)
	v_mfma_f32_16x16x32_bf16 v[126:129], v[58:61], v[194:197], v[126:129]
	v_mfma_f32_16x16x32_bf16 v[126:129], v[62:65], v[198:201], v[126:129]
	s_waitcnt lgkmcnt(1)
	v_mfma_f32_16x16x32_bf16 v[122:125], v[66:69], v[194:197], v[122:125]
	v_mfma_f32_16x16x32_bf16 v[122:125], v[70:73], v[198:201], v[122:125]
	v_mfma_f32_16x16x32_bf16 v[110:113], v[58:61], v[202:205], v[110:113]
	v_mfma_f32_16x16x32_bf16 v[110:113], v[62:65], v[206:209], v[110:113]
	v_mfma_f32_16x16x32_bf16 v[106:109], v[66:69], v[202:205], v[106:109]
	v_mfma_f32_16x16x32_bf16 v[106:109], v[70:73], v[206:209], v[106:109]
	v_mfma_f32_16x16x32_bf16 v[94:97], v[58:61], v[210:213], v[94:97]
	v_mfma_f32_16x16x32_bf16 v[94:97], v[62:65], v[214:217], v[94:97]
	s_waitcnt lgkmcnt(0)
	v_mfma_f32_16x16x32_bf16 v[90:93], v[66:69], v[210:213], v[90:93]
	v_mfma_f32_16x16x32_bf16 v[90:93], v[70:73], v[214:217], v[90:93]
	s_setprio 0
	s_setprio 1
	v_mfma_f32_16x16x32_bf16 v[134:137], v[146:149], v[172:175], v[134:137]
	v_mfma_f32_16x16x32_bf16 v[134:137], v[150:153], v[190:193], v[134:137]
	v_mfma_f32_16x16x32_bf16 v[130:133], v[154:157], v[172:175], v[130:133]
	v_mfma_f32_16x16x32_bf16 v[130:133], v[158:161], v[190:193], v[130:133]
	v_mfma_f32_16x16x32_bf16 v[118:121], v[146:149], v[194:197], v[118:121]
	v_mfma_f32_16x16x32_bf16 v[118:121], v[150:153], v[198:201], v[118:121]
	v_mfma_f32_16x16x32_bf16 v[114:117], v[154:157], v[194:197], v[114:117]
	v_mfma_f32_16x16x32_bf16 v[114:117], v[158:161], v[198:201], v[114:117]
	v_mfma_f32_16x16x32_bf16 v[102:105], v[146:149], v[202:205], v[102:105]
	v_mfma_f32_16x16x32_bf16 v[102:105], v[150:153], v[206:209], v[102:105]
	v_mfma_f32_16x16x32_bf16 v[98:101], v[154:157], v[202:205], v[98:101]
	v_mfma_f32_16x16x32_bf16 v[98:101], v[158:161], v[206:209], v[98:101]
	v_mfma_f32_16x16x32_bf16 v[86:89], v[146:149], v[210:213], v[86:89]
	v_mfma_f32_16x16x32_bf16 v[86:89], v[150:153], v[214:217], v[86:89]
	s_setprio 2
	s_barrier
	v_mfma_f32_16x16x32_bf16 v[82:85], v[154:157], v[210:213], v[82:85]
	v_mfma_f32_16x16x32_bf16 v[82:85], v[158:161], v[214:217], v[82:85]
	s_setprio 0
	ds_read_b128 v[172:175], v183 offset:49152
	ds_read_b128 v[190:193], v183 offset:50176
	ds_read_b128 v[194:197], v183 offset:51200
	ds_read_b128 v[198:201], v183 offset:52224
	ds_read_b128 v[202:205], v183 offset:53248
	ds_read_b128 v[206:209], v183 offset:54272
	ds_read_b128 v[210:213], v183 offset:55296
	ds_read_b128 v[214:217], v183 offset:56320
	s_add_u32 s40, s36, 0x80
	s_addc_u32 s41, s37, 0
	s_mov_b32 s82, m0
	s_mov_b32 m0, s64
	s_nop 0
	global_load_lds_dwordx4 v176, s[40:41]
	s_mov_b32 m0, s82
	s_add_u32 s36, s36, 0x80080
	s_mov_b32 s82, m0
	s_mov_b32 m0, s65
	s_nop 0
	global_load_lds_dwordx4 v178, s[40:41]
	s_mov_b32 m0, s82
	s_addc_u32 s37, s37, 0
	s_mov_b32 s40, m0
	s_mov_b32 m0, s66
	s_nop 0
	global_load_lds_dwordx4 v176, s[36:37]
	s_mov_b32 m0, s40
	s_nop 0
	s_mov_b32 s40, m0
	s_mov_b32 m0, s67
	s_nop 0
	global_load_lds_dwordx4 v178, s[36:37]
	s_mov_b32 m0, s40
	s_waitcnt vmcnt(4)
	s_waitcnt lgkmcnt(0)
	s_barrier
	s_setprio 1
	s_waitcnt lgkmcnt(7)
	v_mfma_f32_16x16x32_bf16 v[78:81], v[58:61], v[172:175], v[78:81]
	v_mfma_f32_16x16x32_bf16 v[78:81], v[62:65], v[190:193], v[78:81]
	s_waitcnt lgkmcnt(5)
	v_mfma_f32_16x16x32_bf16 v[74:77], v[66:69], v[172:175], v[74:77]
	v_mfma_f32_16x16x32_bf16 v[74:77], v[70:73], v[190:193], v[74:77]
	s_waitcnt lgkmcnt(3)
	v_mfma_f32_16x16x32_bf16 v[54:57], v[58:61], v[194:197], v[54:57]
	v_mfma_f32_16x16x32_bf16 v[54:57], v[62:65], v[198:201], v[54:57]
	s_waitcnt lgkmcnt(1)
	v_mfma_f32_16x16x32_bf16 v[50:53], v[66:69], v[194:197], v[50:53]
	v_mfma_f32_16x16x32_bf16 v[50:53], v[70:73], v[198:201], v[50:53]
	v_mfma_f32_16x16x32_bf16 v[30:33], v[58:61], v[202:205], v[30:33]
	v_mfma_f32_16x16x32_bf16 v[30:33], v[62:65], v[206:209], v[30:33]
	v_mfma_f32_16x16x32_bf16 v[26:29], v[66:69], v[202:205], v[26:29]
	v_mfma_f32_16x16x32_bf16 v[26:29], v[70:73], v[206:209], v[26:29]
	v_mfma_f32_16x16x32_bf16 v[14:17], v[58:61], v[210:213], v[14:17]
	v_mfma_f32_16x16x32_bf16 v[14:17], v[62:65], v[214:217], v[14:17]
	s_waitcnt lgkmcnt(0)
	v_mfma_f32_16x16x32_bf16 v[10:13], v[66:69], v[210:213], v[10:13]
	v_mfma_f32_16x16x32_bf16 v[10:13], v[70:73], v[214:217], v[10:13]
	s_setprio 0
	s_setprio 1
	v_mfma_f32_16x16x32_bf16 v[42:45], v[146:149], v[172:175], v[42:45]
	v_mfma_f32_16x16x32_bf16 v[70:73], v[150:153], v[190:193], v[42:45]
	v_mfma_f32_16x16x32_bf16 v[42:45], v[154:157], v[172:175], v[46:49]
	v_mfma_f32_16x16x32_bf16 v[66:69], v[158:161], v[190:193], v[42:45]
	v_mfma_f32_16x16x32_bf16 v[38:41], v[146:149], v[194:197], v[38:41]
	v_mfma_f32_16x16x32_bf16 v[38:41], v[150:153], v[198:201], v[38:41]
	v_mfma_f32_16x16x32_bf16 v[34:37], v[154:157], v[194:197], v[34:37]
	v_mfma_f32_16x16x32_bf16 v[34:37], v[158:161], v[198:201], v[34:37]
	v_mfma_f32_16x16x32_bf16 v[22:25], v[146:149], v[202:205], v[22:25]
	v_mfma_f32_16x16x32_bf16 v[22:25], v[150:153], v[206:209], v[22:25]
	v_mfma_f32_16x16x32_bf16 v[18:21], v[154:157], v[202:205], v[18:21]
	v_mfma_f32_16x16x32_bf16 v[18:21], v[158:161], v[206:209], v[18:21]
	v_mfma_f32_16x16x32_bf16 v[6:9], v[146:149], v[210:213], v[6:9]
	v_mfma_f32_16x16x32_bf16 v[6:9], v[150:153], v[214:217], v[6:9]
	s_setprio 2
	s_barrier
	v_mfma_f32_16x16x32_bf16 v[2:5], v[154:157], v[210:213], v[2:5]
	v_mfma_f32_16x16x32_bf16 v[2:5], v[158:161], v[214:217], v[2:5]
	s_setprio 0
	s_add_i32 s81, s81, 2
	s_add_u32 s77, s77, 0x100
	s_addc_u32 s78, s78, 0
	s_add_u32 s34, s34, 0x100
	s_addc_u32 s35, s35, 0
	s_add_u32 s79, s79, 0x100
	s_addc_u32 s80, s80, 0
	s_cmp_gt_u32 s81, 29
	.p2align 6
.LBB0_2146:
	ds_read_b128 v[42:45], v181
	ds_read_b128 v[46:49], v181 offset:1024
	ds_read_b128 v[58:61], v181 offset:2048
	ds_read_b128 v[62:65], v181 offset:3072
	ds_read_b128 v[146:149], v182
	ds_read_b128 v[150:153], v182 offset:1024
	ds_read_b128 v[154:157], v182 offset:2048
	ds_read_b128 v[158:161], v182 offset:3072
	s_cmp_eq_u32 s81, 28
	s_cselect_b32 s37, s23, s78
	s_cselect_b32 s36, s31, s77
	s_cselect_b32 s41, s5, s80
	s_cselect_b32 s40, s25, s79
	ds_read_b128 v[172:175], v183
	ds_read_b128 v[190:193], v183 offset:1024
	ds_read_b128 v[194:197], v183 offset:2048
	ds_read_b128 v[198:201], v183 offset:3072
	ds_read_b128 v[202:205], v183 offset:4096
	ds_read_b128 v[206:209], v183 offset:5120
	ds_read_b128 v[210:213], v183 offset:6144
	ds_read_b128 v[214:217], v183 offset:7168
	s_add_u32 s82, s34, 0xfff80000
	s_addc_u32 s83, s35, -1
	s_mov_b32 s86, m0
	s_mov_b32 m0, s70
	s_nop 0
	global_load_lds_dwordx4 v1, s[82:83]
	s_mov_b32 m0, s86
	s_nop 0
	s_mov_b32 s86, m0
	s_mov_b32 m0, s73
	s_nop 0
	global_load_lds_dwordx4 v177, s[82:83]
	s_mov_b32 m0, s86
	s_mov_b32 s82, m0
	s_mov_b32 m0, s71
	s_nop 0
	global_load_lds_dwordx4 v1, s[34:35]
	s_mov_b32 m0, s82
	s_nop 0
	s_mov_b32 s82, m0
	s_mov_b32 m0, s74
	s_nop 0
	global_load_lds_dwordx4 v177, s[34:35]
	s_mov_b32 m0, s82
	s_waitcnt vmcnt(8)
	s_waitcnt lgkmcnt(0)
	s_barrier
	s_setprio 1
	s_waitcnt lgkmcnt(7)
	v_mfma_f32_16x16x32_bf16 v[142:145], v[42:45], v[172:175], v[142:145]
	v_mfma_f32_16x16x32_bf16 v[142:145], v[46:49], v[190:193], v[142:145]
	s_waitcnt lgkmcnt(5)
	v_mfma_f32_16x16x32_bf16 v[138:141], v[58:61], v[172:175], v[138:141]
	v_mfma_f32_16x16x32_bf16 v[138:141], v[62:65], v[190:193], v[138:141]
	s_waitcnt lgkmcnt(3)
	v_mfma_f32_16x16x32_bf16 v[126:129], v[42:45], v[194:197], v[126:129]
	v_mfma_f32_16x16x32_bf16 v[126:129], v[46:49], v[198:201], v[126:129]
	s_waitcnt lgkmcnt(1)
	v_mfma_f32_16x16x32_bf16 v[122:125], v[58:61], v[194:197], v[122:125]
	v_mfma_f32_16x16x32_bf16 v[122:125], v[62:65], v[198:201], v[122:125]
	v_mfma_f32_16x16x32_bf16 v[110:113], v[42:45], v[202:205], v[110:113]
	v_mfma_f32_16x16x32_bf16 v[110:113], v[46:49], v[206:209], v[110:113]
	v_mfma_f32_16x16x32_bf16 v[106:109], v[58:61], v[202:205], v[106:109]
	v_mfma_f32_16x16x32_bf16 v[106:109], v[62:65], v[206:209], v[106:109]
	v_mfma_f32_16x16x32_bf16 v[94:97], v[42:45], v[210:213], v[94:97]
	v_mfma_f32_16x16x32_bf16 v[94:97], v[46:49], v[214:217], v[94:97]
	s_waitcnt lgkmcnt(0)
	v_mfma_f32_16x16x32_bf16 v[90:93], v[58:61], v[210:213], v[90:93]
	v_mfma_f32_16x16x32_bf16 v[90:93], v[62:65], v[214:217], v[90:93]
	s_setprio 0
	s_setprio 1
	v_mfma_f32_16x16x32_bf16 v[134:137], v[146:149], v[172:175], v[134:137]
	v_mfma_f32_16x16x32_bf16 v[134:137], v[150:153], v[190:193], v[134:137]
	v_mfma_f32_16x16x32_bf16 v[130:133], v[154:157], v[172:175], v[130:133]
	v_mfma_f32_16x16x32_bf16 v[130:133], v[158:161], v[190:193], v[130:133]
	v_mfma_f32_16x16x32_bf16 v[118:121], v[146:149], v[194:197], v[118:121]
	v_mfma_f32_16x16x32_bf16 v[118:121], v[150:153], v[198:201], v[118:121]
	v_mfma_f32_16x16x32_bf16 v[114:117], v[154:157], v[194:197], v[114:117]
	v_mfma_f32_16x16x32_bf16 v[114:117], v[158:161], v[198:201], v[114:117]
	v_mfma_f32_16x16x32_bf16 v[102:105], v[146:149], v[202:205], v[102:105]
	v_mfma_f32_16x16x32_bf16 v[102:105], v[150:153], v[206:209], v[102:105]
	v_mfma_f32_16x16x32_bf16 v[98:101], v[154:157], v[202:205], v[98:101]
	v_mfma_f32_16x16x32_bf16 v[98:101], v[158:161], v[206:209], v[98:101]
	v_mfma_f32_16x16x32_bf16 v[86:89], v[146:149], v[210:213], v[86:89]
	v_mfma_f32_16x16x32_bf16 v[86:89], v[150:153], v[214:217], v[86:89]
	s_setprio 2
	s_barrier
	v_mfma_f32_16x16x32_bf16 v[82:85], v[154:157], v[210:213], v[82:85]
	v_mfma_f32_16x16x32_bf16 v[82:85], v[158:161], v[214:217], v[82:85]
	s_setprio 0
	ds_read_b128 v[172:175], v183 offset:16384
	ds_read_b128 v[190:193], v183 offset:17408
	ds_read_b128 v[194:197], v183 offset:18432
	ds_read_b128 v[198:201], v183 offset:19456
	ds_read_b128 v[202:205], v183 offset:20480
	ds_read_b128 v[206:209], v183 offset:21504
	ds_read_b128 v[210:213], v183 offset:22528
	ds_read_b128 v[214:217], v183 offset:23552
	s_mov_b32 s82, m0
	s_mov_b32 m0, s49
	s_nop 0
	global_load_lds_dwordx4 v176, s[36:37]
	s_mov_b32 m0, s82
	s_nop 0
	s_mov_b32 s82, m0
	s_mov_b32 m0, s56
	s_nop 0
	global_load_lds_dwordx4 v178, s[36:37]
	s_mov_b32 m0, s82
	s_add_u32 s82, s36, 0x80000
	s_addc_u32 s83, s37, 0
	s_mov_b32 s86, m0
	s_mov_b32 m0, s57
	s_nop 0
	global_load_lds_dwordx4 v176, s[82:83]
	s_mov_b32 m0, s86
	s_nop 0
	s_mov_b32 s86, m0
	s_mov_b32 m0, s58
	s_nop 0
	global_load_lds_dwordx4 v178, s[82:83]
	s_mov_b32 m0, s86
	s_waitcnt vmcnt(4)
	s_waitcnt lgkmcnt(0)
	s_barrier
	s_setprio 1
	s_waitcnt lgkmcnt(7)
	v_mfma_f32_16x16x32_bf16 v[78:81], v[42:45], v[172:175], v[78:81]
	v_mfma_f32_16x16x32_bf16 v[78:81], v[46:49], v[190:193], v[78:81]
	s_waitcnt lgkmcnt(5)
	v_mfma_f32_16x16x32_bf16 v[74:77], v[58:61], v[172:175], v[74:77]
	v_mfma_f32_16x16x32_bf16 v[74:77], v[62:65], v[190:193], v[74:77]
	s_waitcnt lgkmcnt(3)
	v_mfma_f32_16x16x32_bf16 v[54:57], v[42:45], v[194:197], v[54:57]
	v_mfma_f32_16x16x32_bf16 v[54:57], v[46:49], v[198:201], v[54:57]
	s_waitcnt lgkmcnt(1)
	v_mfma_f32_16x16x32_bf16 v[50:53], v[58:61], v[194:197], v[50:53]
	v_mfma_f32_16x16x32_bf16 v[50:53], v[62:65], v[198:201], v[50:53]
	v_mfma_f32_16x16x32_bf16 v[30:33], v[42:45], v[202:205], v[30:33]
	v_mfma_f32_16x16x32_bf16 v[30:33], v[46:49], v[206:209], v[30:33]
	v_mfma_f32_16x16x32_bf16 v[26:29], v[58:61], v[202:205], v[26:29]
	v_mfma_f32_16x16x32_bf16 v[26:29], v[62:65], v[206:209], v[26:29]
	v_mfma_f32_16x16x32_bf16 v[14:17], v[42:45], v[210:213], v[14:17]
	v_mfma_f32_16x16x32_bf16 v[14:17], v[46:49], v[214:217], v[14:17]
	s_waitcnt lgkmcnt(0)
	v_mfma_f32_16x16x32_bf16 v[10:13], v[58:61], v[210:213], v[10:13]
	v_mfma_f32_16x16x32_bf16 v[10:13], v[62:65], v[214:217], v[10:13]
	s_setprio 0
	s_setprio 1
	v_mfma_f32_16x16x32_bf16 v[38:41], v[146:149], v[194:197], v[38:41]
	v_mfma_f32_16x16x32_bf16 v[38:41], v[150:153], v[198:201], v[38:41]
	v_mfma_f32_16x16x32_bf16 v[34:37], v[154:157], v[194:197], v[34:37]
	v_mfma_f32_16x16x32_bf16 v[34:37], v[158:161], v[198:201], v[34:37]
	v_mfma_f32_16x16x32_bf16 v[22:25], v[146:149], v[202:205], v[22:25]
	v_mfma_f32_16x16x32_bf16 v[22:25], v[150:153], v[206:209], v[22:25]
	v_mfma_f32_16x16x32_bf16 v[18:21], v[154:157], v[202:205], v[18:21]
	v_mfma_f32_16x16x32_bf16 v[18:21], v[158:161], v[206:209], v[18:21]
	v_mfma_f32_16x16x32_bf16 v[6:9], v[146:149], v[210:213], v[6:9]
	v_mfma_f32_16x16x32_bf16 v[6:9], v[150:153], v[214:217], v[6:9]
	v_mfma_f32_16x16x32_bf16 v[2:5], v[154:157], v[210:213], v[2:5]
	v_mfma_f32_16x16x32_bf16 v[2:5], v[158:161], v[214:217], v[2:5]
	v_mfma_f32_16x16x32_bf16 v[42:45], v[146:149], v[172:175], v[70:73]
	v_mfma_f32_16x16x32_bf16 v[42:45], v[150:153], v[190:193], v[42:45]
	s_setprio 2
	s_barrier
	v_mfma_f32_16x16x32_bf16 v[46:49], v[154:157], v[172:175], v[66:69]
	v_mfma_f32_16x16x32_bf16 v[46:49], v[158:161], v[190:193], v[46:49]
	s_setprio 0
	ds_read_b128 v[58:61], v184
	ds_read_b128 v[62:65], v184 offset:1024
	ds_read_b128 v[66:69], v184 offset:2048
	ds_read_b128 v[70:73], v184 offset:3072
	ds_read_b128 v[146:149], v185
	ds_read_b128 v[150:153], v185 offset:1024
	ds_read_b128 v[154:157], v185 offset:2048
	ds_read_b128 v[158:161], v185 offset:3072
	ds_read_b128 v[172:175], v183 offset:32768
	ds_read_b128 v[190:193], v183 offset:33792
	ds_read_b128 v[194:197], v183 offset:34816
	ds_read_b128 v[198:201], v183 offset:35840
	ds_read_b128 v[202:205], v183 offset:36864
	ds_read_b128 v[206:209], v183 offset:37888
	ds_read_b128 v[210:213], v183 offset:38912
	ds_read_b128 v[214:217], v183 offset:39936
	s_mov_b32 s82, m0
	s_mov_b32 m0, s48
	s_nop 0
	global_load_lds_dwordx4 v1, s[40:41]
	s_mov_b32 m0, s82
	s_nop 0
	s_mov_b32 s82, m0
	s_mov_b32 m0, s59
	s_nop 0
	global_load_lds_dwordx4 v177, s[40:41]
	s_mov_b32 m0, s82
	s_add_u32 s40, s40, 0x80000
	s_addc_u32 s41, s41, 0
	s_mov_b32 s82, m0
	s_mov_b32 m0, s62
	s_nop 0
	global_load_lds_dwordx4 v1, s[40:41]
	s_mov_b32 m0, s82
	s_nop 0
	s_mov_b32 s82, m0
	s_mov_b32 m0, s63
	s_nop 0
	global_load_lds_dwordx4 v177, s[40:41]
	s_mov_b32 m0, s82
	s_waitcnt vmcnt(8)
	s_waitcnt lgkmcnt(0)
	s_barrier
	s_setprio 1
	s_waitcnt lgkmcnt(7)
	v_mfma_f32_16x16x32_bf16 v[142:145], v[58:61], v[172:175], v[142:145]
	v_mfma_f32_16x16x32_bf16 v[142:145], v[62:65], v[190:193], v[142:145]
	s_waitcnt lgkmcnt(5)
	v_mfma_f32_16x16x32_bf16 v[138:141], v[66:69], v[172:175], v[138:141]
	v_mfma_f32_16x16x32_bf16 v[138:141], v[70:73], v[190:193], v[138:141]
	s_waitcnt lgkmcnt(3)
	v_mfma_f32_16x16x32_bf16 v[126:129], v[58:61], v[194:197], v[126:129]
	v_mfma_f32_16x16x32_bf16 v[126:129], v[62:65], v[198:201], v[126:129]
	s_waitcnt lgkmcnt(1)
	v_mfma_f32_16x16x32_bf16 v[122:125], v[66:69], v[194:197], v[122:125]
	v_mfma_f32_16x16x32_bf16 v[122:125], v[70:73], v[198:201], v[122:125]
	v_mfma_f32_16x16x32_bf16 v[110:113], v[58:61], v[202:205], v[110:113]
	v_mfma_f32_16x16x32_bf16 v[110:113], v[62:65], v[206:209], v[110:113]
	v_mfma_f32_16x16x32_bf16 v[106:109], v[66:69], v[202:205], v[106:109]
	v_mfma_f32_16x16x32_bf16 v[106:109], v[70:73], v[206:209], v[106:109]
	v_mfma_f32_16x16x32_bf16 v[94:97], v[58:61], v[210:213], v[94:97]
	v_mfma_f32_16x16x32_bf16 v[94:97], v[62:65], v[214:217], v[94:97]
	s_waitcnt lgkmcnt(0)
	v_mfma_f32_16x16x32_bf16 v[90:93], v[66:69], v[210:213], v[90:93]
	v_mfma_f32_16x16x32_bf16 v[90:93], v[70:73], v[214:217], v[90:93]
	s_setprio 0
	s_setprio 1
	v_mfma_f32_16x16x32_bf16 v[134:137], v[146:149], v[172:175], v[134:137]
	v_mfma_f32_16x16x32_bf16 v[134:137], v[150:153], v[190:193], v[134:137]
	v_mfma_f32_16x16x32_bf16 v[130:133], v[154:157], v[172:175], v[130:133]
	v_mfma_f32_16x16x32_bf16 v[130:133], v[158:161], v[190:193], v[130:133]
	v_mfma_f32_16x16x32_bf16 v[118:121], v[146:149], v[194:197], v[118:121]
	v_mfma_f32_16x16x32_bf16 v[118:121], v[150:153], v[198:201], v[118:121]
	v_mfma_f32_16x16x32_bf16 v[114:117], v[154:157], v[194:197], v[114:117]
	v_mfma_f32_16x16x32_bf16 v[114:117], v[158:161], v[198:201], v[114:117]
	v_mfma_f32_16x16x32_bf16 v[102:105], v[146:149], v[202:205], v[102:105]
	v_mfma_f32_16x16x32_bf16 v[102:105], v[150:153], v[206:209], v[102:105]
	v_mfma_f32_16x16x32_bf16 v[98:101], v[154:157], v[202:205], v[98:101]
	v_mfma_f32_16x16x32_bf16 v[98:101], v[158:161], v[206:209], v[98:101]
	v_mfma_f32_16x16x32_bf16 v[86:89], v[146:149], v[210:213], v[86:89]
	v_mfma_f32_16x16x32_bf16 v[86:89], v[150:153], v[214:217], v[86:89]
	s_setprio 2
	s_barrier
	v_mfma_f32_16x16x32_bf16 v[82:85], v[154:157], v[210:213], v[82:85]
	v_mfma_f32_16x16x32_bf16 v[82:85], v[158:161], v[214:217], v[82:85]
	s_setprio 0
	ds_read_b128 v[172:175], v183 offset:49152
	ds_read_b128 v[190:193], v183 offset:50176
	ds_read_b128 v[194:197], v183 offset:51200
	ds_read_b128 v[198:201], v183 offset:52224
	ds_read_b128 v[202:205], v183 offset:53248
	ds_read_b128 v[206:209], v183 offset:54272
	ds_read_b128 v[210:213], v183 offset:55296
	ds_read_b128 v[214:217], v183 offset:56320
	s_add_u32 s40, s36, 0x80
	s_addc_u32 s41, s37, 0
	s_mov_b32 s82, m0
	s_mov_b32 m0, s64
	s_nop 0
	global_load_lds_dwordx4 v176, s[40:41]
	s_mov_b32 m0, s82
	s_add_u32 s36, s36, 0x80080
	s_mov_b32 s82, m0
	s_mov_b32 m0, s65
	s_nop 0
	global_load_lds_dwordx4 v178, s[40:41]
	s_mov_b32 m0, s82
	s_addc_u32 s37, s37, 0
	s_mov_b32 s40, m0
	s_mov_b32 m0, s66
	s_nop 0
	global_load_lds_dwordx4 v176, s[36:37]
	s_mov_b32 m0, s40
	s_nop 0
	s_mov_b32 s40, m0
	s_mov_b32 m0, s67
	s_nop 0
	global_load_lds_dwordx4 v178, s[36:37]
	s_mov_b32 m0, s40
	s_waitcnt vmcnt(4)
	s_waitcnt lgkmcnt(0)
	s_barrier
	s_setprio 1
	s_waitcnt lgkmcnt(7)
	v_mfma_f32_16x16x32_bf16 v[78:81], v[58:61], v[172:175], v[78:81]
	v_mfma_f32_16x16x32_bf16 v[78:81], v[62:65], v[190:193], v[78:81]
	s_waitcnt lgkmcnt(5)
	v_mfma_f32_16x16x32_bf16 v[74:77], v[66:69], v[172:175], v[74:77]
	v_mfma_f32_16x16x32_bf16 v[74:77], v[70:73], v[190:193], v[74:77]
	s_waitcnt lgkmcnt(3)
	v_mfma_f32_16x16x32_bf16 v[54:57], v[58:61], v[194:197], v[54:57]
	v_mfma_f32_16x16x32_bf16 v[54:57], v[62:65], v[198:201], v[54:57]
	s_waitcnt lgkmcnt(1)
	v_mfma_f32_16x16x32_bf16 v[50:53], v[66:69], v[194:197], v[50:53]
	v_mfma_f32_16x16x32_bf16 v[50:53], v[70:73], v[198:201], v[50:53]
	v_mfma_f32_16x16x32_bf16 v[30:33], v[58:61], v[202:205], v[30:33]
	v_mfma_f32_16x16x32_bf16 v[30:33], v[62:65], v[206:209], v[30:33]
	v_mfma_f32_16x16x32_bf16 v[26:29], v[66:69], v[202:205], v[26:29]
	v_mfma_f32_16x16x32_bf16 v[26:29], v[70:73], v[206:209], v[26:29]
	v_mfma_f32_16x16x32_bf16 v[14:17], v[58:61], v[210:213], v[14:17]
	v_mfma_f32_16x16x32_bf16 v[14:17], v[62:65], v[214:217], v[14:17]
	s_waitcnt lgkmcnt(0)
	v_mfma_f32_16x16x32_bf16 v[10:13], v[66:69], v[210:213], v[10:13]
	v_mfma_f32_16x16x32_bf16 v[10:13], v[70:73], v[214:217], v[10:13]
	s_setprio 0
	s_setprio 1
	v_mfma_f32_16x16x32_bf16 v[42:45], v[146:149], v[172:175], v[42:45]
	v_mfma_f32_16x16x32_bf16 v[70:73], v[150:153], v[190:193], v[42:45]
	v_mfma_f32_16x16x32_bf16 v[42:45], v[154:157], v[172:175], v[46:49]
	v_mfma_f32_16x16x32_bf16 v[66:69], v[158:161], v[190:193], v[42:45]
	v_mfma_f32_16x16x32_bf16 v[38:41], v[146:149], v[194:197], v[38:41]
	v_mfma_f32_16x16x32_bf16 v[38:41], v[150:153], v[198:201], v[38:41]
	v_mfma_f32_16x16x32_bf16 v[34:37], v[154:157], v[194:197], v[34:37]
	v_mfma_f32_16x16x32_bf16 v[34:37], v[158:161], v[198:201], v[34:37]
	v_mfma_f32_16x16x32_bf16 v[22:25], v[146:149], v[202:205], v[22:25]
	v_mfma_f32_16x16x32_bf16 v[22:25], v[150:153], v[206:209], v[22:25]
	v_mfma_f32_16x16x32_bf16 v[18:21], v[154:157], v[202:205], v[18:21]
	v_mfma_f32_16x16x32_bf16 v[18:21], v[158:161], v[206:209], v[18:21]
	v_mfma_f32_16x16x32_bf16 v[6:9], v[146:149], v[210:213], v[6:9]
	v_mfma_f32_16x16x32_bf16 v[6:9], v[150:153], v[214:217], v[6:9]
	s_setprio 2
	s_barrier
	v_mfma_f32_16x16x32_bf16 v[2:5], v[154:157], v[210:213], v[2:5]
	v_mfma_f32_16x16x32_bf16 v[2:5], v[158:161], v[214:217], v[2:5]
	s_setprio 0
	s_add_i32 s81, s81, 2
	s_add_u32 s77, s77, 0x100
	s_addc_u32 s78, s78, 0
	s_add_u32 s34, s34, 0x100
	s_addc_u32 s35, s35, 0
	s_add_u32 s79, s79, 0x100
	s_addc_u32 s80, s80, 0
	s_cmp_gt_u32 s81, 29
	s_cbranch_scc0 .LBB0_2146
	v_mov_b32_e32 v174, v252
	v_mov_b32_e32 v175, v253
	v_mov_b32_e32 v216, v254
	v_mov_b32_e32 v217, v255
	s_and_b64 vcc, exec, s[14:15]
	s_cbranch_vccz .LBB0_2149
	s_barrier

.LBB0_2409:
	s_ashr_i32 s17, s16, 31
	s_lshl_b64 s[18:19], s[16:17], 20
	s_add_u32 s18, s33, s18
	s_addc_u32 s19, s34, s19
	s_and_b64 s[20:21], s[2:3], exec
	s_cselect_b32 s17, s19, s27
	s_cselect_b32 s71, s18, s26
	s_ashr_i32 s15, s14, 31
	s_lshl_b64 s[20:21], s[14:15], 20
	s_add_u32 s20, s35, s20
	s_addc_u32 s21, s36, s21
	s_and_b64 s[28:29], s[2:3], exec
	s_cselect_b32 s15, s21, s25
	s_cselect_b32 s73, s20, s24
	s_add_u32 s74, s24, 0x100
	s_addc_u32 s75, s25, 0
	s_add_u32 s24, s26, 0x80080
	s_addc_u32 s25, s27, 0
	s_add_u32 s76, s26, 0x100
	s_addc_u32 s77, s27, 0
	s_mov_b32 s78, -2
	s_waitcnt vmcnt(25)
	s_waitcnt vmcnt(24)
	s_waitcnt vmcnt(4)
	s_waitcnt vmcnt(2)
	s_waitcnt vmcnt(1)
	s_waitcnt vmcnt(0)
	v_mov_b32_e32 v252, v174
	v_mov_b32_e32 v253, v175
	v_mov_b32_e32 v254, v210
	v_mov_b32_e32 v255, v211
	ds_read_b128 v[130:133], v181
	ds_read_b128 v[134:137], v181 offset:1024
	ds_read_b128 v[138:141], v181 offset:2048
	ds_read_b128 v[142:145], v181 offset:3072
	ds_read_b128 v[146:149], v182
	ds_read_b128 v[150:153], v182 offset:1024
	ds_read_b128 v[154:157], v182 offset:2048
	ds_read_b128 v[158:161], v182 offset:3072
	s_cmp_eq_u32 s78, 28
	s_cselect_b32 s27, s15, s75
	s_cselect_b32 s26, s73, s74
	s_cselect_b32 s29, s17, s77
	s_cselect_b32 s28, s71, s76
	ds_read_b128 v[168:171], v183
	ds_read_b128 v[172:175], v183 offset:1024
	ds_read_b128 v[188:191], v183 offset:2048
	ds_read_b128 v[192:195], v183 offset:3072
	ds_read_b128 v[196:199], v183 offset:4096
	ds_read_b128 v[200:203], v183 offset:5120
	ds_read_b128 v[204:207], v183 offset:6144
	ds_read_b128 v[208:211], v183 offset:7168
	s_add_u32 s80, s24, 0xfff80000
	s_addc_u32 s81, s25, -1
	s_mov_b32 s79, m0
	s_mov_b32 m0, s64
	s_nop 0
	global_load_lds_dwordx4 v1, s[80:81]
	s_mov_b32 m0, s79
	s_nop 0
	s_mov_b32 s79, m0
	s_mov_b32 m0, s66
	s_nop 0
	global_load_lds_dwordx4 v177, s[80:81]
	s_mov_b32 m0, s79
	s_nop 0
	s_mov_b32 s79, m0
	s_mov_b32 m0, s65
	s_nop 0
	global_load_lds_dwordx4 v1, s[24:25]
	s_mov_b32 m0, s79
	s_nop 0
	s_mov_b32 s79, m0
	s_mov_b32 m0, s67
	s_nop 0
	global_load_lds_dwordx4 v177, s[24:25]
	s_mov_b32 m0, s79
	s_waitcnt vmcnt(8)
	s_waitcnt lgkmcnt(0)
	s_barrier
	s_setprio 1
	s_waitcnt lgkmcnt(7)
	v_mfma_f32_16x16x32_bf16 v[126:129], v[130:133], v[168:171], 0
	v_mfma_f32_16x16x32_bf16 v[126:129], v[134:137], v[172:175], v[126:129]
	s_waitcnt lgkmcnt(5)
	v_mfma_f32_16x16x32_bf16 v[122:125], v[138:141], v[168:171], 0
	v_mfma_f32_16x16x32_bf16 v[122:125], v[142:145], v[172:175], v[122:125]
	s_waitcnt lgkmcnt(3)
	v_mfma_f32_16x16x32_bf16 v[114:117], v[138:141], v[188:191], 0
	v_mfma_f32_16x16x32_bf16 v[114:117], v[142:145], v[192:195], v[114:117]
	s_waitcnt lgkmcnt(1)
	v_mfma_f32_16x16x32_bf16 v[118:121], v[130:133], v[188:191], 0
	v_mfma_f32_16x16x32_bf16 v[118:121], v[134:137], v[192:195], v[118:121]
	v_mfma_f32_16x16x32_bf16 v[94:97], v[130:133], v[196:199], 0
	v_mfma_f32_16x16x32_bf16 v[94:97], v[134:137], v[200:203], v[94:97]
	v_mfma_f32_16x16x32_bf16 v[90:93], v[138:141], v[196:199], 0
	v_mfma_f32_16x16x32_bf16 v[90:93], v[142:145], v[200:203], v[90:93]
	v_mfma_f32_16x16x32_bf16 v[78:81], v[138:141], v[204:207], 0
	v_mfma_f32_16x16x32_bf16 v[78:81], v[142:145], v[208:211], v[78:81]
	s_waitcnt lgkmcnt(0)
	v_mfma_f32_16x16x32_bf16 v[86:89], v[130:133], v[204:207], 0
	v_mfma_f32_16x16x32_bf16 v[86:89], v[134:137], v[208:211], v[86:89]
	s_setprio 0
	s_setprio 1
	v_mfma_f32_16x16x32_bf16 v[110:113], v[146:149], v[168:171], 0
	v_mfma_f32_16x16x32_bf16 v[110:113], v[150:153], v[172:175], v[110:113]
	v_mfma_f32_16x16x32_bf16 v[106:109], v[154:157], v[168:171], 0
	v_mfma_f32_16x16x32_bf16 v[106:109], v[158:161], v[172:175], v[106:109]
	v_mfma_f32_16x16x32_bf16 v[98:101], v[154:157], v[188:191], 0
	v_mfma_f32_16x16x32_bf16 v[98:101], v[158:161], v[192:195], v[98:101]
	v_mfma_f32_16x16x32_bf16 v[102:105], v[146:149], v[188:191], 0
	v_mfma_f32_16x16x32_bf16 v[102:105], v[150:153], v[192:195], v[102:105]
	v_mfma_f32_16x16x32_bf16 v[82:85], v[146:149], v[196:199], 0
	v_mfma_f32_16x16x32_bf16 v[82:85], v[150:153], v[200:203], v[82:85]
	v_mfma_f32_16x16x32_bf16 v[74:77], v[154:157], v[196:199], 0
	v_mfma_f32_16x16x32_bf16 v[74:77], v[158:161], v[200:203], v[74:77]
	v_mfma_f32_16x16x32_bf16 v[66:69], v[154:157], v[204:207], 0
	v_mfma_f32_16x16x32_bf16 v[66:69], v[158:161], v[208:211], v[66:69]
	s_setprio 2
	s_barrier
	v_mfma_f32_16x16x32_bf16 v[70:73], v[146:149], v[204:207], 0
	v_mfma_f32_16x16x32_bf16 v[70:73], v[150:153], v[208:211], v[70:73]
	s_setprio 0
	ds_read_b128 v[168:171], v183 offset:16384
	ds_read_b128 v[172:175], v183 offset:17408
	ds_read_b128 v[188:191], v183 offset:18432
	ds_read_b128 v[192:195], v183 offset:19456
	ds_read_b128 v[196:199], v183 offset:20480
	ds_read_b128 v[200:203], v183 offset:21504
	ds_read_b128 v[204:207], v183 offset:22528
	ds_read_b128 v[208:211], v183 offset:23552
	s_mov_b32 s79, m0
	s_mov_b32 m0, s41
	s_nop 0
	global_load_lds_dwordx4 v176, s[26:27]
	s_mov_b32 m0, s79
	s_add_u32 s80, s26, 0x80000
	s_mov_b32 s79, m0
	s_mov_b32 m0, s42
	s_nop 0
	global_load_lds_dwordx4 v178, s[26:27]
	s_mov_b32 m0, s79
	s_addc_u32 s81, s27, 0
	s_mov_b32 s79, m0
	s_mov_b32 m0, s43
	s_nop 0
	global_load_lds_dwordx4 v176, s[80:81]
	s_mov_b32 m0, s79
	s_nop 0
	s_mov_b32 s79, m0
	s_mov_b32 m0, s46
	s_nop 0
	global_load_lds_dwordx4 v178, s[80:81]
	s_mov_b32 m0, s79
	s_waitcnt vmcnt(4)
	s_waitcnt lgkmcnt(0)
	s_barrier
	s_setprio 1
	s_waitcnt lgkmcnt(7)
	v_mfma_f32_16x16x32_bf16 v[62:65], v[130:133], v[168:171], 0
	v_mfma_f32_16x16x32_bf16 v[62:65], v[134:137], v[172:175], v[62:65]
	s_waitcnt lgkmcnt(5)
	v_mfma_f32_16x16x32_bf16 v[58:61], v[138:141], v[168:171], 0
	v_mfma_f32_16x16x32_bf16 v[58:61], v[142:145], v[172:175], v[58:61]
	s_waitcnt lgkmcnt(3)
	v_mfma_f32_16x16x32_bf16 v[42:45], v[138:141], v[188:191], 0
	v_mfma_f32_16x16x32_bf16 v[42:45], v[142:145], v[192:195], v[42:45]
	s_waitcnt lgkmcnt(1)
	v_mfma_f32_16x16x32_bf16 v[46:49], v[130:133], v[188:191], 0
	v_mfma_f32_16x16x32_bf16 v[46:49], v[134:137], v[192:195], v[46:49]
	v_mfma_f32_16x16x32_bf16 v[30:33], v[130:133], v[196:199], 0
	v_mfma_f32_16x16x32_bf16 v[30:33], v[134:137], v[200:203], v[30:33]
	v_mfma_f32_16x16x32_bf16 v[26:29], v[138:141], v[196:199], 0
	v_mfma_f32_16x16x32_bf16 v[26:29], v[142:145], v[200:203], v[26:29]
	v_mfma_f32_16x16x32_bf16 v[10:13], v[138:141], v[204:207], 0
	v_mfma_f32_16x16x32_bf16 v[10:13], v[142:145], v[208:211], v[10:13]
	s_waitcnt lgkmcnt(0)
	v_mfma_f32_16x16x32_bf16 v[14:17], v[130:133], v[204:207], 0
	v_mfma_f32_16x16x32_bf16 v[14:17], v[134:137], v[208:211], v[14:17]
	s_setprio 0
	s_setprio 1
	v_mfma_f32_16x16x32_bf16 v[54:57], v[146:149], v[168:171], 0
	v_mfma_f32_16x16x32_bf16 v[54:57], v[150:153], v[172:175], v[54:57]
	v_mfma_f32_16x16x32_bf16 v[50:53], v[154:157], v[168:171], 0
	v_mfma_f32_16x16x32_bf16 v[50:53], v[158:161], v[172:175], v[50:53]
	v_mfma_f32_16x16x32_bf16 v[34:37], v[154:157], v[188:191], 0
	v_mfma_f32_16x16x32_bf16 v[34:37], v[158:161], v[192:195], v[34:37]
	v_mfma_f32_16x16x32_bf16 v[38:41], v[146:149], v[188:191], 0
	v_mfma_f32_16x16x32_bf16 v[38:41], v[150:153], v[192:195], v[38:41]
	v_mfma_f32_16x16x32_bf16 v[22:25], v[146:149], v[196:199], 0
	v_mfma_f32_16x16x32_bf16 v[22:25], v[150:153], v[200:203], v[22:25]
	v_mfma_f32_16x16x32_bf16 v[18:21], v[154:157], v[196:199], 0
	v_mfma_f32_16x16x32_bf16 v[18:21], v[158:161], v[200:203], v[18:21]
	v_mfma_f32_16x16x32_bf16 v[2:5], v[154:157], v[204:207], 0
	v_mfma_f32_16x16x32_bf16 v[2:5], v[158:161], v[208:211], v[2:5]
	s_setprio 2
	s_barrier
	v_mfma_f32_16x16x32_bf16 v[6:9], v[146:149], v[204:207], 0
	v_mfma_f32_16x16x32_bf16 v[6:9], v[150:153], v[208:211], v[6:9]
	s_setprio 0
	ds_read_b128 v[130:133], v184
	ds_read_b128 v[134:137], v184 offset:1024
	ds_read_b128 v[138:141], v184 offset:2048
	ds_read_b128 v[142:145], v184 offset:3072
	ds_read_b128 v[146:149], v185
	ds_read_b128 v[150:153], v185 offset:1024
	ds_read_b128 v[154:157], v185 offset:2048
	ds_read_b128 v[158:161], v185 offset:3072
	ds_read_b128 v[168:171], v183 offset:32768
	ds_read_b128 v[172:175], v183 offset:33792
	ds_read_b128 v[188:191], v183 offset:34816
	ds_read_b128 v[192:195], v183 offset:35840
	ds_read_b128 v[196:199], v183 offset:36864
	ds_read_b128 v[200:203], v183 offset:37888
	ds_read_b128 v[204:207], v183 offset:38912
	ds_read_b128 v[208:211], v183 offset:39936
	s_mov_b32 s79, m0
	s_mov_b32 m0, s40
	s_nop 0
	global_load_lds_dwordx4 v1, s[28:29]
	s_mov_b32 m0, s79
	s_nop 0
	s_mov_b32 s79, m0
	s_mov_b32 m0, s47
	s_nop 0
	global_load_lds_dwordx4 v177, s[28:29]
	s_mov_b32 m0, s79
	s_add_u32 s28, s28, 0x80000
	s_addc_u32 s29, s29, 0
	s_mov_b32 s79, m0
	s_mov_b32 m0, s48
	s_nop 0
	global_load_lds_dwordx4 v1, s[28:29]
	s_mov_b32 m0, s79
	s_nop 0
	s_mov_b32 s79, m0
	s_mov_b32 m0, s49
	s_nop 0
	global_load_lds_dwordx4 v177, s[28:29]
	s_mov_b32 m0, s79
	s_waitcnt vmcnt(8)
	s_waitcnt lgkmcnt(0)
	s_barrier
	s_setprio 1
	s_waitcnt lgkmcnt(7)
	v_mfma_f32_16x16x32_bf16 v[126:129], v[130:133], v[168:171], v[126:129]
	v_mfma_f32_16x16x32_bf16 v[126:129], v[134:137], v[172:175], v[126:129]
	s_waitcnt lgkmcnt(5)
	v_mfma_f32_16x16x32_bf16 v[122:125], v[138:141], v[168:171], v[122:125]
	v_mfma_f32_16x16x32_bf16 v[122:125], v[142:145], v[172:175], v[122:125]
	s_waitcnt lgkmcnt(3)
	v_mfma_f32_16x16x32_bf16 v[114:117], v[138:141], v[188:191], v[114:117]
	v_mfma_f32_16x16x32_bf16 v[114:117], v[142:145], v[192:195], v[114:117]
	s_waitcnt lgkmcnt(1)
	v_mfma_f32_16x16x32_bf16 v[118:121], v[130:133], v[188:191], v[118:121]
	v_mfma_f32_16x16x32_bf16 v[118:121], v[134:137], v[192:195], v[118:121]
	v_mfma_f32_16x16x32_bf16 v[94:97], v[130:133], v[196:199], v[94:97]
	v_mfma_f32_16x16x32_bf16 v[94:97], v[134:137], v[200:203], v[94:97]
	v_mfma_f32_16x16x32_bf16 v[90:93], v[138:141], v[196:199], v[90:93]
	v_mfma_f32_16x16x32_bf16 v[90:93], v[142:145], v[200:203], v[90:93]
	v_mfma_f32_16x16x32_bf16 v[78:81], v[138:141], v[204:207], v[78:81]
	v_mfma_f32_16x16x32_bf16 v[78:81], v[142:145], v[208:211], v[78:81]
	s_waitcnt lgkmcnt(0)
	v_mfma_f32_16x16x32_bf16 v[86:89], v[130:133], v[204:207], v[86:89]
	v_mfma_f32_16x16x32_bf16 v[86:89], v[134:137], v[208:211], v[86:89]
	s_setprio 0
	s_setprio 1
	v_mfma_f32_16x16x32_bf16 v[110:113], v[146:149], v[168:171], v[110:113]
	v_mfma_f32_16x16x32_bf16 v[110:113], v[150:153], v[172:175], v[110:113]
	v_mfma_f32_16x16x32_bf16 v[106:109], v[154:157], v[168:171], v[106:109]
	v_mfma_f32_16x16x32_bf16 v[106:109], v[158:161], v[172:175], v[106:109]
	v_mfma_f32_16x16x32_bf16 v[98:101], v[154:157], v[188:191], v[98:101]
	v_mfma_f32_16x16x32_bf16 v[98:101], v[158:161], v[192:195], v[98:101]
	v_mfma_f32_16x16x32_bf16 v[102:105], v[146:149], v[188:191], v[102:105]
	v_mfma_f32_16x16x32_bf16 v[102:105], v[150:153], v[192:195], v[102:105]
	v_mfma_f32_16x16x32_bf16 v[82:85], v[146:149], v[196:199], v[82:85]
	v_mfma_f32_16x16x32_bf16 v[82:85], v[150:153], v[200:203], v[82:85]
	v_mfma_f32_16x16x32_bf16 v[74:77], v[154:157], v[196:199], v[74:77]
	v_mfma_f32_16x16x32_bf16 v[74:77], v[158:161], v[200:203], v[74:77]
	v_mfma_f32_16x16x32_bf16 v[66:69], v[154:157], v[204:207], v[66:69]
	v_mfma_f32_16x16x32_bf16 v[66:69], v[158:161], v[208:211], v[66:69]
	s_setprio 2
	s_barrier
	v_mfma_f32_16x16x32_bf16 v[70:73], v[146:149], v[204:207], v[70:73]
	v_mfma_f32_16x16x32_bf16 v[70:73], v[150:153], v[208:211], v[70:73]
	s_setprio 0
	ds_read_b128 v[168:171], v183 offset:49152
	ds_read_b128 v[172:175], v183 offset:50176
	ds_read_b128 v[188:191], v183 offset:51200
	ds_read_b128 v[192:195], v183 offset:52224
	ds_read_b128 v[196:199], v183 offset:53248
	ds_read_b128 v[200:203], v183 offset:54272
	ds_read_b128 v[204:207], v183 offset:55296
	ds_read_b128 v[208:211], v183 offset:56320
	s_add_u32 s28, s26, 0x80
	s_addc_u32 s29, s27, 0
	s_mov_b32 s79, m0
	s_mov_b32 m0, s56
	s_nop 0
	global_load_lds_dwordx4 v176, s[28:29]
	s_mov_b32 m0, s79
	s_add_u32 s26, s26, 0x80080
	s_mov_b32 s79, m0
	s_mov_b32 m0, s57
	s_nop 0
	global_load_lds_dwordx4 v178, s[28:29]
	s_mov_b32 m0, s79
	s_addc_u32 s27, s27, 0
	s_mov_b32 s28, m0
	s_mov_b32 m0, s58
	s_nop 0
	global_load_lds_dwordx4 v176, s[26:27]
	s_mov_b32 m0, s28
	s_nop 0
	s_mov_b32 s28, m0
	s_mov_b32 m0, s59
	s_nop 0
	global_load_lds_dwordx4 v178, s[26:27]
	s_mov_b32 m0, s28
	s_waitcnt vmcnt(4)
	s_waitcnt lgkmcnt(0)
	s_barrier
	s_setprio 1
	s_waitcnt lgkmcnt(7)
	v_mfma_f32_16x16x32_bf16 v[62:65], v[130:133], v[168:171], v[62:65]
	v_mfma_f32_16x16x32_bf16 v[62:65], v[134:137], v[172:175], v[62:65]
	s_waitcnt lgkmcnt(5)
	v_mfma_f32_16x16x32_bf16 v[58:61], v[138:141], v[168:171], v[58:61]
	v_mfma_f32_16x16x32_bf16 v[58:61], v[142:145], v[172:175], v[58:61]
	s_waitcnt lgkmcnt(3)
	v_mfma_f32_16x16x32_bf16 v[42:45], v[138:141], v[188:191], v[42:45]
	v_mfma_f32_16x16x32_bf16 v[42:45], v[142:145], v[192:195], v[42:45]
	s_waitcnt lgkmcnt(1)
	v_mfma_f32_16x16x32_bf16 v[46:49], v[130:133], v[188:191], v[46:49]
	v_mfma_f32_16x16x32_bf16 v[46:49], v[134:137], v[192:195], v[46:49]
	v_mfma_f32_16x16x32_bf16 v[30:33], v[130:133], v[196:199], v[30:33]
	v_mfma_f32_16x16x32_bf16 v[30:33], v[134:137], v[200:203], v[30:33]
	v_mfma_f32_16x16x32_bf16 v[26:29], v[138:141], v[196:199], v[26:29]
	v_mfma_f32_16x16x32_bf16 v[26:29], v[142:145], v[200:203], v[26:29]
	v_mfma_f32_16x16x32_bf16 v[10:13], v[138:141], v[204:207], v[10:13]
	v_mfma_f32_16x16x32_bf16 v[10:13], v[142:145], v[208:211], v[10:13]
	s_waitcnt lgkmcnt(0)
	v_mfma_f32_16x16x32_bf16 v[14:17], v[130:133], v[204:207], v[14:17]
	v_mfma_f32_16x16x32_bf16 v[14:17], v[134:137], v[208:211], v[14:17]
	s_setprio 0
	s_setprio 1
	v_mfma_f32_16x16x32_bf16 v[54:57], v[146:149], v[168:171], v[54:57]
	v_mfma_f32_16x16x32_bf16 v[54:57], v[150:153], v[172:175], v[54:57]
	v_mfma_f32_16x16x32_bf16 v[50:53], v[154:157], v[168:171], v[50:53]
	v_mfma_f32_16x16x32_bf16 v[50:53], v[158:161], v[172:175], v[50:53]
	v_mfma_f32_16x16x32_bf16 v[34:37], v[154:157], v[188:191], v[34:37]
	v_mfma_f32_16x16x32_bf16 v[34:37], v[158:161], v[192:195], v[34:37]
	v_mfma_f32_16x16x32_bf16 v[38:41], v[146:149], v[188:191], v[38:41]
	v_mfma_f32_16x16x32_bf16 v[38:41], v[150:153], v[192:195], v[38:41]
	v_mfma_f32_16x16x32_bf16 v[22:25], v[146:149], v[196:199], v[22:25]
	v_mfma_f32_16x16x32_bf16 v[22:25], v[150:153], v[200:203], v[22:25]
	v_mfma_f32_16x16x32_bf16 v[18:21], v[154:157], v[196:199], v[18:21]
	v_mfma_f32_16x16x32_bf16 v[18:21], v[158:161], v[200:203], v[18:21]
	v_mfma_f32_16x16x32_bf16 v[2:5], v[154:157], v[204:207], v[2:5]
	v_mfma_f32_16x16x32_bf16 v[2:5], v[158:161], v[208:211], v[2:5]
	s_setprio 2
	s_barrier
	v_mfma_f32_16x16x32_bf16 v[6:9], v[146:149], v[204:207], v[6:9]
	v_mfma_f32_16x16x32_bf16 v[6:9], v[150:153], v[208:211], v[6:9]
	s_setprio 0
	s_add_i32 s78, s78, 2
	s_add_u32 s74, s74, 0x100
	s_addc_u32 s75, s75, 0
	s_add_u32 s24, s24, 0x100
	s_addc_u32 s25, s25, 0
	s_add_u32 s76, s76, 0x100
	s_addc_u32 s77, s77, 0
	s_cmp_gt_u32 s78, 29
	.p2align 6
.LBB0_2410:
	ds_read_b128 v[130:133], v181
	ds_read_b128 v[134:137], v181 offset:1024
	ds_read_b128 v[138:141], v181 offset:2048
	ds_read_b128 v[142:145], v181 offset:3072
	ds_read_b128 v[146:149], v182
	ds_read_b128 v[150:153], v182 offset:1024
	ds_read_b128 v[154:157], v182 offset:2048
	ds_read_b128 v[158:161], v182 offset:3072
	s_cmp_eq_u32 s78, 28
	s_cselect_b32 s27, s15, s75
	s_cselect_b32 s26, s73, s74
	s_cselect_b32 s29, s17, s77
	s_cselect_b32 s28, s71, s76
	ds_read_b128 v[168:171], v183
	ds_read_b128 v[172:175], v183 offset:1024
	ds_read_b128 v[188:191], v183 offset:2048
	ds_read_b128 v[192:195], v183 offset:3072
	ds_read_b128 v[196:199], v183 offset:4096
	ds_read_b128 v[200:203], v183 offset:5120
	ds_read_b128 v[204:207], v183 offset:6144
	ds_read_b128 v[208:211], v183 offset:7168
	s_add_u32 s80, s24, 0xfff80000
	s_addc_u32 s81, s25, -1
	s_mov_b32 s79, m0
	s_mov_b32 m0, s64
	s_nop 0
	global_load_lds_dwordx4 v1, s[80:81]
	s_mov_b32 m0, s79
	s_nop 0
	s_mov_b32 s79, m0
	s_mov_b32 m0, s66
	s_nop 0
	global_load_lds_dwordx4 v177, s[80:81]
	s_mov_b32 m0, s79
	s_nop 0
	s_mov_b32 s79, m0
	s_mov_b32 m0, s65
	s_nop 0
	global_load_lds_dwordx4 v1, s[24:25]
	s_mov_b32 m0, s79
	s_nop 0
	s_mov_b32 s79, m0
	s_mov_b32 m0, s67
	s_nop 0
	global_load_lds_dwordx4 v177, s[24:25]
	s_mov_b32 m0, s79
	s_waitcnt vmcnt(8)
	s_waitcnt lgkmcnt(0)
	s_barrier
	s_setprio 1
	s_waitcnt lgkmcnt(7)
	v_mfma_f32_16x16x32_bf16 v[126:129], v[130:133], v[168:171], v[126:129]
	v_mfma_f32_16x16x32_bf16 v[126:129], v[134:137], v[172:175], v[126:129]
	s_waitcnt lgkmcnt(5)
	v_mfma_f32_16x16x32_bf16 v[122:125], v[138:141], v[168:171], v[122:125]
	v_mfma_f32_16x16x32_bf16 v[122:125], v[142:145], v[172:175], v[122:125]
	s_waitcnt lgkmcnt(3)
	v_mfma_f32_16x16x32_bf16 v[114:117], v[138:141], v[188:191], v[114:117]
	v_mfma_f32_16x16x32_bf16 v[114:117], v[142:145], v[192:195], v[114:117]
	s_waitcnt lgkmcnt(1)
	v_mfma_f32_16x16x32_bf16 v[118:121], v[130:133], v[188:191], v[118:121]
	v_mfma_f32_16x16x32_bf16 v[118:121], v[134:137], v[192:195], v[118:121]
	v_mfma_f32_16x16x32_bf16 v[94:97], v[130:133], v[196:199], v[94:97]
	v_mfma_f32_16x16x32_bf16 v[94:97], v[134:137], v[200:203], v[94:97]
	v_mfma_f32_16x16x32_bf16 v[90:93], v[138:141], v[196:199], v[90:93]
	v_mfma_f32_16x16x32_bf16 v[90:93], v[142:145], v[200:203], v[90:93]
	v_mfma_f32_16x16x32_bf16 v[78:81], v[138:141], v[204:207], v[78:81]
	v_mfma_f32_16x16x32_bf16 v[78:81], v[142:145], v[208:211], v[78:81]
	s_waitcnt lgkmcnt(0)
	v_mfma_f32_16x16x32_bf16 v[86:89], v[130:133], v[204:207], v[86:89]
	v_mfma_f32_16x16x32_bf16 v[86:89], v[134:137], v[208:211], v[86:89]
	s_setprio 0
	s_setprio 1
	v_mfma_f32_16x16x32_bf16 v[110:113], v[146:149], v[168:171], v[110:113]
	v_mfma_f32_16x16x32_bf16 v[110:113], v[150:153], v[172:175], v[110:113]
	v_mfma_f32_16x16x32_bf16 v[106:109], v[154:157], v[168:171], v[106:109]
	v_mfma_f32_16x16x32_bf16 v[106:109], v[158:161], v[172:175], v[106:109]
	v_mfma_f32_16x16x32_bf16 v[98:101], v[154:157], v[188:191], v[98:101]
	v_mfma_f32_16x16x32_bf16 v[98:101], v[158:161], v[192:195], v[98:101]
	v_mfma_f32_16x16x32_bf16 v[102:105], v[146:149], v[188:191], v[102:105]
	v_mfma_f32_16x16x32_bf16 v[102:105], v[150:153], v[192:195], v[102:105]
	v_mfma_f32_16x16x32_bf16 v[82:85], v[146:149], v[196:199], v[82:85]
	v_mfma_f32_16x16x32_bf16 v[82:85], v[150:153], v[200:203], v[82:85]
	v_mfma_f32_16x16x32_bf16 v[74:77], v[154:157], v[196:199], v[74:77]
	v_mfma_f32_16x16x32_bf16 v[74:77], v[158:161], v[200:203], v[74:77]
	v_mfma_f32_16x16x32_bf16 v[66:69], v[154:157], v[204:207], v[66:69]
	v_mfma_f32_16x16x32_bf16 v[66:69], v[158:161], v[208:211], v[66:69]
	s_setprio 2
	s_barrier
	v_mfma_f32_16x16x32_bf16 v[70:73], v[146:149], v[204:207], v[70:73]
	v_mfma_f32_16x16x32_bf16 v[70:73], v[150:153], v[208:211], v[70:73]
	s_setprio 0
	ds_read_b128 v[168:171], v183 offset:16384
	ds_read_b128 v[172:175], v183 offset:17408
	ds_read_b128 v[188:191], v183 offset:18432
	ds_read_b128 v[192:195], v183 offset:19456
	ds_read_b128 v[196:199], v183 offset:20480
	ds_read_b128 v[200:203], v183 offset:21504
	ds_read_b128 v[204:207], v183 offset:22528
	ds_read_b128 v[208:211], v183 offset:23552
	s_mov_b32 s79, m0
	s_mov_b32 m0, s41
	s_nop 0
	global_load_lds_dwordx4 v176, s[26:27]
	s_mov_b32 m0, s79
	s_add_u32 s80, s26, 0x80000
	s_mov_b32 s79, m0
	s_mov_b32 m0, s42
	s_nop 0
	global_load_lds_dwordx4 v178, s[26:27]
	s_mov_b32 m0, s79
	s_addc_u32 s81, s27, 0
	s_mov_b32 s79, m0
	s_mov_b32 m0, s43
	s_nop 0
	global_load_lds_dwordx4 v176, s[80:81]
	s_mov_b32 m0, s79
	s_nop 0
	s_mov_b32 s79, m0
	s_mov_b32 m0, s46
	s_nop 0
	global_load_lds_dwordx4 v178, s[80:81]
	s_mov_b32 m0, s79
	s_waitcnt vmcnt(4)
	s_waitcnt lgkmcnt(0)
	s_barrier
	s_setprio 1
	s_waitcnt lgkmcnt(7)
	v_mfma_f32_16x16x32_bf16 v[62:65], v[130:133], v[168:171], v[62:65]
	v_mfma_f32_16x16x32_bf16 v[62:65], v[134:137], v[172:175], v[62:65]
	s_waitcnt lgkmcnt(5)
	v_mfma_f32_16x16x32_bf16 v[58:61], v[138:141], v[168:171], v[58:61]
	v_mfma_f32_16x16x32_bf16 v[58:61], v[142:145], v[172:175], v[58:61]
	s_waitcnt lgkmcnt(3)
	v_mfma_f32_16x16x32_bf16 v[42:45], v[138:141], v[188:191], v[42:45]
	v_mfma_f32_16x16x32_bf16 v[42:45], v[142:145], v[192:195], v[42:45]
	s_waitcnt lgkmcnt(1)
	v_mfma_f32_16x16x32_bf16 v[46:49], v[130:133], v[188:191], v[46:49]
	v_mfma_f32_16x16x32_bf16 v[46:49], v[134:137], v[192:195], v[46:49]
	v_mfma_f32_16x16x32_bf16 v[30:33], v[130:133], v[196:199], v[30:33]
	v_mfma_f32_16x16x32_bf16 v[30:33], v[134:137], v[200:203], v[30:33]
	v_mfma_f32_16x16x32_bf16 v[26:29], v[138:141], v[196:199], v[26:29]
	v_mfma_f32_16x16x32_bf16 v[26:29], v[142:145], v[200:203], v[26:29]
	v_mfma_f32_16x16x32_bf16 v[10:13], v[138:141], v[204:207], v[10:13]
	v_mfma_f32_16x16x32_bf16 v[10:13], v[142:145], v[208:211], v[10:13]
	s_waitcnt lgkmcnt(0)
	v_mfma_f32_16x16x32_bf16 v[14:17], v[130:133], v[204:207], v[14:17]
	v_mfma_f32_16x16x32_bf16 v[14:17], v[134:137], v[208:211], v[14:17]
	s_setprio 0
	s_setprio 1
	v_mfma_f32_16x16x32_bf16 v[54:57], v[146:149], v[168:171], v[54:57]
	v_mfma_f32_16x16x32_bf16 v[54:57], v[150:153], v[172:175], v[54:57]
	v_mfma_f32_16x16x32_bf16 v[50:53], v[154:157], v[168:171], v[50:53]
	v_mfma_f32_16x16x32_bf16 v[50:53], v[158:161], v[172:175], v[50:53]
	v_mfma_f32_16x16x32_bf16 v[34:37], v[154:157], v[188:191], v[34:37]
	v_mfma_f32_16x16x32_bf16 v[34:37], v[158:161], v[192:195], v[34:37]
	v_mfma_f32_16x16x32_bf16 v[38:41], v[146:149], v[188:191], v[38:41]
	v_mfma_f32_16x16x32_bf16 v[38:41], v[150:153], v[192:195], v[38:41]
	v_mfma_f32_16x16x32_bf16 v[22:25], v[146:149], v[196:199], v[22:25]
	v_mfma_f32_16x16x32_bf16 v[22:25], v[150:153], v[200:203], v[22:25]
	v_mfma_f32_16x16x32_bf16 v[18:21], v[154:157], v[196:199], v[18:21]
	v_mfma_f32_16x16x32_bf16 v[18:21], v[158:161], v[200:203], v[18:21]
	v_mfma_f32_16x16x32_bf16 v[2:5], v[154:157], v[204:207], v[2:5]
	v_mfma_f32_16x16x32_bf16 v[2:5], v[158:161], v[208:211], v[2:5]
	s_setprio 2
	s_barrier
	v_mfma_f32_16x16x32_bf16 v[6:9], v[146:149], v[204:207], v[6:9]
	v_mfma_f32_16x16x32_bf16 v[6:9], v[150:153], v[208:211], v[6:9]
	s_setprio 0
	ds_read_b128 v[130:133], v184
	ds_read_b128 v[134:137], v184 offset:1024
	ds_read_b128 v[138:141], v184 offset:2048
	ds_read_b128 v[142:145], v184 offset:3072
	ds_read_b128 v[146:149], v185
	ds_read_b128 v[150:153], v185 offset:1024
	ds_read_b128 v[154:157], v185 offset:2048
	ds_read_b128 v[158:161], v185 offset:3072
	ds_read_b128 v[168:171], v183 offset:32768
	ds_read_b128 v[172:175], v183 offset:33792
	ds_read_b128 v[188:191], v183 offset:34816
	ds_read_b128 v[192:195], v183 offset:35840
	ds_read_b128 v[196:199], v183 offset:36864
	ds_read_b128 v[200:203], v183 offset:37888
	ds_read_b128 v[204:207], v183 offset:38912
	ds_read_b128 v[208:211], v183 offset:39936
	s_mov_b32 s79, m0
	s_mov_b32 m0, s40
	s_nop 0
	global_load_lds_dwordx4 v1, s[28:29]
	s_mov_b32 m0, s79
	s_nop 0
	s_mov_b32 s79, m0
	s_mov_b32 m0, s47
	s_nop 0
	global_load_lds_dwordx4 v177, s[28:29]
	s_mov_b32 m0, s79
	s_add_u32 s28, s28, 0x80000
	s_addc_u32 s29, s29, 0
	s_mov_b32 s79, m0
	s_mov_b32 m0, s48
	s_nop 0
	global_load_lds_dwordx4 v1, s[28:29]
	s_mov_b32 m0, s79
	s_nop 0
	s_mov_b32 s79, m0
	s_mov_b32 m0, s49
	s_nop 0
	global_load_lds_dwordx4 v177, s[28:29]
	s_mov_b32 m0, s79
	s_waitcnt vmcnt(8)
	s_waitcnt lgkmcnt(0)
	s_barrier
	s_setprio 1
	s_waitcnt lgkmcnt(7)
	v_mfma_f32_16x16x32_bf16 v[126:129], v[130:133], v[168:171], v[126:129]
	v_mfma_f32_16x16x32_bf16 v[126:129], v[134:137], v[172:175], v[126:129]
	s_waitcnt lgkmcnt(5)
	v_mfma_f32_16x16x32_bf16 v[122:125], v[138:141], v[168:171], v[122:125]
	v_mfma_f32_16x16x32_bf16 v[122:125], v[142:145], v[172:175], v[122:125]
	s_waitcnt lgkmcnt(3)
	v_mfma_f32_16x16x32_bf16 v[114:117], v[138:141], v[188:191], v[114:117]
	v_mfma_f32_16x16x32_bf16 v[114:117], v[142:145], v[192:195], v[114:117]
	s_waitcnt lgkmcnt(1)
	v_mfma_f32_16x16x32_bf16 v[118:121], v[130:133], v[188:191], v[118:121]
	v_mfma_f32_16x16x32_bf16 v[118:121], v[134:137], v[192:195], v[118:121]
	v_mfma_f32_16x16x32_bf16 v[94:97], v[130:133], v[196:199], v[94:97]
	v_mfma_f32_16x16x32_bf16 v[94:97], v[134:137], v[200:203], v[94:97]
	v_mfma_f32_16x16x32_bf16 v[90:93], v[138:141], v[196:199], v[90:93]
	v_mfma_f32_16x16x32_bf16 v[90:93], v[142:145], v[200:203], v[90:93]
	v_mfma_f32_16x16x32_bf16 v[78:81], v[138:141], v[204:207], v[78:81]
	v_mfma_f32_16x16x32_bf16 v[78:81], v[142:145], v[208:211], v[78:81]
	s_waitcnt lgkmcnt(0)
	v_mfma_f32_16x16x32_bf16 v[86:89], v[130:133], v[204:207], v[86:89]
	v_mfma_f32_16x16x32_bf16 v[86:89], v[134:137], v[208:211], v[86:89]
	s_setprio 0
	s_setprio 1
	v_mfma_f32_16x16x32_bf16 v[110:113], v[146:149], v[168:171], v[110:113]
	v_mfma_f32_16x16x32_bf16 v[110:113], v[150:153], v[172:175], v[110:113]
	v_mfma_f32_16x16x32_bf16 v[106:109], v[154:157], v[168:171], v[106:109]
	v_mfma_f32_16x16x32_bf16 v[106:109], v[158:161], v[172:175], v[106:109]
	v_mfma_f32_16x16x32_bf16 v[98:101], v[154:157], v[188:191], v[98:101]
	v_mfma_f32_16x16x32_bf16 v[98:101], v[158:161], v[192:195], v[98:101]
	v_mfma_f32_16x16x32_bf16 v[102:105], v[146:149], v[188:191], v[102:105]
	v_mfma_f32_16x16x32_bf16 v[102:105], v[150:153], v[192:195], v[102:105]
	v_mfma_f32_16x16x32_bf16 v[82:85], v[146:149], v[196:199], v[82:85]
	v_mfma_f32_16x16x32_bf16 v[82:85], v[150:153], v[200:203], v[82:85]
	v_mfma_f32_16x16x32_bf16 v[74:77], v[154:157], v[196:199], v[74:77]
	v_mfma_f32_16x16x32_bf16 v[74:77], v[158:161], v[200:203], v[74:77]
	v_mfma_f32_16x16x32_bf16 v[66:69], v[154:157], v[204:207], v[66:69]
	v_mfma_f32_16x16x32_bf16 v[66:69], v[158:161], v[208:211], v[66:69]
	s_setprio 2
	s_barrier
	v_mfma_f32_16x16x32_bf16 v[70:73], v[146:149], v[204:207], v[70:73]
	v_mfma_f32_16x16x32_bf16 v[70:73], v[150:153], v[208:211], v[70:73]
	s_setprio 0
	ds_read_b128 v[168:171], v183 offset:49152
	ds_read_b128 v[172:175], v183 offset:50176
	ds_read_b128 v[188:191], v183 offset:51200
	ds_read_b128 v[192:195], v183 offset:52224
	ds_read_b128 v[196:199], v183 offset:53248
	ds_read_b128 v[200:203], v183 offset:54272
	ds_read_b128 v[204:207], v183 offset:55296
	ds_read_b128 v[208:211], v183 offset:56320
	s_add_u32 s28, s26, 0x80
	s_addc_u32 s29, s27, 0
	s_mov_b32 s79, m0
	s_mov_b32 m0, s56
	s_nop 0
	global_load_lds_dwordx4 v176, s[28:29]
	s_mov_b32 m0, s79
	s_add_u32 s26, s26, 0x80080
	s_mov_b32 s79, m0
	s_mov_b32 m0, s57
	s_nop 0
	global_load_lds_dwordx4 v178, s[28:29]
	s_mov_b32 m0, s79
	s_addc_u32 s27, s27, 0
	s_mov_b32 s28, m0
	s_mov_b32 m0, s58
	s_nop 0
	global_load_lds_dwordx4 v176, s[26:27]
	s_mov_b32 m0, s28
	s_nop 0
	s_mov_b32 s28, m0
	s_mov_b32 m0, s59
	s_nop 0
	global_load_lds_dwordx4 v178, s[26:27]
	s_mov_b32 m0, s28
	s_waitcnt vmcnt(4)
	s_waitcnt lgkmcnt(0)
	s_barrier
	s_setprio 1
	s_waitcnt lgkmcnt(7)
	v_mfma_f32_16x16x32_bf16 v[62:65], v[130:133], v[168:171], v[62:65]
	v_mfma_f32_16x16x32_bf16 v[62:65], v[134:137], v[172:175], v[62:65]
	s_waitcnt lgkmcnt(5)
	v_mfma_f32_16x16x32_bf16 v[58:61], v[138:141], v[168:171], v[58:61]
	v_mfma_f32_16x16x32_bf16 v[58:61], v[142:145], v[172:175], v[58:61]
	s_waitcnt lgkmcnt(3)
	v_mfma_f32_16x16x32_bf16 v[42:45], v[138:141], v[188:191], v[42:45]
	v_mfma_f32_16x16x32_bf16 v[42:45], v[142:145], v[192:195], v[42:45]
	s_waitcnt lgkmcnt(1)
	v_mfma_f32_16x16x32_bf16 v[46:49], v[130:133], v[188:191], v[46:49]
	v_mfma_f32_16x16x32_bf16 v[46:49], v[134:137], v[192:195], v[46:49]
	v_mfma_f32_16x16x32_bf16 v[30:33], v[130:133], v[196:199], v[30:33]
	v_mfma_f32_16x16x32_bf16 v[30:33], v[134:137], v[200:203], v[30:33]
	v_mfma_f32_16x16x32_bf16 v[26:29], v[138:141], v[196:199], v[26:29]
	v_mfma_f32_16x16x32_bf16 v[26:29], v[142:145], v[200:203], v[26:29]
	v_mfma_f32_16x16x32_bf16 v[10:13], v[138:141], v[204:207], v[10:13]
	v_mfma_f32_16x16x32_bf16 v[10:13], v[142:145], v[208:211], v[10:13]
	s_waitcnt lgkmcnt(0)
	v_mfma_f32_16x16x32_bf16 v[14:17], v[130:133], v[204:207], v[14:17]
	v_mfma_f32_16x16x32_bf16 v[14:17], v[134:137], v[208:211], v[14:17]
	s_setprio 0
	s_setprio 1
	v_mfma_f32_16x16x32_bf16 v[54:57], v[146:149], v[168:171], v[54:57]
	v_mfma_f32_16x16x32_bf16 v[54:57], v[150:153], v[172:175], v[54:57]
	v_mfma_f32_16x16x32_bf16 v[50:53], v[154:157], v[168:171], v[50:53]
	v_mfma_f32_16x16x32_bf16 v[50:53], v[158:161], v[172:175], v[50:53]
	v_mfma_f32_16x16x32_bf16 v[34:37], v[154:157], v[188:191], v[34:37]
	v_mfma_f32_16x16x32_bf16 v[34:37], v[158:161], v[192:195], v[34:37]
	v_mfma_f32_16x16x32_bf16 v[38:41], v[146:149], v[188:191], v[38:41]
	v_mfma_f32_16x16x32_bf16 v[38:41], v[150:153], v[192:195], v[38:41]
	v_mfma_f32_16x16x32_bf16 v[22:25], v[146:149], v[196:199], v[22:25]
	v_mfma_f32_16x16x32_bf16 v[22:25], v[150:153], v[200:203], v[22:25]
	v_mfma_f32_16x16x32_bf16 v[18:21], v[154:157], v[196:199], v[18:21]
	v_mfma_f32_16x16x32_bf16 v[18:21], v[158:161], v[200:203], v[18:21]
	v_mfma_f32_16x16x32_bf16 v[2:5], v[154:157], v[204:207], v[2:5]
	v_mfma_f32_16x16x32_bf16 v[2:5], v[158:161], v[208:211], v[2:5]
	s_setprio 2
	s_barrier
	v_mfma_f32_16x16x32_bf16 v[6:9], v[146:149], v[204:207], v[6:9]
	v_mfma_f32_16x16x32_bf16 v[6:9], v[150:153], v[208:211], v[6:9]
	s_setprio 0
	s_add_i32 s78, s78, 2
	s_add_u32 s74, s74, 0x100
	s_addc_u32 s75, s75, 0
	s_add_u32 s24, s24, 0x100
	s_addc_u32 s25, s25, 0
	s_add_u32 s76, s76, 0x100
	s_addc_u32 s77, s77, 0
	s_cmp_gt_u32 s78, 29
	s_cbranch_scc0 .LBB0_2410
	v_mov_b32_e32 v174, v252
	v_mov_b32_e32 v175, v253
	v_mov_b32_e32 v210, v254
	v_mov_b32_e32 v211, v255
	s_and_b64 vcc, exec, s[8:9]
	s_cbranch_vccz .LBB0_2413
	s_barrier

.LBB0_2791:
	s_ashr_i32 s21, s20, 31
	s_lshl_b64 s[22:23], s[20:21], 15
	s_add_u32 s22, s37, s22
	s_addc_u32 s23, s40, s23
	s_and_b64 s[24:25], s[2:3], exec
	s_cselect_b32 s21, s23, s31
	s_cselect_b32 s63, s22, s30
	s_ashr_i32 s19, s18, 31
	s_lshl_b64 s[24:25], s[18:19], 15
	s_add_u32 s24, s41, s24
	s_addc_u32 s25, s42, s25
	s_and_b64 s[34:35], s[2:3], exec
	s_cselect_b32 s19, s25, s29
	s_cselect_b32 s64, s24, s28
	s_add_u32 s65, s28, 0x80000
	s_addc_u32 s66, s29, 0
	s_add_u32 s28, s30, 0x204000
	s_addc_u32 s29, s31, 0
	s_add_u32 s67, s30, 0x400000
	s_addc_u32 s68, s31, 0
	s_mov_b32 s69, -2
	s_waitcnt vmcnt(25)
	s_waitcnt vmcnt(24)
	s_waitcnt vmcnt(4)
	s_waitcnt vmcnt(2)
	s_waitcnt vmcnt(1)
	s_waitcnt vmcnt(0)
	v_mov_b32_e32 v252, v174
	v_mov_b32_e32 v253, v175
	v_mov_b32_e32 v254, v210
	v_mov_b32_e32 v255, v211
	ds_read_b128 v[130:133], v181
	ds_read_b128 v[134:137], v181 offset:1024
	ds_read_b128 v[138:141], v181 offset:2048
	ds_read_b128 v[142:145], v181 offset:3072
	ds_read_b128 v[150:153], v182
	ds_read_b128 v[154:157], v182 offset:1024
	ds_read_b128 v[158:161], v182 offset:2048
	ds_read_b128 v[162:165], v182 offset:3072
	s_cmpk_eq_i32 s69, 0x52
	s_cselect_b32 s31, s19, s66
	s_cselect_b32 s30, s64, s65
	s_cselect_b32 s35, s21, s68
	s_cselect_b32 s34, s63, s67
	ds_read_b128 v[168:171], v183
	ds_read_b128 v[172:175], v183 offset:1024
	ds_read_b128 v[188:191], v183 offset:2048
	ds_read_b128 v[192:195], v183 offset:3072
	ds_read_b128 v[196:199], v183 offset:4096
	ds_read_b128 v[200:203], v183 offset:5120
	ds_read_b128 v[204:207], v183 offset:6144
	ds_read_b128 v[208:211], v183 offset:7168
	s_add_u32 s70, s28, 0xffffc000
	s_addc_u32 s71, s29, -1
	s_mov_b32 s73, m0
	s_mov_b32 m0, s57
	s_nop 0
	global_load_lds_dwordx4 v1, s[70:71]
	s_mov_b32 m0, s73
	s_nop 0
	s_mov_b32 s73, m0
	s_mov_b32 m0, s59
	s_nop 0
	global_load_lds_dwordx4 v177, s[70:71]
	s_mov_b32 m0, s73
	s_mov_b32 s70, m0
	s_mov_b32 m0, s58
	s_nop 0
	global_load_lds_dwordx4 v1, s[28:29]
	s_mov_b32 m0, s70
	s_nop 0
	s_mov_b32 s70, m0
	s_mov_b32 m0, s60
	s_nop 0
	global_load_lds_dwordx4 v177, s[28:29]
	s_mov_b32 m0, s70
	s_waitcnt vmcnt(8)
	s_waitcnt lgkmcnt(0)
	s_barrier
	s_setprio 1
	s_waitcnt lgkmcnt(7)
	v_mfma_f32_16x16x32_bf16 v[126:129], v[130:133], v[168:171], 0
	v_mfma_f32_16x16x32_bf16 v[126:129], v[134:137], v[172:175], v[126:129]
	s_waitcnt lgkmcnt(5)
	v_mfma_f32_16x16x32_bf16 v[122:125], v[138:141], v[168:171], 0
	v_mfma_f32_16x16x32_bf16 v[122:125], v[142:145], v[172:175], v[122:125]
	s_waitcnt lgkmcnt(3)
	v_mfma_f32_16x16x32_bf16 v[110:113], v[138:141], v[188:191], 0
	v_mfma_f32_16x16x32_bf16 v[110:113], v[142:145], v[192:195], v[110:113]
	s_waitcnt lgkmcnt(1)
	v_mfma_f32_16x16x32_bf16 v[118:121], v[130:133], v[188:191], 0
	v_mfma_f32_16x16x32_bf16 v[118:121], v[134:137], v[192:195], v[118:121]
	v_mfma_f32_16x16x32_bf16 v[94:97], v[130:133], v[196:199], 0
	v_mfma_f32_16x16x32_bf16 v[94:97], v[134:137], v[200:203], v[94:97]
	v_mfma_f32_16x16x32_bf16 v[90:93], v[138:141], v[196:199], 0
	v_mfma_f32_16x16x32_bf16 v[90:93], v[142:145], v[200:203], v[90:93]
	v_mfma_f32_16x16x32_bf16 v[78:81], v[138:141], v[204:207], 0
	v_mfma_f32_16x16x32_bf16 v[78:81], v[142:145], v[208:211], v[78:81]
	s_waitcnt lgkmcnt(0)
	v_mfma_f32_16x16x32_bf16 v[86:89], v[130:133], v[204:207], 0
	v_mfma_f32_16x16x32_bf16 v[86:89], v[134:137], v[208:211], v[86:89]
	s_setprio 0
	s_setprio 1
	v_mfma_f32_16x16x32_bf16 v[114:117], v[150:153], v[168:171], 0
	v_mfma_f32_16x16x32_bf16 v[114:117], v[154:157], v[172:175], v[114:117]
	v_mfma_f32_16x16x32_bf16 v[106:109], v[158:161], v[168:171], 0
	v_mfma_f32_16x16x32_bf16 v[106:109], v[162:165], v[172:175], v[106:109]
	v_mfma_f32_16x16x32_bf16 v[98:101], v[158:161], v[188:191], 0
	v_mfma_f32_16x16x32_bf16 v[98:101], v[162:165], v[192:195], v[98:101]
	v_mfma_f32_16x16x32_bf16 v[102:105], v[150:153], v[188:191], 0
	v_mfma_f32_16x16x32_bf16 v[102:105], v[154:157], v[192:195], v[102:105]
	v_mfma_f32_16x16x32_bf16 v[82:85], v[150:153], v[196:199], 0
	v_mfma_f32_16x16x32_bf16 v[82:85], v[154:157], v[200:203], v[82:85]
	v_mfma_f32_16x16x32_bf16 v[74:77], v[158:161], v[196:199], 0
	v_mfma_f32_16x16x32_bf16 v[74:77], v[162:165], v[200:203], v[74:77]
	v_mfma_f32_16x16x32_bf16 v[66:69], v[158:161], v[204:207], 0
	v_mfma_f32_16x16x32_bf16 v[66:69], v[162:165], v[208:211], v[66:69]
	s_setprio 2
	s_barrier
	v_mfma_f32_16x16x32_bf16 v[70:73], v[150:153], v[204:207], 0
	v_mfma_f32_16x16x32_bf16 v[70:73], v[154:157], v[208:211], v[70:73]
	s_setprio 0
	ds_read_b128 v[168:171], v183 offset:16384
	ds_read_b128 v[172:175], v183 offset:17408
	ds_read_b128 v[188:191], v183 offset:18432
	ds_read_b128 v[192:195], v183 offset:19456
	ds_read_b128 v[196:199], v183 offset:20480
	ds_read_b128 v[200:203], v183 offset:21504
	ds_read_b128 v[204:207], v183 offset:22528
	ds_read_b128 v[208:211], v183 offset:23552
	s_mov_b32 s70, m0
	s_mov_b32 m0, s27
	s_nop 0
	global_load_lds_dwordx4 v176, s[30:31]
	s_mov_b32 m0, s70
	s_nop 0
	s_mov_b32 s70, m0
	s_mov_b32 m0, s45
	s_nop 0
	global_load_lds_dwordx4 v178, s[30:31]
	s_mov_b32 m0, s70
	s_add_u32 s70, s30, 0x4000
	s_addc_u32 s71, s31, 0
	s_mov_b32 s73, m0
	s_mov_b32 m0, s46
	s_nop 0
	global_load_lds_dwordx4 v176, s[70:71]
	s_mov_b32 m0, s73
	s_nop 0
	s_mov_b32 s73, m0
	s_mov_b32 m0, s47
	s_nop 0
	global_load_lds_dwordx4 v178, s[70:71]
	s_mov_b32 m0, s73
	s_waitcnt vmcnt(4)
	s_waitcnt lgkmcnt(0)
	s_barrier
	s_setprio 1
	s_waitcnt lgkmcnt(7)
	v_mfma_f32_16x16x32_bf16 v[62:65], v[130:133], v[168:171], 0
	v_mfma_f32_16x16x32_bf16 v[62:65], v[134:137], v[172:175], v[62:65]
	s_waitcnt lgkmcnt(5)
	v_mfma_f32_16x16x32_bf16 v[58:61], v[138:141], v[168:171], 0
	v_mfma_f32_16x16x32_bf16 v[58:61], v[142:145], v[172:175], v[58:61]
	s_waitcnt lgkmcnt(3)
	v_mfma_f32_16x16x32_bf16 v[42:45], v[138:141], v[188:191], 0
	v_mfma_f32_16x16x32_bf16 v[42:45], v[142:145], v[192:195], v[42:45]
	s_waitcnt lgkmcnt(1)
	v_mfma_f32_16x16x32_bf16 v[46:49], v[130:133], v[188:191], 0
	v_mfma_f32_16x16x32_bf16 v[46:49], v[134:137], v[192:195], v[46:49]
	v_mfma_f32_16x16x32_bf16 v[30:33], v[130:133], v[196:199], 0
	v_mfma_f32_16x16x32_bf16 v[30:33], v[134:137], v[200:203], v[30:33]
	v_mfma_f32_16x16x32_bf16 v[26:29], v[138:141], v[196:199], 0
	v_mfma_f32_16x16x32_bf16 v[26:29], v[142:145], v[200:203], v[26:29]
	v_mfma_f32_16x16x32_bf16 v[10:13], v[138:141], v[204:207], 0
	v_mfma_f32_16x16x32_bf16 v[10:13], v[142:145], v[208:211], v[10:13]
	s_waitcnt lgkmcnt(0)
	v_mfma_f32_16x16x32_bf16 v[14:17], v[130:133], v[204:207], 0
	v_mfma_f32_16x16x32_bf16 v[14:17], v[134:137], v[208:211], v[14:17]
	s_setprio 0
	s_setprio 1
	v_mfma_f32_16x16x32_bf16 v[54:57], v[150:153], v[168:171], 0
	v_mfma_f32_16x16x32_bf16 v[54:57], v[154:157], v[172:175], v[54:57]
	v_mfma_f32_16x16x32_bf16 v[50:53], v[158:161], v[168:171], 0
	v_mfma_f32_16x16x32_bf16 v[50:53], v[162:165], v[172:175], v[50:53]
	v_mfma_f32_16x16x32_bf16 v[34:37], v[158:161], v[188:191], 0
	v_mfma_f32_16x16x32_bf16 v[34:37], v[162:165], v[192:195], v[34:37]
	v_mfma_f32_16x16x32_bf16 v[38:41], v[150:153], v[188:191], 0
	v_mfma_f32_16x16x32_bf16 v[38:41], v[154:157], v[192:195], v[38:41]
	v_mfma_f32_16x16x32_bf16 v[22:25], v[150:153], v[196:199], 0
	v_mfma_f32_16x16x32_bf16 v[22:25], v[154:157], v[200:203], v[22:25]
	v_mfma_f32_16x16x32_bf16 v[18:21], v[158:161], v[196:199], 0
	v_mfma_f32_16x16x32_bf16 v[18:21], v[162:165], v[200:203], v[18:21]
	v_mfma_f32_16x16x32_bf16 v[2:5], v[158:161], v[204:207], 0
	v_mfma_f32_16x16x32_bf16 v[2:5], v[162:165], v[208:211], v[2:5]
	s_setprio 2
	s_barrier
	v_mfma_f32_16x16x32_bf16 v[6:9], v[150:153], v[204:207], 0
	v_mfma_f32_16x16x32_bf16 v[6:9], v[154:157], v[208:211], v[6:9]
	s_setprio 0
	ds_read_b128 v[130:133], v184
	ds_read_b128 v[134:137], v184 offset:1024
	ds_read_b128 v[138:141], v184 offset:2048
	ds_read_b128 v[142:145], v184 offset:3072
	ds_read_b128 v[150:153], v185
	ds_read_b128 v[154:157], v185 offset:1024
	ds_read_b128 v[158:161], v185 offset:2048
	ds_read_b128 v[162:165], v185 offset:3072
	ds_read_b128 v[168:171], v183 offset:32768
	ds_read_b128 v[172:175], v183 offset:33792
	ds_read_b128 v[188:191], v183 offset:34816
	ds_read_b128 v[192:195], v183 offset:35840
	ds_read_b128 v[196:199], v183 offset:36864
	ds_read_b128 v[200:203], v183 offset:37888
	ds_read_b128 v[204:207], v183 offset:38912
	ds_read_b128 v[208:211], v183 offset:39936
	s_mov_b32 s70, m0
	s_mov_b32 m0, s44
	s_nop 0
	global_load_lds_dwordx4 v1, s[34:35]
	s_mov_b32 m0, s70
	s_nop 0
	s_mov_b32 s70, m0
	s_mov_b32 m0, s48
	s_nop 0
	global_load_lds_dwordx4 v177, s[34:35]
	s_mov_b32 m0, s70
	s_add_u32 s34, s34, 0x4000
	s_addc_u32 s35, s35, 0
	s_mov_b32 s70, m0
	s_mov_b32 m0, s49
	s_nop 0
	global_load_lds_dwordx4 v1, s[34:35]
	s_mov_b32 m0, s70
	s_nop 0
	s_mov_b32 s70, m0
	s_mov_b32 m0, s50
	s_nop 0
	global_load_lds_dwordx4 v177, s[34:35]
	s_mov_b32 m0, s70
	s_waitcnt vmcnt(8)
	s_waitcnt lgkmcnt(0)
	s_barrier
	s_setprio 1
	s_waitcnt lgkmcnt(7)
	v_mfma_f32_16x16x32_bf16 v[126:129], v[130:133], v[168:171], v[126:129]
	v_mfma_f32_16x16x32_bf16 v[126:129], v[134:137], v[172:175], v[126:129]
	s_waitcnt lgkmcnt(5)
	v_mfma_f32_16x16x32_bf16 v[122:125], v[138:141], v[168:171], v[122:125]
	v_mfma_f32_16x16x32_bf16 v[122:125], v[142:145], v[172:175], v[122:125]
	s_waitcnt lgkmcnt(3)
	v_mfma_f32_16x16x32_bf16 v[110:113], v[138:141], v[188:191], v[110:113]
	v_mfma_f32_16x16x32_bf16 v[110:113], v[142:145], v[192:195], v[110:113]
	s_waitcnt lgkmcnt(1)
	v_mfma_f32_16x16x32_bf16 v[118:121], v[130:133], v[188:191], v[118:121]
	v_mfma_f32_16x16x32_bf16 v[118:121], v[134:137], v[192:195], v[118:121]
	v_mfma_f32_16x16x32_bf16 v[94:97], v[130:133], v[196:199], v[94:97]
	v_mfma_f32_16x16x32_bf16 v[94:97], v[134:137], v[200:203], v[94:97]
	v_mfma_f32_16x16x32_bf16 v[90:93], v[138:141], v[196:199], v[90:93]
	v_mfma_f32_16x16x32_bf16 v[90:93], v[142:145], v[200:203], v[90:93]
	v_mfma_f32_16x16x32_bf16 v[78:81], v[138:141], v[204:207], v[78:81]
	v_mfma_f32_16x16x32_bf16 v[78:81], v[142:145], v[208:211], v[78:81]
	s_waitcnt lgkmcnt(0)
	v_mfma_f32_16x16x32_bf16 v[86:89], v[130:133], v[204:207], v[86:89]
	v_mfma_f32_16x16x32_bf16 v[86:89], v[134:137], v[208:211], v[86:89]
	s_setprio 0
	s_setprio 1
	v_mfma_f32_16x16x32_bf16 v[114:117], v[150:153], v[168:171], v[114:117]
	v_mfma_f32_16x16x32_bf16 v[114:117], v[154:157], v[172:175], v[114:117]
	v_mfma_f32_16x16x32_bf16 v[106:109], v[158:161], v[168:171], v[106:109]
	v_mfma_f32_16x16x32_bf16 v[106:109], v[162:165], v[172:175], v[106:109]
	v_mfma_f32_16x16x32_bf16 v[98:101], v[158:161], v[188:191], v[98:101]
	v_mfma_f32_16x16x32_bf16 v[98:101], v[162:165], v[192:195], v[98:101]
	v_mfma_f32_16x16x32_bf16 v[102:105], v[150:153], v[188:191], v[102:105]
	v_mfma_f32_16x16x32_bf16 v[102:105], v[154:157], v[192:195], v[102:105]
	v_mfma_f32_16x16x32_bf16 v[82:85], v[150:153], v[196:199], v[82:85]
	v_mfma_f32_16x16x32_bf16 v[82:85], v[154:157], v[200:203], v[82:85]
	v_mfma_f32_16x16x32_bf16 v[74:77], v[158:161], v[196:199], v[74:77]
	v_mfma_f32_16x16x32_bf16 v[74:77], v[162:165], v[200:203], v[74:77]
	v_mfma_f32_16x16x32_bf16 v[66:69], v[158:161], v[204:207], v[66:69]
	v_mfma_f32_16x16x32_bf16 v[66:69], v[162:165], v[208:211], v[66:69]
	s_setprio 2
	s_barrier
	v_mfma_f32_16x16x32_bf16 v[70:73], v[150:153], v[204:207], v[70:73]
	v_mfma_f32_16x16x32_bf16 v[70:73], v[154:157], v[208:211], v[70:73]
	s_setprio 0
	ds_read_b128 v[168:171], v183 offset:49152
	ds_read_b128 v[172:175], v183 offset:50176
	ds_read_b128 v[188:191], v183 offset:51200
	ds_read_b128 v[192:195], v183 offset:52224
	ds_read_b128 v[196:199], v183 offset:53248
	ds_read_b128 v[200:203], v183 offset:54272
	ds_read_b128 v[204:207], v183 offset:55296
	ds_read_b128 v[208:211], v183 offset:56320
	s_add_u32 s34, s30, 0x40000
	s_addc_u32 s35, s31, 0
	s_mov_b32 s70, m0
	s_mov_b32 m0, s51
	s_nop 0
	global_load_lds_dwordx4 v176, s[34:35]
	s_mov_b32 m0, s70
	s_add_u32 s30, s30, 0x44000
	s_mov_b32 s70, m0
	s_mov_b32 m0, s52
	s_nop 0
	global_load_lds_dwordx4 v178, s[34:35]
	s_mov_b32 m0, s70
	s_addc_u32 s31, s31, 0
	s_mov_b32 s34, m0
	s_mov_b32 m0, s53
	s_nop 0
	global_load_lds_dwordx4 v176, s[30:31]
	s_mov_b32 m0, s34
	s_nop 0
	s_mov_b32 s34, m0
	s_mov_b32 m0, s54
	s_nop 0
	global_load_lds_dwordx4 v178, s[30:31]
	s_mov_b32 m0, s34
	s_waitcnt vmcnt(4)
	s_waitcnt lgkmcnt(0)
	s_barrier
	s_setprio 1
	s_waitcnt lgkmcnt(7)
	v_mfma_f32_16x16x32_bf16 v[62:65], v[130:133], v[168:171], v[62:65]
	v_mfma_f32_16x16x32_bf16 v[62:65], v[134:137], v[172:175], v[62:65]
	s_waitcnt lgkmcnt(5)
	v_mfma_f32_16x16x32_bf16 v[58:61], v[138:141], v[168:171], v[58:61]
	v_mfma_f32_16x16x32_bf16 v[58:61], v[142:145], v[172:175], v[58:61]
	s_waitcnt lgkmcnt(3)
	v_mfma_f32_16x16x32_bf16 v[42:45], v[138:141], v[188:191], v[42:45]
	v_mfma_f32_16x16x32_bf16 v[42:45], v[142:145], v[192:195], v[42:45]
	s_waitcnt lgkmcnt(1)
	v_mfma_f32_16x16x32_bf16 v[46:49], v[130:133], v[188:191], v[46:49]
	v_mfma_f32_16x16x32_bf16 v[46:49], v[134:137], v[192:195], v[46:49]
	v_mfma_f32_16x16x32_bf16 v[30:33], v[130:133], v[196:199], v[30:33]
	v_mfma_f32_16x16x32_bf16 v[30:33], v[134:137], v[200:203], v[30:33]
	v_mfma_f32_16x16x32_bf16 v[26:29], v[138:141], v[196:199], v[26:29]
	v_mfma_f32_16x16x32_bf16 v[26:29], v[142:145], v[200:203], v[26:29]
	v_mfma_f32_16x16x32_bf16 v[10:13], v[138:141], v[204:207], v[10:13]
	v_mfma_f32_16x16x32_bf16 v[10:13], v[142:145], v[208:211], v[10:13]
	s_waitcnt lgkmcnt(0)
	v_mfma_f32_16x16x32_bf16 v[14:17], v[130:133], v[204:207], v[14:17]
	v_mfma_f32_16x16x32_bf16 v[14:17], v[134:137], v[208:211], v[14:17]
	s_setprio 0
	s_setprio 1
	v_mfma_f32_16x16x32_bf16 v[54:57], v[150:153], v[168:171], v[54:57]
	v_mfma_f32_16x16x32_bf16 v[54:57], v[154:157], v[172:175], v[54:57]
	v_mfma_f32_16x16x32_bf16 v[50:53], v[158:161], v[168:171], v[50:53]
	v_mfma_f32_16x16x32_bf16 v[50:53], v[162:165], v[172:175], v[50:53]
	v_mfma_f32_16x16x32_bf16 v[34:37], v[158:161], v[188:191], v[34:37]
	v_mfma_f32_16x16x32_bf16 v[34:37], v[162:165], v[192:195], v[34:37]
	v_mfma_f32_16x16x32_bf16 v[38:41], v[150:153], v[188:191], v[38:41]
	v_mfma_f32_16x16x32_bf16 v[38:41], v[154:157], v[192:195], v[38:41]
	v_mfma_f32_16x16x32_bf16 v[22:25], v[150:153], v[196:199], v[22:25]
	v_mfma_f32_16x16x32_bf16 v[22:25], v[154:157], v[200:203], v[22:25]
	v_mfma_f32_16x16x32_bf16 v[18:21], v[158:161], v[196:199], v[18:21]
	v_mfma_f32_16x16x32_bf16 v[18:21], v[162:165], v[200:203], v[18:21]
	v_mfma_f32_16x16x32_bf16 v[2:5], v[158:161], v[204:207], v[2:5]
	v_mfma_f32_16x16x32_bf16 v[2:5], v[162:165], v[208:211], v[2:5]
	s_setprio 2
	s_barrier
	v_mfma_f32_16x16x32_bf16 v[6:9], v[150:153], v[204:207], v[6:9]
	v_mfma_f32_16x16x32_bf16 v[6:9], v[154:157], v[208:211], v[6:9]
	s_setprio 0
	s_add_i32 s69, s69, 2
	s_add_u32 s65, s65, 0x80000
	s_addc_u32 s66, s66, 0
	s_add_u32 s28, s28, 0x400000
	s_addc_u32 s29, s29, 0
	s_add_u32 s67, s67, 0x400000
	s_addc_u32 s68, s68, 0
	s_cmpk_gt_u32 s69, 0x53
	.p2align 6
.LBB0_2792:
	ds_read_b128 v[130:133], v181
	ds_read_b128 v[134:137], v181 offset:1024
	ds_read_b128 v[138:141], v181 offset:2048
	ds_read_b128 v[142:145], v181 offset:3072
	ds_read_b128 v[150:153], v182
	ds_read_b128 v[154:157], v182 offset:1024
	ds_read_b128 v[158:161], v182 offset:2048
	ds_read_b128 v[162:165], v182 offset:3072
	s_cmpk_eq_i32 s69, 0x52
	s_cselect_b32 s31, s19, s66
	s_cselect_b32 s30, s64, s65
	s_cselect_b32 s35, s21, s68
	s_cselect_b32 s34, s63, s67
	ds_read_b128 v[168:171], v183
	ds_read_b128 v[172:175], v183 offset:1024
	ds_read_b128 v[188:191], v183 offset:2048
	ds_read_b128 v[192:195], v183 offset:3072
	ds_read_b128 v[196:199], v183 offset:4096
	ds_read_b128 v[200:203], v183 offset:5120
	ds_read_b128 v[204:207], v183 offset:6144
	ds_read_b128 v[208:211], v183 offset:7168
	s_add_u32 s70, s28, 0xffffc000
	s_addc_u32 s71, s29, -1
	s_mov_b32 s73, m0
	s_mov_b32 m0, s57
	s_nop 0
	global_load_lds_dwordx4 v1, s[70:71]
	s_mov_b32 m0, s73
	s_nop 0
	s_mov_b32 s73, m0
	s_mov_b32 m0, s59
	s_nop 0
	global_load_lds_dwordx4 v177, s[70:71]
	s_mov_b32 m0, s73
	s_mov_b32 s70, m0
	s_mov_b32 m0, s58
	s_nop 0
	global_load_lds_dwordx4 v1, s[28:29]
	s_mov_b32 m0, s70
	s_nop 0
	s_mov_b32 s70, m0
	s_mov_b32 m0, s60
	s_nop 0
	global_load_lds_dwordx4 v177, s[28:29]
	s_mov_b32 m0, s70
	s_waitcnt vmcnt(8)
	s_waitcnt lgkmcnt(0)
	s_barrier
	s_setprio 1
	s_waitcnt lgkmcnt(7)
	v_mfma_f32_16x16x32_bf16 v[126:129], v[130:133], v[168:171], v[126:129]
	v_mfma_f32_16x16x32_bf16 v[126:129], v[134:137], v[172:175], v[126:129]
	s_waitcnt lgkmcnt(5)
	v_mfma_f32_16x16x32_bf16 v[122:125], v[138:141], v[168:171], v[122:125]
	v_mfma_f32_16x16x32_bf16 v[122:125], v[142:145], v[172:175], v[122:125]
	s_waitcnt lgkmcnt(3)
	v_mfma_f32_16x16x32_bf16 v[110:113], v[138:141], v[188:191], v[110:113]
	v_mfma_f32_16x16x32_bf16 v[110:113], v[142:145], v[192:195], v[110:113]
	s_waitcnt lgkmcnt(1)
	v_mfma_f32_16x16x32_bf16 v[118:121], v[130:133], v[188:191], v[118:121]
	v_mfma_f32_16x16x32_bf16 v[118:121], v[134:137], v[192:195], v[118:121]
	v_mfma_f32_16x16x32_bf16 v[94:97], v[130:133], v[196:199], v[94:97]
	v_mfma_f32_16x16x32_bf16 v[94:97], v[134:137], v[200:203], v[94:97]
	v_mfma_f32_16x16x32_bf16 v[90:93], v[138:141], v[196:199], v[90:93]
	v_mfma_f32_16x16x32_bf16 v[90:93], v[142:145], v[200:203], v[90:93]
	v_mfma_f32_16x16x32_bf16 v[78:81], v[138:141], v[204:207], v[78:81]
	v_mfma_f32_16x16x32_bf16 v[78:81], v[142:145], v[208:211], v[78:81]
	s_waitcnt lgkmcnt(0)
	v_mfma_f32_16x16x32_bf16 v[86:89], v[130:133], v[204:207], v[86:89]
	v_mfma_f32_16x16x32_bf16 v[86:89], v[134:137], v[208:211], v[86:89]
	s_setprio 0
	s_setprio 1
	v_mfma_f32_16x16x32_bf16 v[114:117], v[150:153], v[168:171], v[114:117]
	v_mfma_f32_16x16x32_bf16 v[114:117], v[154:157], v[172:175], v[114:117]
	v_mfma_f32_16x16x32_bf16 v[106:109], v[158:161], v[168:171], v[106:109]
	v_mfma_f32_16x16x32_bf16 v[106:109], v[162:165], v[172:175], v[106:109]
	v_mfma_f32_16x16x32_bf16 v[98:101], v[158:161], v[188:191], v[98:101]
	v_mfma_f32_16x16x32_bf16 v[98:101], v[162:165], v[192:195], v[98:101]
	v_mfma_f32_16x16x32_bf16 v[102:105], v[150:153], v[188:191], v[102:105]
	v_mfma_f32_16x16x32_bf16 v[102:105], v[154:157], v[192:195], v[102:105]
	v_mfma_f32_16x16x32_bf16 v[82:85], v[150:153], v[196:199], v[82:85]
	v_mfma_f32_16x16x32_bf16 v[82:85], v[154:157], v[200:203], v[82:85]
	v_mfma_f32_16x16x32_bf16 v[74:77], v[158:161], v[196:199], v[74:77]
	v_mfma_f32_16x16x32_bf16 v[74:77], v[162:165], v[200:203], v[74:77]
	v_mfma_f32_16x16x32_bf16 v[66:69], v[158:161], v[204:207], v[66:69]
	v_mfma_f32_16x16x32_bf16 v[66:69], v[162:165], v[208:211], v[66:69]
	s_setprio 2
	s_barrier
	v_mfma_f32_16x16x32_bf16 v[70:73], v[150:153], v[204:207], v[70:73]
	v_mfma_f32_16x16x32_bf16 v[70:73], v[154:157], v[208:211], v[70:73]
	s_setprio 0
	ds_read_b128 v[168:171], v183 offset:16384
	ds_read_b128 v[172:175], v183 offset:17408
	ds_read_b128 v[188:191], v183 offset:18432
	ds_read_b128 v[192:195], v183 offset:19456
	ds_read_b128 v[196:199], v183 offset:20480
	ds_read_b128 v[200:203], v183 offset:21504
	ds_read_b128 v[204:207], v183 offset:22528
	ds_read_b128 v[208:211], v183 offset:23552
	s_mov_b32 s70, m0
	s_mov_b32 m0, s27
	s_nop 0
	global_load_lds_dwordx4 v176, s[30:31]
	s_mov_b32 m0, s70
	s_nop 0
	s_mov_b32 s70, m0
	s_mov_b32 m0, s45
	s_nop 0
	global_load_lds_dwordx4 v178, s[30:31]
	s_mov_b32 m0, s70
	s_add_u32 s70, s30, 0x4000
	s_addc_u32 s71, s31, 0
	s_mov_b32 s73, m0
	s_mov_b32 m0, s46
	s_nop 0
	global_load_lds_dwordx4 v176, s[70:71]
	s_mov_b32 m0, s73
	s_nop 0
	s_mov_b32 s73, m0
	s_mov_b32 m0, s47
	s_nop 0
	global_load_lds_dwordx4 v178, s[70:71]
	s_mov_b32 m0, s73
	s_waitcnt vmcnt(4)
	s_waitcnt lgkmcnt(0)
	s_barrier
	s_setprio 1
	s_waitcnt lgkmcnt(7)
	v_mfma_f32_16x16x32_bf16 v[62:65], v[130:133], v[168:171], v[62:65]
	v_mfma_f32_16x16x32_bf16 v[62:65], v[134:137], v[172:175], v[62:65]
	s_waitcnt lgkmcnt(5)
	v_mfma_f32_16x16x32_bf16 v[58:61], v[138:141], v[168:171], v[58:61]
	v_mfma_f32_16x16x32_bf16 v[58:61], v[142:145], v[172:175], v[58:61]
	s_waitcnt lgkmcnt(3)
	v_mfma_f32_16x16x32_bf16 v[42:45], v[138:141], v[188:191], v[42:45]
	v_mfma_f32_16x16x32_bf16 v[42:45], v[142:145], v[192:195], v[42:45]
	s_waitcnt lgkmcnt(1)
	v_mfma_f32_16x16x32_bf16 v[46:49], v[130:133], v[188:191], v[46:49]
	v_mfma_f32_16x16x32_bf16 v[46:49], v[134:137], v[192:195], v[46:49]
	v_mfma_f32_16x16x32_bf16 v[30:33], v[130:133], v[196:199], v[30:33]
	v_mfma_f32_16x16x32_bf16 v[30:33], v[134:137], v[200:203], v[30:33]
	v_mfma_f32_16x16x32_bf16 v[26:29], v[138:141], v[196:199], v[26:29]
	v_mfma_f32_16x16x32_bf16 v[26:29], v[142:145], v[200:203], v[26:29]
	v_mfma_f32_16x16x32_bf16 v[10:13], v[138:141], v[204:207], v[10:13]
	v_mfma_f32_16x16x32_bf16 v[10:13], v[142:145], v[208:211], v[10:13]
	s_waitcnt lgkmcnt(0)
	v_mfma_f32_16x16x32_bf16 v[14:17], v[130:133], v[204:207], v[14:17]
	v_mfma_f32_16x16x32_bf16 v[14:17], v[134:137], v[208:211], v[14:17]
	s_setprio 0
	s_setprio 1
	v_mfma_f32_16x16x32_bf16 v[54:57], v[150:153], v[168:171], v[54:57]
	v_mfma_f32_16x16x32_bf16 v[54:57], v[154:157], v[172:175], v[54:57]
	v_mfma_f32_16x16x32_bf16 v[50:53], v[158:161], v[168:171], v[50:53]
	v_mfma_f32_16x16x32_bf16 v[50:53], v[162:165], v[172:175], v[50:53]
	v_mfma_f32_16x16x32_bf16 v[34:37], v[158:161], v[188:191], v[34:37]
	v_mfma_f32_16x16x32_bf16 v[34:37], v[162:165], v[192:195], v[34:37]
	v_mfma_f32_16x16x32_bf16 v[38:41], v[150:153], v[188:191], v[38:41]
	v_mfma_f32_16x16x32_bf16 v[38:41], v[154:157], v[192:195], v[38:41]
	v_mfma_f32_16x16x32_bf16 v[22:25], v[150:153], v[196:199], v[22:25]
	v_mfma_f32_16x16x32_bf16 v[22:25], v[154:157], v[200:203], v[22:25]
	v_mfma_f32_16x16x32_bf16 v[18:21], v[158:161], v[196:199], v[18:21]
	v_mfma_f32_16x16x32_bf16 v[18:21], v[162:165], v[200:203], v[18:21]
	v_mfma_f32_16x16x32_bf16 v[2:5], v[158:161], v[204:207], v[2:5]
	v_mfma_f32_16x16x32_bf16 v[2:5], v[162:165], v[208:211], v[2:5]
	s_setprio 2
	s_barrier
	v_mfma_f32_16x16x32_bf16 v[6:9], v[150:153], v[204:207], v[6:9]
	v_mfma_f32_16x16x32_bf16 v[6:9], v[154:157], v[208:211], v[6:9]
	s_setprio 0
	ds_read_b128 v[130:133], v184
	ds_read_b128 v[134:137], v184 offset:1024
	ds_read_b128 v[138:141], v184 offset:2048
	ds_read_b128 v[142:145], v184 offset:3072
	ds_read_b128 v[150:153], v185
	ds_read_b128 v[154:157], v185 offset:1024
	ds_read_b128 v[158:161], v185 offset:2048
	ds_read_b128 v[162:165], v185 offset:3072
	ds_read_b128 v[168:171], v183 offset:32768
	ds_read_b128 v[172:175], v183 offset:33792
	ds_read_b128 v[188:191], v183 offset:34816
	ds_read_b128 v[192:195], v183 offset:35840
	ds_read_b128 v[196:199], v183 offset:36864
	ds_read_b128 v[200:203], v183 offset:37888
	ds_read_b128 v[204:207], v183 offset:38912
	ds_read_b128 v[208:211], v183 offset:39936
	s_mov_b32 s70, m0
	s_mov_b32 m0, s44
	s_nop 0
	global_load_lds_dwordx4 v1, s[34:35]
	s_mov_b32 m0, s70
	s_nop 0
	s_mov_b32 s70, m0
	s_mov_b32 m0, s48
	s_nop 0
	global_load_lds_dwordx4 v177, s[34:35]
	s_mov_b32 m0, s70
	s_add_u32 s34, s34, 0x4000
	s_addc_u32 s35, s35, 0
	s_mov_b32 s70, m0
	s_mov_b32 m0, s49
	s_nop 0
	global_load_lds_dwordx4 v1, s[34:35]
	s_mov_b32 m0, s70
	s_nop 0
	s_mov_b32 s70, m0
	s_mov_b32 m0, s50
	s_nop 0
	global_load_lds_dwordx4 v177, s[34:35]
	s_mov_b32 m0, s70
	s_waitcnt vmcnt(8)
	s_waitcnt lgkmcnt(0)
	s_barrier
	s_setprio 1
	s_waitcnt lgkmcnt(7)
	v_mfma_f32_16x16x32_bf16 v[126:129], v[130:133], v[168:171], v[126:129]
	v_mfma_f32_16x16x32_bf16 v[126:129], v[134:137], v[172:175], v[126:129]
	s_waitcnt lgkmcnt(5)
	v_mfma_f32_16x16x32_bf16 v[122:125], v[138:141], v[168:171], v[122:125]
	v_mfma_f32_16x16x32_bf16 v[122:125], v[142:145], v[172:175], v[122:125]
	s_waitcnt lgkmcnt(3)
	v_mfma_f32_16x16x32_bf16 v[110:113], v[138:141], v[188:191], v[110:113]
	v_mfma_f32_16x16x32_bf16 v[110:113], v[142:145], v[192:195], v[110:113]
	s_waitcnt lgkmcnt(1)
	v_mfma_f32_16x16x32_bf16 v[118:121], v[130:133], v[188:191], v[118:121]
	v_mfma_f32_16x16x32_bf16 v[118:121], v[134:137], v[192:195], v[118:121]
	v_mfma_f32_16x16x32_bf16 v[94:97], v[130:133], v[196:199], v[94:97]
	v_mfma_f32_16x16x32_bf16 v[94:97], v[134:137], v[200:203], v[94:97]
	v_mfma_f32_16x16x32_bf16 v[90:93], v[138:141], v[196:199], v[90:93]
	v_mfma_f32_16x16x32_bf16 v[90:93], v[142:145], v[200:203], v[90:93]
	v_mfma_f32_16x16x32_bf16 v[78:81], v[138:141], v[204:207], v[78:81]
	v_mfma_f32_16x16x32_bf16 v[78:81], v[142:145], v[208:211], v[78:81]
	s_waitcnt lgkmcnt(0)
	v_mfma_f32_16x16x32_bf16 v[86:89], v[130:133], v[204:207], v[86:89]
	v_mfma_f32_16x16x32_bf16 v[86:89], v[134:137], v[208:211], v[86:89]
	s_setprio 0
	s_setprio 1
	v_mfma_f32_16x16x32_bf16 v[114:117], v[150:153], v[168:171], v[114:117]
	v_mfma_f32_16x16x32_bf16 v[114:117], v[154:157], v[172:175], v[114:117]
	v_mfma_f32_16x16x32_bf16 v[106:109], v[158:161], v[168:171], v[106:109]
	v_mfma_f32_16x16x32_bf16 v[106:109], v[162:165], v[172:175], v[106:109]
	v_mfma_f32_16x16x32_bf16 v[98:101], v[158:161], v[188:191], v[98:101]
	v_mfma_f32_16x16x32_bf16 v[98:101], v[162:165], v[192:195], v[98:101]
	v_mfma_f32_16x16x32_bf16 v[102:105], v[150:153], v[188:191], v[102:105]
	v_mfma_f32_16x16x32_bf16 v[102:105], v[154:157], v[192:195], v[102:105]
	v_mfma_f32_16x16x32_bf16 v[82:85], v[150:153], v[196:199], v[82:85]
	v_mfma_f32_16x16x32_bf16 v[82:85], v[154:157], v[200:203], v[82:85]
	v_mfma_f32_16x16x32_bf16 v[74:77], v[158:161], v[196:199], v[74:77]
	v_mfma_f32_16x16x32_bf16 v[74:77], v[162:165], v[200:203], v[74:77]
	v_mfma_f32_16x16x32_bf16 v[66:69], v[158:161], v[204:207], v[66:69]
	v_mfma_f32_16x16x32_bf16 v[66:69], v[162:165], v[208:211], v[66:69]
	s_setprio 2
	s_barrier
	v_mfma_f32_16x16x32_bf16 v[70:73], v[150:153], v[204:207], v[70:73]
	v_mfma_f32_16x16x32_bf16 v[70:73], v[154:157], v[208:211], v[70:73]
	s_setprio 0
	ds_read_b128 v[168:171], v183 offset:49152
	ds_read_b128 v[172:175], v183 offset:50176
	ds_read_b128 v[188:191], v183 offset:51200
	ds_read_b128 v[192:195], v183 offset:52224
	ds_read_b128 v[196:199], v183 offset:53248
	ds_read_b128 v[200:203], v183 offset:54272
	ds_read_b128 v[204:207], v183 offset:55296
	ds_read_b128 v[208:211], v183 offset:56320
	s_add_u32 s34, s30, 0x40000
	s_addc_u32 s35, s31, 0
	s_mov_b32 s70, m0
	s_mov_b32 m0, s51
	s_nop 0
	global_load_lds_dwordx4 v176, s[34:35]
	s_mov_b32 m0, s70
	s_add_u32 s30, s30, 0x44000
	s_mov_b32 s70, m0
	s_mov_b32 m0, s52
	s_nop 0
	global_load_lds_dwordx4 v178, s[34:35]
	s_mov_b32 m0, s70
	s_addc_u32 s31, s31, 0
	s_mov_b32 s34, m0
	s_mov_b32 m0, s53
	s_nop 0
	global_load_lds_dwordx4 v176, s[30:31]
	s_mov_b32 m0, s34
	s_nop 0
	s_mov_b32 s34, m0
	s_mov_b32 m0, s54
	s_nop 0
	global_load_lds_dwordx4 v178, s[30:31]
	s_mov_b32 m0, s34
	s_waitcnt vmcnt(4)
	s_waitcnt lgkmcnt(0)
	s_barrier
	s_setprio 1
	s_waitcnt lgkmcnt(7)
	v_mfma_f32_16x16x32_bf16 v[62:65], v[130:133], v[168:171], v[62:65]
	v_mfma_f32_16x16x32_bf16 v[62:65], v[134:137], v[172:175], v[62:65]
	s_waitcnt lgkmcnt(5)
	v_mfma_f32_16x16x32_bf16 v[58:61], v[138:141], v[168:171], v[58:61]
	v_mfma_f32_16x16x32_bf16 v[58:61], v[142:145], v[172:175], v[58:61]
	s_waitcnt lgkmcnt(3)
	v_mfma_f32_16x16x32_bf16 v[42:45], v[138:141], v[188:191], v[42:45]
	v_mfma_f32_16x16x32_bf16 v[42:45], v[142:145], v[192:195], v[42:45]
	s_waitcnt lgkmcnt(1)
	v_mfma_f32_16x16x32_bf16 v[46:49], v[130:133], v[188:191], v[46:49]
	v_mfma_f32_16x16x32_bf16 v[46:49], v[134:137], v[192:195], v[46:49]
	v_mfma_f32_16x16x32_bf16 v[30:33], v[130:133], v[196:199], v[30:33]
	v_mfma_f32_16x16x32_bf16 v[30:33], v[134:137], v[200:203], v[30:33]
	v_mfma_f32_16x16x32_bf16 v[26:29], v[138:141], v[196:199], v[26:29]
	v_mfma_f32_16x16x32_bf16 v[26:29], v[142:145], v[200:203], v[26:29]
	v_mfma_f32_16x16x32_bf16 v[10:13], v[138:141], v[204:207], v[10:13]
	v_mfma_f32_16x16x32_bf16 v[10:13], v[142:145], v[208:211], v[10:13]
	s_waitcnt lgkmcnt(0)
	v_mfma_f32_16x16x32_bf16 v[14:17], v[130:133], v[204:207], v[14:17]
	v_mfma_f32_16x16x32_bf16 v[14:17], v[134:137], v[208:211], v[14:17]
	s_setprio 0
	s_setprio 1
	v_mfma_f32_16x16x32_bf16 v[54:57], v[150:153], v[168:171], v[54:57]
	v_mfma_f32_16x16x32_bf16 v[54:57], v[154:157], v[172:175], v[54:57]
	v_mfma_f32_16x16x32_bf16 v[50:53], v[158:161], v[168:171], v[50:53]
	v_mfma_f32_16x16x32_bf16 v[50:53], v[162:165], v[172:175], v[50:53]
	v_mfma_f32_16x16x32_bf16 v[34:37], v[158:161], v[188:191], v[34:37]
	v_mfma_f32_16x16x32_bf16 v[34:37], v[162:165], v[192:195], v[34:37]
	v_mfma_f32_16x16x32_bf16 v[38:41], v[150:153], v[188:191], v[38:41]
	v_mfma_f32_16x16x32_bf16 v[38:41], v[154:157], v[192:195], v[38:41]
	v_mfma_f32_16x16x32_bf16 v[22:25], v[150:153], v[196:199], v[22:25]
	v_mfma_f32_16x16x32_bf16 v[22:25], v[154:157], v[200:203], v[22:25]
	v_mfma_f32_16x16x32_bf16 v[18:21], v[158:161], v[196:199], v[18:21]
	v_mfma_f32_16x16x32_bf16 v[18:21], v[162:165], v[200:203], v[18:21]
	v_mfma_f32_16x16x32_bf16 v[2:5], v[158:161], v[204:207], v[2:5]
	v_mfma_f32_16x16x32_bf16 v[2:5], v[162:165], v[208:211], v[2:5]
	s_setprio 2
	s_barrier
	v_mfma_f32_16x16x32_bf16 v[6:9], v[150:153], v[204:207], v[6:9]
	v_mfma_f32_16x16x32_bf16 v[6:9], v[154:157], v[208:211], v[6:9]
	s_setprio 0
	s_add_i32 s69, s69, 2
	s_add_u32 s65, s65, 0x80000
	s_addc_u32 s66, s66, 0
	s_add_u32 s28, s28, 0x400000
	s_addc_u32 s29, s29, 0
	s_add_u32 s67, s67, 0x400000
	s_addc_u32 s68, s68, 0
	s_cmpk_gt_u32 s69, 0x53
	s_cbranch_scc0 .LBB0_2792
	v_mov_b32_e32 v174, v252
	v_mov_b32_e32 v175, v253
	v_mov_b32_e32 v210, v254
	v_mov_b32_e32 v211, v255
	s_and_b64 vcc, exec, s[8:9]
	s_cbranch_vccz .LBB0_2795
	s_barrier
